# write-through: all 154 global_store_dwordx4 nt -> sc1 (phase outputs leave L2 as they are stored; the grid barrier's write-back finds a clean L2)
# speedup vs baseline: 1.0130x; 1.0130x over previous
; __device__ __forceinline__ void titem_finish(const TItem& t, const f32x4 (&x)[16], const float (&sc)[16], LAS float* scr_f, int lane) {
;     ...
;         for (int e = 0; e < 4; ++e) inv[e] = 127.0f / fmaxf(__uint_as_float(t.cmax[n0 - t.noff + 4 * c + e]), 1e-30f);
; #pragma unroll
;         for (int p = 0; p < 4; ++p)
; #pragma unroll
;             for (int e = 0; e < 4; ++e) {
;                 unsigned w = 0;
; #pragma unroll
;                 for (int j = 0; j < 4; ++j) { const float v = __builtin_amdgcn_fmed3f(__builtin_rintf(x[4 * p + j][e] * sc[4 * p + j] * inv[e]), -127.f, 127.f); w |= ((unsigned)(int)v & 255u) << (8 * j); }
;                 scr[(4 * c + e) * 17 + 4 * p + r] = w;
.LBB0_168:
	s_abs_i32 s8, s86
	v_cvt_f32_u32_e32 v130, s8
	s_sub_i32 s9, 0, s8
	s_abs_i32 s7, s85
	s_xor_b32 s6, s85, s86
	v_rcp_iflag_f32_e32 v130, v130
	s_ashr_i32 s6, s6, 31
	v_cmp_eq_u32_e32 vcc, 0, v176
	v_mul_f32_e32 v130, 0x4f7ffffe, v130
	v_cvt_u32_f32_e32 v130, v130
	s_nop 0
	v_readfirstlane_b32 s47, v130
	s_mul_i32 s9, s9, s47
	s_mul_hi_u32 s9, s47, s9
	s_add_i32 s47, s47, s9
	s_mul_hi_u32 s9, s7, s47
	s_mul_i32 s47, s9, s8
	s_sub_i32 s7, s7, s47
	s_add_i32 s47, s9, 1
	s_sub_i32 s60, s7, s8
	s_cmp_ge_u32 s7, s8
	s_cselect_b32 s9, s47, s9
	s_cselect_b32 s7, s60, s7
	s_add_i32 s47, s9, 1
	s_cmp_ge_u32 s7, s8
	s_cselect_b32 s7, s47, s9
	s_xor_b32 s7, s7, s6
	s_sub_i32 s6, s7, s6
	s_mul_i32 s7, s6, s86
	s_sub_i32 s7, s85, s7
	s_lshl_b32 s66, s7, 6
	s_lshl_b32 s8, s6, 6
	s_add_i32 s60, s66, s46
	s_cbranch_vccnz .LBB0_189
	v_or_b32_e32 v130, s66, v195
	s_waitcnt lgkmcnt(0)
	v_ashrrev_i32_e32 v131, 31, v130
	v_lshl_add_u64 v[130:131], v[130:131], 2, s[42:43]
	global_load_dwordx4 v[208:211], v[130:131], off
	s_waitcnt vmcnt(9)
	v_mul_f32_e32 v212, v30, v143
	s_lshl_b32 s6, s6, 7
	s_and_b32 s6, s6, 0xfffff800
	s_ashr_i32 s9, s8, 31
	s_ashr_i32 s61, s60, 31
	s_waitcnt vmcnt(0)
	v_max_f32_e32 v130, v208, v208
	v_max_f32_e32 v130, 0xda24260, v130
	v_div_scale_f32 v131, s[62:63], v130, v130, s90
	v_rcp_f32_e32 v132, v131
	s_nop 0
	v_fma_f32 v133, -v131, v132, 1.0
	v_fmac_f32_e32 v132, v133, v132
	v_div_scale_f32 v133, vcc, s90, v130, s90
	v_mul_f32_e32 v157, v133, v132
	v_fma_f32 v159, -v131, v157, v133
	v_fmac_f32_e32 v157, v159, v132
	v_fma_f32 v131, -v131, v157, v133
	v_div_fmas_f32 v131, v131, v132, v157
	v_div_fixup_f32 v133, v131, v130, s90
	v_max_f32_e32 v130, v209, v209
	v_max_f32_e32 v130, 0xda24260, v130
	v_div_scale_f32 v131, s[62:63], v130, v130, s90
	v_rcp_f32_e32 v132, v131
	v_mul_f32_e32 v212, v212, v133
	v_rndne_f32_e32 v212, v212
	v_med3_f32 v212, v212, s91, v203
	v_fma_f32 v157, -v131, v132, 1.0
	v_fmac_f32_e32 v132, v157, v132
	v_div_scale_f32 v157, vcc, s90, v130, s90
	v_mul_f32_e32 v159, v157, v132
	v_fma_f32 v207, -v131, v159, v157
	v_fmac_f32_e32 v159, v207, v132
	v_fma_f32 v131, -v131, v159, v157
	v_div_fmas_f32 v131, v131, v132, v159
	v_div_fixup_f32 v132, v131, v130, s90
	v_max_f32_e32 v130, v210, v210
	v_max_f32_e32 v130, 0xda24260, v130
	v_div_scale_f32 v131, s[62:63], v130, v130, s90
	v_rcp_f32_e32 v157, v131
	v_mul_f32_e32 v210, v16, v139
	v_cvt_i32_f32_e32 v212, v212
	v_fma_f32 v159, -v131, v157, 1.0
	v_fmac_f32_e32 v157, v159, v157
	v_div_scale_f32 v159, vcc, s90, v130, s90
	v_mul_f32_e32 v207, v159, v157
	v_fma_f32 v208, -v131, v207, v159
	v_fmac_f32_e32 v207, v208, v157
	v_fma_f32 v131, -v131, v207, v159
	v_div_fmas_f32 v131, v131, v157, v207
	v_div_fixup_f32 v131, v131, v130, s90
	v_max_f32_e32 v130, v211, v211
	v_max_f32_e32 v130, 0xda24260, v130
	v_div_scale_f32 v157, s[62:63], v130, v130, s90
	v_rcp_f32_e32 v159, v157
	v_mul_f32_e32 v210, v210, v131
	v_rndne_f32_e32 v210, v210
	v_med3_f32 v210, v210, s91, v203
	v_fma_f32 v207, -v157, v159, 1.0
	v_fmac_f32_e32 v159, v207, v159
	v_div_scale_f32 v207, vcc, s90, v130, s90
	v_mul_f32_e32 v208, v207, v159
	v_fma_f32 v209, -v157, v208, v207
	v_fmac_f32_e32 v208, v209, v159
	v_fma_f32 v157, -v157, v208, v207
	v_div_fmas_f32 v157, v157, v159, v208
	v_mul_f32_e32 v159, v6, v137
	v_div_fixup_f32 v130, v157, v130, s90
	v_mul_f32_e32 v157, v2, v136
	v_mul_f32_e32 v159, v159, v133
	v_mul_f32_e32 v207, v10, v138
	v_mul_f32_e32 v208, v14, v139
	v_mul_f32_e32 v157, v157, v133
	v_rndne_f32_e32 v159, v159
	v_mul_f32_e32 v207, v207, v133
	v_mul_f32_e32 v208, v208, v133
	v_rndne_f32_e32 v157, v157
	v_med3_f32 v159, v159, s91, v203
	v_rndne_f32_e32 v207, v207
	v_rndne_f32_e32 v208, v208
	v_med3_f32 v157, v157, s91, v203
	v_cvt_i32_f32_e32 v159, v159
	v_med3_f32 v207, v207, s91, v203
	v_med3_f32 v208, v208, s91, v203
	v_cvt_i32_f32_e32 v157, v157
	v_cvt_i32_f32_sdwa v207, v207 dst_sel:WORD_1 dst_unused:UNUSED_PAD src0_sel:DWORD
	v_cvt_i32_f32_e32 v208, v208
	v_lshlrev_b32_e32 v159, 8, v159
	v_and_b32_e32 v159, 0xff00, v159
	v_and_b32_e32 v207, 0xff0000, v207
	v_perm_b32 v157, v208, v157, s92
	v_or3_b32 v157, v157, v159, v207
	v_mul_f32_e32 v207, v7, v137
	v_mul_f32_e32 v159, v3, v136
	v_mul_f32_e32 v207, v207, v132
	v_mul_f32_e32 v208, v11, v138
	v_mul_f32_e32 v209, v15, v139
	v_mul_f32_e32 v159, v159, v132
	v_rndne_f32_e32 v207, v207
	v_mul_f32_e32 v208, v208, v132
	v_mul_f32_e32 v209, v209, v132
	v_rndne_f32_e32 v159, v159
	v_med3_f32 v207, v207, s91, v203
	v_rndne_f32_e32 v208, v208
	v_rndne_f32_e32 v209, v209
	v_med3_f32 v159, v159, s91, v203
	v_cvt_i32_f32_e32 v207, v207
	v_med3_f32 v208, v208, s91, v203
	v_med3_f32 v209, v209, s91, v203
	v_cvt_i32_f32_e32 v159, v159
	v_cvt_i32_f32_sdwa v208, v208 dst_sel:WORD_1 dst_unused:UNUSED_PAD src0_sel:DWORD
	v_cvt_i32_f32_e32 v209, v209
	v_lshlrev_b32_e32 v207, 8, v207
	v_and_b32_e32 v207, 0xff00, v207
	v_and_b32_e32 v208, 0xff0000, v208
	v_perm_b32 v159, v209, v159, s92
	v_or3_b32 v159, v159, v207, v208
	v_mul_f32_e32 v208, v8, v137
	v_mul_f32_e32 v207, v4, v136
	v_mul_f32_e32 v208, v208, v131
	v_mul_f32_e32 v209, v12, v138
	v_mul_f32_e32 v207, v207, v131
	v_rndne_f32_e32 v208, v208
	v_mul_f32_e32 v209, v209, v131
	v_rndne_f32_e32 v207, v207
	v_med3_f32 v208, v208, s91, v203
	v_rndne_f32_e32 v209, v209
	v_med3_f32 v207, v207, s91, v203
	v_cvt_i32_f32_e32 v208, v208
	v_med3_f32 v209, v209, s91, v203
	v_cvt_i32_f32_e32 v207, v207
	v_cvt_i32_f32_sdwa v209, v209 dst_sel:WORD_1 dst_unused:UNUSED_PAD src0_sel:DWORD
	v_cvt_i32_f32_e32 v210, v210
	v_lshlrev_b32_e32 v208, 8, v208
	v_and_b32_e32 v208, 0xff00, v208
	v_and_b32_e32 v209, 0xff0000, v209
; __device__ __forceinline__ void titem_finish(const TItem& t, const f32x4 (&x)[16], const float (&sc)[16], LAS float* scr_f, int lane) {
;     ...
;         for (int p = 0; p < 4; ++p)
; #pragma unroll
;             for (int e = 0; e < 4; ++e) {
;                 unsigned w = 0;
; #pragma unroll
;                 for (int j = 0; j < 4; ++j) { const float v = __builtin_amdgcn_fmed3f(__builtin_rintf(x[4 * p + j][e] * sc[4 * p + j] * inv[e]), -127.f, 127.f); w |= ((unsigned)(int)v & 255u) << (8 * j); }
;                 scr[(4 * c + e) * 17 + 4 * p + r] = w;
	v_perm_b32 v207, v210, v207, s92
	v_or3_b32 v207, v207, v208, v209
	v_mul_f32_e32 v209, v9, v137
	v_mul_f32_e32 v208, v5, v136
	v_mul_f32_e32 v209, v209, v130
	v_mul_f32_e32 v210, v13, v138
	v_mul_f32_e32 v211, v17, v139
	v_mul_f32_e32 v208, v208, v130
	v_rndne_f32_e32 v209, v209
	v_mul_f32_e32 v210, v210, v130
	v_mul_f32_e32 v211, v211, v130
	v_rndne_f32_e32 v208, v208
	v_med3_f32 v209, v209, s91, v203
	v_rndne_f32_e32 v210, v210
	v_rndne_f32_e32 v211, v211
	v_med3_f32 v208, v208, s91, v203
	v_cvt_i32_f32_e32 v209, v209
	v_med3_f32 v210, v210, s91, v203
	v_med3_f32 v211, v211, s91, v203
	v_cvt_i32_f32_e32 v208, v208
	v_cvt_i32_f32_sdwa v210, v210 dst_sel:WORD_1 dst_unused:UNUSED_PAD src0_sel:DWORD
	v_cvt_i32_f32_e32 v211, v211
	v_lshlrev_b32_e32 v209, 8, v209
	v_and_b32_e32 v209, 0xff00, v209
	v_and_b32_e32 v210, 0xff0000, v210
	v_perm_b32 v208, v211, v208, s92
	v_or3_b32 v208, v208, v209, v210
	v_mul_f32_e32 v210, v22, v141
	v_mul_f32_e32 v209, v18, v140
	v_mul_f32_e32 v210, v210, v133
	v_mul_f32_e32 v211, v26, v142
	v_mul_f32_e32 v209, v209, v133
	v_rndne_f32_e32 v210, v210
	v_mul_f32_e32 v211, v211, v133
	v_rndne_f32_e32 v209, v209
	v_med3_f32 v210, v210, s91, v203
	v_rndne_f32_e32 v211, v211
	v_med3_f32 v209, v209, s91, v203
	v_cvt_i32_f32_e32 v210, v210
	v_med3_f32 v211, v211, s91, v203
	v_cvt_i32_f32_e32 v209, v209
	v_cvt_i32_f32_sdwa v211, v211 dst_sel:WORD_1 dst_unused:UNUSED_PAD src0_sel:DWORD
	v_lshlrev_b32_e32 v210, 8, v210
	v_and_b32_e32 v210, 0xff00, v210
	v_perm_b32 v209, v212, v209, s92
	v_and_b32_e32 v211, 0xff0000, v211
	v_or3_b32 v209, v209, v210, v211
	ds_write2_b32 v200, v157, v209 offset1:4
	v_mul_f32_e32 v209, v23, v141
	v_mul_f32_e32 v157, v19, v140
	v_mul_f32_e32 v209, v209, v132
	v_mul_f32_e32 v210, v27, v142
	v_mul_f32_e32 v211, v31, v143
	v_mul_f32_e32 v157, v157, v132
	v_rndne_f32_e32 v209, v209
	v_mul_f32_e32 v210, v210, v132
	v_mul_f32_e32 v211, v211, v132
	v_rndne_f32_e32 v157, v157
	v_med3_f32 v209, v209, s91, v203
	v_rndne_f32_e32 v210, v210
	v_rndne_f32_e32 v211, v211
	v_med3_f32 v157, v157, s91, v203
	v_cvt_i32_f32_e32 v209, v209
	v_med3_f32 v210, v210, s91, v203
	v_med3_f32 v211, v211, s91, v203
	v_cvt_i32_f32_e32 v157, v157
	v_cvt_i32_f32_sdwa v210, v210 dst_sel:WORD_1 dst_unused:UNUSED_PAD src0_sel:DWORD
	v_cvt_i32_f32_e32 v211, v211
	v_lshlrev_b32_e32 v209, 8, v209
	v_and_b32_e32 v209, 0xff00, v209
	v_and_b32_e32 v210, 0xff0000, v210
	v_perm_b32 v157, v211, v157, s92
	v_or3_b32 v157, v157, v209, v210
	ds_write2_b32 v200, v159, v157 offset0:17 offset1:21
	v_mul_f32_e32 v159, v24, v141
	v_mul_f32_e32 v157, v20, v140
	v_mul_f32_e32 v159, v159, v131
	v_mul_f32_e32 v209, v28, v142
	v_mul_f32_e32 v210, v32, v143
	v_mul_f32_e32 v157, v157, v131
	v_rndne_f32_e32 v159, v159
	v_mul_f32_e32 v209, v209, v131
	v_mul_f32_e32 v210, v210, v131
	v_rndne_f32_e32 v157, v157
	v_med3_f32 v159, v159, s91, v203
	v_rndne_f32_e32 v209, v209
	v_rndne_f32_e32 v210, v210
	v_med3_f32 v157, v157, s91, v203
	v_cvt_i32_f32_e32 v159, v159
	v_med3_f32 v209, v209, s91, v203
	v_med3_f32 v210, v210, s91, v203
	v_cvt_i32_f32_e32 v157, v157
	v_cvt_i32_f32_sdwa v209, v209 dst_sel:WORD_1 dst_unused:UNUSED_PAD src0_sel:DWORD
	v_cvt_i32_f32_e32 v210, v210
	v_lshlrev_b32_e32 v159, 8, v159
	v_and_b32_e32 v159, 0xff00, v159
	v_and_b32_e32 v209, 0xff0000, v209
	v_perm_b32 v157, v210, v157, s92
	v_or3_b32 v157, v157, v159, v209
	v_mul_f32_e32 v159, v25, v141
	ds_write2_b32 v200, v207, v157 offset0:34 offset1:38
	v_mul_f32_e32 v157, v21, v140
	v_mul_f32_e32 v159, v159, v130
	v_mul_f32_e32 v207, v29, v142
	v_mul_f32_e32 v209, v33, v143
	v_mul_f32_e32 v157, v157, v130
	v_rndne_f32_e32 v159, v159
	v_mul_f32_e32 v207, v207, v130
	v_mul_f32_e32 v209, v209, v130
	v_rndne_f32_e32 v157, v157
	v_med3_f32 v159, v159, s91, v203
	v_rndne_f32_e32 v207, v207
	v_rndne_f32_e32 v209, v209
	v_med3_f32 v157, v157, s91, v203
	v_cvt_i32_f32_e32 v159, v159
	v_med3_f32 v207, v207, s91, v203
	v_med3_f32 v209, v209, s91, v203
	v_cvt_i32_f32_e32 v157, v157
	v_cvt_i32_f32_sdwa v207, v207 dst_sel:WORD_1 dst_unused:UNUSED_PAD src0_sel:DWORD
	v_cvt_i32_f32_e32 v209, v209
	v_lshlrev_b32_e32 v159, 8, v159
	v_and_b32_e32 v159, 0xff00, v159
	v_and_b32_e32 v207, 0xff0000, v207
	v_perm_b32 v157, v209, v157, s92
	v_or3_b32 v157, v157, v159, v207
	v_mul_f32_e32 v159, v38, v145
	ds_write2_b32 v200, v208, v157 offset0:51 offset1:55
	v_mul_f32_e32 v157, v34, v144
	v_mul_f32_e32 v159, v159, v133
	v_mul_f32_e32 v207, v42, v146
	v_mul_f32_e32 v208, v46, v147
	v_mul_f32_e32 v157, v157, v133
	v_rndne_f32_e32 v159, v159
	v_mul_f32_e32 v207, v207, v133
	v_mul_f32_e32 v208, v208, v133
	v_rndne_f32_e32 v157, v157
	v_med3_f32 v159, v159, s91, v203
	v_rndne_f32_e32 v207, v207
	v_rndne_f32_e32 v208, v208
	v_med3_f32 v157, v157, s91, v203
	v_cvt_i32_f32_e32 v159, v159
	v_med3_f32 v207, v207, s91, v203
	v_med3_f32 v208, v208, s91, v203
	v_cvt_i32_f32_e32 v157, v157
	v_cvt_i32_f32_sdwa v207, v207 dst_sel:WORD_1 dst_unused:UNUSED_PAD src0_sel:DWORD
	v_cvt_i32_f32_e32 v208, v208
	v_lshlrev_b32_e32 v159, 8, v159
	v_and_b32_e32 v159, 0xff00, v159
	v_and_b32_e32 v207, 0xff0000, v207
	v_perm_b32 v157, v208, v157, s92
	v_or3_b32 v157, v157, v159, v207
	v_mul_f32_e32 v207, v39, v145
	v_mul_f32_e32 v159, v35, v144
	v_mul_f32_e32 v207, v207, v132
	v_mul_f32_e32 v208, v43, v146
	v_mul_f32_e32 v209, v47, v147
	v_mul_f32_e32 v159, v159, v132
	v_rndne_f32_e32 v207, v207
	v_mul_f32_e32 v208, v208, v132
	v_mul_f32_e32 v209, v209, v132
	v_rndne_f32_e32 v159, v159
	v_med3_f32 v207, v207, s91, v203
	v_rndne_f32_e32 v208, v208
	v_rndne_f32_e32 v209, v209
	v_med3_f32 v159, v159, s91, v203
	v_cvt_i32_f32_e32 v207, v207
; #define LAS __attribute__((address_space(3)))
; #define LDS_WAIT() asm volatile("s_waitcnt lgkmcnt(0)" ::: "memory")
; __device__ __forceinline__ void titem_finish(const TItem& t, const f32x4 (&x)[16], const float (&sc)[16], LAS float* scr_f, int lane) {
;     ...
;                 for (int j = 0; j < 4; ++j) { const float v = __builtin_amdgcn_fmed3f(__builtin_rintf(x[4 * p + j][e] * sc[4 * p + j] * inv[e]), -127.f, 127.f); w |= ((unsigned)(int)v & 255u) << (8 * j); }
;                 scr[(4 * c + e) * 17 + 4 * p + r] = w;
;             }
;         LDS_WAIT(); asm volatile("" ::: "memory");
;         const int q4 = lane & 3;
; #pragma unroll
;         for (int j = 0; j < 4; ++j) { const int n = (lane >> 2) + 16 * j; const LAS unsigned* s = scr + n * 17 + 4 * q4;
;             u32x4 o; o.x = s[0]; o.y = s[1]; o.z = s[2]; o.w = s[3];
;             __builtin_nontemporal_store(o, (u32x4*)((unsigned char*)t.WT + (size_t)(n0 - t.noff + n) * t.K + k0 + 16 * q4));
	v_med3_f32 v208, v208, s91, v203
	v_med3_f32 v209, v209, s91, v203
	v_cvt_i32_f32_e32 v159, v159
	v_cvt_i32_f32_sdwa v208, v208 dst_sel:WORD_1 dst_unused:UNUSED_PAD src0_sel:DWORD
	v_cvt_i32_f32_e32 v209, v209
	v_lshlrev_b32_e32 v207, 8, v207
	v_and_b32_e32 v207, 0xff00, v207
	v_and_b32_e32 v208, 0xff0000, v208
	v_perm_b32 v159, v209, v159, s92
	v_or3_b32 v159, v159, v207, v208
	v_mul_f32_e32 v208, v40, v145
	v_mul_f32_e32 v207, v36, v144
	v_mul_f32_e32 v208, v208, v131
	v_mul_f32_e32 v209, v44, v146
	v_mul_f32_e32 v210, v48, v147
	v_mul_f32_e32 v207, v207, v131
	v_rndne_f32_e32 v208, v208
	v_mul_f32_e32 v209, v209, v131
	v_mul_f32_e32 v210, v210, v131
	v_rndne_f32_e32 v207, v207
	v_med3_f32 v208, v208, s91, v203
	v_rndne_f32_e32 v209, v209
	v_rndne_f32_e32 v210, v210
	v_med3_f32 v207, v207, s91, v203
	v_cvt_i32_f32_e32 v208, v208
	v_med3_f32 v209, v209, s91, v203
	v_med3_f32 v210, v210, s91, v203
	v_cvt_i32_f32_e32 v207, v207
	v_cvt_i32_f32_sdwa v209, v209 dst_sel:WORD_1 dst_unused:UNUSED_PAD src0_sel:DWORD
	v_cvt_i32_f32_e32 v210, v210
	v_lshlrev_b32_e32 v208, 8, v208
	v_and_b32_e32 v208, 0xff00, v208
	v_and_b32_e32 v209, 0xff0000, v209
	v_perm_b32 v207, v210, v207, s92
	v_or3_b32 v207, v207, v208, v209
	v_mul_f32_e32 v209, v41, v145
	v_mul_f32_e32 v208, v37, v144
	v_mul_f32_e32 v209, v209, v130
	v_mul_f32_e32 v210, v45, v146
	v_mul_f32_e32 v211, v49, v147
	v_mul_f32_e32 v208, v208, v130
	v_rndne_f32_e32 v209, v209
	v_mul_f32_e32 v210, v210, v130
	v_mul_f32_e32 v211, v211, v130
	v_rndne_f32_e32 v208, v208
	v_med3_f32 v209, v209, s91, v203
	v_rndne_f32_e32 v210, v210
	v_rndne_f32_e32 v211, v211
	v_med3_f32 v208, v208, s91, v203
	v_cvt_i32_f32_e32 v209, v209
	v_med3_f32 v210, v210, s91, v203
	v_med3_f32 v211, v211, s91, v203
	v_cvt_i32_f32_e32 v208, v208
	v_cvt_i32_f32_sdwa v210, v210 dst_sel:WORD_1 dst_unused:UNUSED_PAD src0_sel:DWORD
	v_cvt_i32_f32_e32 v211, v211
	v_lshlrev_b32_e32 v209, 8, v209
	v_and_b32_e32 v209, 0xff00, v209
	v_and_b32_e32 v210, 0xff0000, v210
	v_perm_b32 v208, v211, v208, s92
	v_or3_b32 v208, v208, v209, v210
	v_mul_f32_e32 v210, v54, v149
	v_mul_f32_e32 v209, v50, v148
	v_mul_f32_e32 v210, v210, v133
	v_mul_f32_e32 v211, v58, v150
	v_mul_f32_e32 v212, v62, v151
	v_mul_f32_e32 v209, v209, v133
	v_rndne_f32_e32 v210, v210
	v_mul_f32_e32 v211, v211, v133
	v_mul_f32_e32 v133, v212, v133
	v_rndne_f32_e32 v209, v209
	v_med3_f32 v210, v210, s91, v203
	v_rndne_f32_e32 v211, v211
	v_rndne_f32_e32 v133, v133
	v_med3_f32 v209, v209, s91, v203
	v_cvt_i32_f32_e32 v210, v210
	v_med3_f32 v211, v211, s91, v203
	v_med3_f32 v133, v133, s91, v203
	v_cvt_i32_f32_e32 v209, v209
	v_cvt_i32_f32_sdwa v211, v211 dst_sel:WORD_1 dst_unused:UNUSED_PAD src0_sel:DWORD
	v_cvt_i32_f32_e32 v133, v133
	v_lshlrev_b32_e32 v210, 8, v210
	v_and_b32_e32 v210, 0xff00, v210
	v_and_b32_e32 v211, 0xff0000, v211
	v_perm_b32 v133, v133, v209, s92
	v_or3_b32 v133, v133, v210, v211
	ds_write2_b32 v200, v157, v133 offset0:8 offset1:12
	v_mul_f32_e32 v157, v55, v149
	v_mul_f32_e32 v133, v51, v148
	v_mul_f32_e32 v157, v157, v132
	v_mul_f32_e32 v209, v59, v150
	v_mul_f32_e32 v210, v63, v151
	v_mul_f32_e32 v133, v133, v132
	v_rndne_f32_e32 v157, v157
	v_mul_f32_e32 v209, v209, v132
	v_mul_f32_e32 v132, v210, v132
	v_rndne_f32_e32 v133, v133
	v_med3_f32 v157, v157, s91, v203
	v_rndne_f32_e32 v209, v209
	v_rndne_f32_e32 v132, v132
	v_med3_f32 v133, v133, s91, v203
	v_cvt_i32_f32_e32 v157, v157
	v_med3_f32 v209, v209, s91, v203
	v_med3_f32 v132, v132, s91, v203
	v_cvt_i32_f32_e32 v133, v133
	v_cvt_i32_f32_sdwa v209, v209 dst_sel:WORD_1 dst_unused:UNUSED_PAD src0_sel:DWORD
	v_cvt_i32_f32_e32 v132, v132
	v_lshlrev_b32_e32 v157, 8, v157
	v_and_b32_e32 v157, 0xff00, v157
	v_and_b32_e32 v209, 0xff0000, v209
	v_perm_b32 v132, v132, v133, s92
	v_or3_b32 v132, v132, v157, v209
	v_mul_f32_e32 v133, v56, v149
	ds_write2_b32 v200, v159, v132 offset0:25 offset1:29
	v_mul_f32_e32 v132, v52, v148
	v_mul_f32_e32 v133, v133, v131
	v_mul_f32_e32 v157, v60, v150
	v_mul_f32_e32 v159, v64, v151
	v_mul_f32_e32 v132, v132, v131
	v_rndne_f32_e32 v133, v133
	v_mul_f32_e32 v157, v157, v131
	v_mul_f32_e32 v131, v159, v131
	v_rndne_f32_e32 v132, v132
	v_med3_f32 v133, v133, s91, v203
	v_rndne_f32_e32 v157, v157
	v_rndne_f32_e32 v131, v131
	v_med3_f32 v132, v132, s91, v203
	v_cvt_i32_f32_e32 v133, v133
	v_med3_f32 v157, v157, s91, v203
	v_med3_f32 v131, v131, s91, v203
	v_cvt_i32_f32_e32 v132, v132
	v_cvt_i32_f32_sdwa v157, v157 dst_sel:WORD_1 dst_unused:UNUSED_PAD src0_sel:DWORD
	v_cvt_i32_f32_e32 v131, v131
	v_lshlrev_b32_e32 v133, 8, v133
	v_and_b32_e32 v133, 0xff00, v133
	v_and_b32_e32 v157, 0xff0000, v157
	v_perm_b32 v131, v131, v132, s92
	v_or3_b32 v131, v131, v133, v157
	v_mul_f32_e32 v132, v57, v149
	ds_write2_b32 v200, v207, v131 offset0:42 offset1:46
	v_mul_f32_e32 v131, v53, v148
	v_mul_f32_e32 v132, v132, v130
	v_mul_f32_e32 v133, v61, v150
	v_mul_f32_e32 v157, v65, v151
	v_mul_f32_e32 v131, v131, v130
	v_rndne_f32_e32 v132, v132
	v_mul_f32_e32 v133, v133, v130
	v_mul_f32_e32 v130, v157, v130
	v_rndne_f32_e32 v131, v131
	v_med3_f32 v132, v132, s91, v203
	v_rndne_f32_e32 v133, v133
	v_rndne_f32_e32 v130, v130
	v_med3_f32 v131, v131, s91, v203
	v_cvt_i32_f32_e32 v132, v132
	v_med3_f32 v133, v133, s91, v203
	v_med3_f32 v130, v130, s91, v203
	v_cvt_i32_f32_e32 v131, v131
	v_cvt_i32_f32_sdwa v133, v133 dst_sel:WORD_1 dst_unused:UNUSED_PAD src0_sel:DWORD
	v_cvt_i32_f32_e32 v130, v130
	v_lshlrev_b32_e32 v132, 8, v132
	v_and_b32_e32 v132, 0xff00, v132
	v_and_b32_e32 v133, 0xff0000, v133
	v_perm_b32 v130, v130, v131, s92
	v_or3_b32 v130, v130, v132, v133
	ds_write2_b32 v200, v208, v130 offset0:59 offset1:63
	s_waitcnt lgkmcnt(0)
	v_add_u32_e32 v157, s66, v152
	v_mov_b64_e32 v[208:209], s[40:41]
	s_add_i32 s62, s6, 0x800
	v_mad_u64_u32 v[208:209], s[6:7], v157, s87, v[208:209]
	ds_read2_b32 v[130:131], v204 offset1:1
	ds_read2_b32 v[132:133], v204 offset0:2 offset1:3
	v_ashrrev_i32_e32 v159, 31, v157
	v_mov_b32_e32 v210, v209
	s_ashr_i32 s63, s62, 31
	v_mad_u64_u32 v[210:211], s[6:7], v159, s87, v[210:211]
	v_mov_b32_e32 v209, v210
	s_cmp_lg_u64 s[44:45], 0
	v_lshl_add_u64 v[208:209], v[208:209], 0, s[8:9]
	s_cselect_b64 s[64:65], -1, 0
	v_lshl_add_u64 v[208:209], v[208:209], 0, v[154:155]
	s_and_b64 vcc, exec, s[64:65]
	v_mbcnt_hi_u32_b32 v157, -1, v205
	s_waitcnt lgkmcnt(0)
	global_store_dwordx4 v[208:209], v[130:133], off sc1
	s_cbranch_vccz .LBB0_190
; #define LAS __attribute__((address_space(3)))
; __device__ __forceinline__ void titem_finish(const TItem& t, const f32x4 (&x)[16], const float (&sc)[16], LAS float* scr_f, int lane) {
;     ...
;         for (int j = 0; j < 4; ++j) { const int n = (lane >> 2) + 16 * j; const LAS unsigned* s = scr + n * 17 + 4 * q4;
;             u32x4 o; o.x = s[0]; o.y = s[1]; o.z = s[2]; o.w = s[3];
;             __builtin_nontemporal_store(o, (u32x4*)((unsigned char*)t.WT + (size_t)(n0 - t.noff + n) * t.K + k0 + 16 * q4));
;             if (t.csum) {
;                 int cs = __builtin_amdgcn_sdot4((int)o.x, 0x01010101, 0, false); cs = __builtin_amdgcn_sdot4((int)o.y, 0x01010101, cs, false); cs = __builtin_amdgcn_sdot4((int)o.z, 0x01010101, cs, false); cs = __builtin_amdgcn_sdot4((int)o.w, 0x01010101, cs, false);
;                 cs += __shfl_xor(cs, 1); cs += __shfl_xor(cs, 2);
;                 if (q4 == 0) { atomicAdd(t.csum + n0 - t.noff + n, cs * 128); atomicAdd(t.csum + (1 + (k0 >> 10)) * DM + n0 - t.noff + n, cs * 128); }
;             } }
	v_mov_b32_e32 v159, v135
	v_dot4c_i32_i8_e32 v159, 0x1010101, v130
	v_dot4c_i32_i8_e32 v159, 0x1010101, v131
	v_dot4c_i32_i8_e32 v159, 0x1010101, v132
	v_and_b32_e32 v131, 64, v157
	v_dot4c_i32_i8_e32 v159, 0x1010101, v133
	v_xor_b32_e32 v130, 1, v157
	v_add_u32_e32 v133, 64, v131
	v_cmp_lt_i32_e32 vcc, v130, v133
	s_nop 1
	v_cndmask_b32_e32 v130, v157, v130, vcc
	v_lshlrev_b32_e32 v131, 2, v130
	ds_bpermute_b32 v130, v131, v159
	s_waitcnt lgkmcnt(0)
	v_add_u32_e32 v132, v130, v159
	v_xor_b32_e32 v130, 2, v157
	v_cmp_lt_i32_e32 vcc, v130, v133
	s_nop 1
	v_cndmask_b32_e32 v130, v157, v130, vcc
	v_lshlrev_b32_e32 v130, 2, v130
	ds_bpermute_b32 v133, v130, v132
	s_and_saveexec_b64 s[6:7], s[4:5]
	s_cbranch_execz .LBB0_172
	s_lshl_b64 s[68:69], s[60:61], 2
	s_add_u32 s67, s44, s68
	s_mov_b32 s47, s49
	s_addc_u32 vcc_hi, s45, s69
	s_lshl_b64 s[70:71], s[46:47], 2
	s_sub_u32 vcc_lo, s67, s70
	s_subb_u32 vcc_hi, vcc_hi, s71
	v_lshlrev_b64 v[208:209], 2, v[152:153]
	v_lshl_add_u64 v[210:211], vcc, 0, v[208:209]
	s_lshl_b64 vcc, s[62:63], 2
	s_add_u32 s47, s44, vcc_lo
	s_addc_u32 s67, s45, vcc_hi
	s_add_u32 s47, s47, s68
	s_addc_u32 s67, s67, s69
	s_sub_u32 s68, s47, s70
	s_waitcnt lgkmcnt(0)
	v_add_lshl_u32 v159, v132, v133, 7
	s_subb_u32 s69, s67, s71
	global_atomic_add v[210:211], v159, off
	v_lshl_add_u64 v[132:133], s[68:69], 0, v[208:209]
	global_atomic_add v[132:133], v159, off
.LBB0_172:
	s_or_b64 exec, exec, s[6:7]
	v_add_u32_e32 v132, 0x440, v204
	ds_read2_b32 v[208:209], v132 offset1:1
	v_add_u32_e32 v132, 0x448, v204
	ds_read2_b32 v[210:211], v132 offset1:1
	v_add_u32_e32 v159, s66, v196
	s_waitcnt lgkmcnt(2)
	v_mov_b64_e32 v[132:133], s[40:41]
	v_mad_u64_u32 v[132:133], s[6:7], v159, s87, v[132:133]
	v_ashrrev_i32_e32 v207, 31, v159
	v_mov_b32_e32 v212, v133
	v_mad_u64_u32 v[212:213], s[6:7], v207, s87, v[212:213]
	v_mov_b32_e32 v133, v212
	v_lshl_add_u64 v[132:133], v[132:133], 0, s[8:9]
	v_lshl_add_u64 v[132:133], v[132:133], 0, v[154:155]
	s_waitcnt lgkmcnt(0)
	global_store_dwordx4 v[132:133], v[208:211], off sc1
	v_mov_b32_e32 v132, v135
	v_dot4c_i32_i8_e32 v132, 0x1010101, v208
	v_dot4c_i32_i8_e32 v132, 0x1010101, v209
	v_dot4c_i32_i8_e32 v132, 0x1010101, v210
	v_dot4c_i32_i8_e32 v132, 0x1010101, v211
	s_nop 2
	ds_bpermute_b32 v131, v131, v132
	s_waitcnt lgkmcnt(0)
	v_add_u32_e32 v131, v131, v132
	ds_bpermute_b32 v130, v130, v131
	s_and_saveexec_b64 s[6:7], s[4:5]
	s_cbranch_execz .LBB0_174
	s_lshl_b64 s[68:69], s[60:61], 2
	s_add_u32 s67, s44, s68
	s_mov_b32 s47, s49
	s_addc_u32 vcc_hi, s45, s69
	s_lshl_b64 s[70:71], s[46:47], 2
	s_sub_u32 vcc_lo, s67, s70
	s_subb_u32 vcc_hi, vcc_hi, s71
	v_lshlrev_b64 v[132:133], 2, v[152:153]
	v_lshl_add_u64 v[208:209], vcc, 0, v[132:133]
	s_lshl_b64 vcc, s[62:63], 2
	s_add_u32 s47, s44, vcc_lo
	s_addc_u32 s67, s45, vcc_hi
	s_add_u32 s47, s47, s68
	s_addc_u32 s67, s67, s69
	s_sub_u32 s68, s47, s70
	s_waitcnt lgkmcnt(0)
	v_add_lshl_u32 v159, v131, v130, 7
	s_subb_u32 s69, s67, s71
	global_atomic_add v[208:209], v159, off offset:64
	v_lshl_add_u64 v[130:131], s[68:69], 0, v[132:133]
	global_atomic_add v[130:131], v159, off offset:64

; #define LAS __attribute__((address_space(3)))
; __device__ __forceinline__ void titem_finish(const TItem& t, const f32x4 (&x)[16], const float (&sc)[16], LAS float* scr_f, int lane) {
;     ...
;         for (int j = 0; j < 4; ++j) { const int n = (lane >> 2) + 16 * j; const LAS unsigned* s = scr + n * 17 + 4 * q4;
;             u32x4 o; o.x = s[0]; o.y = s[1]; o.z = s[2]; o.w = s[3];
;             __builtin_nontemporal_store(o, (u32x4*)((unsigned char*)t.WT + (size_t)(n0 - t.noff + n) * t.K + k0 + 16 * q4));
;             if (t.csum) {
;                 int cs = __builtin_amdgcn_sdot4((int)o.x, 0x01010101, 0, false); cs = __builtin_amdgcn_sdot4((int)o.y, 0x01010101, cs, false); cs = __builtin_amdgcn_sdot4((int)o.z, 0x01010101, cs, false); cs = __builtin_amdgcn_sdot4((int)o.w, 0x01010101, cs, false);
;                 cs += __shfl_xor(cs, 1); cs += __shfl_xor(cs, 2);
;                 if (q4 == 0) { atomicAdd(t.csum + n0 - t.noff + n, cs * 128); atomicAdd(t.csum + (1 + (k0 >> 10)) * DM + n0 - t.noff + n, cs * 128); }
;             } }
.LBB0_175:
	v_add_u32_e32 v159, s66, v196
	v_mov_b64_e32 v[208:209], s[40:41]
	s_waitcnt lgkmcnt(0)
	v_add_u32_e32 v130, 0x440, v204
	v_add_u32_e32 v132, 0x448, v204
	v_mad_u64_u32 v[208:209], s[6:7], v159, s87, v[208:209]
	ds_read2_b32 v[130:131], v130 offset1:1
	ds_read2_b32 v[132:133], v132 offset1:1
	v_ashrrev_i32_e32 v207, 31, v159
	v_mov_b32_e32 v210, v209
	v_mad_u64_u32 v[210:211], s[6:7], v207, s87, v[210:211]
	v_mov_b32_e32 v209, v210
	v_lshl_add_u64 v[208:209], v[208:209], 0, s[8:9]
	v_lshl_add_u64 v[208:209], v[208:209], 0, v[154:155]
	s_waitcnt lgkmcnt(0)
	global_store_dwordx4 v[208:209], v[130:133], off sc1
.LBB0_176:
	v_add_u32_e32 v159, s66, v197
	v_mov_b64_e32 v[208:209], s[40:41]
	s_waitcnt lgkmcnt(0)
	v_add_u32_e32 v130, 0x880, v204
	v_add_u32_e32 v132, 0x888, v204
	v_mad_u64_u32 v[208:209], s[6:7], v159, s87, v[208:209]
	ds_read2_b32 v[130:131], v130 offset1:1
	ds_read2_b32 v[132:133], v132 offset1:1
	v_ashrrev_i32_e32 v207, 31, v159
	v_mov_b32_e32 v210, v209
	v_mad_u64_u32 v[210:211], s[6:7], v207, s87, v[210:211]
	v_mov_b32_e32 v209, v210
	v_lshl_add_u64 v[208:209], v[208:209], 0, s[8:9]
	v_cndmask_b32_e64 v159, 0, 1, s[64:65]
	v_lshl_add_u64 v[208:209], v[208:209], 0, v[154:155]
	v_cmp_ne_u32_e64 s[6:7], 1, v159
	s_andn2_b64 vcc, exec, s[64:65]
	s_waitcnt lgkmcnt(0)
	global_store_dwordx4 v[208:209], v[130:133], off sc1
	s_cbranch_vccnz .LBB0_191
	v_mov_b32_e32 v208, v135
	v_dot4c_i32_i8_e32 v208, 0x1010101, v130
	v_and_b32_e32 v130, 64, v157
	v_xor_b32_e32 v207, 1, v157
	v_add_u32_e32 v159, 64, v130
	v_dot4c_i32_i8_e32 v208, 0x1010101, v131
	v_cmp_lt_i32_e32 vcc, v207, v159
	v_dot4c_i32_i8_e32 v208, 0x1010101, v132
	v_dot4c_i32_i8_e32 v208, 0x1010101, v133
	v_cndmask_b32_e32 v130, v157, v207, vcc
	v_lshlrev_b32_e32 v130, 2, v130
	s_nop 0
	ds_bpermute_b32 v130, v130, v208
	s_waitcnt lgkmcnt(0)
	v_add_u32_e32 v130, v130, v208
	v_xor_b32_e32 v208, 2, v157
	v_cmp_lt_i32_e32 vcc, v208, v159
	s_nop 1
	v_cndmask_b32_e32 v131, v157, v208, vcc
	v_lshlrev_b32_e32 v131, 2, v131
	ds_bpermute_b32 v131, v131, v130
	s_and_saveexec_b64 s[64:65], s[4:5]
	s_cbranch_execz .LBB0_179
	s_lshl_b64 s[68:69], s[60:61], 2
	s_add_u32 s67, s44, s68
	s_mov_b32 s47, s49
	s_addc_u32 vcc_hi, s45, s69
	s_lshl_b64 s[70:71], s[46:47], 2
	s_sub_u32 vcc_lo, s67, s70
	s_subb_u32 vcc_hi, vcc_hi, s71
	v_lshlrev_b64 v[132:133], 2, v[152:153]
	v_lshl_add_u64 v[210:211], vcc, 0, v[132:133]
	s_lshl_b64 vcc, s[62:63], 2
	s_add_u32 s47, s44, vcc_lo
	s_addc_u32 s67, s45, vcc_hi
	s_add_u32 s47, s47, s68
	s_addc_u32 s67, s67, s69
	s_sub_u32 s68, s47, s70
	s_waitcnt lgkmcnt(0)
	v_add_lshl_u32 v209, v130, v131, 7
	s_subb_u32 s69, s67, s71
	global_atomic_add v[210:211], v209, off offset:128
	v_lshl_add_u64 v[130:131], s[68:69], 0, v[132:133]
	global_atomic_add v[130:131], v209, off offset:128
.LBB0_179:
	s_or_b64 exec, exec, s[64:65]
	v_add_u32_e32 v209, s66, v198
	v_mov_b64_e32 v[210:211], s[40:41]
	v_add_u32_e32 v130, 0xcc0, v204
	v_add_u32_e32 v132, 0xcc8, v204
	v_mad_u64_u32 v[210:211], s[64:65], v209, s87, v[210:211]
	s_waitcnt lgkmcnt(0)
	ds_read2_b32 v[130:131], v130 offset1:1
	ds_read2_b32 v[132:133], v132 offset1:1
	v_ashrrev_i32_e32 v213, 31, v209
	v_mov_b32_e32 v212, v211
	v_mad_u64_u32 v[212:213], s[64:65], v213, s87, v[212:213]
	v_mov_b32_e32 v211, v212
	v_lshl_add_u64 v[210:211], v[210:211], 0, s[8:9]
	v_lshl_add_u64 v[210:211], v[210:211], 0, v[154:155]
	s_and_b64 vcc, exec, s[6:7]
	s_waitcnt lgkmcnt(0)
	global_store_dwordx4 v[210:211], v[130:133], off sc1
	s_cbranch_vccnz .LBB0_183
	v_mov_b32_e32 v209, v135
	v_dot4c_i32_i8_e32 v209, 0x1010101, v130
	v_dot4c_i32_i8_e32 v209, 0x1010101, v131
	v_cmp_lt_i32_e32 vcc, v207, v159
	v_dot4c_i32_i8_e32 v209, 0x1010101, v132
	v_dot4c_i32_i8_e32 v209, 0x1010101, v133
	v_cndmask_b32_e32 v130, v157, v207, vcc
	v_lshlrev_b32_e32 v130, 2, v130
	v_cmp_lt_i32_e32 vcc, v208, v159
	ds_bpermute_b32 v130, v130, v209
	s_waitcnt lgkmcnt(0)
	v_add_u32_e32 v130, v130, v209
	v_cndmask_b32_e32 v131, v157, v208, vcc
	v_lshlrev_b32_e32 v131, 2, v131
	ds_bpermute_b32 v131, v131, v130
	s_and_saveexec_b64 s[6:7], s[4:5]
	s_cbranch_execz .LBB0_182
	s_lshl_b64 s[64:65], s[60:61], 2
	s_add_u32 s61, s44, s64
	s_mov_b32 s47, s49
	s_addc_u32 s67, s45, s65
	s_lshl_b64 s[68:69], s[46:47], 2
	s_sub_u32 s70, s61, s68
	s_subb_u32 s71, s67, s69
	s_lshl_b64 s[62:63], s[62:63], 2
	s_add_u32 s47, s44, s62
	s_addc_u32 s61, s45, s63
	s_add_u32 s47, s47, s64
	s_addc_u32 s61, s61, s65
	v_lshlrev_b64 v[132:133], 2, v[152:153]
	s_sub_u32 s62, s47, s68
	v_lshl_add_u64 v[208:209], s[70:71], 0, v[132:133]
	s_waitcnt lgkmcnt(0)
	v_add_lshl_u32 v157, v130, v131, 7
	s_subb_u32 s63, s61, s69
	global_atomic_add v[208:209], v157, off offset:192
	v_lshl_add_u64 v[130:131], s[62:63], 0, v[132:133]
	global_atomic_add v[130:131], v157, off offset:192

; #define LAS __attribute__((address_space(3)))
; __device__ __forceinline__ void titem_finish(const TItem& t, const f32x4 (&x)[16], const float (&sc)[16], LAS float* scr_f, int lane) {
;     ...
;         for (int j = 0; j < 4; ++j) { const int n = (lane >> 2) + 16 * j; const LAS unsigned* s = scr + n * 17 + 4 * q4;
;             u32x4 o; o.x = s[0]; o.y = s[1]; o.z = s[2]; o.w = s[3];
;             __builtin_nontemporal_store(o, (u32x4*)((unsigned char*)t.WT + (size_t)(n0 - t.noff + n) * t.K + k0 + 16 * q4));
.LBB0_184:
	v_add_u32_e32 v157, s66, v198
	v_mov_b64_e32 v[208:209], s[40:41]
	v_add_u32_e32 v130, 0xcc0, v204
	v_add_u32_e32 v132, 0xcc8, v204
	v_mad_u64_u32 v[208:209], s[6:7], v157, s87, v[208:209]
	s_waitcnt lgkmcnt(0)
	ds_read2_b32 v[130:131], v130 offset1:1
	ds_read2_b32 v[132:133], v132 offset1:1
	v_ashrrev_i32_e32 v159, 31, v157
	v_mov_b32_e32 v210, v209
	v_mad_u64_u32 v[210:211], s[6:7], v159, s87, v[210:211]
	v_mov_b32_e32 v209, v210
	v_lshl_add_u64 v[208:209], v[208:209], 0, s[8:9]
	v_lshl_add_u64 v[208:209], v[208:209], 0, v[154:155]
	s_waitcnt lgkmcnt(0)
	global_store_dwordx4 v[208:209], v[130:133], off sc1

; __device__ __forceinline__ unsigned cvtpk(float lo, float hi) { f32x2 v = {lo, hi}; bf16x2_t b = __builtin_convertvector(v, bf16x2_t); return __builtin_bit_cast(unsigned, b); }
; __device__ __forceinline__ void titem_finish(const TItem& t, const f32x4 (&x)[16], const float (&sc)[16], LAS float* scr_f, int lane) {
;     ...
; #pragma unroll
;     for (int p = 0; p < 8; ++p)
; #pragma unroll
;         for (int e = 0; e < 4; ++e) scr[(4 * c + e) * 33 + 4 * p + r] = cvtpk(x[2 * p][e] * sc[2 * p], x[2 * p + 1][e] * sc[2 * p + 1]);
.LBB0_186:
	s_waitcnt vmcnt(15)
	v_mov_b32_e32 v130, v2
	s_waitcnt vmcnt(14) lgkmcnt(0)
	v_mov_b32_e32 v131, v6
	v_pk_mul_f32 v[130:131], v[130:131], v[136:137]
	s_ashr_i32 s9, s8, 31
	v_cvt_pk_bf16_f32 v132, v130, v131
	v_mov_b32_e32 v130, v3
	v_mov_b32_e32 v131, v7
	v_pk_mul_f32 v[130:131], v[130:131], v[136:137]
	s_nop 0
	v_cvt_pk_bf16_f32 v133, v130, v131
	v_mov_b32_e32 v130, v4
	v_mov_b32_e32 v131, v8
	v_pk_mul_f32 v[130:131], v[130:131], v[136:137]
	s_nop 0
	v_cvt_pk_bf16_f32 v157, v130, v131
	v_mov_b32_e32 v130, v5
	v_mov_b32_e32 v131, v9
	v_pk_mul_f32 v[130:131], v[130:131], v[136:137]
	s_nop 0
	v_cvt_pk_bf16_f32 v159, v130, v131
	s_waitcnt vmcnt(13)
	v_mov_b32_e32 v130, v10
	s_waitcnt vmcnt(12)
	v_mov_b32_e32 v131, v14
	v_pk_mul_f32 v[130:131], v[130:131], v[138:139]
	s_nop 0
	v_cvt_pk_bf16_f32 v130, v130, v131
	ds_write2_b32 v201, v132, v130 offset1:4
	v_mov_b32_e32 v130, v11
	v_mov_b32_e32 v131, v15
	v_pk_mul_f32 v[130:131], v[130:131], v[138:139]
	s_nop 0
	v_cvt_pk_bf16_f32 v130, v130, v131
	ds_write2_b32 v201, v133, v130 offset0:33 offset1:37
	v_mov_b32_e32 v130, v12
	v_mov_b32_e32 v131, v16
	v_pk_mul_f32 v[130:131], v[130:131], v[138:139]
	s_nop 0
	v_cvt_pk_bf16_f32 v130, v130, v131
	ds_write2_b32 v201, v157, v130 offset0:66 offset1:70
	v_mov_b32_e32 v130, v13
	v_mov_b32_e32 v131, v17
	v_pk_mul_f32 v[130:131], v[130:131], v[138:139]
	s_nop 0
	v_cvt_pk_bf16_f32 v130, v130, v131
	ds_write2_b32 v201, v159, v130 offset0:99 offset1:103
	s_waitcnt vmcnt(11)
	v_mov_b32_e32 v130, v18
	s_waitcnt vmcnt(10)
	v_mov_b32_e32 v131, v22
	v_pk_mul_f32 v[130:131], v[130:131], v[140:141]
	s_nop 0
	v_cvt_pk_bf16_f32 v132, v130, v131
	v_mov_b32_e32 v130, v19
	v_mov_b32_e32 v131, v23
	v_pk_mul_f32 v[130:131], v[130:131], v[140:141]
	s_nop 0
	v_cvt_pk_bf16_f32 v133, v130, v131
	v_mov_b32_e32 v130, v20
	v_mov_b32_e32 v131, v24
	v_pk_mul_f32 v[130:131], v[130:131], v[140:141]
	s_nop 0
	v_cvt_pk_bf16_f32 v157, v130, v131
	v_mov_b32_e32 v130, v21
	v_mov_b32_e32 v131, v25
	v_pk_mul_f32 v[130:131], v[130:131], v[140:141]
	s_nop 0
	v_cvt_pk_bf16_f32 v159, v130, v131
	s_waitcnt vmcnt(9)
	v_mov_b32_e32 v130, v26
	s_waitcnt vmcnt(8)
	v_mov_b32_e32 v131, v30
	v_pk_mul_f32 v[130:131], v[130:131], v[142:143]
	s_nop 0
	v_cvt_pk_bf16_f32 v130, v130, v131
	ds_write2_b32 v201, v132, v130 offset0:8 offset1:12
	v_mov_b32_e32 v130, v27
	v_mov_b32_e32 v131, v31
	v_pk_mul_f32 v[130:131], v[130:131], v[142:143]
	s_nop 0
	v_cvt_pk_bf16_f32 v130, v130, v131
	ds_write2_b32 v201, v133, v130 offset0:41 offset1:45
	v_mov_b32_e32 v130, v28
	v_mov_b32_e32 v131, v32
	v_pk_mul_f32 v[130:131], v[130:131], v[142:143]
	s_nop 0
	v_cvt_pk_bf16_f32 v130, v130, v131
	ds_write2_b32 v201, v157, v130 offset0:74 offset1:78
	v_mov_b32_e32 v130, v29
	v_mov_b32_e32 v131, v33
	v_pk_mul_f32 v[130:131], v[130:131], v[142:143]
	s_nop 0
	v_cvt_pk_bf16_f32 v130, v130, v131
	ds_write2_b32 v201, v159, v130 offset0:107 offset1:111
	s_waitcnt vmcnt(7)
	v_mov_b32_e32 v130, v34
	s_waitcnt vmcnt(6)
	v_mov_b32_e32 v131, v38
	v_pk_mul_f32 v[130:131], v[130:131], v[144:145]
	s_nop 0
	v_cvt_pk_bf16_f32 v132, v130, v131
	v_mov_b32_e32 v130, v35
	v_mov_b32_e32 v131, v39
	v_pk_mul_f32 v[130:131], v[130:131], v[144:145]
	s_nop 0
	v_cvt_pk_bf16_f32 v133, v130, v131
	v_mov_b32_e32 v130, v36
	v_mov_b32_e32 v131, v40
	v_pk_mul_f32 v[130:131], v[130:131], v[144:145]
	s_nop 0
	v_cvt_pk_bf16_f32 v157, v130, v131
	v_mov_b32_e32 v130, v37
	v_mov_b32_e32 v131, v41
	v_pk_mul_f32 v[130:131], v[130:131], v[144:145]
	s_nop 0
	v_cvt_pk_bf16_f32 v159, v130, v131
	s_waitcnt vmcnt(5)
	v_mov_b32_e32 v130, v42
	s_waitcnt vmcnt(4)
	v_mov_b32_e32 v131, v46
	v_pk_mul_f32 v[130:131], v[130:131], v[146:147]
	s_nop 0
	v_cvt_pk_bf16_f32 v130, v130, v131
	ds_write2_b32 v201, v132, v130 offset0:16 offset1:20
	v_mov_b32_e32 v130, v43
	v_mov_b32_e32 v131, v47
	v_pk_mul_f32 v[130:131], v[130:131], v[146:147]
	s_nop 0
	v_cvt_pk_bf16_f32 v130, v130, v131
	ds_write2_b32 v201, v133, v130 offset0:49 offset1:53
	v_mov_b32_e32 v130, v44
	v_mov_b32_e32 v131, v48
	v_pk_mul_f32 v[130:131], v[130:131], v[146:147]
	s_nop 0
	v_cvt_pk_bf16_f32 v130, v130, v131
	ds_write2_b32 v201, v157, v130 offset0:82 offset1:86
	v_mov_b32_e32 v130, v45
	v_mov_b32_e32 v131, v49
	v_pk_mul_f32 v[130:131], v[130:131], v[146:147]
	s_nop 0
	v_cvt_pk_bf16_f32 v130, v130, v131
	ds_write2_b32 v201, v159, v130 offset0:115 offset1:119
	s_waitcnt vmcnt(3)
	v_mov_b32_e32 v130, v50
	s_waitcnt vmcnt(2)
	v_mov_b32_e32 v131, v54
	v_pk_mul_f32 v[130:131], v[130:131], v[148:149]
	s_nop 0
	v_cvt_pk_bf16_f32 v132, v130, v131
	v_mov_b32_e32 v130, v51
	v_mov_b32_e32 v131, v55
	v_pk_mul_f32 v[130:131], v[130:131], v[148:149]
	s_nop 0
	v_cvt_pk_bf16_f32 v133, v130, v131
	v_mov_b32_e32 v130, v52
	v_mov_b32_e32 v131, v56
	v_pk_mul_f32 v[130:131], v[130:131], v[148:149]
	s_nop 0
	v_cvt_pk_bf16_f32 v157, v130, v131
	v_mov_b32_e32 v130, v53
	v_mov_b32_e32 v131, v57
	v_pk_mul_f32 v[130:131], v[130:131], v[148:149]
	s_nop 0
	v_cvt_pk_bf16_f32 v159, v130, v131
	s_waitcnt vmcnt(1)
	v_mov_b32_e32 v130, v58
	s_waitcnt vmcnt(0)
; #define LAS __attribute__((address_space(3)))
; __device__ __forceinline__ unsigned cvtpk(float lo, float hi) { f32x2 v = {lo, hi}; bf16x2_t b = __builtin_convertvector(v, bf16x2_t); return __builtin_bit_cast(unsigned, b); }
; #define LDS_WAIT() asm volatile("s_waitcnt lgkmcnt(0)" ::: "memory")
; __device__ __forceinline__ void titem_finish(const TItem& t, const f32x4 (&x)[16], const float (&sc)[16], LAS float* scr_f, int lane) {
;     ...
;         for (int e = 0; e < 4; ++e) scr[(4 * c + e) * 33 + 4 * p + r] = cvtpk(x[2 * p][e] * sc[2 * p], x[2 * p + 1][e] * sc[2 * p + 1]);
;     LDS_WAIT(); asm volatile("" ::: "memory");
;     const int q = lane & 7;
; #pragma unroll
;     for (int j = 0; j < 8; ++j) { const int n = (lane >> 3) + 8 * j; const LAS unsigned* s = scr + n * 33 + 4 * q;
;         u32x4 o; o.x = s[0]; o.y = s[1]; o.z = s[2]; o.w = s[3];
;         __builtin_nontemporal_store(o, (u32x4*)(t.WT + (size_t)(n0 + n) * t.K + k0 + 8 * q)); }
;     LDS_WAIT(); asm volatile("" ::: "memory");
	v_mov_b32_e32 v131, v62
	v_pk_mul_f32 v[130:131], v[130:131], v[150:151]
	s_nop 0
	v_cvt_pk_bf16_f32 v130, v130, v131
	ds_write2_b32 v201, v132, v130 offset0:24 offset1:28
	v_mov_b32_e32 v130, v59
	v_mov_b32_e32 v131, v63
	v_pk_mul_f32 v[130:131], v[130:131], v[150:151]
	s_nop 0
	v_cvt_pk_bf16_f32 v130, v130, v131
	ds_write2_b32 v201, v133, v130 offset0:57 offset1:61
	v_mov_b32_e32 v130, v60
	v_mov_b32_e32 v131, v64
	v_pk_mul_f32 v[130:131], v[130:131], v[150:151]
	s_nop 0
	v_cvt_pk_bf16_f32 v130, v130, v131
	ds_write2_b32 v201, v157, v130 offset0:90 offset1:94
	v_mov_b32_e32 v130, v61
	v_mov_b32_e32 v131, v65
	v_pk_mul_f32 v[130:131], v[130:131], v[150:151]
	s_nop 0
	v_cvt_pk_bf16_f32 v130, v130, v131
	ds_write2_b32 v201, v159, v130 offset0:123 offset1:127
	v_add_u32_e32 v159, s60, v199
	s_waitcnt lgkmcnt(0)
	v_mad_u64_u32 v[208:209], s[6:7], v159, s87, 0
	v_ashrrev_i32_e32 v157, 31, v159
	v_mov_b32_e32 v210, v209
	ds_read2_b32 v[130:131], v202 offset1:1
	ds_read2_b32 v[132:133], v202 offset0:2 offset1:3
	v_mad_u64_u32 v[210:211], s[6:7], v157, s87, v[210:211]
	v_mov_b32_e32 v209, v210
	v_lshl_add_u64 v[208:209], v[208:209], 1, s[40:41]
	s_lshl_b64 s[6:7], s[8:9], 1
	v_lshl_add_u64 v[208:209], v[208:209], 0, s[6:7]
	v_mov_b32_e32 v157, v135
	v_lshl_add_u64 v[208:209], v[208:209], 0, v[156:157]
	v_add_u32_e32 v207, 8, v159
	s_waitcnt lgkmcnt(0)
	global_store_dwordx4 v[208:209], v[130:133], off sc1
	v_mad_u64_u32 v[208:209], s[8:9], v207, s87, 0
	s_nop 0
	v_add_u32_e32 v130, 0x420, v202
	v_add_u32_e32 v132, 0x428, v202
	v_ashrrev_i32_e32 v211, 31, v207
	v_mov_b32_e32 v210, v209
	ds_read2_b32 v[130:131], v130 offset1:1
	ds_read2_b32 v[132:133], v132 offset1:1
	v_mad_u64_u32 v[210:211], s[8:9], v211, s87, v[210:211]
	v_mov_b32_e32 v209, v210
	v_lshl_add_u64 v[208:209], v[208:209], 1, s[40:41]
	v_lshl_add_u64 v[208:209], v[208:209], 0, s[6:7]
	v_lshl_add_u64 v[208:209], v[208:209], 0, v[156:157]
	v_add_u32_e32 v207, 16, v159
	s_waitcnt lgkmcnt(0)
	global_store_dwordx4 v[208:209], v[130:133], off sc1
	v_mad_u64_u32 v[208:209], s[8:9], v207, s87, 0
	s_nop 0
	v_add_u32_e32 v130, 0x840, v202
	v_add_u32_e32 v132, 0x848, v202
	v_ashrrev_i32_e32 v211, 31, v207
	v_mov_b32_e32 v210, v209
	ds_read2_b32 v[130:131], v130 offset1:1
	ds_read2_b32 v[132:133], v132 offset1:1
	v_mad_u64_u32 v[210:211], s[8:9], v211, s87, v[210:211]
	v_mov_b32_e32 v209, v210
	v_lshl_add_u64 v[208:209], v[208:209], 1, s[40:41]
	v_lshl_add_u64 v[208:209], v[208:209], 0, s[6:7]
	v_lshl_add_u64 v[208:209], v[208:209], 0, v[156:157]
	v_add_u32_e32 v207, 24, v159
	s_waitcnt lgkmcnt(0)
	global_store_dwordx4 v[208:209], v[130:133], off sc1
	v_mad_u64_u32 v[208:209], s[8:9], v207, s87, 0
	s_nop 0
	v_add_u32_e32 v130, 0xc60, v202
	v_add_u32_e32 v132, 0xc68, v202
	v_ashrrev_i32_e32 v211, 31, v207
	v_mov_b32_e32 v210, v209
	ds_read2_b32 v[130:131], v130 offset1:1
	ds_read2_b32 v[132:133], v132 offset1:1
	v_mad_u64_u32 v[210:211], s[8:9], v211, s87, v[210:211]
	v_mov_b32_e32 v209, v210
	v_lshl_add_u64 v[208:209], v[208:209], 1, s[40:41]
	v_lshl_add_u64 v[208:209], v[208:209], 0, s[6:7]
	v_lshl_add_u64 v[208:209], v[208:209], 0, v[156:157]
	v_add_u32_e32 v207, 32, v159
	s_waitcnt lgkmcnt(0)
	global_store_dwordx4 v[208:209], v[130:133], off sc1
	v_mad_u64_u32 v[208:209], s[8:9], v207, s87, 0
	s_nop 0
	v_add_u32_e32 v130, 0x1080, v202
	v_add_u32_e32 v132, 0x1088, v202
	v_ashrrev_i32_e32 v211, 31, v207
	v_mov_b32_e32 v210, v209
	ds_read2_b32 v[130:131], v130 offset1:1
	ds_read2_b32 v[132:133], v132 offset1:1
	v_mad_u64_u32 v[210:211], s[8:9], v211, s87, v[210:211]
	v_mov_b32_e32 v209, v210
	v_lshl_add_u64 v[208:209], v[208:209], 1, s[40:41]
	v_lshl_add_u64 v[208:209], v[208:209], 0, s[6:7]
	v_lshl_add_u64 v[208:209], v[208:209], 0, v[156:157]
	v_add_u32_e32 v207, 40, v159
	s_waitcnt lgkmcnt(0)
	global_store_dwordx4 v[208:209], v[130:133], off sc1
	v_mad_u64_u32 v[208:209], s[8:9], v207, s87, 0
	s_nop 0
	v_add_u32_e32 v130, 0x14a0, v202
	v_add_u32_e32 v132, 0x14a8, v202
	v_ashrrev_i32_e32 v211, 31, v207
	v_mov_b32_e32 v210, v209
	ds_read2_b32 v[130:131], v130 offset1:1
	ds_read2_b32 v[132:133], v132 offset1:1
	v_mad_u64_u32 v[210:211], s[8:9], v211, s87, v[210:211]
	v_mov_b32_e32 v209, v210
	v_lshl_add_u64 v[208:209], v[208:209], 1, s[40:41]
	v_lshl_add_u64 v[208:209], v[208:209], 0, s[6:7]
	v_lshl_add_u64 v[208:209], v[208:209], 0, v[156:157]
	v_add_u32_e32 v207, 48, v159
	s_waitcnt lgkmcnt(0)
	global_store_dwordx4 v[208:209], v[130:133], off sc1
	v_mad_u64_u32 v[208:209], s[8:9], v207, s87, 0
	s_nop 0
	v_add_u32_e32 v130, 0x18c0, v202
	v_add_u32_e32 v132, 0x18c8, v202
	v_ashrrev_i32_e32 v211, 31, v207
	v_mov_b32_e32 v210, v209
	ds_read2_b32 v[130:131], v130 offset1:1
	ds_read2_b32 v[132:133], v132 offset1:1
	v_mad_u64_u32 v[210:211], s[8:9], v211, s87, v[210:211]
	v_mov_b32_e32 v209, v210
	v_lshl_add_u64 v[208:209], v[208:209], 1, s[40:41]
	v_lshl_add_u64 v[208:209], v[208:209], 0, s[6:7]
	v_lshl_add_u64 v[208:209], v[208:209], 0, v[156:157]
	v_add_u32_e32 v159, 56, v159
	s_waitcnt lgkmcnt(0)
	global_store_dwordx4 v[208:209], v[130:133], off sc1
	v_mad_u64_u32 v[208:209], s[8:9], v159, s87, 0
	s_nop 0
	v_add_u32_e32 v130, 0x1ce0, v202
	v_add_u32_e32 v132, 0x1ce8, v202
	v_ashrrev_i32_e32 v207, 31, v159
	v_mov_b32_e32 v210, v209
	ds_read2_b32 v[130:131], v130 offset1:1
	ds_read2_b32 v[132:133], v132 offset1:1
	v_mad_u64_u32 v[210:211], s[8:9], v207, s87, v[210:211]
	v_mov_b32_e32 v209, v210
	v_lshl_add_u64 v[208:209], v[208:209], 1, s[40:41]
	v_lshl_add_u64 v[208:209], v[208:209], 0, s[6:7]
	v_lshl_add_u64 v[208:209], v[208:209], 0, v[156:157]
	s_waitcnt lgkmcnt(0)
	global_store_dwordx4 v[208:209], v[130:133], off sc1
	s_waitcnt lgkmcnt(0)

; __device__ __forceinline__ u32x4 pack8(f32x4 a, f32x4 b) { u32x4 w; w.x = cvtpk(a[0], a[1]); w.y = cvtpk(a[2], a[3]); w.z = cvtpk(b[0], b[1]); w.w = cvtpk(b[2], b[3]); return w; }
; __device__ __forceinline__ float fsigmoid(float v) { return __builtin_amdgcn_rcpf(1.0f + __builtin_amdgcn_exp2f(-LOG2E * v)); }
; __device__ __forceinline__ float fgelu_tanh(float v) { const float t = v + 0.044715f * v * v * v; return v * __builtin_amdgcn_rcpf(1.0f + __builtin_amdgcn_exp2f(-2.3022081985f * t)); }
; __device__ __forceinline__ unsigned dpp_ror8(unsigned v) { return (unsigned)__builtin_amdgcn_update_dpp(0, (int)v, 0x128, 0xF, 0xF, false); }
; __device__ __forceinline__ void store_pair(bf16_t* grp  , size_t ld, int fr, int fq, u32x4 P0, u32x4 P1) {
;     const bool up = (fr & 8) != 0;
;     u32x4 snd, rcv;
;     snd.x = up ? P0.x : P1.x; snd.y = up ? P0.y : P1.y; snd.z = up ? P0.z : P1.z; snd.w = up ? P0.w : P1.w;
;     rcv.x = dpp_ror8(snd.x); rcv.y = dpp_ror8(snd.y); rcv.z = dpp_ror8(snd.z); rcv.w = dpp_ror8(snd.w);
;     u32x4 dA, dB;
;     dA.x = up ? rcv.x : P0.x; dA.y = up ? rcv.y : P0.y; dA.z = up ? rcv.z : P0.z; dA.w = up ? rcv.w : P0.w;
;     dB.x = up ? P1.x : rcv.x; dB.y = up ? P1.y : rcv.y; dB.z = up ? P1.z : rcv.z; dB.w = up ? P1.w : rcv.w;
;     bf16_t* p = grp + (size_t)(fr & 7) * ld + (up ? CBJ : 0) + 8 * fq;
;     __builtin_nontemporal_store(dA, (u32x4*)p); __builtin_nontemporal_store(dB, (u32x4*)(p + 8 * ld));
; }
;     __device__ __forceinline__ void operator()(f32x4 (&acc)[2][2][4][2], const Unit& u, int wr, int wc, int fr, int fq) const {
;     ...
;                     if (mode == 1) {
; #pragma unroll
;                         for (int j = 0; j < 4; ++j) { v0[j] = fgelu_tanh(v0[j]); v1[j] = fgelu_tanh(v1[j]); }
;                     } else if (mode == 2) { v0 = v0 * (0.0625f * LOG2E); v1 = v1 * (0.0625f * LOG2E); }
;                     else if (mode == 3) {
;                         v0 = v0 + *(const f32x4*)(bgate + (col0 - C_GT) + bj * CBJ); v1 = v1 + *(const f32x4*)(bgate + (col0 - C_GT) + bj * CBJ + 4);
; #pragma unroll
;                         for (int j = 0; j < 4; ++j) { v0[j] = fsigmoid(v0[j]); v1[j] = fsigmoid(v1[j]); }
;                     }
;                     pk[bj] = pack8(v0, v1);
;                 }
;                 store_pair(P + (size_t)(rowg + ai * HALF + m * 16) * INC + colw, INC, fr, fq, pk[0], pk[1]);
.LBB0_388:
	s_lshl_b32 s7, s2, 8
	s_add_i32 s7, s7, s45
	s_ashr_i32 s1, s0, 31
	s_mul_i32 s3, s7, 0x6000
	s_mul_hi_i32 s2, s7, 0x6000
	s_add_u32 s3, s33, s3
	v_cvt_pk_bf16_f32 v114, v152, v153
	v_cvt_pk_bf16_f32 v115, v156, v157
	v_cvt_pk_bf16_f32 v116, v154, v155
	v_cvt_pk_bf16_f32 v117, v158, v159
	v_cvt_pk_bf16_f32 v122, v122, v123
	v_cvt_pk_bf16_f32 v123, v128, v129
	v_cvt_pk_bf16_f32 v126, v126, v127
	v_cvt_pk_bf16_f32 v125, v124, v125
	s_addc_u32 s2, s15, s2
	s_lshl_b64 s[4:5], s[0:1], 1
	s_add_u32 s0, s3, s4
	v_cndmask_b32_e64 v118, v114, v122, s[52:53]
	v_cndmask_b32_e64 v119, v115, v123, s[52:53]
	v_cndmask_b32_e64 v120, v116, v126, s[52:53]
	v_cndmask_b32_e64 v121, v117, v125, s[52:53]
	v_mov_b32_e32 v124, v131
	v_mov_b32_e32 v127, v131
	v_mov_b32_e32 v128, v131
	v_mov_b32_e32 v129, v131
	s_addc_u32 s1, s2, s5
	v_mov_b32_dpp v124, v118 row_ror:8 row_mask:0xf bank_mask:0xf
	v_mov_b32_dpp v127, v119 row_ror:8 row_mask:0xf bank_mask:0xf
	v_mov_b32_dpp v128, v120 row_ror:8 row_mask:0xf bank_mask:0xf
	v_mov_b32_dpp v129, v121 row_ror:8 row_mask:0xf bank_mask:0xf
	v_lshlrev_b32_e32 v130, 1, v142
	v_cndmask_b32_e64 v118, v124, v114, s[52:53]
	v_cndmask_b32_e64 v119, v127, v115, s[52:53]
	v_cndmask_b32_e64 v120, v128, v116, s[52:53]
	v_cndmask_b32_e64 v121, v129, v117, s[52:53]
	v_lshl_add_u64 v[116:117], s[0:1], 0, v[130:131]
	v_lshlrev_b32_e32 v114, 1, v144
	v_mov_b32_e32 v115, v131
	v_cndmask_b32_e64 v122, v122, v124, s[52:53]
	v_cndmask_b32_e64 v123, v123, v127, s[52:53]
	v_cndmask_b32_e64 v124, v126, v128, s[52:53]
	v_lshl_add_u64 v[126:127], v[116:117], 0, v[114:115]
	v_lshlrev_b32_e32 v116, 1, v140
	v_mov_b32_e32 v117, v131
	v_lshl_add_u64 v[126:127], v[126:127], 0, v[116:117]
	global_store_dwordx4 v[126:127], v[118:121], off sc1
	v_cndmask_b32_e64 v125, v125, v129, s[52:53]
	s_cmp_lt_i32 s6, 2
	v_add_co_u32_e32 v118, vcc, 0x30000, v126
	s_mov_b64 s[0:1], -1
	s_nop 0
	v_addc_co_u32_e32 v119, vcc, 0, v127, vcc
	global_store_dwordx4 v[118:119], v[122:125], off sc1
	s_cbranch_scc1 .LBB0_400
	s_cmp_gt_i32 s6, 2
	s_cbranch_scc0 .LBB0_391
	s_movk_i32 s0, 0xa000
	v_add_co_u32_e32 v118, vcc, 0xffffa000, v150
	s_mov_b32 s1, -1
	s_nop 0
	v_addc_co_u32_e32 v119, vcc, -1, v151, vcc
	v_lshl_add_u64 v[122:123], v[150:151], 0, s[0:1]
	global_load_dwordx4 v[118:121], v[118:119], off
	s_mov_b64 s[0:1], 0
	global_load_dwordx4 v[122:125], v[122:123], off offset:16
	s_waitcnt vmcnt(0)
	v_pk_add_f32 v[120:121], v[112:113], v[120:121]
	v_pk_add_f32 v[118:119], v[110:111], v[118:119]
	v_pk_add_f32 v[124:125], v[108:109], v[124:125]
	v_pk_add_f32 v[122:123], v[106:107], v[122:123]
	v_mul_f32_e32 v115, 0xbfb8aa3b, v118
	v_mul_f32_e32 v117, 0xbfb8aa3b, v122
	v_mul_f32_e32 v118, 0xbfb8aa3b, v119
	v_mul_f32_e32 v119, 0xbfb8aa3b, v123
	v_mul_f32_e32 v120, 0xbfb8aa3b, v120
	v_mul_f32_e32 v122, 0xbfb8aa3b, v124
	v_mul_f32_e32 v121, 0xbfb8aa3b, v121
	v_mul_f32_e32 v123, 0xbfb8aa3b, v125
	v_exp_f32_e32 v115, v115
	v_exp_f32_e32 v117, v117
	v_exp_f32_e32 v118, v118
	v_exp_f32_e32 v119, v119
	v_exp_f32_e32 v120, v120
	v_exp_f32_e32 v122, v122
	v_exp_f32_e32 v121, v121
	v_exp_f32_e32 v123, v123
	v_add_f32_e32 v115, 1.0, v115
	v_add_f32_e32 v117, 1.0, v117
	v_add_f32_e32 v124, 1.0, v118
	v_add_f32_e32 v125, 1.0, v119
	v_add_f32_e32 v126, 1.0, v120
	v_add_f32_e32 v127, 1.0, v122
	v_add_f32_e32 v128, 1.0, v121
	v_add_f32_e32 v129, 1.0, v123
	v_rcp_f32_e32 v118, v115
	v_rcp_f32_e32 v120, v117
	v_rcp_f32_e32 v119, v124
	v_rcp_f32_e32 v121, v125
	v_rcp_f32_e32 v122, v126
	v_rcp_f32_e32 v124, v127
	v_rcp_f32_e32 v123, v128
	v_rcp_f32_e32 v125, v129

; __device__ __forceinline__ u32x4 pack8(f32x4 a, f32x4 b) { u32x4 w; w.x = cvtpk(a[0], a[1]); w.y = cvtpk(a[2], a[3]); w.z = cvtpk(b[0], b[1]); w.w = cvtpk(b[2], b[3]); return w; }
; __device__ __forceinline__ float fsigmoid(float v) { return __builtin_amdgcn_rcpf(1.0f + __builtin_amdgcn_exp2f(-LOG2E * v)); }
; __device__ __forceinline__ float fgelu_tanh(float v) { const float t = v + 0.044715f * v * v * v; return v * __builtin_amdgcn_rcpf(1.0f + __builtin_amdgcn_exp2f(-2.3022081985f * t)); }
; __device__ __forceinline__ unsigned dpp_ror8(unsigned v) { return (unsigned)__builtin_amdgcn_update_dpp(0, (int)v, 0x128, 0xF, 0xF, false); }
; __device__ __forceinline__ void store_pair(bf16_t* grp  , size_t ld, int fr, int fq, u32x4 P0, u32x4 P1) {
;     const bool up = (fr & 8) != 0;
;     u32x4 snd, rcv;
;     snd.x = up ? P0.x : P1.x; snd.y = up ? P0.y : P1.y; snd.z = up ? P0.z : P1.z; snd.w = up ? P0.w : P1.w;
;     rcv.x = dpp_ror8(snd.x); rcv.y = dpp_ror8(snd.y); rcv.z = dpp_ror8(snd.z); rcv.w = dpp_ror8(snd.w);
;     u32x4 dA, dB;
;     dA.x = up ? rcv.x : P0.x; dA.y = up ? rcv.y : P0.y; dA.z = up ? rcv.z : P0.z; dA.w = up ? rcv.w : P0.w;
;     dB.x = up ? P1.x : rcv.x; dB.y = up ? P1.y : rcv.y; dB.z = up ? P1.z : rcv.z; dB.w = up ? P1.w : rcv.w;
;     bf16_t* p = grp + (size_t)(fr & 7) * ld + (up ? CBJ : 0) + 8 * fq;
;     __builtin_nontemporal_store(dA, (u32x4*)p); __builtin_nontemporal_store(dB, (u32x4*)(p + 8 * ld));
; }
;     __device__ __forceinline__ void operator()(f32x4 (&acc)[2][2][4][2], const Unit& u, int wr, int wc, int fr, int fq) const {
;     ...
;                     if (mode == 1) {
; #pragma unroll
;                         for (int j = 0; j < 4; ++j) { v0[j] = fgelu_tanh(v0[j]); v1[j] = fgelu_tanh(v1[j]); }
;                     } else if (mode == 2) { v0 = v0 * (0.0625f * LOG2E); v1 = v1 * (0.0625f * LOG2E); }
;                     else if (mode == 3) {
;                         v0 = v0 + *(const f32x4*)(bgate + (col0 - C_GT) + bj * CBJ); v1 = v1 + *(const f32x4*)(bgate + (col0 - C_GT) + bj * CBJ + 4);
; #pragma unroll
;                         for (int j = 0; j < 4; ++j) { v0[j] = fsigmoid(v0[j]); v1[j] = fsigmoid(v1[j]); }
;                     }
;                     pk[bj] = pack8(v0, v1);
;                 }
;                 store_pair(P + (size_t)(rowg + ai * HALF + m * 16) * INC + colw, INC, fr, fq, pk[0], pk[1]);
.LBB0_408:
	s_or_b32 s0, s7, 16
	v_cvt_pk_bf16_f32 v98, v118, v119
	v_cvt_pk_bf16_f32 v102, v106, v107
	s_mul_hi_i32 s1, s0, 0x6000
	s_mulk_i32 s0, 0x6000
	v_cvt_pk_bf16_f32 v99, v122, v123
	v_cvt_pk_bf16_f32 v103, v112, v113
	v_cvt_pk_bf16_f32 v104, v110, v111
	s_add_u32 s0, s33, s0
	v_cndmask_b32_e64 v106, v98, v102, s[52:53]
	v_mov_b32_e32 v110, v131
	v_cvt_pk_bf16_f32 v100, v120, v121
	s_addc_u32 s1, s15, s1
	v_cndmask_b32_e64 v107, v99, v103, s[52:53]
	v_mov_b32_dpp v110, v106 row_ror:8 row_mask:0xf bank_mask:0xf
	v_mov_b32_e32 v106, v131
	v_cvt_pk_bf16_f32 v105, v108, v109
	s_add_u32 s0, s0, s4
	v_cndmask_b32_e64 v108, v100, v104, s[52:53]
	v_mov_b32_dpp v106, v107 row_ror:8 row_mask:0xf bank_mask:0xf
	v_mov_b32_e32 v107, v131
	v_cvt_pk_bf16_f32 v101, v124, v125
	s_addc_u32 s1, s1, s5
	v_mov_b32_dpp v107, v108 row_ror:8 row_mask:0xf bank_mask:0xf
	v_cndmask_b32_e64 v109, v101, v105, s[52:53]
	v_mov_b32_e32 v108, v131
	v_cndmask_b32_e64 v99, v106, v99, s[52:53]
	v_cndmask_b32_e64 v100, v107, v100, s[52:53]
	v_cndmask_b32_e64 v103, v103, v106, s[52:53]
	v_cndmask_b32_e64 v104, v104, v107, s[52:53]
	v_lshl_add_u64 v[106:107], s[0:1], 0, v[130:131]
	v_mov_b32_e32 v115, v131
	v_mov_b32_dpp v108, v109 row_ror:8 row_mask:0xf bank_mask:0xf
	v_lshl_add_u64 v[106:107], v[106:107], 0, v[114:115]
	v_mov_b32_e32 v117, v131
	v_cndmask_b32_e64 v98, v110, v98, s[52:53]
	v_cndmask_b32_e64 v101, v108, v101, s[52:53]
	v_lshl_add_u64 v[106:107], v[106:107], 0, v[116:117]
	global_store_dwordx4 v[106:107], v[98:101], off sc1
	v_cndmask_b32_e64 v102, v102, v110, s[52:53]
	v_cndmask_b32_e64 v105, v105, v108, s[52:53]
	v_add_co_u32_e32 v98, vcc, 0x30000, v106
	s_cmp_lt_i32 s6, 2
	s_nop 0
	v_addc_co_u32_e32 v99, vcc, 0, v107, vcc
	s_mov_b64 s[0:1], -1
	global_store_dwordx4 v[98:99], v[102:105], off sc1
	s_cbranch_scc1 .LBB0_420
	s_cmp_gt_i32 s6, 2
	s_cbranch_scc0 .LBB0_411
	s_movk_i32 s0, 0xa000
	v_add_co_u32_e32 v98, vcc, 0xffffa000, v150
	s_mov_b32 s1, -1
	s_nop 0
	v_addc_co_u32_e32 v99, vcc, -1, v151, vcc
	v_lshl_add_u64 v[102:103], v[150:151], 0, s[0:1]
	global_load_dwordx4 v[98:101], v[98:99], off
	s_mov_b64 s[0:1], 0
	global_load_dwordx4 v[102:105], v[102:103], off offset:16
	s_waitcnt vmcnt(0)
	v_pk_add_f32 v[100:101], v[96:97], v[100:101]
	v_pk_add_f32 v[98:99], v[94:95], v[98:99]
	v_pk_add_f32 v[104:105], v[92:93], v[104:105]
	v_pk_add_f32 v[102:103], v[90:91], v[102:103]
	v_mul_f32_e32 v98, 0xbfb8aa3b, v98
	v_mul_f32_e32 v102, 0xbfb8aa3b, v102
	v_mul_f32_e32 v99, 0xbfb8aa3b, v99
	v_mul_f32_e32 v103, 0xbfb8aa3b, v103
	v_mul_f32_e32 v100, 0xbfb8aa3b, v100
	v_mul_f32_e32 v104, 0xbfb8aa3b, v104
	v_mul_f32_e32 v101, 0xbfb8aa3b, v101
	v_mul_f32_e32 v105, 0xbfb8aa3b, v105
	v_exp_f32_e32 v98, v98
	v_exp_f32_e32 v102, v102
	v_exp_f32_e32 v99, v99
	v_exp_f32_e32 v103, v103
	v_exp_f32_e32 v100, v100
	v_exp_f32_e32 v104, v104
	v_exp_f32_e32 v101, v101
	v_exp_f32_e32 v105, v105
	v_add_f32_e32 v98, 1.0, v98
	v_add_f32_e32 v102, 1.0, v102
	v_add_f32_e32 v99, 1.0, v99
	v_add_f32_e32 v103, 1.0, v103
	v_add_f32_e32 v106, 1.0, v100
	v_add_f32_e32 v104, 1.0, v104
	v_add_f32_e32 v107, 1.0, v101
	v_add_f32_e32 v105, 1.0, v105
	v_rcp_f32_e32 v98, v98
	v_rcp_f32_e32 v100, v102
	v_rcp_f32_e32 v99, v99
	v_rcp_f32_e32 v101, v103
	v_rcp_f32_e32 v102, v106
	v_rcp_f32_e32 v104, v104
	v_rcp_f32_e32 v103, v107
	v_rcp_f32_e32 v105, v105

; __device__ __forceinline__ u32x4 pack8(f32x4 a, f32x4 b) { u32x4 w; w.x = cvtpk(a[0], a[1]); w.y = cvtpk(a[2], a[3]); w.z = cvtpk(b[0], b[1]); w.w = cvtpk(b[2], b[3]); return w; }
; __device__ __forceinline__ float fsigmoid(float v) { return __builtin_amdgcn_rcpf(1.0f + __builtin_amdgcn_exp2f(-LOG2E * v)); }
; __device__ __forceinline__ float fgelu_tanh(float v) { const float t = v + 0.044715f * v * v * v; return v * __builtin_amdgcn_rcpf(1.0f + __builtin_amdgcn_exp2f(-2.3022081985f * t)); }
; __device__ __forceinline__ unsigned dpp_ror8(unsigned v) { return (unsigned)__builtin_amdgcn_update_dpp(0, (int)v, 0x128, 0xF, 0xF, false); }
; __device__ __forceinline__ void store_pair(bf16_t* grp  , size_t ld, int fr, int fq, u32x4 P0, u32x4 P1) {
;     const bool up = (fr & 8) != 0;
;     u32x4 snd, rcv;
;     snd.x = up ? P0.x : P1.x; snd.y = up ? P0.y : P1.y; snd.z = up ? P0.z : P1.z; snd.w = up ? P0.w : P1.w;
;     rcv.x = dpp_ror8(snd.x); rcv.y = dpp_ror8(snd.y); rcv.z = dpp_ror8(snd.z); rcv.w = dpp_ror8(snd.w);
;     u32x4 dA, dB;
;     dA.x = up ? rcv.x : P0.x; dA.y = up ? rcv.y : P0.y; dA.z = up ? rcv.z : P0.z; dA.w = up ? rcv.w : P0.w;
;     dB.x = up ? P1.x : rcv.x; dB.y = up ? P1.y : rcv.y; dB.z = up ? P1.z : rcv.z; dB.w = up ? P1.w : rcv.w;
;     bf16_t* p = grp + (size_t)(fr & 7) * ld + (up ? CBJ : 0) + 8 * fq;
;     __builtin_nontemporal_store(dA, (u32x4*)p); __builtin_nontemporal_store(dB, (u32x4*)(p + 8 * ld));
; }
;     __device__ __forceinline__ void operator()(f32x4 (&acc)[2][2][4][2], const Unit& u, int wr, int wc, int fr, int fq) const {
;     ...
;                     if (mode == 1) {
; #pragma unroll
;                         for (int j = 0; j < 4; ++j) { v0[j] = fgelu_tanh(v0[j]); v1[j] = fgelu_tanh(v1[j]); }
;                     } else if (mode == 2) { v0 = v0 * (0.0625f * LOG2E); v1 = v1 * (0.0625f * LOG2E); }
;                     else if (mode == 3) {
;                         v0 = v0 + *(const f32x4*)(bgate + (col0 - C_GT) + bj * CBJ); v1 = v1 + *(const f32x4*)(bgate + (col0 - C_GT) + bj * CBJ + 4);
; #pragma unroll
;                         for (int j = 0; j < 4; ++j) { v0[j] = fsigmoid(v0[j]); v1[j] = fsigmoid(v1[j]); }
;                     }
;                     pk[bj] = pack8(v0, v1);
;                 }
;                 store_pair(P + (size_t)(rowg + ai * HALF + m * 16) * INC + colw, INC, fr, fq, pk[0], pk[1]);
.LBB0_428:
	s_or_b32 s0, s7, 32
	v_cvt_pk_bf16_f32 v82, v98, v99
	v_cvt_pk_bf16_f32 v86, v90, v91
	s_mul_hi_i32 s1, s0, 0x6000
	s_mulk_i32 s0, 0x6000
	v_cvt_pk_bf16_f32 v83, v102, v103
	v_cvt_pk_bf16_f32 v87, v96, v97
	v_cvt_pk_bf16_f32 v88, v94, v95
	s_add_u32 s0, s33, s0
	v_cndmask_b32_e64 v90, v82, v86, s[52:53]
	v_mov_b32_e32 v94, v131
	v_cvt_pk_bf16_f32 v84, v100, v101
	s_addc_u32 s1, s15, s1
	v_cndmask_b32_e64 v91, v83, v87, s[52:53]
	v_mov_b32_dpp v94, v90 row_ror:8 row_mask:0xf bank_mask:0xf
	v_mov_b32_e32 v90, v131
	v_cvt_pk_bf16_f32 v89, v92, v93
	s_add_u32 s0, s0, s4
	v_cndmask_b32_e64 v92, v84, v88, s[52:53]
	v_mov_b32_dpp v90, v91 row_ror:8 row_mask:0xf bank_mask:0xf
	v_mov_b32_e32 v91, v131
	v_cvt_pk_bf16_f32 v85, v104, v105
	s_addc_u32 s1, s1, s5
	v_mov_b32_dpp v91, v92 row_ror:8 row_mask:0xf bank_mask:0xf
	v_cndmask_b32_e64 v93, v85, v89, s[52:53]
	v_mov_b32_e32 v92, v131
	v_cndmask_b32_e64 v83, v90, v83, s[52:53]
	v_cndmask_b32_e64 v84, v91, v84, s[52:53]
	v_cndmask_b32_e64 v87, v87, v90, s[52:53]
	v_cndmask_b32_e64 v88, v88, v91, s[52:53]
	v_lshl_add_u64 v[90:91], s[0:1], 0, v[130:131]
	v_mov_b32_e32 v115, v131
	v_mov_b32_dpp v92, v93 row_ror:8 row_mask:0xf bank_mask:0xf
	v_lshl_add_u64 v[90:91], v[90:91], 0, v[114:115]
	v_mov_b32_e32 v117, v131
	v_cndmask_b32_e64 v82, v94, v82, s[52:53]
	v_cndmask_b32_e64 v85, v92, v85, s[52:53]
	v_lshl_add_u64 v[90:91], v[90:91], 0, v[116:117]
	global_store_dwordx4 v[90:91], v[82:85], off sc1
	v_cndmask_b32_e64 v86, v86, v94, s[52:53]
	v_cndmask_b32_e64 v89, v89, v92, s[52:53]
	v_add_co_u32_e32 v82, vcc, 0x30000, v90
	s_cmp_lt_i32 s6, 2
	s_nop 0
	v_addc_co_u32_e32 v83, vcc, 0, v91, vcc
	s_mov_b64 s[0:1], -1
	global_store_dwordx4 v[82:83], v[86:89], off sc1
	s_cbranch_scc1 .LBB0_440
	s_cmp_gt_i32 s6, 2
	s_cbranch_scc0 .LBB0_431
	s_movk_i32 s0, 0xa000
	v_add_co_u32_e32 v82, vcc, 0xffffa000, v150
	s_mov_b32 s1, -1
	s_nop 0
	v_addc_co_u32_e32 v83, vcc, -1, v151, vcc
	v_lshl_add_u64 v[86:87], v[150:151], 0, s[0:1]
	global_load_dwordx4 v[82:85], v[82:83], off
	s_mov_b64 s[0:1], 0
	global_load_dwordx4 v[86:89], v[86:87], off offset:16
	s_waitcnt vmcnt(0)
	v_pk_add_f32 v[84:85], v[80:81], v[84:85]
	v_pk_add_f32 v[82:83], v[78:79], v[82:83]
	v_pk_add_f32 v[88:89], v[76:77], v[88:89]
	v_pk_add_f32 v[86:87], v[74:75], v[86:87]
	v_mul_f32_e32 v82, 0xbfb8aa3b, v82
	v_mul_f32_e32 v86, 0xbfb8aa3b, v86
	v_mul_f32_e32 v83, 0xbfb8aa3b, v83
	v_mul_f32_e32 v87, 0xbfb8aa3b, v87
	v_mul_f32_e32 v84, 0xbfb8aa3b, v84
	v_mul_f32_e32 v88, 0xbfb8aa3b, v88
	v_mul_f32_e32 v85, 0xbfb8aa3b, v85
	v_mul_f32_e32 v89, 0xbfb8aa3b, v89
	v_exp_f32_e32 v82, v82
	v_exp_f32_e32 v86, v86
	v_exp_f32_e32 v83, v83
	v_exp_f32_e32 v87, v87
	v_exp_f32_e32 v84, v84
	v_exp_f32_e32 v88, v88
	v_exp_f32_e32 v85, v85
	v_exp_f32_e32 v89, v89
	v_add_f32_e32 v82, 1.0, v82
	v_add_f32_e32 v86, 1.0, v86
	v_add_f32_e32 v83, 1.0, v83
	v_add_f32_e32 v87, 1.0, v87
	v_add_f32_e32 v90, 1.0, v84
	v_add_f32_e32 v88, 1.0, v88
	v_add_f32_e32 v91, 1.0, v85
	v_add_f32_e32 v89, 1.0, v89
	v_rcp_f32_e32 v82, v82
	v_rcp_f32_e32 v84, v86
	v_rcp_f32_e32 v83, v83
	v_rcp_f32_e32 v85, v87
	v_rcp_f32_e32 v86, v90
	v_rcp_f32_e32 v88, v88
	v_rcp_f32_e32 v87, v91
	v_rcp_f32_e32 v89, v89

; __device__ __forceinline__ u32x4 pack8(f32x4 a, f32x4 b) { u32x4 w; w.x = cvtpk(a[0], a[1]); w.y = cvtpk(a[2], a[3]); w.z = cvtpk(b[0], b[1]); w.w = cvtpk(b[2], b[3]); return w; }
; __device__ __forceinline__ float fsigmoid(float v) { return __builtin_amdgcn_rcpf(1.0f + __builtin_amdgcn_exp2f(-LOG2E * v)); }
; __device__ __forceinline__ float fgelu_tanh(float v) { const float t = v + 0.044715f * v * v * v; return v * __builtin_amdgcn_rcpf(1.0f + __builtin_amdgcn_exp2f(-2.3022081985f * t)); }
; __device__ __forceinline__ unsigned dpp_ror8(unsigned v) { return (unsigned)__builtin_amdgcn_update_dpp(0, (int)v, 0x128, 0xF, 0xF, false); }
; __device__ __forceinline__ void store_pair(bf16_t* grp  , size_t ld, int fr, int fq, u32x4 P0, u32x4 P1) {
;     const bool up = (fr & 8) != 0;
;     u32x4 snd, rcv;
;     snd.x = up ? P0.x : P1.x; snd.y = up ? P0.y : P1.y; snd.z = up ? P0.z : P1.z; snd.w = up ? P0.w : P1.w;
;     rcv.x = dpp_ror8(snd.x); rcv.y = dpp_ror8(snd.y); rcv.z = dpp_ror8(snd.z); rcv.w = dpp_ror8(snd.w);
;     u32x4 dA, dB;
;     dA.x = up ? rcv.x : P0.x; dA.y = up ? rcv.y : P0.y; dA.z = up ? rcv.z : P0.z; dA.w = up ? rcv.w : P0.w;
;     dB.x = up ? P1.x : rcv.x; dB.y = up ? P1.y : rcv.y; dB.z = up ? P1.z : rcv.z; dB.w = up ? P1.w : rcv.w;
;     bf16_t* p = grp + (size_t)(fr & 7) * ld + (up ? CBJ : 0) + 8 * fq;
;     __builtin_nontemporal_store(dA, (u32x4*)p); __builtin_nontemporal_store(dB, (u32x4*)(p + 8 * ld));
; }
;     __device__ __forceinline__ void operator()(f32x4 (&acc)[2][2][4][2], const Unit& u, int wr, int wc, int fr, int fq) const {
;     ...
;                     if (mode == 1) {
; #pragma unroll
;                         for (int j = 0; j < 4; ++j) { v0[j] = fgelu_tanh(v0[j]); v1[j] = fgelu_tanh(v1[j]); }
;                     } else if (mode == 2) { v0 = v0 * (0.0625f * LOG2E); v1 = v1 * (0.0625f * LOG2E); }
;                     else if (mode == 3) {
;                         v0 = v0 + *(const f32x4*)(bgate + (col0 - C_GT) + bj * CBJ); v1 = v1 + *(const f32x4*)(bgate + (col0 - C_GT) + bj * CBJ + 4);
; #pragma unroll
;                         for (int j = 0; j < 4; ++j) { v0[j] = fsigmoid(v0[j]); v1[j] = fsigmoid(v1[j]); }
;                     }
;                     pk[bj] = pack8(v0, v1);
;                 }
;                 store_pair(P + (size_t)(rowg + ai * HALF + m * 16) * INC + colw, INC, fr, fq, pk[0], pk[1]);
.LBB0_448:
	s_or_b32 s0, s7, 48
	v_cvt_pk_bf16_f32 v66, v82, v83
	v_cvt_pk_bf16_f32 v70, v74, v75
	s_mul_hi_i32 s1, s0, 0x6000
	s_mulk_i32 s0, 0x6000
	v_cvt_pk_bf16_f32 v67, v86, v87
	v_cvt_pk_bf16_f32 v71, v80, v81
	v_cvt_pk_bf16_f32 v72, v78, v79
	s_add_u32 s0, s33, s0
	v_cndmask_b32_e64 v74, v66, v70, s[52:53]
	v_mov_b32_e32 v78, v131
	v_cvt_pk_bf16_f32 v68, v84, v85
	s_addc_u32 s1, s15, s1
	v_cndmask_b32_e64 v75, v67, v71, s[52:53]
	v_mov_b32_dpp v78, v74 row_ror:8 row_mask:0xf bank_mask:0xf
	v_mov_b32_e32 v74, v131
	v_cvt_pk_bf16_f32 v73, v76, v77
	s_add_u32 s0, s0, s4
	v_cndmask_b32_e64 v76, v68, v72, s[52:53]
	v_mov_b32_dpp v74, v75 row_ror:8 row_mask:0xf bank_mask:0xf
	v_mov_b32_e32 v75, v131
	v_cvt_pk_bf16_f32 v69, v88, v89
	s_addc_u32 s1, s1, s5
	v_mov_b32_dpp v75, v76 row_ror:8 row_mask:0xf bank_mask:0xf
	v_cndmask_b32_e64 v77, v69, v73, s[52:53]
	v_mov_b32_e32 v76, v131
	v_cndmask_b32_e64 v67, v74, v67, s[52:53]
	v_cndmask_b32_e64 v68, v75, v68, s[52:53]
	v_cndmask_b32_e64 v71, v71, v74, s[52:53]
	v_cndmask_b32_e64 v72, v72, v75, s[52:53]
	v_lshl_add_u64 v[74:75], s[0:1], 0, v[130:131]
	v_mov_b32_e32 v115, v131
	v_mov_b32_dpp v76, v77 row_ror:8 row_mask:0xf bank_mask:0xf
	v_lshl_add_u64 v[74:75], v[74:75], 0, v[114:115]
	v_mov_b32_e32 v117, v131
	v_cndmask_b32_e64 v66, v78, v66, s[52:53]
	v_cndmask_b32_e64 v69, v76, v69, s[52:53]
	v_lshl_add_u64 v[74:75], v[74:75], 0, v[116:117]
	global_store_dwordx4 v[74:75], v[66:69], off sc1
	v_cndmask_b32_e64 v70, v70, v78, s[52:53]
	v_cndmask_b32_e64 v73, v73, v76, s[52:53]
	v_add_co_u32_e32 v66, vcc, 0x30000, v74
	s_cmp_lt_i32 s6, 2
	s_nop 0
	v_addc_co_u32_e32 v67, vcc, 0, v75, vcc
	s_mov_b64 s[0:1], -1
	global_store_dwordx4 v[66:67], v[70:73], off sc1
	s_cbranch_scc1 .LBB0_460
	s_cmp_gt_i32 s6, 2
	s_cbranch_scc0 .LBB0_451
	s_movk_i32 s0, 0xa000
	v_add_co_u32_e32 v66, vcc, 0xffffa000, v150
	s_mov_b32 s1, -1
	s_nop 0
	v_addc_co_u32_e32 v67, vcc, -1, v151, vcc
	v_lshl_add_u64 v[70:71], v[150:151], 0, s[0:1]
	global_load_dwordx4 v[66:69], v[66:67], off
	s_mov_b64 s[0:1], 0
	global_load_dwordx4 v[70:73], v[70:71], off offset:16
	s_waitcnt vmcnt(0)
	v_pk_add_f32 v[68:69], v[64:65], v[68:69]
	v_pk_add_f32 v[66:67], v[62:63], v[66:67]
	v_pk_add_f32 v[72:73], v[60:61], v[72:73]
	v_pk_add_f32 v[70:71], v[58:59], v[70:71]
	v_mul_f32_e32 v66, 0xbfb8aa3b, v66
	v_mul_f32_e32 v70, 0xbfb8aa3b, v70
	v_mul_f32_e32 v67, 0xbfb8aa3b, v67
	v_mul_f32_e32 v71, 0xbfb8aa3b, v71
	v_mul_f32_e32 v68, 0xbfb8aa3b, v68
	v_mul_f32_e32 v72, 0xbfb8aa3b, v72
	v_mul_f32_e32 v69, 0xbfb8aa3b, v69
	v_mul_f32_e32 v73, 0xbfb8aa3b, v73
	v_exp_f32_e32 v66, v66
	v_exp_f32_e32 v70, v70
	v_exp_f32_e32 v67, v67
	v_exp_f32_e32 v71, v71
	v_exp_f32_e32 v68, v68
	v_exp_f32_e32 v72, v72
	v_exp_f32_e32 v69, v69
	v_exp_f32_e32 v73, v73
	v_add_f32_e32 v66, 1.0, v66
	v_add_f32_e32 v70, 1.0, v70
	v_add_f32_e32 v67, 1.0, v67
	v_add_f32_e32 v71, 1.0, v71
	v_add_f32_e32 v74, 1.0, v68
	v_add_f32_e32 v72, 1.0, v72
	v_add_f32_e32 v75, 1.0, v69
	v_add_f32_e32 v73, 1.0, v73
	v_rcp_f32_e32 v66, v66
	v_rcp_f32_e32 v68, v70
	v_rcp_f32_e32 v67, v67
	v_rcp_f32_e32 v69, v71
	v_rcp_f32_e32 v70, v74
	v_rcp_f32_e32 v72, v72
	v_rcp_f32_e32 v71, v75
	v_rcp_f32_e32 v73, v73

; __device__ __forceinline__ u32x4 pack8(f32x4 a, f32x4 b) { u32x4 w; w.x = cvtpk(a[0], a[1]); w.y = cvtpk(a[2], a[3]); w.z = cvtpk(b[0], b[1]); w.w = cvtpk(b[2], b[3]); return w; }
; __device__ __forceinline__ float fsigmoid(float v) { return __builtin_amdgcn_rcpf(1.0f + __builtin_amdgcn_exp2f(-LOG2E * v)); }
; __device__ __forceinline__ float fgelu_tanh(float v) { const float t = v + 0.044715f * v * v * v; return v * __builtin_amdgcn_rcpf(1.0f + __builtin_amdgcn_exp2f(-2.3022081985f * t)); }
; __device__ __forceinline__ unsigned dpp_ror8(unsigned v) { return (unsigned)__builtin_amdgcn_update_dpp(0, (int)v, 0x128, 0xF, 0xF, false); }
; __device__ __forceinline__ void store_pair(bf16_t* grp  , size_t ld, int fr, int fq, u32x4 P0, u32x4 P1) {
;     const bool up = (fr & 8) != 0;
;     u32x4 snd, rcv;
;     snd.x = up ? P0.x : P1.x; snd.y = up ? P0.y : P1.y; snd.z = up ? P0.z : P1.z; snd.w = up ? P0.w : P1.w;
;     rcv.x = dpp_ror8(snd.x); rcv.y = dpp_ror8(snd.y); rcv.z = dpp_ror8(snd.z); rcv.w = dpp_ror8(snd.w);
;     u32x4 dA, dB;
;     dA.x = up ? rcv.x : P0.x; dA.y = up ? rcv.y : P0.y; dA.z = up ? rcv.z : P0.z; dA.w = up ? rcv.w : P0.w;
;     dB.x = up ? P1.x : rcv.x; dB.y = up ? P1.y : rcv.y; dB.z = up ? P1.z : rcv.z; dB.w = up ? P1.w : rcv.w;
;     bf16_t* p = grp + (size_t)(fr & 7) * ld + (up ? CBJ : 0) + 8 * fq;
;     __builtin_nontemporal_store(dA, (u32x4*)p); __builtin_nontemporal_store(dB, (u32x4*)(p + 8 * ld));
; }
;     __device__ __forceinline__ void operator()(f32x4 (&acc)[2][2][4][2], const Unit& u, int wr, int wc, int fr, int fq) const {
;     ...
;                     if (mode == 1) {
; #pragma unroll
;                         for (int j = 0; j < 4; ++j) { v0[j] = fgelu_tanh(v0[j]); v1[j] = fgelu_tanh(v1[j]); }
;                     } else if (mode == 2) { v0 = v0 * (0.0625f * LOG2E); v1 = v1 * (0.0625f * LOG2E); }
;                     else if (mode == 3) {
;                         v0 = v0 + *(const f32x4*)(bgate + (col0 - C_GT) + bj * CBJ); v1 = v1 + *(const f32x4*)(bgate + (col0 - C_GT) + bj * CBJ + 4);
; #pragma unroll
;                         for (int j = 0; j < 4; ++j) { v0[j] = fsigmoid(v0[j]); v1[j] = fsigmoid(v1[j]); }
;                     }
;                     pk[bj] = pack8(v0, v1);
;                 }
;                 store_pair(P + (size_t)(rowg + ai * HALF + m * 16) * INC + colw, INC, fr, fq, pk[0], pk[1]);
.LBB0_468:
	s_add_i32 s0, s7, 0x80
	v_cvt_pk_bf16_f32 v50, v66, v67
	v_cvt_pk_bf16_f32 v54, v58, v59
	s_mul_hi_i32 s1, s0, 0x6000
	s_mulk_i32 s0, 0x6000
	v_cvt_pk_bf16_f32 v51, v70, v71
	v_cvt_pk_bf16_f32 v55, v64, v65
	v_cvt_pk_bf16_f32 v56, v62, v63
	s_add_u32 s0, s33, s0
	v_cndmask_b32_e64 v58, v50, v54, s[52:53]
	v_mov_b32_e32 v62, v131
	v_cvt_pk_bf16_f32 v52, v68, v69
	s_addc_u32 s1, s15, s1
	v_cndmask_b32_e64 v59, v51, v55, s[52:53]
	v_mov_b32_dpp v62, v58 row_ror:8 row_mask:0xf bank_mask:0xf
	v_mov_b32_e32 v58, v131
	v_cvt_pk_bf16_f32 v57, v60, v61
	s_add_u32 s0, s0, s4
	v_cndmask_b32_e64 v60, v52, v56, s[52:53]
	v_mov_b32_dpp v58, v59 row_ror:8 row_mask:0xf bank_mask:0xf
	v_mov_b32_e32 v59, v131
	v_cvt_pk_bf16_f32 v53, v72, v73
	s_addc_u32 s1, s1, s5
	v_mov_b32_dpp v59, v60 row_ror:8 row_mask:0xf bank_mask:0xf
	v_cndmask_b32_e64 v61, v53, v57, s[52:53]
	v_mov_b32_e32 v60, v131
	v_cndmask_b32_e64 v51, v58, v51, s[52:53]
	v_cndmask_b32_e64 v52, v59, v52, s[52:53]
	v_cndmask_b32_e64 v55, v55, v58, s[52:53]
	v_cndmask_b32_e64 v56, v56, v59, s[52:53]
	v_lshl_add_u64 v[58:59], s[0:1], 0, v[130:131]
	v_mov_b32_e32 v115, v131
	v_mov_b32_dpp v60, v61 row_ror:8 row_mask:0xf bank_mask:0xf
	v_lshl_add_u64 v[58:59], v[58:59], 0, v[114:115]
	v_mov_b32_e32 v117, v131
	v_cndmask_b32_e64 v50, v62, v50, s[52:53]
	v_cndmask_b32_e64 v53, v60, v53, s[52:53]
	v_lshl_add_u64 v[58:59], v[58:59], 0, v[116:117]
	global_store_dwordx4 v[58:59], v[50:53], off sc1
	v_cndmask_b32_e64 v54, v54, v62, s[52:53]
	v_cndmask_b32_e64 v57, v57, v60, s[52:53]
	v_add_co_u32_e32 v50, vcc, 0x30000, v58
	s_cmp_lt_i32 s6, 2
	s_nop 0
	v_addc_co_u32_e32 v51, vcc, 0, v59, vcc
	s_mov_b64 s[0:1], -1
	global_store_dwordx4 v[50:51], v[54:57], off sc1
	s_cbranch_scc1 .LBB0_480
	s_cmp_gt_i32 s6, 2
	s_cbranch_scc0 .LBB0_471
	s_movk_i32 s0, 0xa000
	v_add_co_u32_e32 v50, vcc, 0xffffa000, v150
	s_mov_b32 s1, -1
	s_nop 0
	v_addc_co_u32_e32 v51, vcc, -1, v151, vcc
	v_lshl_add_u64 v[54:55], v[150:151], 0, s[0:1]
	global_load_dwordx4 v[50:53], v[50:51], off
	s_mov_b64 s[0:1], 0
	global_load_dwordx4 v[54:57], v[54:55], off offset:16
	s_waitcnt vmcnt(0)
	v_pk_add_f32 v[52:53], v[48:49], v[52:53]
	v_pk_add_f32 v[50:51], v[46:47], v[50:51]
	v_pk_add_f32 v[56:57], v[44:45], v[56:57]
	v_pk_add_f32 v[54:55], v[42:43], v[54:55]
	v_mul_f32_e32 v50, 0xbfb8aa3b, v50
	v_mul_f32_e32 v54, 0xbfb8aa3b, v54
	v_mul_f32_e32 v51, 0xbfb8aa3b, v51
	v_mul_f32_e32 v55, 0xbfb8aa3b, v55
	v_mul_f32_e32 v52, 0xbfb8aa3b, v52
	v_mul_f32_e32 v56, 0xbfb8aa3b, v56
	v_mul_f32_e32 v53, 0xbfb8aa3b, v53
	v_mul_f32_e32 v57, 0xbfb8aa3b, v57
	v_exp_f32_e32 v50, v50
	v_exp_f32_e32 v54, v54
	v_exp_f32_e32 v51, v51
	v_exp_f32_e32 v55, v55
	v_exp_f32_e32 v52, v52
	v_exp_f32_e32 v56, v56
	v_exp_f32_e32 v53, v53
	v_exp_f32_e32 v57, v57
	v_add_f32_e32 v50, 1.0, v50
	v_add_f32_e32 v54, 1.0, v54
	v_add_f32_e32 v51, 1.0, v51
	v_add_f32_e32 v55, 1.0, v55
	v_add_f32_e32 v58, 1.0, v52
	v_add_f32_e32 v56, 1.0, v56
	v_add_f32_e32 v59, 1.0, v53
	v_add_f32_e32 v57, 1.0, v57
	v_rcp_f32_e32 v50, v50
	v_rcp_f32_e32 v52, v54
	v_rcp_f32_e32 v51, v51
	v_rcp_f32_e32 v53, v55
	v_rcp_f32_e32 v54, v58
	v_rcp_f32_e32 v56, v56
	v_rcp_f32_e32 v55, v59
	v_rcp_f32_e32 v57, v57

; __device__ __forceinline__ u32x4 pack8(f32x4 a, f32x4 b) { u32x4 w; w.x = cvtpk(a[0], a[1]); w.y = cvtpk(a[2], a[3]); w.z = cvtpk(b[0], b[1]); w.w = cvtpk(b[2], b[3]); return w; }
; __device__ __forceinline__ float fsigmoid(float v) { return __builtin_amdgcn_rcpf(1.0f + __builtin_amdgcn_exp2f(-LOG2E * v)); }
; __device__ __forceinline__ float fgelu_tanh(float v) { const float t = v + 0.044715f * v * v * v; return v * __builtin_amdgcn_rcpf(1.0f + __builtin_amdgcn_exp2f(-2.3022081985f * t)); }
; __device__ __forceinline__ unsigned dpp_ror8(unsigned v) { return (unsigned)__builtin_amdgcn_update_dpp(0, (int)v, 0x128, 0xF, 0xF, false); }
; __device__ __forceinline__ void store_pair(bf16_t* grp  , size_t ld, int fr, int fq, u32x4 P0, u32x4 P1) {
;     const bool up = (fr & 8) != 0;
;     u32x4 snd, rcv;
;     snd.x = up ? P0.x : P1.x; snd.y = up ? P0.y : P1.y; snd.z = up ? P0.z : P1.z; snd.w = up ? P0.w : P1.w;
;     rcv.x = dpp_ror8(snd.x); rcv.y = dpp_ror8(snd.y); rcv.z = dpp_ror8(snd.z); rcv.w = dpp_ror8(snd.w);
;     u32x4 dA, dB;
;     dA.x = up ? rcv.x : P0.x; dA.y = up ? rcv.y : P0.y; dA.z = up ? rcv.z : P0.z; dA.w = up ? rcv.w : P0.w;
;     dB.x = up ? P1.x : rcv.x; dB.y = up ? P1.y : rcv.y; dB.z = up ? P1.z : rcv.z; dB.w = up ? P1.w : rcv.w;
;     bf16_t* p = grp + (size_t)(fr & 7) * ld + (up ? CBJ : 0) + 8 * fq;
;     __builtin_nontemporal_store(dA, (u32x4*)p); __builtin_nontemporal_store(dB, (u32x4*)(p + 8 * ld));
; }
;     __device__ __forceinline__ void operator()(f32x4 (&acc)[2][2][4][2], const Unit& u, int wr, int wc, int fr, int fq) const {
;     ...
;                     if (mode == 1) {
; #pragma unroll
;                         for (int j = 0; j < 4; ++j) { v0[j] = fgelu_tanh(v0[j]); v1[j] = fgelu_tanh(v1[j]); }
;                     } else if (mode == 2) { v0 = v0 * (0.0625f * LOG2E); v1 = v1 * (0.0625f * LOG2E); }
;                     else if (mode == 3) {
;                         v0 = v0 + *(const f32x4*)(bgate + (col0 - C_GT) + bj * CBJ); v1 = v1 + *(const f32x4*)(bgate + (col0 - C_GT) + bj * CBJ + 4);
; #pragma unroll
;                         for (int j = 0; j < 4; ++j) { v0[j] = fsigmoid(v0[j]); v1[j] = fsigmoid(v1[j]); }
;                     }
;                     pk[bj] = pack8(v0, v1);
;                 }
;                 store_pair(P + (size_t)(rowg + ai * HALF + m * 16) * INC + colw, INC, fr, fq, pk[0], pk[1]);
.LBB0_488:
	s_add_i32 s0, s7, 0x90
	v_cvt_pk_bf16_f32 v34, v50, v51
	v_cvt_pk_bf16_f32 v38, v42, v43
	s_mul_hi_i32 s1, s0, 0x6000
	s_mulk_i32 s0, 0x6000
	v_cvt_pk_bf16_f32 v35, v54, v55
	v_cvt_pk_bf16_f32 v39, v48, v49
	v_cvt_pk_bf16_f32 v40, v46, v47
	s_add_u32 s0, s33, s0
	v_cndmask_b32_e64 v42, v34, v38, s[52:53]
	v_mov_b32_e32 v46, v131
	v_cvt_pk_bf16_f32 v36, v52, v53
	s_addc_u32 s1, s15, s1
	v_cndmask_b32_e64 v43, v35, v39, s[52:53]
	v_mov_b32_dpp v46, v42 row_ror:8 row_mask:0xf bank_mask:0xf
	v_mov_b32_e32 v42, v131
	v_cvt_pk_bf16_f32 v41, v44, v45
	s_add_u32 s0, s0, s4
	v_cndmask_b32_e64 v44, v36, v40, s[52:53]
	v_mov_b32_dpp v42, v43 row_ror:8 row_mask:0xf bank_mask:0xf
	v_mov_b32_e32 v43, v131
	v_cvt_pk_bf16_f32 v37, v56, v57
	s_addc_u32 s1, s1, s5
	v_mov_b32_dpp v43, v44 row_ror:8 row_mask:0xf bank_mask:0xf
	v_cndmask_b32_e64 v45, v37, v41, s[52:53]
	v_mov_b32_e32 v44, v131
	v_cndmask_b32_e64 v35, v42, v35, s[52:53]
	v_cndmask_b32_e64 v36, v43, v36, s[52:53]
	v_cndmask_b32_e64 v39, v39, v42, s[52:53]
	v_cndmask_b32_e64 v40, v40, v43, s[52:53]
	v_lshl_add_u64 v[42:43], s[0:1], 0, v[130:131]
	v_mov_b32_e32 v115, v131
	v_mov_b32_dpp v44, v45 row_ror:8 row_mask:0xf bank_mask:0xf
	v_lshl_add_u64 v[42:43], v[42:43], 0, v[114:115]
	v_mov_b32_e32 v117, v131
	v_cndmask_b32_e64 v34, v46, v34, s[52:53]
	v_cndmask_b32_e64 v37, v44, v37, s[52:53]
	v_lshl_add_u64 v[42:43], v[42:43], 0, v[116:117]
	global_store_dwordx4 v[42:43], v[34:37], off sc1
	v_cndmask_b32_e64 v38, v38, v46, s[52:53]
	v_cndmask_b32_e64 v41, v41, v44, s[52:53]
	v_add_co_u32_e32 v34, vcc, 0x30000, v42
	s_cmp_lt_i32 s6, 2
	s_nop 0
	v_addc_co_u32_e32 v35, vcc, 0, v43, vcc
	s_mov_b64 s[0:1], -1
	global_store_dwordx4 v[34:35], v[38:41], off sc1
	s_cbranch_scc1 .LBB0_500
	s_cmp_gt_i32 s6, 2
	s_cbranch_scc0 .LBB0_491
	s_movk_i32 s0, 0xa000
	v_add_co_u32_e32 v34, vcc, 0xffffa000, v150
	s_mov_b32 s1, -1
	s_nop 0
	v_addc_co_u32_e32 v35, vcc, -1, v151, vcc
	v_lshl_add_u64 v[38:39], v[150:151], 0, s[0:1]
	global_load_dwordx4 v[34:37], v[34:35], off
	s_mov_b64 s[0:1], 0
	global_load_dwordx4 v[38:41], v[38:39], off offset:16
	s_waitcnt vmcnt(0)
	v_pk_add_f32 v[36:37], v[32:33], v[36:37]
	v_pk_add_f32 v[34:35], v[30:31], v[34:35]
	v_pk_add_f32 v[40:41], v[28:29], v[40:41]
	v_pk_add_f32 v[38:39], v[26:27], v[38:39]
	v_mul_f32_e32 v34, 0xbfb8aa3b, v34
	v_mul_f32_e32 v38, 0xbfb8aa3b, v38
	v_mul_f32_e32 v35, 0xbfb8aa3b, v35
	v_mul_f32_e32 v39, 0xbfb8aa3b, v39
	v_mul_f32_e32 v36, 0xbfb8aa3b, v36
	v_mul_f32_e32 v40, 0xbfb8aa3b, v40
	v_mul_f32_e32 v37, 0xbfb8aa3b, v37
	v_mul_f32_e32 v41, 0xbfb8aa3b, v41
	v_exp_f32_e32 v34, v34
	v_exp_f32_e32 v38, v38
	v_exp_f32_e32 v35, v35
	v_exp_f32_e32 v39, v39
	v_exp_f32_e32 v36, v36
	v_exp_f32_e32 v40, v40
	v_exp_f32_e32 v37, v37
	v_exp_f32_e32 v41, v41
	v_add_f32_e32 v34, 1.0, v34
	v_add_f32_e32 v38, 1.0, v38
	v_add_f32_e32 v35, 1.0, v35
	v_add_f32_e32 v39, 1.0, v39
	v_add_f32_e32 v42, 1.0, v36
	v_add_f32_e32 v40, 1.0, v40
	v_add_f32_e32 v43, 1.0, v37
	v_add_f32_e32 v41, 1.0, v41
	v_rcp_f32_e32 v34, v34
	v_rcp_f32_e32 v36, v38
	v_rcp_f32_e32 v35, v35
	v_rcp_f32_e32 v37, v39
	v_rcp_f32_e32 v38, v42
	v_rcp_f32_e32 v40, v40
	v_rcp_f32_e32 v39, v43
	v_rcp_f32_e32 v41, v41

; __device__ __forceinline__ u32x4 pack8(f32x4 a, f32x4 b) { u32x4 w; w.x = cvtpk(a[0], a[1]); w.y = cvtpk(a[2], a[3]); w.z = cvtpk(b[0], b[1]); w.w = cvtpk(b[2], b[3]); return w; }
; __device__ __forceinline__ float fsigmoid(float v) { return __builtin_amdgcn_rcpf(1.0f + __builtin_amdgcn_exp2f(-LOG2E * v)); }
; __device__ __forceinline__ float fgelu_tanh(float v) { const float t = v + 0.044715f * v * v * v; return v * __builtin_amdgcn_rcpf(1.0f + __builtin_amdgcn_exp2f(-2.3022081985f * t)); }
; __device__ __forceinline__ unsigned dpp_ror8(unsigned v) { return (unsigned)__builtin_amdgcn_update_dpp(0, (int)v, 0x128, 0xF, 0xF, false); }
; __device__ __forceinline__ void store_pair(bf16_t* grp  , size_t ld, int fr, int fq, u32x4 P0, u32x4 P1) {
;     const bool up = (fr & 8) != 0;
;     u32x4 snd, rcv;
;     snd.x = up ? P0.x : P1.x; snd.y = up ? P0.y : P1.y; snd.z = up ? P0.z : P1.z; snd.w = up ? P0.w : P1.w;
;     rcv.x = dpp_ror8(snd.x); rcv.y = dpp_ror8(snd.y); rcv.z = dpp_ror8(snd.z); rcv.w = dpp_ror8(snd.w);
;     u32x4 dA, dB;
;     dA.x = up ? rcv.x : P0.x; dA.y = up ? rcv.y : P0.y; dA.z = up ? rcv.z : P0.z; dA.w = up ? rcv.w : P0.w;
;     dB.x = up ? P1.x : rcv.x; dB.y = up ? P1.y : rcv.y; dB.z = up ? P1.z : rcv.z; dB.w = up ? P1.w : rcv.w;
;     bf16_t* p = grp + (size_t)(fr & 7) * ld + (up ? CBJ : 0) + 8 * fq;
;     __builtin_nontemporal_store(dA, (u32x4*)p); __builtin_nontemporal_store(dB, (u32x4*)(p + 8 * ld));
; }
;     __device__ __forceinline__ void operator()(f32x4 (&acc)[2][2][4][2], const Unit& u, int wr, int wc, int fr, int fq) const {
;     ...
;                     if (mode == 1) {
; #pragma unroll
;                         for (int j = 0; j < 4; ++j) { v0[j] = fgelu_tanh(v0[j]); v1[j] = fgelu_tanh(v1[j]); }
;                     } else if (mode == 2) { v0 = v0 * (0.0625f * LOG2E); v1 = v1 * (0.0625f * LOG2E); }
;                     else if (mode == 3) {
;                         v0 = v0 + *(const f32x4*)(bgate + (col0 - C_GT) + bj * CBJ); v1 = v1 + *(const f32x4*)(bgate + (col0 - C_GT) + bj * CBJ + 4);
; #pragma unroll
;                         for (int j = 0; j < 4; ++j) { v0[j] = fsigmoid(v0[j]); v1[j] = fsigmoid(v1[j]); }
;                     }
;                     pk[bj] = pack8(v0, v1);
;                 }
;                 store_pair(P + (size_t)(rowg + ai * HALF + m * 16) * INC + colw, INC, fr, fq, pk[0], pk[1]);
.LBB0_508:
	s_add_i32 s0, s7, 0xa0
	v_cvt_pk_bf16_f32 v18, v34, v35
	v_cvt_pk_bf16_f32 v22, v26, v27
	s_mul_hi_i32 s1, s0, 0x6000
	s_mulk_i32 s0, 0x6000
	v_cvt_pk_bf16_f32 v19, v38, v39
	v_cvt_pk_bf16_f32 v23, v32, v33
	v_cvt_pk_bf16_f32 v24, v30, v31
	s_add_u32 s0, s33, s0
	v_cndmask_b32_e64 v26, v18, v22, s[52:53]
	v_mov_b32_e32 v30, v131
	v_cvt_pk_bf16_f32 v20, v36, v37
	s_addc_u32 s1, s15, s1
	v_cndmask_b32_e64 v27, v19, v23, s[52:53]
	v_mov_b32_dpp v30, v26 row_ror:8 row_mask:0xf bank_mask:0xf
	v_mov_b32_e32 v26, v131
	v_cvt_pk_bf16_f32 v25, v28, v29
	s_add_u32 s0, s0, s4
	v_cndmask_b32_e64 v28, v20, v24, s[52:53]
	v_mov_b32_dpp v26, v27 row_ror:8 row_mask:0xf bank_mask:0xf
	v_mov_b32_e32 v27, v131
	v_cvt_pk_bf16_f32 v21, v40, v41
	s_addc_u32 s1, s1, s5
	v_mov_b32_dpp v27, v28 row_ror:8 row_mask:0xf bank_mask:0xf
	v_cndmask_b32_e64 v29, v21, v25, s[52:53]
	v_mov_b32_e32 v28, v131
	v_cndmask_b32_e64 v19, v26, v19, s[52:53]
	v_cndmask_b32_e64 v20, v27, v20, s[52:53]
	v_cndmask_b32_e64 v23, v23, v26, s[52:53]
	v_cndmask_b32_e64 v24, v24, v27, s[52:53]
	v_lshl_add_u64 v[26:27], s[0:1], 0, v[130:131]
	v_mov_b32_e32 v115, v131
	v_mov_b32_dpp v28, v29 row_ror:8 row_mask:0xf bank_mask:0xf
	v_lshl_add_u64 v[26:27], v[26:27], 0, v[114:115]
	v_mov_b32_e32 v117, v131
	v_cndmask_b32_e64 v18, v30, v18, s[52:53]
	v_cndmask_b32_e64 v21, v28, v21, s[52:53]
	v_lshl_add_u64 v[26:27], v[26:27], 0, v[116:117]
	global_store_dwordx4 v[26:27], v[18:21], off sc1
	v_cndmask_b32_e64 v22, v22, v30, s[52:53]
	v_cndmask_b32_e64 v25, v25, v28, s[52:53]
	v_add_co_u32_e32 v18, vcc, 0x30000, v26
	s_cmp_lt_i32 s6, 2
	s_nop 0
	v_addc_co_u32_e32 v19, vcc, 0, v27, vcc
	s_mov_b64 s[0:1], -1
	global_store_dwordx4 v[18:19], v[22:25], off sc1
	s_cbranch_scc1 .LBB0_520
	s_cmp_gt_i32 s6, 2
	s_cbranch_scc0 .LBB0_511
	s_movk_i32 s0, 0xa000
	v_add_co_u32_e32 v18, vcc, 0xffffa000, v150
	s_mov_b32 s1, -1
	s_nop 0
	v_addc_co_u32_e32 v19, vcc, -1, v151, vcc
	v_lshl_add_u64 v[22:23], v[150:151], 0, s[0:1]
	global_load_dwordx4 v[18:21], v[18:19], off
	s_mov_b64 s[0:1], 0
	global_load_dwordx4 v[22:25], v[22:23], off offset:16
	s_waitcnt vmcnt(0)
	v_pk_add_f32 v[20:21], v[16:17], v[20:21]
	v_pk_add_f32 v[18:19], v[14:15], v[18:19]
	v_pk_add_f32 v[24:25], v[12:13], v[24:25]
	v_pk_add_f32 v[22:23], v[10:11], v[22:23]
	v_mul_f32_e32 v18, 0xbfb8aa3b, v18
	v_mul_f32_e32 v22, 0xbfb8aa3b, v22
	v_mul_f32_e32 v19, 0xbfb8aa3b, v19
	v_mul_f32_e32 v23, 0xbfb8aa3b, v23
	v_mul_f32_e32 v20, 0xbfb8aa3b, v20
	v_mul_f32_e32 v24, 0xbfb8aa3b, v24
	v_mul_f32_e32 v21, 0xbfb8aa3b, v21
	v_mul_f32_e32 v25, 0xbfb8aa3b, v25
	v_exp_f32_e32 v18, v18
	v_exp_f32_e32 v22, v22
	v_exp_f32_e32 v19, v19
	v_exp_f32_e32 v23, v23
	v_exp_f32_e32 v20, v20
	v_exp_f32_e32 v24, v24
	v_exp_f32_e32 v21, v21
	v_exp_f32_e32 v25, v25
	v_add_f32_e32 v18, 1.0, v18
	v_add_f32_e32 v22, 1.0, v22
	v_add_f32_e32 v19, 1.0, v19
	v_add_f32_e32 v23, 1.0, v23
	v_add_f32_e32 v20, 1.0, v20
	v_add_f32_e32 v24, 1.0, v24
	v_add_f32_e32 v21, 1.0, v21
	v_add_f32_e32 v25, 1.0, v25
	v_rcp_f32_e32 v18, v18
	v_rcp_f32_e32 v22, v22
	v_rcp_f32_e32 v19, v19
	v_rcp_f32_e32 v23, v23
	v_rcp_f32_e32 v20, v20
	v_rcp_f32_e32 v24, v24
	v_rcp_f32_e32 v21, v21
	v_rcp_f32_e32 v25, v25

; __device__ __forceinline__ unsigned dpp_ror8(unsigned v) { return (unsigned)__builtin_amdgcn_update_dpp(0, (int)v, 0x128, 0xF, 0xF, false); }
; __device__ __forceinline__ void store_pair(bf16_t* grp  , size_t ld, int fr, int fq, u32x4 P0, u32x4 P1) {
;     const bool up = (fr & 8) != 0;
;     u32x4 snd, rcv;
;     snd.x = up ? P0.x : P1.x; snd.y = up ? P0.y : P1.y; snd.z = up ? P0.z : P1.z; snd.w = up ? P0.w : P1.w;
;     rcv.x = dpp_ror8(snd.x); rcv.y = dpp_ror8(snd.y); rcv.z = dpp_ror8(snd.z); rcv.w = dpp_ror8(snd.w);
;     u32x4 dA, dB;
;     dA.x = up ? rcv.x : P0.x; dA.y = up ? rcv.y : P0.y; dA.z = up ? rcv.z : P0.z; dA.w = up ? rcv.w : P0.w;
;     dB.x = up ? P1.x : rcv.x; dB.y = up ? P1.y : rcv.y; dB.z = up ? P1.z : rcv.z; dB.w = up ? P1.w : rcv.w;
;     bf16_t* p = grp + (size_t)(fr & 7) * ld + (up ? CBJ : 0) + 8 * fq;
;     __builtin_nontemporal_store(dA, (u32x4*)p); __builtin_nontemporal_store(dB, (u32x4*)(p + 8 * ld));
; }
;     __device__ __forceinline__ void operator()(f32x4 (&acc)[2][2][4][2], const Unit& u, int wr, int wc, int fr, int fq) const {
;     ...
;                 store_pair(P + (size_t)(rowg + ai * HALF + m * 16) * INC + colw, INC, fr, fq, pk[0], pk[1]);
;             }
;     }
.LBB0_528:
	s_add_i32 s0, s7, 0xb0
	v_cvt_pk_bf16_f32 v2, v18, v19
	v_cvt_pk_bf16_f32 v6, v10, v11
	s_mul_hi_i32 s1, s0, 0x6000
	s_mulk_i32 s0, 0x6000
	v_cvt_pk_bf16_f32 v3, v20, v21
	v_cvt_pk_bf16_f32 v7, v16, v17
	v_cvt_pk_bf16_f32 v8, v14, v15
	s_add_u32 s0, s33, s0
	v_cndmask_b32_e64 v10, v2, v6, s[52:53]
	v_mov_b32_e32 v14, v131
	v_cvt_pk_bf16_f32 v4, v22, v23
	s_addc_u32 s1, s15, s1
	v_cndmask_b32_e64 v11, v3, v7, s[52:53]
	v_mov_b32_dpp v14, v10 row_ror:8 row_mask:0xf bank_mask:0xf
	v_mov_b32_e32 v10, v131
	v_cvt_pk_bf16_f32 v9, v12, v13
	s_add_u32 s0, s0, s4
	v_cndmask_b32_e64 v12, v4, v8, s[52:53]
	v_mov_b32_dpp v10, v11 row_ror:8 row_mask:0xf bank_mask:0xf
	v_mov_b32_e32 v11, v131
	v_cvt_pk_bf16_f32 v5, v24, v25
	s_addc_u32 s1, s1, s5
	v_mov_b32_dpp v11, v12 row_ror:8 row_mask:0xf bank_mask:0xf
	v_cndmask_b32_e64 v13, v5, v9, s[52:53]
	v_mov_b32_e32 v12, v131
	v_cndmask_b32_e64 v3, v10, v3, s[52:53]
	v_cndmask_b32_e64 v4, v11, v4, s[52:53]
	v_cndmask_b32_e64 v7, v7, v10, s[52:53]
	v_cndmask_b32_e64 v8, v8, v11, s[52:53]
	v_lshl_add_u64 v[10:11], s[0:1], 0, v[130:131]
	v_mov_b32_e32 v115, v131
	v_mov_b32_dpp v12, v13 row_ror:8 row_mask:0xf bank_mask:0xf
	v_lshl_add_u64 v[10:11], v[10:11], 0, v[114:115]
	v_mov_b32_e32 v117, v131
	v_cndmask_b32_e64 v2, v14, v2, s[52:53]
	v_cndmask_b32_e64 v5, v12, v5, s[52:53]
	v_lshl_add_u64 v[10:11], v[10:11], 0, v[116:117]
	global_store_dwordx4 v[10:11], v[2:5], off sc1
	v_cndmask_b32_e64 v6, v6, v14, s[52:53]
	v_cndmask_b32_e64 v9, v9, v12, s[52:53]
	v_add_co_u32_e32 v2, vcc, 0x30000, v10
	s_mov_b64 s[0:1], -1
	s_nop 0
	v_addc_co_u32_e32 v3, vcc, 0, v11, vcc
	s_andn2_b64 vcc, exec, s[54:55]
	global_store_dwordx4 v[2:3], v[6:9], off sc1
	s_cbranch_vccnz .LBB0_354
	s_andn2_b64 vcc, exec, s[58:59]
	s_cbranch_vccnz .LBB0_353
	s_barrier
	s_branch .LBB0_353

;     __device__ __forceinline__ void operator()(f32x4 (&acc)[2][2][4][2], const Unit& u, int wr, int wc, int fr, int fq) const {
;         const int rowg = u.pm * BM + wr * 64, colw = u.pn * BM + wc * 64, col0 = colw + 8 * fq;
;         const int grp = (u.pn + C_I8 / BM) >> 2, mode = grp >= 6 ? 3 : (grp == 5 ? 2 : 0);
;         if (mode == 3) {
;     ...
;         f32x4 cq[4]; float sq[8];
;         const float qs = mode == 2 ? 0.0625f * LOG2E : 1.0f;
; #pragma unroll
;         for (int k = 0; k < 4; ++k) { const u32x4 c_ = *(const u32x4*)(cmax + col0 + (k >> 1) * CBJ + (k & 1) * 4);
; #pragma unroll
;             for (int j = 0; j < 4; ++j) cq[k][j] = __uint_as_float(c_[j]) * qs; }
; #pragma unroll
;         for (int k = 0; k < 8; ++k) sq[k] = sa[rowg + (k >> 2) * HALF + (k & 3) * 16 + fr] * (1.0f / 127.0f);
.LBB0_542:
	s_mov_b32 s0, 0
	s_mov_b32 s1, -1
	s_lshl_b32 s14, s2, 8
	s_lshl_b32 s0, s3, 8
	v_cvt_f32_i32_e32 v167, v127
	v_cvt_f32_i32_e32 v166, v126
	v_cvt_f32_i32_e32 v165, v123
	v_cvt_f32_i32_e32 v164, v122
	v_cvt_f32_i32_e32 v163, v129
	v_cvt_f32_i32_e32 v162, v128
	v_cvt_f32_i32_e32 v161, v125
	v_cvt_f32_i32_e32 v160, v124
	v_cvt_f32_i32_e32 v159, v111
	v_cvt_f32_i32_e32 v158, v110
	v_cvt_f32_i32_e32 v157, v107
	v_cvt_f32_i32_e32 v156, v106
	v_cvt_f32_i32_e32 v155, v113
	v_cvt_f32_i32_e32 v154, v112
	v_cvt_f32_i32_e32 v153, v109
	v_cvt_f32_i32_e32 v152, v108
	v_cvt_f32_i32_e32 v129, v119
	v_cvt_f32_i32_e32 v128, v118
	v_cvt_f32_i32_e32 v127, v115
	v_cvt_f32_i32_e32 v126, v114
	v_cvt_f32_i32_e32 v125, v121
	v_cvt_f32_i32_e32 v124, v120
	v_cvt_f32_i32_e32 v123, v117
	v_cvt_f32_i32_e32 v122, v116
	v_cvt_f32_i32_e32 v121, v95
	v_cvt_f32_i32_e32 v120, v94
	v_cvt_f32_i32_e32 v119, v91
	v_cvt_f32_i32_e32 v118, v90
	v_cvt_f32_i32_e32 v117, v97
	v_cvt_f32_i32_e32 v116, v96
	v_cvt_f32_i32_e32 v115, v93
	v_cvt_f32_i32_e32 v114, v92
	v_cvt_f32_i32_e32 v113, v103
	v_cvt_f32_i32_e32 v112, v102
	v_cvt_f32_i32_e32 v111, v99
	v_cvt_f32_i32_e32 v110, v98
	v_cvt_f32_i32_e32 v109, v105
	v_cvt_f32_i32_e32 v108, v104
	v_cvt_f32_i32_e32 v107, v101
	v_cvt_f32_i32_e32 v106, v100
	v_cvt_f32_i32_e32 v105, v79
	v_cvt_f32_i32_e32 v104, v78
	v_cvt_f32_i32_e32 v103, v75
	v_cvt_f32_i32_e32 v102, v74
	v_cvt_f32_i32_e32 v101, v81
	v_cvt_f32_i32_e32 v100, v80
	v_cvt_f32_i32_e32 v99, v77
	v_cvt_f32_i32_e32 v98, v76
	v_cvt_f32_i32_e32 v97, v87
	v_cvt_f32_i32_e32 v96, v86
	v_cvt_f32_i32_e32 v95, v83
	v_cvt_f32_i32_e32 v94, v82
	v_cvt_f32_i32_e32 v93, v89
	v_cvt_f32_i32_e32 v92, v88
	v_cvt_f32_i32_e32 v91, v85
	v_cvt_f32_i32_e32 v90, v84
	v_cvt_f32_i32_e32 v89, v71
	v_cvt_f32_i32_e32 v88, v70
	v_cvt_f32_i32_e32 v87, v67
	v_cvt_f32_i32_e32 v86, v66
	v_cvt_f32_i32_e32 v85, v73
	v_cvt_f32_i32_e32 v84, v72
	v_cvt_f32_i32_e32 v83, v69
	v_cvt_f32_i32_e32 v82, v68
	v_cvt_f32_i32_e32 v77, v63
	v_cvt_f32_i32_e32 v76, v62
	v_cvt_f32_i32_e32 v75, v59
	v_cvt_f32_i32_e32 v74, v58
	v_cvt_f32_i32_e32 v69, v65
	v_cvt_f32_i32_e32 v68, v64
	v_cvt_f32_i32_e32 v67, v61
	v_cvt_f32_i32_e32 v66, v60
	v_cvt_f32_i32_e32 v65, v47
	v_cvt_f32_i32_e32 v64, v46
	v_cvt_f32_i32_e32 v63, v43
	v_cvt_f32_i32_e32 v62, v42
	v_cvt_f32_i32_e32 v61, v49
	v_cvt_f32_i32_e32 v60, v48
	v_cvt_f32_i32_e32 v59, v45
	v_cvt_f32_i32_e32 v58, v44
	v_cvt_f32_i32_e32 v49, v55
	v_cvt_f32_i32_e32 v48, v54
	v_cvt_f32_i32_e32 v47, v51
	v_cvt_f32_i32_e32 v46, v50
	v_cvt_f32_i32_e32 v45, v57
	v_cvt_f32_i32_e32 v44, v56
	v_cvt_f32_i32_e32 v43, v53
	v_cvt_f32_i32_e32 v42, v52
	s_add_i32 s14, s14, s80
	s_or_b32 s0, s0, s95
	s_add_i32 s1, s3, 20
	v_or_b32_e32 v168, s0, v140
	s_ashr_i32 s1, s1, 2
	v_or_b32_e32 v50, s14, v141
	s_mov_b64 s[6:7], -1
	s_cmp_lt_i32 s1, 6
	v_ashrrev_i32_e32 v169, 31, v168
	v_ashrrev_i32_e32 v51, 31, v50
	s_cbranch_scc0 .LBB0_544
	v_readlane_b32 s22, v249, 57
	v_readlane_b32 s23, v249, 58
	s_cmp_eq_u32 s1, 5
	v_lshl_add_u64 v[56:57], v[168:169], 2, s[16:17]
	v_lshl_add_u64 v[52:53], v[50:51], 2, s[22:23]
	global_load_dword v79, v[52:53], off
	global_load_dword v80, v[52:53], off offset:64
	global_load_dword v81, v[52:53], off offset:128
	global_load_dword v149, v[52:53], off offset:192
	s_nop 0
	global_load_dwordx4 v[52:55], v[56:57], off
	global_load_dwordx4 v[70:73], v[56:57], off offset:16
	global_load_dwordx4 v[182:185], v[56:57], off offset:128
	global_load_dwordx4 v[186:189], v[56:57], off offset:144
	s_cselect_b64 vcc, -1, 0
	s_add_i32 s7, s14, 0x80
	v_or_b32_e32 v56, s7, v141
	v_ashrrev_i32_e32 v57, 31, v56
	v_lshl_add_u64 v[56:57], v[56:57], 2, s[22:23]
	global_load_dword v151, v[56:57], off
	global_load_dword v176, v[56:57], off offset:64
	global_load_dword v181, v[56:57], off offset:128
	global_load_dword v191, v[56:57], off offset:192
	v_mov_b32_e32 v56, 0x3db8aa3b
	v_cndmask_b32_e32 v78, 1.0, v56, vcc
	s_mul_i32 s6, s14, 0x6000
	s_ashr_i32 s1, s0, 31
	s_mul_hi_i32 s21, s14, 0x6000
	s_add_u32 s22, s33, s6
	s_addc_u32 s21, s15, s21
	s_lshl_b64 s[0:1], s[0:1], 1
	v_mov_b32_e32 v200, v131
	s_add_u32 s22, s22, s0
	v_mov_b32_e32 v202, v131
	s_addc_u32 s23, s21, s1
	v_mov_b32_e32 v193, v131
	v_mov_b32_e32 v201, v131
	s_movk_i32 s24, 0x2000
	s_mov_b32 s25, 0x32000
	s_or_b32 s21, s14, 16
	s_mul_hi_i32 s7, s7, 0x6000
	s_waitcnt vmcnt(0)
; __device__ __forceinline__ u32x4 pack8(f32x4 a, f32x4 b) { u32x4 w; w.x = cvtpk(a[0], a[1]); w.y = cvtpk(a[2], a[3]); w.z = cvtpk(b[0], b[1]); w.w = cvtpk(b[2], b[3]); return w; }
;     __device__ __forceinline__ void operator()(f32x4 (&acc)[2][2][4][2], const Unit& u, int wr, int wc, int fr, int fq) const {
;     ...
; #pragma unroll
;         for (int ai = 0; ai < 2; ++ai)
; #pragma unroll
;             for (int m = 0; m < 4; ++m) {
;                 const float s = sq[ai * 4 + m];
;                 u32x4 pk[2];
; #pragma unroll
;                 for (int bj = 0; bj < 2; ++bj) {
;                     const v4i_t i0 = __builtin_bit_cast(v4i_t, acc[ai][bj][m][0]), i1 = __builtin_bit_cast(v4i_t, acc[ai][bj][m][1]);
;                     f32x4 v0, v1;
; #pragma unroll
;                     for (int j = 0; j < 4; ++j) { v0[j] = (float)i0[j] * (s * cq[bj * 2][j]); v1[j] = (float)i1[j] * (s * cq[bj * 2 + 1][j]); }
;                     pk[bj] = pack8(v0, v1);
;                 }
;                 store_pair(P + (size_t)(rowg + ai * HALF + m * 16) * INC + C_I8 + colw, INC, fr, fq, pk[0], pk[1]);
	v_mul_f32_e32 v174, 0x3c010204, v79
	v_mul_f32_e32 v190, 0x3c010204, v80
	v_mul_f32_e32 v192, 0x3c010204, v81
	v_mul_f32_e32 v180, 0x3c010204, v149
	v_pk_mul_f32 v[80:81], v[78:79], v[54:55] op_sel_hi:[0,1]
	v_pk_mul_f32 v[72:73], v[78:79], v[72:73] op_sel_hi:[0,1]
	v_pk_mul_f32 v[54:55], v[78:79], v[184:185] op_sel_hi:[0,1]
	v_pk_mul_f32 v[172:173], v[78:79], v[52:53] op_sel_hi:[0,1]
	v_pk_mul_f32 v[170:171], v[78:79], v[70:71] op_sel_hi:[0,1]
	v_pk_mul_f32 v[70:71], v[78:79], v[182:183] op_sel_hi:[0,1]
	v_pk_mul_f32 v[56:57], v[78:79], v[186:187] op_sel_hi:[0,1]
	v_pk_mul_f32 v[52:53], v[78:79], v[188:189] op_sel_hi:[0,1]
	v_pk_mul_f32 v[184:185], v[80:81], v[174:175] op_sel_hi:[1,0]
	v_pk_mul_f32 v[186:187], v[72:73], v[174:175] op_sel_hi:[1,0]
	v_pk_mul_f32 v[196:197], v[54:55], v[174:175] op_sel_hi:[1,0]
	v_pk_mul_f32 v[188:189], v[70:71], v[174:175] op_sel_hi:[1,0]
	v_pk_mul_f32 v[198:199], v[52:53], v[174:175] op_sel_hi:[1,0]
	v_pk_mul_f32 v[184:185], v[184:185], v[162:163]
	v_pk_mul_f32 v[186:187], v[186:187], v[160:161]
	v_pk_mul_f32 v[196:197], v[196:197], v[154:155]
	v_pk_mul_f32 v[78:79], v[172:173], v[174:175] op_sel_hi:[1,0]
	v_pk_mul_f32 v[182:183], v[170:171], v[174:175] op_sel_hi:[1,0]
	v_pk_mul_f32 v[188:189], v[188:189], v[158:159]
	v_pk_mul_f32 v[198:199], v[198:199], v[152:153]
	v_cvt_pk_bf16_f32 v149, v184, v185
	v_cvt_pk_bf16_f32 v185, v186, v187
	v_cvt_pk_bf16_f32 v187, v196, v197
	v_pk_mul_f32 v[194:195], v[56:57], v[174:175] op_sel_hi:[1,0]
	v_pk_mul_f32 v[78:79], v[78:79], v[166:167]
	v_pk_mul_f32 v[182:183], v[182:183], v[164:165]
	v_cvt_pk_bf16_f32 v186, v188, v189
	v_cvt_pk_bf16_f32 v189, v198, v199
	v_mul_f32_e32 v174, 0x3c010204, v181
	v_cndmask_b32_e64 v181, v149, v187, s[52:53]
	v_pk_mul_f32 v[194:195], v[194:195], v[156:157]
	v_cvt_pk_bf16_f32 v79, v78, v79
	v_cvt_pk_bf16_f32 v184, v182, v183
	v_cndmask_b32_e64 v183, v185, v189, s[52:53]
	v_mov_b32_dpp v200, v181 row_ror:8 row_mask:0xf bank_mask:0xf
	v_cvt_pk_bf16_f32 v188, v194, v195
	v_mul_f32_e32 v178, 0x3c010204, v151
	v_cndmask_b32_e64 v151, v79, v186, s[52:53]
	v_mov_b32_dpp v202, v183 row_ror:8 row_mask:0xf bank_mask:0xf
	v_cndmask_b32_e64 v183, v200, v149, s[52:53]
	v_lshl_add_u64 v[194:195], s[22:23], 0, v[130:131]
	v_mov_b32_e32 v149, v131
	v_mov_b32_dpp v193, v151 row_ror:8 row_mask:0xf bank_mask:0xf
	v_lshl_add_u64 v[194:195], v[194:195], 0, v[148:149]
	v_mov_b32_e32 v151, v131
	v_cndmask_b32_e64 v182, v184, v188, s[52:53]
	v_lshl_add_u64 v[194:195], v[194:195], 0, v[150:151]
	v_add_co_u32_e32 v196, vcc, s24, v194
	v_mov_b32_dpp v201, v182 row_ror:8 row_mask:0xf bank_mask:0xf
	v_cndmask_b32_e64 v182, v193, v79, s[52:53]
	v_cndmask_b32_e64 v184, v201, v184, s[52:53]
	v_cndmask_b32_e64 v185, v202, v185, s[52:53]
	v_addc_co_u32_e32 v197, vcc, 0, v195, vcc
	global_store_dwordx4 v[196:197], v[182:185], off offset:2048 sc1
	v_cndmask_b32_e64 v186, v186, v193, s[52:53]
	v_cndmask_b32_e64 v187, v187, v200, s[52:53]
	v_add_co_u32_e32 v182, vcc, s25, v194
	v_cndmask_b32_e64 v188, v188, v201, s[52:53]
	v_cndmask_b32_e64 v189, v189, v202, s[52:53]
	v_addc_co_u32_e32 v183, vcc, 0, v195, vcc
	v_pk_mul_f32 v[184:185], v[170:171], v[190:191] op_sel_hi:[1,0]
	global_store_dwordx4 v[182:183], v[186:189], off offset:2048 sc1
	v_pk_mul_f32 v[182:183], v[172:173], v[190:191] op_sel_hi:[1,0]
	v_pk_mul_f32 v[184:185], v[184:185], v[126:127]
	v_mul_f32_e32 v78, 0x3c010204, v191
	v_pk_mul_f32 v[182:183], v[182:183], v[128:129]
	v_pk_mul_f32 v[186:187], v[80:81], v[190:191] op_sel_hi:[1,0]
	v_pk_mul_f32 v[188:189], v[72:73], v[190:191] op_sel_hi:[1,0]
	v_cvt_pk_bf16_f32 v191, v184, v185
	v_pk_mul_f32 v[186:187], v[186:187], v[124:125]
	v_cvt_pk_bf16_f32 v79, v182, v183
	v_pk_mul_f32 v[182:183], v[70:71], v[190:191] op_sel_hi:[1,0]
	v_pk_mul_f32 v[184:185], v[56:57], v[190:191] op_sel_hi:[1,0]
	s_mul_hi_i32 s22, s21, 0x6000
	s_mulk_i32 s21, 0x6000
	v_pk_mul_f32 v[188:189], v[188:189], v[122:123]
	v_cvt_pk_bf16_f32 v181, v186, v187
	v_pk_mul_f32 v[182:183], v[182:183], v[120:121]
	v_pk_mul_f32 v[184:185], v[184:185], v[118:119]
	v_pk_mul_f32 v[186:187], v[54:55], v[190:191] op_sel_hi:[1,0]
	s_add_u32 s21, s33, s21
	v_cvt_pk_bf16_f32 v193, v188, v189
	v_pk_mul_f32 v[186:187], v[186:187], v[116:117]
	v_pk_mul_f32 v[188:189], v[52:53], v[190:191] op_sel_hi:[1,0]
	v_cvt_pk_bf16_f32 v190, v182, v183
	v_cvt_pk_bf16_f32 v194, v184, v185
	s_addc_u32 s23, s15, s22
	v_cvt_pk_bf16_f32 v187, v186, v187
	s_add_u32 s22, s21, s0
	v_cndmask_b32_e64 v182, v79, v190, s[52:53]
	v_cndmask_b32_e64 v184, v191, v194, s[52:53]
	v_mov_b32_e32 v186, v131
	v_mov_b32_e32 v195, v131
	s_addc_u32 s23, s23, s1
	v_mov_b32_dpp v186, v182 row_ror:8 row_mask:0xf bank_mask:0xf
	v_mov_b32_dpp v195, v184 row_ror:8 row_mask:0xf bank_mask:0xf
	v_pk_mul_f32 v[188:189], v[188:189], v[114:115]
	v_cndmask_b32_e64 v182, v186, v79, s[52:53]
	v_cndmask_b32_e64 v184, v195, v191, s[52:53]
	v_cndmask_b32_e64 v186, v190, v186, s[52:53]
	v_lshl_add_u64 v[190:191], s[22:23], 0, v[130:131]
	v_cvt_pk_bf16_f32 v189, v188, v189
	v_cndmask_b32_e64 v183, v181, v187, s[52:53]
	v_mov_b32_e32 v188, v131
	v_lshl_add_u64 v[190:191], v[190:191], 0, v[148:149]
	v_cndmask_b32_e64 v185, v193, v189, s[52:53]
	v_mov_b32_dpp v188, v183 row_ror:8 row_mask:0xf bank_mask:0xf
	v_mov_b32_e32 v196, v131
	v_lshl_add_u64 v[190:191], v[190:191], 0, v[150:151]
	v_cndmask_b32_e64 v183, v188, v181, s[52:53]
	v_mov_b32_dpp v196, v185 row_ror:8 row_mask:0xf bank_mask:0xf
	v_cndmask_b32_e64 v187, v187, v188, s[52:53]
	v_cndmask_b32_e64 v188, v194, v195, s[52:53]
	v_add_co_u32_e32 v194, vcc, s24, v190
	v_cndmask_b32_e64 v185, v196, v193, s[52:53]
; __device__ __forceinline__ u32x4 pack8(f32x4 a, f32x4 b) { u32x4 w; w.x = cvtpk(a[0], a[1]); w.y = cvtpk(a[2], a[3]); w.z = cvtpk(b[0], b[1]); w.w = cvtpk(b[2], b[3]); return w; }
; __device__ __forceinline__ unsigned dpp_ror8(unsigned v) { return (unsigned)__builtin_amdgcn_update_dpp(0, (int)v, 0x128, 0xF, 0xF, false); }
; __device__ __forceinline__ void store_pair(bf16_t* grp  , size_t ld, int fr, int fq, u32x4 P0, u32x4 P1) {
;     const bool up = (fr & 8) != 0;
;     u32x4 snd, rcv;
;     snd.x = up ? P0.x : P1.x; snd.y = up ? P0.y : P1.y; snd.z = up ? P0.z : P1.z; snd.w = up ? P0.w : P1.w;
;     rcv.x = dpp_ror8(snd.x); rcv.y = dpp_ror8(snd.y); rcv.z = dpp_ror8(snd.z); rcv.w = dpp_ror8(snd.w);
;     u32x4 dA, dB;
;     dA.x = up ? rcv.x : P0.x; dA.y = up ? rcv.y : P0.y; dA.z = up ? rcv.z : P0.z; dA.w = up ? rcv.w : P0.w;
;     dB.x = up ? P1.x : rcv.x; dB.y = up ? P1.y : rcv.y; dB.z = up ? P1.z : rcv.z; dB.w = up ? P1.w : rcv.w;
;     bf16_t* p = grp + (size_t)(fr & 7) * ld + (up ? CBJ : 0) + 8 * fq;
;     __builtin_nontemporal_store(dA, (u32x4*)p); __builtin_nontemporal_store(dB, (u32x4*)(p + 8 * ld));
; }
;     __device__ __forceinline__ void operator()(f32x4 (&acc)[2][2][4][2], const Unit& u, int wr, int wc, int fr, int fq) const {
;     ...
;                 for (int bj = 0; bj < 2; ++bj) {
;                     const v4i_t i0 = __builtin_bit_cast(v4i_t, acc[ai][bj][m][0]), i1 = __builtin_bit_cast(v4i_t, acc[ai][bj][m][1]);
;                     f32x4 v0, v1;
; #pragma unroll
;                     for (int j = 0; j < 4; ++j) { v0[j] = (float)i0[j] * (s * cq[bj * 2][j]); v1[j] = (float)i1[j] * (s * cq[bj * 2 + 1][j]); }
;                     pk[bj] = pack8(v0, v1);
;                 }
;                 store_pair(P + (size_t)(rowg + ai * HALF + m * 16) * INC + C_I8 + colw, INC, fr, fq, pk[0], pk[1]);
	s_nop 0
	v_addc_co_u32_e32 v195, vcc, 0, v191, vcc
	global_store_dwordx4 v[194:195], v[182:185], off offset:2048 sc1
	v_cndmask_b32_e64 v189, v189, v196, s[52:53]
	s_or_b32 s21, s14, 32
	v_add_co_u32_e32 v182, vcc, s25, v190
	v_pk_mul_f32 v[184:185], v[170:171], v[192:193] op_sel_hi:[1,0]
	s_nop 0
	v_addc_co_u32_e32 v183, vcc, 0, v191, vcc
	global_store_dwordx4 v[182:183], v[186:189], off offset:2048 sc1
	v_pk_mul_f32 v[184:185], v[184:185], v[110:111]
	v_pk_mul_f32 v[182:183], v[172:173], v[192:193] op_sel_hi:[1,0]
	v_pk_mul_f32 v[188:189], v[72:73], v[192:193] op_sel_hi:[1,0]
	v_pk_mul_f32 v[186:187], v[80:81], v[192:193] op_sel_hi:[1,0]
	v_pk_mul_f32 v[188:189], v[188:189], v[106:107]
	v_cvt_pk_bf16_f32 v190, v184, v185
	v_cvt_pk_bf16_f32 v191, v188, v189
	v_pk_mul_f32 v[184:185], v[56:57], v[192:193] op_sel_hi:[1,0]
	v_pk_mul_f32 v[188:189], v[52:53], v[192:193] op_sel_hi:[1,0]
	s_mul_hi_i32 s22, s21, 0x6000
	s_mulk_i32 s21, 0x6000
	v_pk_mul_f32 v[182:183], v[182:183], v[112:113]
	v_pk_mul_f32 v[186:187], v[186:187], v[108:109]
	v_pk_mul_f32 v[184:185], v[184:185], v[102:103]
	v_pk_mul_f32 v[188:189], v[188:189], v[98:99]
	s_add_u32 s21, s33, s21
	v_cvt_pk_bf16_f32 v79, v182, v183
	v_cvt_pk_bf16_f32 v181, v186, v187
	v_pk_mul_f32 v[182:183], v[70:71], v[192:193] op_sel_hi:[1,0]
	v_pk_mul_f32 v[186:187], v[54:55], v[192:193] op_sel_hi:[1,0]
	v_cvt_pk_bf16_f32 v193, v184, v185
	v_cvt_pk_bf16_f32 v189, v188, v189
	s_addc_u32 s23, s15, s22
	s_add_u32 s22, s21, s0
	v_cndmask_b32_e64 v184, v190, v193, s[52:53]
	v_cndmask_b32_e64 v185, v191, v189, s[52:53]
	v_mov_b32_e32 v194, v131
	v_mov_b32_e32 v195, v131
	v_pk_mul_f32 v[182:183], v[182:183], v[104:105]
	s_addc_u32 s23, s23, s1
	v_mov_b32_dpp v194, v184 row_ror:8 row_mask:0xf bank_mask:0xf
	v_mov_b32_dpp v195, v185 row_ror:8 row_mask:0xf bank_mask:0xf
	v_pk_mul_f32 v[186:187], v[186:187], v[100:101]
	v_cvt_pk_bf16_f32 v192, v182, v183
	v_cndmask_b32_e64 v184, v194, v190, s[52:53]
	v_cndmask_b32_e64 v185, v195, v191, s[52:53]
	v_lshl_add_u64 v[190:191], s[22:23], 0, v[130:131]
	v_cvt_pk_bf16_f32 v187, v186, v187
	v_cndmask_b32_e64 v182, v79, v192, s[52:53]
	v_mov_b32_e32 v186, v131
	v_lshl_add_u64 v[190:191], v[190:191], 0, v[148:149]
	v_cndmask_b32_e64 v183, v181, v187, s[52:53]
	v_mov_b32_dpp v186, v182 row_ror:8 row_mask:0xf bank_mask:0xf
	v_mov_b32_e32 v188, v131
	v_lshl_add_u64 v[190:191], v[190:191], 0, v[150:151]
	v_cndmask_b32_e64 v182, v186, v79, s[52:53]
	v_mov_b32_dpp v188, v183 row_ror:8 row_mask:0xf bank_mask:0xf
	v_cndmask_b32_e64 v186, v192, v186, s[52:53]
	v_add_co_u32_e32 v192, vcc, s24, v190
	v_cndmask_b32_e64 v183, v188, v181, s[52:53]
	v_cndmask_b32_e64 v187, v187, v188, s[52:53]
	v_cndmask_b32_e64 v188, v193, v194, s[52:53]
	v_addc_co_u32_e32 v193, vcc, 0, v191, vcc
	global_store_dwordx4 v[192:193], v[182:185], off offset:2048 sc1
	v_cndmask_b32_e64 v189, v189, v195, s[52:53]
	s_or_b32 s21, s14, 48
	v_add_co_u32_e32 v182, vcc, s25, v190
	v_pk_mul_f32 v[184:185], v[170:171], v[180:181] op_sel_hi:[1,0]
	s_nop 0
	v_addc_co_u32_e32 v183, vcc, 0, v191, vcc
	global_store_dwordx4 v[182:183], v[186:189], off offset:2048 sc1
	v_pk_mul_f32 v[182:183], v[172:173], v[180:181] op_sel_hi:[1,0]
	v_pk_mul_f32 v[184:185], v[184:185], v[94:95]
	v_pk_mul_f32 v[186:187], v[80:81], v[180:181] op_sel_hi:[1,0]
	v_pk_mul_f32 v[182:183], v[182:183], v[96:97]
	v_pk_mul_f32 v[186:187], v[186:187], v[92:93]
	v_pk_mul_f32 v[188:189], v[72:73], v[180:181] op_sel_hi:[1,0]
	v_cvt_pk_bf16_f32 v79, v182, v183
	v_cvt_pk_bf16_f32 v190, v186, v187
	v_cvt_pk_bf16_f32 v191, v184, v185
	v_pk_mul_f32 v[182:183], v[70:71], v[180:181] op_sel_hi:[1,0]
	v_pk_mul_f32 v[184:185], v[56:57], v[180:181] op_sel_hi:[1,0]
	v_pk_mul_f32 v[186:187], v[54:55], v[180:181] op_sel_hi:[1,0]
	v_pk_mul_f32 v[180:181], v[52:53], v[180:181] op_sel_hi:[1,0]
	s_mul_hi_i32 s22, s21, 0x6000
	s_mulk_i32 s21, 0x6000
	v_pk_mul_f32 v[188:189], v[188:189], v[90:91]
	v_pk_mul_f32 v[182:183], v[182:183], v[88:89]
	v_pk_mul_f32 v[180:181], v[180:181], v[82:83]
	s_add_u32 s21, s33, s21
	v_cvt_pk_bf16_f32 v188, v188, v189
	v_pk_mul_f32 v[184:185], v[184:185], v[86:87]
	v_pk_mul_f32 v[186:187], v[186:187], v[84:85]
	v_cvt_pk_bf16_f32 v189, v182, v183
	v_cvt_pk_bf16_f32 v192, v180, v181
	s_addc_u32 s23, s15, s22
	v_cvt_pk_bf16_f32 v186, v186, v187
	v_cvt_pk_bf16_f32 v187, v184, v185
	s_add_u32 s22, s21, s0
	v_cndmask_b32_e64 v180, v79, v189, s[52:53]
	v_cndmask_b32_e64 v183, v188, v192, s[52:53]
	v_mov_b32_e32 v184, v131
	v_mov_b32_e32 v194, v131
	s_addc_u32 s23, s23, s1
	v_mov_b32_dpp v184, v180 row_ror:8 row_mask:0xf bank_mask:0xf
	v_mov_b32_dpp v194, v183 row_ror:8 row_mask:0xf bank_mask:0xf
	v_cndmask_b32_e64 v180, v184, v79, s[52:53]
	v_cndmask_b32_e64 v183, v194, v188, s[52:53]
	v_cndmask_b32_e64 v184, v189, v184, s[52:53]
	v_lshl_add_u64 v[188:189], s[22:23], 0, v[130:131]
	v_cndmask_b32_e64 v181, v190, v186, s[52:53]
	v_mov_b32_e32 v185, v131
	v_lshl_add_u64 v[188:189], v[188:189], 0, v[148:149]
	v_cndmask_b32_e64 v182, v191, v187, s[52:53]
	v_mov_b32_dpp v185, v181 row_ror:8 row_mask:0xf bank_mask:0xf
	v_mov_b32_e32 v193, v131
	v_lshl_add_u64 v[188:189], v[188:189], 0, v[150:151]
	v_cndmask_b32_e64 v181, v185, v190, s[52:53]
	v_mov_b32_dpp v193, v182 row_ror:8 row_mask:0xf bank_mask:0xf
	v_add_co_u32_e32 v190, vcc, s24, v188
	v_cndmask_b32_e64 v182, v193, v191, s[52:53]
	s_nop 0
	v_addc_co_u32_e32 v191, vcc, 0, v189, vcc
	global_store_dwordx4 v[190:191], v[180:183], off offset:2048 sc1
	v_cndmask_b32_e64 v185, v186, v185, s[52:53]
	v_cndmask_b32_e64 v186, v187, v193, s[52:53]
	v_add_co_u32_e32 v180, vcc, s25, v188
; __device__ __forceinline__ u32x4 pack8(f32x4 a, f32x4 b) { u32x4 w; w.x = cvtpk(a[0], a[1]); w.y = cvtpk(a[2], a[3]); w.z = cvtpk(b[0], b[1]); w.w = cvtpk(b[2], b[3]); return w; }
; __device__ __forceinline__ unsigned dpp_ror8(unsigned v) { return (unsigned)__builtin_amdgcn_update_dpp(0, (int)v, 0x128, 0xF, 0xF, false); }
; __device__ __forceinline__ void store_pair(bf16_t* grp  , size_t ld, int fr, int fq, u32x4 P0, u32x4 P1) {
;     const bool up = (fr & 8) != 0;
;     u32x4 snd, rcv;
;     snd.x = up ? P0.x : P1.x; snd.y = up ? P0.y : P1.y; snd.z = up ? P0.z : P1.z; snd.w = up ? P0.w : P1.w;
;     rcv.x = dpp_ror8(snd.x); rcv.y = dpp_ror8(snd.y); rcv.z = dpp_ror8(snd.z); rcv.w = dpp_ror8(snd.w);
;     u32x4 dA, dB;
;     dA.x = up ? rcv.x : P0.x; dA.y = up ? rcv.y : P0.y; dA.z = up ? rcv.z : P0.z; dA.w = up ? rcv.w : P0.w;
;     dB.x = up ? P1.x : rcv.x; dB.y = up ? P1.y : rcv.y; dB.z = up ? P1.z : rcv.z; dB.w = up ? P1.w : rcv.w;
;     bf16_t* p = grp + (size_t)(fr & 7) * ld + (up ? CBJ : 0) + 8 * fq;
;     __builtin_nontemporal_store(dA, (u32x4*)p); __builtin_nontemporal_store(dB, (u32x4*)(p + 8 * ld));
; }
;     __device__ __forceinline__ void operator()(f32x4 (&acc)[2][2][4][2], const Unit& u, int wr, int wc, int fr, int fq) const {
;     ...
;                 for (int bj = 0; bj < 2; ++bj) {
;                     const v4i_t i0 = __builtin_bit_cast(v4i_t, acc[ai][bj][m][0]), i1 = __builtin_bit_cast(v4i_t, acc[ai][bj][m][1]);
;                     f32x4 v0, v1;
; #pragma unroll
;                     for (int j = 0; j < 4; ++j) { v0[j] = (float)i0[j] * (s * cq[bj * 2][j]); v1[j] = (float)i1[j] * (s * cq[bj * 2 + 1][j]); }
;                     pk[bj] = pack8(v0, v1);
;                 }
;                 store_pair(P + (size_t)(rowg + ai * HALF + m * 16) * INC + C_I8 + colw, INC, fr, fq, pk[0], pk[1]);
	v_cndmask_b32_e64 v187, v192, v194, s[52:53]
	s_nop 0
	v_addc_co_u32_e32 v181, vcc, 0, v189, vcc
	global_store_dwordx4 v[180:181], v[184:187], off offset:2048 sc1
	v_pk_mul_f32 v[182:183], v[170:171], v[178:179] op_sel_hi:[1,0]
	v_pk_mul_f32 v[180:181], v[172:173], v[178:179] op_sel_hi:[1,0]
	v_pk_mul_f32 v[184:185], v[80:81], v[178:179] op_sel_hi:[1,0]
	v_pk_mul_f32 v[182:183], v[182:183], v[74:75]
	v_pk_mul_f32 v[184:185], v[184:185], v[68:69]
	v_pk_mul_f32 v[186:187], v[72:73], v[178:179] op_sel_hi:[1,0]
	v_pk_mul_f32 v[180:181], v[180:181], v[76:77]
	v_pk_mul_f32 v[186:187], v[186:187], v[66:67]
	v_cvt_pk_bf16_f32 v188, v184, v185
	v_cvt_pk_bf16_f32 v189, v182, v183
	v_pk_mul_f32 v[182:183], v[56:57], v[178:179] op_sel_hi:[1,0]
	v_pk_mul_f32 v[184:185], v[54:55], v[178:179] op_sel_hi:[1,0]
	s_add_i32 s21, s6, 0x300000
	v_cvt_pk_bf16_f32 v79, v180, v181
	v_cvt_pk_bf16_f32 v190, v186, v187
	v_pk_mul_f32 v[180:181], v[70:71], v[178:179] op_sel_hi:[1,0]
	v_pk_mul_f32 v[182:183], v[182:183], v[62:63]
	v_pk_mul_f32 v[184:185], v[184:185], v[60:61]
	v_pk_mul_f32 v[186:187], v[52:53], v[178:179] op_sel_hi:[1,0]
	s_add_u32 s21, s33, s21
	v_pk_mul_f32 v[180:181], v[180:181], v[64:65]
	v_pk_mul_f32 v[186:187], v[186:187], v[58:59]
	v_cvt_pk_bf16_f32 v185, v184, v185
	v_cvt_pk_bf16_f32 v191, v182, v183
	s_addc_u32 s7, s15, s7
	v_cvt_pk_bf16_f32 v178, v180, v181
	v_cvt_pk_bf16_f32 v187, v186, v187
	s_add_u32 s22, s21, s0
	v_cndmask_b32_e64 v181, v188, v185, s[52:53]
	v_cndmask_b32_e64 v182, v189, v191, s[52:53]
	v_mov_b32_e32 v186, v131
	v_mov_b32_e32 v192, v131
	s_addc_u32 s23, s7, s1
	v_mov_b32_dpp v186, v181 row_ror:8 row_mask:0xf bank_mask:0xf
	v_mov_b32_dpp v192, v182 row_ror:8 row_mask:0xf bank_mask:0xf
	v_cndmask_b32_e64 v181, v186, v188, s[52:53]
	v_cndmask_b32_e64 v182, v192, v189, s[52:53]
	v_lshl_add_u64 v[188:189], s[22:23], 0, v[130:131]
	v_cndmask_b32_e64 v183, v190, v187, s[52:53]
	v_mov_b32_e32 v193, v131
	v_lshl_add_u64 v[188:189], v[188:189], 0, v[148:149]
	v_cndmask_b32_e64 v180, v79, v178, s[52:53]
	v_mov_b32_e32 v184, v131
	v_mov_b32_dpp v193, v183 row_ror:8 row_mask:0xf bank_mask:0xf
	v_lshl_add_u64 v[188:189], v[188:189], 0, v[150:151]
	v_mov_b32_dpp v184, v180 row_ror:8 row_mask:0xf bank_mask:0xf
	v_cndmask_b32_e64 v183, v193, v190, s[52:53]
	v_add_co_u32_e32 v190, vcc, s24, v188
	v_cndmask_b32_e64 v180, v184, v79, s[52:53]
	v_cndmask_b32_e64 v185, v185, v186, s[52:53]
	v_cndmask_b32_e64 v186, v191, v192, s[52:53]
	v_addc_co_u32_e32 v191, vcc, 0, v189, vcc
	global_store_dwordx4 v[190:191], v[180:183], off offset:2048 sc1
	v_mul_f32_e32 v176, 0x3c010204, v176
	v_cndmask_b32_e64 v184, v178, v184, s[52:53]
	v_add_co_u32_e32 v180, vcc, s25, v188
	v_cndmask_b32_e64 v187, v187, v193, s[52:53]
	s_nop 0
	v_addc_co_u32_e32 v181, vcc, 0, v189, vcc
	global_store_dwordx4 v[180:181], v[184:187], off offset:2048 sc1
	v_pk_mul_f32 v[180:181], v[172:173], v[176:177] op_sel_hi:[1,0]
	v_pk_mul_f32 v[182:183], v[170:171], v[176:177] op_sel_hi:[1,0]
	v_pk_mul_f32 v[180:181], v[180:181], v[48:49]
	v_pk_mul_f32 v[182:183], v[182:183], v[46:47]
	v_cvt_pk_bf16_f32 v79, v180, v181
	v_cvt_f32_i32_e32 v181, v39
	v_cvt_f32_i32_e32 v180, v38
	v_pk_mul_f32 v[184:185], v[80:81], v[176:177] op_sel_hi:[1,0]
	v_cvt_pk_bf16_f32 v190, v182, v183
	v_cvt_f32_i32_e32 v183, v35
	v_cvt_f32_i32_e32 v182, v34
	v_pk_mul_f32 v[184:185], v[184:185], v[44:45]
	v_pk_mul_f32 v[186:187], v[72:73], v[176:177] op_sel_hi:[1,0]
	v_cvt_pk_bf16_f32 v178, v184, v185
	v_pk_mul_f32 v[184:185], v[70:71], v[176:177] op_sel_hi:[1,0]
	v_pk_mul_f32 v[186:187], v[186:187], v[42:43]
	v_pk_mul_f32 v[180:181], v[184:185], v[180:181]
	v_pk_mul_f32 v[184:185], v[56:57], v[176:177] op_sel_hi:[1,0]
	v_cvt_pk_bf16_f32 v191, v186, v187
	v_pk_mul_f32 v[182:183], v[184:185], v[182:183]
	v_cvt_f32_i32_e32 v185, v41
	v_cvt_f32_i32_e32 v184, v40
	v_cvt_f32_i32_e32 v187, v37
	v_cvt_f32_i32_e32 v186, v36
	v_pk_mul_f32 v[188:189], v[54:55], v[176:177] op_sel_hi:[1,0]
	s_add_i32 s7, s14, 0x90
	s_add_i32 s21, s6, 0x360000
	v_pk_mul_f32 v[184:185], v[188:189], v[184:185]
	v_pk_mul_f32 v[188:189], v[52:53], v[176:177] op_sel_hi:[1,0]
	s_mul_hi_i32 s7, s7, 0x6000
	s_add_u32 s21, s33, s21
	v_pk_mul_f32 v[186:187], v[188:189], v[186:187]
	v_cvt_pk_bf16_f32 v185, v184, v185
	v_cvt_pk_bf16_f32 v188, v182, v183
	s_addc_u32 s7, s15, s7
	v_cvt_pk_bf16_f32 v176, v180, v181
	v_cvt_pk_bf16_f32 v187, v186, v187
	s_add_u32 s22, s21, s0
	v_cndmask_b32_e64 v181, v178, v185, s[52:53]
	v_cndmask_b32_e64 v182, v190, v188, s[52:53]
	v_mov_b32_e32 v186, v131
	v_mov_b32_e32 v189, v131
	s_addc_u32 s23, s7, s1
	v_mov_b32_dpp v186, v181 row_ror:8 row_mask:0xf bank_mask:0xf
	v_mov_b32_dpp v189, v182 row_ror:8 row_mask:0xf bank_mask:0xf
	v_cndmask_b32_e64 v181, v186, v178, s[52:53]
	v_cndmask_b32_e64 v182, v189, v190, s[52:53]
	v_cndmask_b32_e64 v185, v185, v186, s[52:53]
	v_cndmask_b32_e64 v186, v188, v189, s[52:53]
	v_lshl_add_u64 v[188:189], s[22:23], 0, v[130:131]
	v_lshl_add_u64 v[188:189], v[188:189], 0, v[148:149]
	v_cndmask_b32_e64 v180, v79, v176, s[52:53]
	v_cndmask_b32_e64 v183, v191, v187, s[52:53]
	v_mov_b32_e32 v184, v131
	v_mov_b32_e32 v192, v131
	v_lshl_add_u64 v[188:189], v[188:189], 0, v[150:151]
	v_mov_b32_dpp v184, v180 row_ror:8 row_mask:0xf bank_mask:0xf
	v_mov_b32_dpp v192, v183 row_ror:8 row_mask:0xf bank_mask:0xf
	v_add_co_u32_e32 v190, vcc, s24, v188
	v_cndmask_b32_e64 v180, v184, v79, s[52:53]
	v_cndmask_b32_e64 v183, v192, v191, s[52:53]
	v_addc_co_u32_e32 v191, vcc, 0, v189, vcc
	global_store_dwordx4 v[190:191], v[180:183], off offset:2048 sc1
	v_cndmask_b32_e64 v184, v176, v184, s[52:53]
; __device__ __forceinline__ u32x4 pack8(f32x4 a, f32x4 b) { u32x4 w; w.x = cvtpk(a[0], a[1]); w.y = cvtpk(a[2], a[3]); w.z = cvtpk(b[0], b[1]); w.w = cvtpk(b[2], b[3]); return w; }
; __device__ __forceinline__ unsigned dpp_ror8(unsigned v) { return (unsigned)__builtin_amdgcn_update_dpp(0, (int)v, 0x128, 0xF, 0xF, false); }
; __device__ __forceinline__ void store_pair(bf16_t* grp  , size_t ld, int fr, int fq, u32x4 P0, u32x4 P1) {
;     const bool up = (fr & 8) != 0;
;     u32x4 snd, rcv;
;     snd.x = up ? P0.x : P1.x; snd.y = up ? P0.y : P1.y; snd.z = up ? P0.z : P1.z; snd.w = up ? P0.w : P1.w;
;     rcv.x = dpp_ror8(snd.x); rcv.y = dpp_ror8(snd.y); rcv.z = dpp_ror8(snd.z); rcv.w = dpp_ror8(snd.w);
;     u32x4 dA, dB;
;     dA.x = up ? rcv.x : P0.x; dA.y = up ? rcv.y : P0.y; dA.z = up ? rcv.z : P0.z; dA.w = up ? rcv.w : P0.w;
;     dB.x = up ? P1.x : rcv.x; dB.y = up ? P1.y : rcv.y; dB.z = up ? P1.z : rcv.z; dB.w = up ? P1.w : rcv.w;
;     bf16_t* p = grp + (size_t)(fr & 7) * ld + (up ? CBJ : 0) + 8 * fq;
;     __builtin_nontemporal_store(dA, (u32x4*)p); __builtin_nontemporal_store(dB, (u32x4*)(p + 8 * ld));
; }
;     __device__ __forceinline__ void operator()(f32x4 (&acc)[2][2][4][2], const Unit& u, int wr, int wc, int fr, int fq) const {
;     ...
;                 for (int bj = 0; bj < 2; ++bj) {
;                     const v4i_t i0 = __builtin_bit_cast(v4i_t, acc[ai][bj][m][0]), i1 = __builtin_bit_cast(v4i_t, acc[ai][bj][m][1]);
;                     f32x4 v0, v1;
; #pragma unroll
;                     for (int j = 0; j < 4; ++j) { v0[j] = (float)i0[j] * (s * cq[bj * 2][j]); v1[j] = (float)i1[j] * (s * cq[bj * 2 + 1][j]); }
;                     pk[bj] = pack8(v0, v1);
;                 }
;                 store_pair(P + (size_t)(rowg + ai * HALF + m * 16) * INC + C_I8 + colw, INC, fr, fq, pk[0], pk[1]);
	v_cndmask_b32_e64 v187, v187, v192, s[52:53]
	v_add_co_u32_e32 v180, vcc, s25, v188
	v_cvt_f32_i32_e32 v183, v27
	s_nop 0
	v_addc_co_u32_e32 v181, vcc, 0, v189, vcc
	global_store_dwordx4 v[180:181], v[184:187], off offset:2048 sc1
	v_cvt_f32_i32_e32 v181, v31
	v_cvt_f32_i32_e32 v180, v30
	v_cvt_f32_i32_e32 v182, v26
	v_pk_mul_f32 v[184:185], v[172:173], v[174:175] op_sel_hi:[1,0]
	v_cvt_f32_i32_e32 v187, v29
	v_pk_mul_f32 v[180:181], v[184:185], v[180:181]
	v_pk_mul_f32 v[184:185], v[170:171], v[174:175] op_sel_hi:[1,0]
	v_cvt_pk_bf16_f32 v79, v180, v181
	v_pk_mul_f32 v[182:183], v[184:185], v[182:183]
	v_cvt_f32_i32_e32 v185, v33
	v_cvt_f32_i32_e32 v184, v32
	v_cvt_f32_i32_e32 v181, v23
	v_cvt_f32_i32_e32 v180, v22
	v_cvt_f32_i32_e32 v186, v28
	v_pk_mul_f32 v[188:189], v[80:81], v[174:175] op_sel_hi:[1,0]
	v_cvt_pk_bf16_f32 v178, v182, v183
	v_cvt_f32_i32_e32 v183, v19
	v_cvt_f32_i32_e32 v182, v18
	v_pk_mul_f32 v[184:185], v[188:189], v[184:185]
	v_pk_mul_f32 v[188:189], v[72:73], v[174:175] op_sel_hi:[1,0]
	v_cvt_pk_bf16_f32 v176, v184, v185
	v_pk_mul_f32 v[184:185], v[70:71], v[174:175] op_sel_hi:[1,0]
	v_pk_mul_f32 v[186:187], v[188:189], v[186:187]
	v_pk_mul_f32 v[180:181], v[184:185], v[180:181]
	v_pk_mul_f32 v[184:185], v[56:57], v[174:175] op_sel_hi:[1,0]
	v_cvt_pk_bf16_f32 v190, v186, v187
	v_pk_mul_f32 v[182:183], v[184:185], v[182:183]
	v_cvt_f32_i32_e32 v185, v25
	v_cvt_f32_i32_e32 v184, v24
	v_cvt_f32_i32_e32 v187, v21
	v_cvt_f32_i32_e32 v186, v20
	v_pk_mul_f32 v[188:189], v[54:55], v[174:175] op_sel_hi:[1,0]
	s_add_i32 s7, s14, 0xa0
	s_add_i32 s21, s6, 0x3c0000
	v_pk_mul_f32 v[184:185], v[188:189], v[184:185]
	v_pk_mul_f32 v[188:189], v[52:53], v[174:175] op_sel_hi:[1,0]
	s_mul_hi_i32 s7, s7, 0x6000
	s_add_u32 s21, s33, s21
	v_pk_mul_f32 v[186:187], v[188:189], v[186:187]
	v_cvt_pk_bf16_f32 v185, v184, v185
	v_cvt_pk_bf16_f32 v188, v182, v183
	s_addc_u32 s7, s15, s7
	v_cvt_pk_bf16_f32 v174, v180, v181
	v_cvt_pk_bf16_f32 v187, v186, v187
	s_add_u32 s22, s21, s0
	v_cndmask_b32_e64 v181, v176, v185, s[52:53]
	v_cndmask_b32_e64 v182, v178, v188, s[52:53]
	v_mov_b32_e32 v186, v131
	v_mov_b32_e32 v189, v131
	s_addc_u32 s23, s7, s1
	v_mov_b32_dpp v186, v181 row_ror:8 row_mask:0xf bank_mask:0xf
	v_mov_b32_dpp v189, v182 row_ror:8 row_mask:0xf bank_mask:0xf
	v_cndmask_b32_e64 v181, v186, v176, s[52:53]
	v_cndmask_b32_e64 v182, v189, v178, s[52:53]
	v_cndmask_b32_e64 v185, v185, v186, s[52:53]
	v_cndmask_b32_e64 v186, v188, v189, s[52:53]
	v_lshl_add_u64 v[188:189], s[22:23], 0, v[130:131]
	v_cndmask_b32_e64 v183, v190, v187, s[52:53]
	v_mov_b32_e32 v191, v131
	v_lshl_add_u64 v[188:189], v[188:189], 0, v[148:149]
	v_cndmask_b32_e64 v180, v79, v174, s[52:53]
	v_mov_b32_e32 v184, v131
	v_mov_b32_dpp v191, v183 row_ror:8 row_mask:0xf bank_mask:0xf
	v_lshl_add_u64 v[188:189], v[188:189], 0, v[150:151]
	v_mov_b32_dpp v184, v180 row_ror:8 row_mask:0xf bank_mask:0xf
	v_cndmask_b32_e64 v183, v191, v190, s[52:53]
	v_add_co_u32_e32 v190, vcc, s24, v188
	v_cndmask_b32_e64 v180, v184, v79, s[52:53]
	v_cndmask_b32_e64 v187, v187, v191, s[52:53]
	v_addc_co_u32_e32 v191, vcc, 0, v189, vcc
	global_store_dwordx4 v[190:191], v[180:183], off offset:2048 sc1
	v_cndmask_b32_e64 v184, v174, v184, s[52:53]
	v_pk_mul_f32 v[172:173], v[172:173], v[78:79] op_sel_hi:[1,0]
	v_add_co_u32_e32 v180, vcc, s25, v188
	v_cvt_f32_i32_e32 v183, v11
	s_nop 0
	v_addc_co_u32_e32 v181, vcc, 0, v189, vcc
	global_store_dwordx4 v[180:181], v[184:187], off offset:2048 sc1
	v_cvt_f32_i32_e32 v181, v15
	v_cvt_f32_i32_e32 v180, v14
	v_cvt_f32_i32_e32 v182, v10
	v_pk_mul_f32 v[170:171], v[170:171], v[78:79] op_sel_hi:[1,0]
	v_pk_mul_f32 v[80:81], v[80:81], v[78:79] op_sel_hi:[1,0]
	v_pk_mul_f32 v[172:173], v[172:173], v[180:181]
	v_pk_mul_f32 v[170:171], v[170:171], v[182:183]
	v_cvt_f32_i32_e32 v181, v17
	v_cvt_f32_i32_e32 v180, v16
	v_cvt_f32_i32_e32 v183, v13
	v_cvt_f32_i32_e32 v182, v12
	v_pk_mul_f32 v[72:73], v[72:73], v[78:79] op_sel_hi:[1,0]
	v_pk_mul_f32 v[80:81], v[80:81], v[180:181]
	v_cvt_pk_bf16_f32 v79, v172, v173
	v_pk_mul_f32 v[72:73], v[72:73], v[182:183]
	v_cvt_pk_bf16_f32 v172, v80, v81
	v_cvt_pk_bf16_f32 v170, v170, v171
	v_cvt_pk_bf16_f32 v171, v72, v73
	v_cvt_f32_i32_e32 v73, v7
	v_cvt_f32_i32_e32 v72, v6
	v_cvt_f32_i32_e32 v81, v3
	v_cvt_f32_i32_e32 v80, v2
	v_pk_mul_f32 v[70:71], v[70:71], v[78:79] op_sel_hi:[1,0]
	v_pk_mul_f32 v[56:57], v[56:57], v[78:79] op_sel_hi:[1,0]
	v_pk_mul_f32 v[70:71], v[70:71], v[72:73]
	v_pk_mul_f32 v[56:57], v[56:57], v[80:81]
	v_cvt_f32_i32_e32 v73, v9
	v_cvt_f32_i32_e32 v72, v8
	v_cvt_f32_i32_e32 v81, v5
	v_cvt_f32_i32_e32 v80, v4
	v_pk_mul_f32 v[54:55], v[54:55], v[78:79] op_sel_hi:[1,0]
	v_pk_mul_f32 v[52:53], v[52:53], v[78:79] op_sel_hi:[1,0]
	s_add_i32 s7, s14, 0xb0
	s_add_i32 s6, s6, 0x420000
	v_pk_mul_f32 v[54:55], v[54:55], v[72:73]
	v_pk_mul_f32 v[52:53], v[52:53], v[80:81]
	s_mul_hi_i32 s7, s7, 0x6000
	s_add_u32 s6, s33, s6
	v_cvt_pk_bf16_f32 v70, v70, v71
	v_cvt_pk_bf16_f32 v71, v54, v55
	v_cvt_pk_bf16_f32 v56, v56, v57
	v_cvt_pk_bf16_f32 v57, v52, v53
	s_addc_u32 s7, s15, s7
	s_add_u32 s0, s6, s0
	v_cndmask_b32_e64 v52, v79, v70, s[52:53]
	v_cndmask_b32_e64 v53, v172, v71, s[52:53]
	v_cndmask_b32_e64 v54, v170, v56, s[52:53]
	v_cndmask_b32_e64 v55, v171, v57, s[52:53]
	v_mov_b32_e32 v72, v131
	v_mov_b32_e32 v73, v131
	v_mov_b32_e32 v78, v131
	v_mov_b32_e32 v80, v131
	s_addc_u32 s1, s7, s1
	v_mov_b32_dpp v72, v52 row_ror:8 row_mask:0xf bank_mask:0xf
	v_mov_b32_dpp v73, v53 row_ror:8 row_mask:0xf bank_mask:0xf
	v_mov_b32_dpp v78, v54 row_ror:8 row_mask:0xf bank_mask:0xf
	v_mov_b32_dpp v80, v55 row_ror:8 row_mask:0xf bank_mask:0xf
	v_cndmask_b32_e64 v52, v72, v79, s[52:53]
	v_cndmask_b32_e64 v53, v73, v172, s[52:53]
	v_cndmask_b32_e64 v70, v70, v72, s[52:53]
	v_cndmask_b32_e64 v71, v71, v73, s[52:53]
	v_cndmask_b32_e64 v72, v56, v78, s[52:53]
	v_cndmask_b32_e64 v73, v57, v80, s[52:53]
	v_lshl_add_u64 v[56:57], s[0:1], 0, v[130:131]
	v_lshl_add_u64 v[56:57], v[56:57], 0, v[148:149]
	v_lshl_add_u64 v[56:57], v[56:57], 0, v[150:151]
	v_cndmask_b32_e64 v54, v78, v170, s[52:53]
	v_add_co_u32_e32 v78, vcc, 0x2000, v56
	v_cndmask_b32_e64 v55, v80, v171, s[52:53]
	s_nop 0
	v_addc_co_u32_e32 v79, vcc, 0, v57, vcc
	global_store_dwordx4 v[78:79], v[52:55], off offset:2048 sc1
	s_mov_b64 s[6:7], 0
	s_nop 0
	v_add_co_u32_e32 v52, vcc, 0x32000, v56
	s_nop 1
	v_addc_co_u32_e32 v53, vcc, 0, v57, vcc
	global_store_dwordx4 v[52:53], v[70:73], off offset:2048 sc1

; __device__ __forceinline__ u32x4 pack8(f32x4 a, f32x4 b) { u32x4 w; w.x = cvtpk(a[0], a[1]); w.y = cvtpk(a[2], a[3]); w.z = cvtpk(b[0], b[1]); w.w = cvtpk(b[2], b[3]); return w; }
; __device__ __forceinline__ unsigned dpp_ror8(unsigned v) { return (unsigned)__builtin_amdgcn_update_dpp(0, (int)v, 0x128, 0xF, 0xF, false); }
; __device__ __forceinline__ void store_pair(bf16_t* grp  , size_t ld, int fr, int fq, u32x4 P0, u32x4 P1) {
;     const bool up = (fr & 8) != 0;
;     u32x4 snd, rcv;
;     snd.x = up ? P0.x : P1.x; snd.y = up ? P0.y : P1.y; snd.z = up ? P0.z : P1.z; snd.w = up ? P0.w : P1.w;
;     rcv.x = dpp_ror8(snd.x); rcv.y = dpp_ror8(snd.y); rcv.z = dpp_ror8(snd.z); rcv.w = dpp_ror8(snd.w);
;     u32x4 dA, dB;
;     dA.x = up ? rcv.x : P0.x; dA.y = up ? rcv.y : P0.y; dA.z = up ? rcv.z : P0.z; dA.w = up ? rcv.w : P0.w;
;     dB.x = up ? P1.x : rcv.x; dB.y = up ? P1.y : rcv.y; dB.z = up ? P1.z : rcv.z; dB.w = up ? P1.w : rcv.w;
;     bf16_t* p = grp + (size_t)(fr & 7) * ld + (up ? CBJ : 0) + 8 * fq;
;     __builtin_nontemporal_store(dA, (u32x4*)p); __builtin_nontemporal_store(dB, (u32x4*)(p + 8 * ld));
; }
;     __device__ __forceinline__ void operator()(f32x4 (&acc)[2][2][4][2], const Unit& u, int wr, int wc, int fr, int fq) const {
;     ...
;                     } else pk[bj] = pack8(acc[ai][bj][m][0] * (g0 * (1.0f / 255.0f)), acc[ai][bj][m][1] * (g1 * (1.0f / 255.0f)));
;                 }
;                 if (seg == 2) store_pair(Mg + (size_t)(rowg + ai * HALF + m * 16) * DM + colw, DM, fr, fq, pk[0], pk[1]);
.LBB0_812:
	s_lshl_b32 s0, s38, 8
	s_add_i32 s40, s0, s25
	s_lshl_b32 s0, s39, 8
	s_or_b32 s0, s0, s31
	s_cmp_eq_u32 s35, 2
	s_cselect_b64 s[42:43], -1, 0
	s_ashr_i32 s1, s0, 31
	v_mov_b32_e32 v248, 0x441000
	v_mov_b32_e32 v1, 0x600
	s_cmp_lg_u32 s35, 2
	v_lshlrev_b32_e32 v130, 1, v166
	v_lshlrev_b32_e32 v134, 1, v168
	v_lshlrev_b32_e32 v132, 1, v162
	s_cbranch_scc1 .LBB0_814
	s_ashr_i32 s41, s40, 31
	s_lshl_b64 s[38:39], s[40:41], 12
	s_add_u32 s9, s88, s38
	s_addc_u32 s17, s89, s39
	s_lshl_b64 s[38:39], s[0:1], 1
	s_add_u32 s38, s9, s38
	s_addc_u32 s39, s17, s39
	v_cndmask_b32_e64 v10, v2, v6, s[52:53]
	v_cndmask_b32_e64 v11, v3, v7, s[52:53]
	v_cndmask_b32_e64 v12, v4, v8, s[52:53]
	v_cndmask_b32_e64 v13, v5, v9, s[52:53]
	v_mov_b32_e32 v14, v131
	v_mov_b32_e32 v15, v131
	v_mov_b32_e32 v16, v131
	v_mov_b32_e32 v17, v131
	v_lshl_add_u64 v[136:137], s[38:39], 0, v[130:131]
	v_mov_b32_e32 v135, v131
	v_mov_b32_dpp v14, v10 row_ror:8 row_mask:0xf bank_mask:0xf
	v_mov_b32_dpp v15, v11 row_ror:8 row_mask:0xf bank_mask:0xf
	v_mov_b32_dpp v16, v12 row_ror:8 row_mask:0xf bank_mask:0xf
	v_mov_b32_dpp v17, v13 row_ror:8 row_mask:0xf bank_mask:0xf
	v_lshl_add_u64 v[136:137], v[136:137], 0, v[134:135]
	v_mov_b32_e32 v133, v131
	v_cndmask_b32_e64 v10, v14, v2, s[52:53]
	v_cndmask_b32_e64 v11, v15, v3, s[52:53]
	v_cndmask_b32_e64 v12, v16, v4, s[52:53]
	v_cndmask_b32_e64 v13, v17, v5, s[52:53]
	v_lshl_add_u64 v[136:137], v[136:137], 0, v[132:133]
	global_store_dwordx4 v[136:137], v[10:13], off sc1
	v_cndmask_b32_e64 v14, v6, v14, s[52:53]
	v_cndmask_b32_e64 v15, v7, v15, s[52:53]
	v_add_co_u32_e32 v10, vcc, 0x8000, v136
	v_cndmask_b32_e64 v16, v8, v16, s[52:53]
	v_cndmask_b32_e64 v17, v9, v17, s[52:53]
	v_addc_co_u32_e32 v11, vcc, 0, v137, vcc
	global_store_dwordx4 v[10:11], v[14:17], off sc1

; __device__ __forceinline__ u32x4 pack8(f32x4 a, f32x4 b) { u32x4 w; w.x = cvtpk(a[0], a[1]); w.y = cvtpk(a[2], a[3]); w.z = cvtpk(b[0], b[1]); w.w = cvtpk(b[2], b[3]); return w; }
; __device__ __forceinline__ unsigned dpp_ror8(unsigned v) { return (unsigned)__builtin_amdgcn_update_dpp(0, (int)v, 0x128, 0xF, 0xF, false); }
; __device__ __forceinline__ void store_pair(bf16_t* grp  , size_t ld, int fr, int fq, u32x4 P0, u32x4 P1) {
;     const bool up = (fr & 8) != 0;
;     u32x4 snd, rcv;
;     snd.x = up ? P0.x : P1.x; snd.y = up ? P0.y : P1.y; snd.z = up ? P0.z : P1.z; snd.w = up ? P0.w : P1.w;
;     rcv.x = dpp_ror8(snd.x); rcv.y = dpp_ror8(snd.y); rcv.z = dpp_ror8(snd.z); rcv.w = dpp_ror8(snd.w);
;     u32x4 dA, dB;
;     dA.x = up ? rcv.x : P0.x; dA.y = up ? rcv.y : P0.y; dA.z = up ? rcv.z : P0.z; dA.w = up ? rcv.w : P0.w;
;     dB.x = up ? P1.x : rcv.x; dB.y = up ? P1.y : rcv.y; dB.z = up ? P1.z : rcv.z; dB.w = up ? P1.w : rcv.w;
;     bf16_t* p = grp + (size_t)(fr & 7) * ld + (up ? CBJ : 0) + 8 * fq;
;     __builtin_nontemporal_store(dA, (u32x4*)p); __builtin_nontemporal_store(dB, (u32x4*)(p + 8 * ld));
; }
;     __device__ __forceinline__ void operator()(f32x4 (&acc)[2][2][4][2], const Unit& u, int wr, int wc, int fr, int fq) const {
;     ...
;                     } else pk[bj] = pack8(acc[ai][bj][m][0] * (g0 * (1.0f / 255.0f)), acc[ai][bj][m][1] * (g1 * (1.0f / 255.0f)));
;                 }
;                 if (seg == 2) store_pair(Mg + (size_t)(rowg + ai * HALF + m * 16) * DM + colw, DM, fr, fq, pk[0], pk[1]);
.LBB0_824:
	s_or_b32 s38, s40, 16
	s_ashr_i32 s39, s38, 31
	s_lshl_b64 s[38:39], s[38:39], 12
	s_add_u32 s9, s88, s38
	s_addc_u32 s17, s89, s39
	s_lshl_b64 s[38:39], s[0:1], 1
	s_add_u32 s38, s9, s38
	s_addc_u32 s39, s17, s39
	v_cndmask_b32_e64 v10, v2, v6, s[52:53]
	v_cndmask_b32_e64 v11, v3, v7, s[52:53]
	v_cndmask_b32_e64 v12, v4, v8, s[52:53]
	v_cndmask_b32_e64 v13, v5, v9, s[52:53]
	v_mov_b32_e32 v14, v131
	v_mov_b32_e32 v15, v131
	v_mov_b32_e32 v16, v131
	v_mov_b32_e32 v17, v131
	v_lshl_add_u64 v[136:137], s[38:39], 0, v[130:131]
	v_mov_b32_e32 v135, v131
	v_mov_b32_dpp v14, v10 row_ror:8 row_mask:0xf bank_mask:0xf
	v_mov_b32_dpp v15, v11 row_ror:8 row_mask:0xf bank_mask:0xf
	v_mov_b32_dpp v16, v12 row_ror:8 row_mask:0xf bank_mask:0xf
	v_mov_b32_dpp v17, v13 row_ror:8 row_mask:0xf bank_mask:0xf
	v_lshl_add_u64 v[136:137], v[136:137], 0, v[134:135]
	v_mov_b32_e32 v133, v131
	v_cndmask_b32_e64 v10, v14, v2, s[52:53]
	v_cndmask_b32_e64 v11, v15, v3, s[52:53]
	v_cndmask_b32_e64 v12, v16, v4, s[52:53]
	v_cndmask_b32_e64 v13, v17, v5, s[52:53]
	v_lshl_add_u64 v[136:137], v[136:137], 0, v[132:133]
	global_store_dwordx4 v[136:137], v[10:13], off sc1
	v_cndmask_b32_e64 v14, v6, v14, s[52:53]
	v_cndmask_b32_e64 v15, v7, v15, s[52:53]
	v_add_co_u32_e32 v10, vcc, 0x8000, v136
	v_cndmask_b32_e64 v16, v8, v16, s[52:53]
	v_cndmask_b32_e64 v17, v9, v17, s[52:53]
	v_addc_co_u32_e32 v11, vcc, 0, v137, vcc
	global_store_dwordx4 v[10:11], v[14:17], off sc1

; __device__ __forceinline__ u32x4 pack8(f32x4 a, f32x4 b) { u32x4 w; w.x = cvtpk(a[0], a[1]); w.y = cvtpk(a[2], a[3]); w.z = cvtpk(b[0], b[1]); w.w = cvtpk(b[2], b[3]); return w; }
; __device__ __forceinline__ unsigned dpp_ror8(unsigned v) { return (unsigned)__builtin_amdgcn_update_dpp(0, (int)v, 0x128, 0xF, 0xF, false); }
; __device__ __forceinline__ void store_pair(bf16_t* grp  , size_t ld, int fr, int fq, u32x4 P0, u32x4 P1) {
;     const bool up = (fr & 8) != 0;
;     u32x4 snd, rcv;
;     snd.x = up ? P0.x : P1.x; snd.y = up ? P0.y : P1.y; snd.z = up ? P0.z : P1.z; snd.w = up ? P0.w : P1.w;
;     rcv.x = dpp_ror8(snd.x); rcv.y = dpp_ror8(snd.y); rcv.z = dpp_ror8(snd.z); rcv.w = dpp_ror8(snd.w);
;     u32x4 dA, dB;
;     dA.x = up ? rcv.x : P0.x; dA.y = up ? rcv.y : P0.y; dA.z = up ? rcv.z : P0.z; dA.w = up ? rcv.w : P0.w;
;     dB.x = up ? P1.x : rcv.x; dB.y = up ? P1.y : rcv.y; dB.z = up ? P1.z : rcv.z; dB.w = up ? P1.w : rcv.w;
;     bf16_t* p = grp + (size_t)(fr & 7) * ld + (up ? CBJ : 0) + 8 * fq;
;     __builtin_nontemporal_store(dA, (u32x4*)p); __builtin_nontemporal_store(dB, (u32x4*)(p + 8 * ld));
; }
;     __device__ __forceinline__ void operator()(f32x4 (&acc)[2][2][4][2], const Unit& u, int wr, int wc, int fr, int fq) const {
;     ...
;                     } else pk[bj] = pack8(acc[ai][bj][m][0] * (g0 * (1.0f / 255.0f)), acc[ai][bj][m][1] * (g1 * (1.0f / 255.0f)));
;                 }
;                 if (seg == 2) store_pair(Mg + (size_t)(rowg + ai * HALF + m * 16) * DM + colw, DM, fr, fq, pk[0], pk[1]);
.LBB0_835:
	s_or_b32 s38, s40, 32
	s_ashr_i32 s39, s38, 31
	s_lshl_b64 s[38:39], s[38:39], 12
	s_add_u32 s9, s88, s38
	s_addc_u32 s17, s89, s39
	s_lshl_b64 s[38:39], s[0:1], 1
	s_add_u32 s38, s9, s38
	s_addc_u32 s39, s17, s39
	v_cndmask_b32_e64 v10, v2, v6, s[52:53]
	v_cndmask_b32_e64 v11, v3, v7, s[52:53]
	v_cndmask_b32_e64 v12, v4, v8, s[52:53]
	v_cndmask_b32_e64 v13, v5, v9, s[52:53]
	v_mov_b32_e32 v14, v131
	v_mov_b32_e32 v15, v131
	v_mov_b32_e32 v16, v131
	v_mov_b32_e32 v17, v131
	v_lshl_add_u64 v[136:137], s[38:39], 0, v[130:131]
	v_mov_b32_e32 v135, v131
	v_mov_b32_dpp v14, v10 row_ror:8 row_mask:0xf bank_mask:0xf
	v_mov_b32_dpp v15, v11 row_ror:8 row_mask:0xf bank_mask:0xf
	v_mov_b32_dpp v16, v12 row_ror:8 row_mask:0xf bank_mask:0xf
	v_mov_b32_dpp v17, v13 row_ror:8 row_mask:0xf bank_mask:0xf
	v_lshl_add_u64 v[136:137], v[136:137], 0, v[134:135]
	v_mov_b32_e32 v133, v131
	v_cndmask_b32_e64 v10, v14, v2, s[52:53]
	v_cndmask_b32_e64 v11, v15, v3, s[52:53]
	v_cndmask_b32_e64 v12, v16, v4, s[52:53]
	v_cndmask_b32_e64 v13, v17, v5, s[52:53]
	v_lshl_add_u64 v[136:137], v[136:137], 0, v[132:133]
	global_store_dwordx4 v[136:137], v[10:13], off sc1
	v_cndmask_b32_e64 v14, v6, v14, s[52:53]
	v_cndmask_b32_e64 v15, v7, v15, s[52:53]
	v_add_co_u32_e32 v10, vcc, 0x8000, v136
	v_cndmask_b32_e64 v16, v8, v16, s[52:53]
	v_cndmask_b32_e64 v17, v9, v17, s[52:53]
	v_addc_co_u32_e32 v11, vcc, 0, v137, vcc
	global_store_dwordx4 v[10:11], v[14:17], off sc1

; __device__ __forceinline__ u32x4 pack8(f32x4 a, f32x4 b) { u32x4 w; w.x = cvtpk(a[0], a[1]); w.y = cvtpk(a[2], a[3]); w.z = cvtpk(b[0], b[1]); w.w = cvtpk(b[2], b[3]); return w; }
; __device__ __forceinline__ unsigned dpp_ror8(unsigned v) { return (unsigned)__builtin_amdgcn_update_dpp(0, (int)v, 0x128, 0xF, 0xF, false); }
; __device__ __forceinline__ void store_pair(bf16_t* grp  , size_t ld, int fr, int fq, u32x4 P0, u32x4 P1) {
;     const bool up = (fr & 8) != 0;
;     u32x4 snd, rcv;
;     snd.x = up ? P0.x : P1.x; snd.y = up ? P0.y : P1.y; snd.z = up ? P0.z : P1.z; snd.w = up ? P0.w : P1.w;
;     rcv.x = dpp_ror8(snd.x); rcv.y = dpp_ror8(snd.y); rcv.z = dpp_ror8(snd.z); rcv.w = dpp_ror8(snd.w);
;     u32x4 dA, dB;
;     dA.x = up ? rcv.x : P0.x; dA.y = up ? rcv.y : P0.y; dA.z = up ? rcv.z : P0.z; dA.w = up ? rcv.w : P0.w;
;     dB.x = up ? P1.x : rcv.x; dB.y = up ? P1.y : rcv.y; dB.z = up ? P1.z : rcv.z; dB.w = up ? P1.w : rcv.w;
;     bf16_t* p = grp + (size_t)(fr & 7) * ld + (up ? CBJ : 0) + 8 * fq;
;     __builtin_nontemporal_store(dA, (u32x4*)p); __builtin_nontemporal_store(dB, (u32x4*)(p + 8 * ld));
; }
;     __device__ __forceinline__ void operator()(f32x4 (&acc)[2][2][4][2], const Unit& u, int wr, int wc, int fr, int fq) const {
;     ...
;                     } else pk[bj] = pack8(acc[ai][bj][m][0] * (g0 * (1.0f / 255.0f)), acc[ai][bj][m][1] * (g1 * (1.0f / 255.0f)));
;                 }
;                 if (seg == 2) store_pair(Mg + (size_t)(rowg + ai * HALF + m * 16) * DM + colw, DM, fr, fq, pk[0], pk[1]);
.LBB0_846:
	s_or_b32 s38, s40, 48
	s_ashr_i32 s39, s38, 31
	s_lshl_b64 s[38:39], s[38:39], 12
	s_add_u32 s9, s88, s38
	s_addc_u32 s17, s89, s39
	s_lshl_b64 s[38:39], s[0:1], 1
	s_add_u32 s38, s9, s38
	s_addc_u32 s39, s17, s39
	v_cndmask_b32_e64 v10, v2, v6, s[52:53]
	v_cndmask_b32_e64 v11, v3, v7, s[52:53]
	v_cndmask_b32_e64 v12, v4, v8, s[52:53]
	v_cndmask_b32_e64 v13, v5, v9, s[52:53]
	v_mov_b32_e32 v14, v131
	v_mov_b32_e32 v15, v131
	v_mov_b32_e32 v16, v131
	v_mov_b32_e32 v17, v131
	v_lshl_add_u64 v[136:137], s[38:39], 0, v[130:131]
	v_mov_b32_e32 v135, v131
	v_mov_b32_dpp v14, v10 row_ror:8 row_mask:0xf bank_mask:0xf
	v_mov_b32_dpp v15, v11 row_ror:8 row_mask:0xf bank_mask:0xf
	v_mov_b32_dpp v16, v12 row_ror:8 row_mask:0xf bank_mask:0xf
	v_mov_b32_dpp v17, v13 row_ror:8 row_mask:0xf bank_mask:0xf
	v_lshl_add_u64 v[136:137], v[136:137], 0, v[134:135]
	v_mov_b32_e32 v133, v131
	v_cndmask_b32_e64 v10, v14, v2, s[52:53]
	v_cndmask_b32_e64 v11, v15, v3, s[52:53]
	v_cndmask_b32_e64 v12, v16, v4, s[52:53]
	v_cndmask_b32_e64 v13, v17, v5, s[52:53]
	v_lshl_add_u64 v[136:137], v[136:137], 0, v[132:133]
	global_store_dwordx4 v[136:137], v[10:13], off sc1
	v_cndmask_b32_e64 v14, v6, v14, s[52:53]
	v_cndmask_b32_e64 v15, v7, v15, s[52:53]
	v_add_co_u32_e32 v10, vcc, 0x8000, v136
	v_cndmask_b32_e64 v16, v8, v16, s[52:53]
	v_cndmask_b32_e64 v17, v9, v17, s[52:53]
	v_addc_co_u32_e32 v11, vcc, 0, v137, vcc
	global_store_dwordx4 v[10:11], v[14:17], off sc1

; __device__ __forceinline__ u32x4 pack8(f32x4 a, f32x4 b) { u32x4 w; w.x = cvtpk(a[0], a[1]); w.y = cvtpk(a[2], a[3]); w.z = cvtpk(b[0], b[1]); w.w = cvtpk(b[2], b[3]); return w; }
; __device__ __forceinline__ unsigned dpp_ror8(unsigned v) { return (unsigned)__builtin_amdgcn_update_dpp(0, (int)v, 0x128, 0xF, 0xF, false); }
; __device__ __forceinline__ void store_pair(bf16_t* grp  , size_t ld, int fr, int fq, u32x4 P0, u32x4 P1) {
;     const bool up = (fr & 8) != 0;
;     u32x4 snd, rcv;
;     snd.x = up ? P0.x : P1.x; snd.y = up ? P0.y : P1.y; snd.z = up ? P0.z : P1.z; snd.w = up ? P0.w : P1.w;
;     rcv.x = dpp_ror8(snd.x); rcv.y = dpp_ror8(snd.y); rcv.z = dpp_ror8(snd.z); rcv.w = dpp_ror8(snd.w);
;     u32x4 dA, dB;
;     dA.x = up ? rcv.x : P0.x; dA.y = up ? rcv.y : P0.y; dA.z = up ? rcv.z : P0.z; dA.w = up ? rcv.w : P0.w;
;     dB.x = up ? P1.x : rcv.x; dB.y = up ? P1.y : rcv.y; dB.z = up ? P1.z : rcv.z; dB.w = up ? P1.w : rcv.w;
;     bf16_t* p = grp + (size_t)(fr & 7) * ld + (up ? CBJ : 0) + 8 * fq;
;     __builtin_nontemporal_store(dA, (u32x4*)p); __builtin_nontemporal_store(dB, (u32x4*)(p + 8 * ld));
; }
;     __device__ __forceinline__ void operator()(f32x4 (&acc)[2][2][4][2], const Unit& u, int wr, int wc, int fr, int fq) const {
;     ...
;                     } else pk[bj] = pack8(acc[ai][bj][m][0] * (g0 * (1.0f / 255.0f)), acc[ai][bj][m][1] * (g1 * (1.0f / 255.0f)));
;                 }
;                 if (seg == 2) store_pair(Mg + (size_t)(rowg + ai * HALF + m * 16) * DM + colw, DM, fr, fq, pk[0], pk[1]);
.LBB0_857:
	s_ashr_i32 s41, s40, 31
	s_lshl_b64 s[38:39], s[40:41], 12
	s_add_u32 s9, s88, s38
	s_addc_u32 s17, s89, s39
	s_lshl_b64 s[38:39], s[0:1], 1
	s_add_u32 s38, s9, s38
	s_addc_u32 s39, s17, s39
	v_lshl_add_u64 v[136:137], s[38:39], 0, v[130:131]
	v_mov_b32_e32 v135, v131
	v_lshl_add_u64 v[136:137], v[136:137], 0, v[134:135]
	v_mov_b32_e32 v133, v131
	v_cndmask_b32_e64 v10, v2, v6, s[52:53]
	v_cndmask_b32_e64 v11, v3, v7, s[52:53]
	v_cndmask_b32_e64 v12, v4, v8, s[52:53]
	v_cndmask_b32_e64 v13, v5, v9, s[52:53]
	v_mov_b32_e32 v14, v131
	v_mov_b32_e32 v15, v131
	v_mov_b32_e32 v16, v131
	v_mov_b32_e32 v17, v131
	v_lshl_add_u64 v[136:137], v[136:137], 0, v[132:133]
	v_mov_b32_dpp v14, v10 row_ror:8 row_mask:0xf bank_mask:0xf
	v_mov_b32_dpp v15, v11 row_ror:8 row_mask:0xf bank_mask:0xf
	v_mov_b32_dpp v16, v12 row_ror:8 row_mask:0xf bank_mask:0xf
	v_mov_b32_dpp v17, v13 row_ror:8 row_mask:0xf bank_mask:0xf
	v_add_co_u32_e32 v198, vcc, 0x80000, v136
	v_cndmask_b32_e64 v10, v14, v2, s[52:53]
	v_cndmask_b32_e64 v11, v15, v3, s[52:53]
	v_cndmask_b32_e64 v12, v16, v4, s[52:53]
	v_cndmask_b32_e64 v13, v17, v5, s[52:53]
	v_addc_co_u32_e32 v199, vcc, 0, v137, vcc
	global_store_dwordx4 v[198:199], v[10:13], off sc1
	v_cndmask_b32_e64 v14, v6, v14, s[52:53]
	v_cndmask_b32_e64 v15, v7, v15, s[52:53]
	v_add_co_u32_e32 v10, vcc, 0x88000, v136
	v_cndmask_b32_e64 v16, v8, v16, s[52:53]
	v_cndmask_b32_e64 v17, v9, v17, s[52:53]
	v_addc_co_u32_e32 v11, vcc, 0, v137, vcc
	global_store_dwordx4 v[10:11], v[14:17], off sc1

; __device__ __forceinline__ u32x4 pack8(f32x4 a, f32x4 b) { u32x4 w; w.x = cvtpk(a[0], a[1]); w.y = cvtpk(a[2], a[3]); w.z = cvtpk(b[0], b[1]); w.w = cvtpk(b[2], b[3]); return w; }
; __device__ __forceinline__ unsigned dpp_ror8(unsigned v) { return (unsigned)__builtin_amdgcn_update_dpp(0, (int)v, 0x128, 0xF, 0xF, false); }
; __device__ __forceinline__ void store_pair(bf16_t* grp  , size_t ld, int fr, int fq, u32x4 P0, u32x4 P1) {
;     const bool up = (fr & 8) != 0;
;     u32x4 snd, rcv;
;     snd.x = up ? P0.x : P1.x; snd.y = up ? P0.y : P1.y; snd.z = up ? P0.z : P1.z; snd.w = up ? P0.w : P1.w;
;     rcv.x = dpp_ror8(snd.x); rcv.y = dpp_ror8(snd.y); rcv.z = dpp_ror8(snd.z); rcv.w = dpp_ror8(snd.w);
;     u32x4 dA, dB;
;     dA.x = up ? rcv.x : P0.x; dA.y = up ? rcv.y : P0.y; dA.z = up ? rcv.z : P0.z; dA.w = up ? rcv.w : P0.w;
;     dB.x = up ? P1.x : rcv.x; dB.y = up ? P1.y : rcv.y; dB.z = up ? P1.z : rcv.z; dB.w = up ? P1.w : rcv.w;
;     bf16_t* p = grp + (size_t)(fr & 7) * ld + (up ? CBJ : 0) + 8 * fq;
;     __builtin_nontemporal_store(dA, (u32x4*)p); __builtin_nontemporal_store(dB, (u32x4*)(p + 8 * ld));
; }
;     __device__ __forceinline__ void operator()(f32x4 (&acc)[2][2][4][2], const Unit& u, int wr, int wc, int fr, int fq) const {
;     ...
;                     } else pk[bj] = pack8(acc[ai][bj][m][0] * (g0 * (1.0f / 255.0f)), acc[ai][bj][m][1] * (g1 * (1.0f / 255.0f)));
;                 }
;                 if (seg == 2) store_pair(Mg + (size_t)(rowg + ai * HALF + m * 16) * DM + colw, DM, fr, fq, pk[0], pk[1]);
.LBB0_868:
	s_ashr_i32 s41, s40, 31
	s_lshl_b64 s[38:39], s[40:41], 12
	s_add_u32 s9, s88, s38
	s_addc_u32 s17, s89, s39
	s_lshl_b64 s[38:39], s[0:1], 1
	s_add_u32 s38, s9, s38
	s_addc_u32 s39, s17, s39
	v_lshl_add_u64 v[136:137], s[38:39], 0, v[130:131]
	v_mov_b32_e32 v135, v131
	v_lshl_add_u64 v[136:137], v[136:137], 0, v[134:135]
	v_mov_b32_e32 v133, v131
	v_cndmask_b32_e64 v10, v2, v6, s[52:53]
	v_cndmask_b32_e64 v11, v3, v7, s[52:53]
	v_cndmask_b32_e64 v12, v4, v8, s[52:53]
	v_cndmask_b32_e64 v13, v5, v9, s[52:53]
	v_mov_b32_e32 v14, v131
	v_mov_b32_e32 v15, v131
	v_mov_b32_e32 v16, v131
	v_mov_b32_e32 v17, v131
	v_lshl_add_u64 v[136:137], v[136:137], 0, v[132:133]
	v_mov_b32_dpp v14, v10 row_ror:8 row_mask:0xf bank_mask:0xf
	v_mov_b32_dpp v15, v11 row_ror:8 row_mask:0xf bank_mask:0xf
	v_mov_b32_dpp v16, v12 row_ror:8 row_mask:0xf bank_mask:0xf
	v_mov_b32_dpp v17, v13 row_ror:8 row_mask:0xf bank_mask:0xf
	v_add_co_u32_e32 v190, vcc, 0x90000, v136
	v_cndmask_b32_e64 v10, v14, v2, s[52:53]
	v_cndmask_b32_e64 v11, v15, v3, s[52:53]
	v_cndmask_b32_e64 v12, v16, v4, s[52:53]
	v_cndmask_b32_e64 v13, v17, v5, s[52:53]
	v_addc_co_u32_e32 v191, vcc, 0, v137, vcc
	global_store_dwordx4 v[190:191], v[10:13], off sc1
	v_cndmask_b32_e64 v14, v6, v14, s[52:53]
	v_cndmask_b32_e64 v15, v7, v15, s[52:53]
	v_add_co_u32_e32 v10, vcc, 0x98000, v136
	v_cndmask_b32_e64 v16, v8, v16, s[52:53]
	v_cndmask_b32_e64 v17, v9, v17, s[52:53]
	v_addc_co_u32_e32 v11, vcc, 0, v137, vcc
	global_store_dwordx4 v[10:11], v[14:17], off sc1

; __device__ __forceinline__ u32x4 pack8(f32x4 a, f32x4 b) { u32x4 w; w.x = cvtpk(a[0], a[1]); w.y = cvtpk(a[2], a[3]); w.z = cvtpk(b[0], b[1]); w.w = cvtpk(b[2], b[3]); return w; }
; __device__ __forceinline__ unsigned dpp_ror8(unsigned v) { return (unsigned)__builtin_amdgcn_update_dpp(0, (int)v, 0x128, 0xF, 0xF, false); }
; __device__ __forceinline__ void store_pair(bf16_t* grp  , size_t ld, int fr, int fq, u32x4 P0, u32x4 P1) {
;     const bool up = (fr & 8) != 0;
;     u32x4 snd, rcv;
;     snd.x = up ? P0.x : P1.x; snd.y = up ? P0.y : P1.y; snd.z = up ? P0.z : P1.z; snd.w = up ? P0.w : P1.w;
;     rcv.x = dpp_ror8(snd.x); rcv.y = dpp_ror8(snd.y); rcv.z = dpp_ror8(snd.z); rcv.w = dpp_ror8(snd.w);
;     u32x4 dA, dB;
;     dA.x = up ? rcv.x : P0.x; dA.y = up ? rcv.y : P0.y; dA.z = up ? rcv.z : P0.z; dA.w = up ? rcv.w : P0.w;
;     dB.x = up ? P1.x : rcv.x; dB.y = up ? P1.y : rcv.y; dB.z = up ? P1.z : rcv.z; dB.w = up ? P1.w : rcv.w;
;     bf16_t* p = grp + (size_t)(fr & 7) * ld + (up ? CBJ : 0) + 8 * fq;
;     __builtin_nontemporal_store(dA, (u32x4*)p); __builtin_nontemporal_store(dB, (u32x4*)(p + 8 * ld));
; }
;     __device__ __forceinline__ void operator()(f32x4 (&acc)[2][2][4][2], const Unit& u, int wr, int wc, int fr, int fq) const {
;     ...
;                     } else pk[bj] = pack8(acc[ai][bj][m][0] * (g0 * (1.0f / 255.0f)), acc[ai][bj][m][1] * (g1 * (1.0f / 255.0f)));
;                 }
;                 if (seg == 2) store_pair(Mg + (size_t)(rowg + ai * HALF + m * 16) * DM + colw, DM, fr, fq, pk[0], pk[1]);
.LBB0_879:
	s_ashr_i32 s41, s40, 31
	s_lshl_b64 s[38:39], s[40:41], 12
	s_add_u32 s9, s88, s38
	s_addc_u32 s17, s89, s39
	s_lshl_b64 s[38:39], s[0:1], 1
	s_add_u32 s38, s9, s38
	s_addc_u32 s39, s17, s39
	v_lshl_add_u64 v[136:137], s[38:39], 0, v[130:131]
	v_mov_b32_e32 v135, v131
	v_lshl_add_u64 v[136:137], v[136:137], 0, v[134:135]
	v_mov_b32_e32 v133, v131
	v_cndmask_b32_e64 v10, v2, v6, s[52:53]
	v_cndmask_b32_e64 v11, v3, v7, s[52:53]
	v_cndmask_b32_e64 v12, v4, v8, s[52:53]
	v_cndmask_b32_e64 v13, v5, v9, s[52:53]
	v_mov_b32_e32 v14, v131
	v_mov_b32_e32 v15, v131
	v_mov_b32_e32 v16, v131
	v_mov_b32_e32 v17, v131
	v_lshl_add_u64 v[136:137], v[136:137], 0, v[132:133]
	v_mov_b32_dpp v14, v10 row_ror:8 row_mask:0xf bank_mask:0xf
	v_mov_b32_dpp v15, v11 row_ror:8 row_mask:0xf bank_mask:0xf
	v_mov_b32_dpp v16, v12 row_ror:8 row_mask:0xf bank_mask:0xf
	v_mov_b32_dpp v17, v13 row_ror:8 row_mask:0xf bank_mask:0xf
	v_add_co_u32_e32 v182, vcc, 0xa0000, v136
	v_cndmask_b32_e64 v10, v14, v2, s[52:53]
	v_cndmask_b32_e64 v11, v15, v3, s[52:53]
	v_cndmask_b32_e64 v12, v16, v4, s[52:53]
	v_cndmask_b32_e64 v13, v17, v5, s[52:53]
	v_addc_co_u32_e32 v183, vcc, 0, v137, vcc
	global_store_dwordx4 v[182:183], v[10:13], off sc1
	v_cndmask_b32_e64 v14, v6, v14, s[52:53]
	v_cndmask_b32_e64 v15, v7, v15, s[52:53]
	v_add_co_u32_e32 v10, vcc, 0xa8000, v136
	v_cndmask_b32_e64 v16, v8, v16, s[52:53]
	v_cndmask_b32_e64 v17, v9, v17, s[52:53]
	v_addc_co_u32_e32 v11, vcc, 0, v137, vcc
	global_store_dwordx4 v[10:11], v[14:17], off sc1

; __device__ __forceinline__ u32x4 pack8(f32x4 a, f32x4 b) { u32x4 w; w.x = cvtpk(a[0], a[1]); w.y = cvtpk(a[2], a[3]); w.z = cvtpk(b[0], b[1]); w.w = cvtpk(b[2], b[3]); return w; }
; __device__ __forceinline__ unsigned dpp_ror8(unsigned v) { return (unsigned)__builtin_amdgcn_update_dpp(0, (int)v, 0x128, 0xF, 0xF, false); }
; __device__ __forceinline__ void store_pair(bf16_t* grp  , size_t ld, int fr, int fq, u32x4 P0, u32x4 P1) {
;     const bool up = (fr & 8) != 0;
;     u32x4 snd, rcv;
;     snd.x = up ? P0.x : P1.x; snd.y = up ? P0.y : P1.y; snd.z = up ? P0.z : P1.z; snd.w = up ? P0.w : P1.w;
;     rcv.x = dpp_ror8(snd.x); rcv.y = dpp_ror8(snd.y); rcv.z = dpp_ror8(snd.z); rcv.w = dpp_ror8(snd.w);
;     u32x4 dA, dB;
;     dA.x = up ? rcv.x : P0.x; dA.y = up ? rcv.y : P0.y; dA.z = up ? rcv.z : P0.z; dA.w = up ? rcv.w : P0.w;
;     dB.x = up ? P1.x : rcv.x; dB.y = up ? P1.y : rcv.y; dB.z = up ? P1.z : rcv.z; dB.w = up ? P1.w : rcv.w;
;     bf16_t* p = grp + (size_t)(fr & 7) * ld + (up ? CBJ : 0) + 8 * fq;
;     __builtin_nontemporal_store(dA, (u32x4*)p); __builtin_nontemporal_store(dB, (u32x4*)(p + 8 * ld));
; }
;     __device__ __forceinline__ void operator()(f32x4 (&acc)[2][2][4][2], const Unit& u, int wr, int wc, int fr, int fq) const {
;     ...
;                     } else pk[bj] = pack8(acc[ai][bj][m][0] * (g0 * (1.0f / 255.0f)), acc[ai][bj][m][1] * (g1 * (1.0f / 255.0f)));
;                 }
;                 if (seg == 2) store_pair(Mg + (size_t)(rowg + ai * HALF + m * 16) * DM + colw, DM, fr, fq, pk[0], pk[1]);
.LBB0_890:
	s_ashr_i32 s41, s40, 31
	s_lshl_b64 s[38:39], s[40:41], 12
	s_add_u32 s9, s88, s38
	v_cndmask_b32_e64 v10, v2, v6, s[52:53]
	v_mov_b32_e32 v14, v131
	s_addc_u32 s17, s89, s39
	s_lshl_b64 s[0:1], s[0:1], 1
	v_cndmask_b32_e64 v11, v3, v7, s[52:53]
	v_mov_b32_dpp v14, v10 row_ror:8 row_mask:0xf bank_mask:0xf
	v_mov_b32_e32 v10, v131
	s_add_u32 s0, s9, s0
	v_cndmask_b32_e64 v12, v4, v8, s[52:53]
	v_mov_b32_dpp v10, v11 row_ror:8 row_mask:0xf bank_mask:0xf
	v_mov_b32_e32 v11, v131
	s_addc_u32 s1, s17, s1
	v_cndmask_b32_e64 v3, v10, v3, s[52:53]
	v_mov_b32_dpp v11, v12 row_ror:8 row_mask:0xf bank_mask:0xf
	v_cndmask_b32_e64 v4, v11, v4, s[52:53]
	v_cndmask_b32_e64 v7, v7, v10, s[52:53]
	v_cndmask_b32_e64 v8, v8, v11, s[52:53]
	v_lshl_add_u64 v[10:11], s[0:1], 0, v[130:131]
	v_mov_b32_e32 v135, v131
	v_cndmask_b32_e64 v13, v5, v9, s[52:53]
	v_mov_b32_e32 v12, v131
	v_lshl_add_u64 v[10:11], v[10:11], 0, v[134:135]
	v_mov_b32_e32 v133, v131
	v_mov_b32_dpp v12, v13 row_ror:8 row_mask:0xf bank_mask:0xf
	v_lshl_add_u64 v[10:11], v[10:11], 0, v[132:133]
	v_cndmask_b32_e64 v5, v12, v5, s[52:53]
	v_cndmask_b32_e64 v9, v9, v12, s[52:53]
	v_add_co_u32_e32 v12, vcc, 0xb0000, v10
	v_cndmask_b32_e64 v2, v14, v2, s[52:53]
	s_nop 0
	v_addc_co_u32_e32 v13, vcc, 0, v11, vcc
	global_store_dwordx4 v[12:13], v[2:5], off sc1
	v_cndmask_b32_e64 v6, v6, v14, s[52:53]
	s_nop 0
	v_add_co_u32_e32 v2, vcc, 0xb8000, v10
	s_nop 1
	v_addc_co_u32_e32 v3, vcc, 0, v11, vcc
	global_store_dwordx4 v[2:3], v[6:9], off sc1

; __device__ __forceinline__ void titem_finish(const TItem& t, const f32x4 (&x)[16], const float (&sc)[16], LAS float* scr_f, int lane) {
;     ...
;     const int nblk = t.nblk, kb = t.r / nblk, nb = t.r - kb * nblk, k0 = 64 * kb, n0 = t.noff + 64 * nb, c = lane & 15, r = lane >> 4;
;     if (t.kind) {
;         float inv[4];
; #pragma unroll
;         for (int e = 0; e < 4; ++e) inv[e] = 127.0f / fmaxf(__uint_as_float(t.cmax[n0 - t.noff + 4 * c + e]), 1e-30f);
; #pragma unroll
;         for (int p = 0; p < 4; ++p)
; #pragma unroll
;             for (int e = 0; e < 4; ++e) {
;                 unsigned w = 0;
; #pragma unroll
;                 for (int j = 0; j < 4; ++j) { const float v = __builtin_amdgcn_fmed3f(__builtin_rintf(x[4 * p + j][e] * sc[4 * p + j] * inv[e]), -127.f, 127.f); w |= ((unsigned)(int)v & 255u) << (8 * j); }
;                 scr[(4 * c + e) * 17 + 4 * p + r] = w;
.LBB0_1003:
	s_abs_i32 s23, s84
	v_cvt_f32_u32_e32 v132, s23
	s_sub_i32 s24, 0, s23
	s_abs_i32 s1, s97
	s_xor_b32 s0, s97, s84
	v_rcp_iflag_f32_e32 v132, v132
	s_ashr_i32 s0, s0, 31
	v_cmp_eq_u32_e32 vcc, 0, v174
	v_mul_f32_e32 v132, 0x4f7ffffe, v132
	v_cvt_u32_f32_e32 v132, v132
	s_nop 0
	v_readfirstlane_b32 s25, v132
	s_mul_i32 s24, s24, s25
	s_mul_hi_u32 s24, s25, s24
	s_add_i32 s25, s25, s24
	s_mul_hi_u32 s24, s1, s25
	s_mul_i32 s25, s24, s23
	s_sub_i32 s1, s1, s25
	s_add_i32 s25, s24, 1
	s_sub_i32 s30, s1, s23
	s_cmp_ge_u32 s1, s23
	s_cselect_b32 s24, s25, s24
	s_cselect_b32 s1, s30, s1
	s_add_i32 s25, s24, 1
	s_cmp_ge_u32 s1, s23
	s_cselect_b32 s1, s25, s24
	s_xor_b32 s1, s1, s0
	s_sub_i32 s24, s1, s0
	s_mul_i32 s0, s24, s84
	s_sub_i32 s1, s97, s0
	s_lshl_b32 s23, s1, 6
	s_lshl_b32 s0, s24, 6
	s_add_i32 s40, s23, s80
	s_cbranch_vccnz .LBB0_1024
	v_or_b32_e32 v132, s23, v193
	s_waitcnt lgkmcnt(0)
	v_ashrrev_i32_e32 v133, 31, v132
	v_lshl_add_u64 v[132:133], v[132:133], 2, s[8:9]
	global_load_dwordx4 v[212:215], v[132:133], off
	s_waitcnt vmcnt(9)
	v_mul_f32_e32 v216, v30, v143
	s_lshl_b32 s24, s24, 7
	s_and_b32 s24, s24, 0xfffff800
	s_add_i32 s42, s24, 0x800
	s_ashr_i32 s1, s0, 31
	s_ashr_i32 s41, s40, 31
	s_ashr_i32 s43, s42, 31
	s_cmp_lg_u64 s[16:17], 0
	s_cselect_b64 s[56:57], -1, 0
	s_waitcnt vmcnt(0)
	v_max_f32_e32 v132, v212, v212
	v_max_f32_e32 v132, 0xda24260, v132
	v_div_scale_f32 v133, s[30:31], v132, v132, s51
	v_rcp_f32_e32 v134, v133
	s_nop 0
	v_fma_f32 v135, -v133, v134, 1.0
	v_fmac_f32_e32 v134, v135, v134
	v_div_scale_f32 v135, vcc, s51, v132, s51
	v_mul_f32_e32 v157, v135, v134
	v_fma_f32 v203, -v133, v157, v135
	v_fmac_f32_e32 v157, v203, v134
	v_fma_f32 v133, -v133, v157, v135
	v_div_fmas_f32 v133, v133, v134, v157
	v_div_fixup_f32 v135, v133, v132, s51
	v_max_f32_e32 v132, v213, v213
	v_max_f32_e32 v132, 0xda24260, v132
	v_div_scale_f32 v133, s[30:31], v132, v132, s51
	v_rcp_f32_e32 v134, v133
	v_mul_f32_e32 v216, v216, v135
	v_rndne_f32_e32 v216, v216
	v_med3_f32 v216, v216, s92, v207
	v_fma_f32 v157, -v133, v134, 1.0
	v_fmac_f32_e32 v134, v157, v134
	v_div_scale_f32 v157, vcc, s51, v132, s51
	v_mul_f32_e32 v203, v157, v134
	v_fma_f32 v211, -v133, v203, v157
	v_fmac_f32_e32 v203, v211, v134
	v_fma_f32 v133, -v133, v203, v157
	v_div_fmas_f32 v133, v133, v134, v203
	v_div_fixup_f32 v134, v133, v132, s51
	v_max_f32_e32 v132, v214, v214
	v_max_f32_e32 v132, 0xda24260, v132
	v_div_scale_f32 v133, s[30:31], v132, v132, s51
	v_rcp_f32_e32 v157, v133
	v_mul_f32_e32 v214, v16, v139
	v_cvt_i32_f32_e32 v216, v216
	v_fma_f32 v203, -v133, v157, 1.0
	v_fmac_f32_e32 v157, v203, v157
	v_div_scale_f32 v203, vcc, s51, v132, s51
	v_mul_f32_e32 v211, v203, v157
	v_fma_f32 v212, -v133, v211, v203
	v_fmac_f32_e32 v211, v212, v157
	v_fma_f32 v133, -v133, v211, v203
	v_div_fmas_f32 v133, v133, v157, v211
	v_div_fixup_f32 v133, v133, v132, s51
	v_max_f32_e32 v132, v215, v215
	v_max_f32_e32 v132, 0xda24260, v132
	v_div_scale_f32 v157, s[30:31], v132, v132, s51
	v_rcp_f32_e32 v203, v157
	v_mul_f32_e32 v214, v214, v133
	v_rndne_f32_e32 v214, v214
	v_med3_f32 v214, v214, s92, v207
	v_fma_f32 v211, -v157, v203, 1.0
	v_fmac_f32_e32 v203, v211, v203
	v_div_scale_f32 v211, vcc, s51, v132, s51
	v_mul_f32_e32 v212, v211, v203
	v_fma_f32 v213, -v157, v212, v211
	v_fmac_f32_e32 v212, v213, v203
	v_fma_f32 v157, -v157, v212, v211
	v_div_fmas_f32 v157, v157, v203, v212
	v_mul_f32_e32 v203, v6, v137
	v_div_fixup_f32 v132, v157, v132, s51
	v_mul_f32_e32 v157, v2, v136
	v_mul_f32_e32 v203, v203, v135
	v_mul_f32_e32 v211, v10, v138
	v_mul_f32_e32 v212, v14, v139
	v_mul_f32_e32 v157, v157, v135
	v_rndne_f32_e32 v203, v203
	v_mul_f32_e32 v211, v211, v135
	v_mul_f32_e32 v212, v212, v135
	v_rndne_f32_e32 v157, v157
	v_med3_f32 v203, v203, s92, v207
	v_rndne_f32_e32 v211, v211
	v_rndne_f32_e32 v212, v212
	v_med3_f32 v157, v157, s92, v207
	v_cvt_i32_f32_e32 v203, v203
	v_med3_f32 v211, v211, s92, v207
	v_med3_f32 v212, v212, s92, v207
	v_cvt_i32_f32_e32 v157, v157
	v_cvt_i32_f32_sdwa v211, v211 dst_sel:WORD_1 dst_unused:UNUSED_PAD src0_sel:DWORD
	v_cvt_i32_f32_e32 v212, v212
	v_lshlrev_b32_e32 v203, 8, v203
	v_and_b32_e32 v203, 0xff00, v203
	v_and_b32_e32 v211, 0xff0000, v211
	v_perm_b32 v157, v212, v157, s93
	v_or3_b32 v157, v157, v203, v211
	v_mul_f32_e32 v211, v7, v137
	v_mul_f32_e32 v203, v3, v136
	v_mul_f32_e32 v211, v211, v134
	v_mul_f32_e32 v212, v11, v138
	v_mul_f32_e32 v213, v15, v139
	v_mul_f32_e32 v203, v203, v134
	v_rndne_f32_e32 v211, v211
	v_mul_f32_e32 v212, v212, v134
	v_mul_f32_e32 v213, v213, v134
	v_rndne_f32_e32 v203, v203
	v_med3_f32 v211, v211, s92, v207
	v_rndne_f32_e32 v212, v212
	v_rndne_f32_e32 v213, v213
	v_med3_f32 v203, v203, s92, v207
	v_cvt_i32_f32_e32 v211, v211
	v_med3_f32 v212, v212, s92, v207
	v_med3_f32 v213, v213, s92, v207
	v_cvt_i32_f32_e32 v203, v203
	v_cvt_i32_f32_sdwa v212, v212 dst_sel:WORD_1 dst_unused:UNUSED_PAD src0_sel:DWORD
	v_cvt_i32_f32_e32 v213, v213
	v_lshlrev_b32_e32 v211, 8, v211
	v_and_b32_e32 v211, 0xff00, v211
	v_and_b32_e32 v212, 0xff0000, v212
	v_perm_b32 v203, v213, v203, s93
	v_or3_b32 v203, v203, v211, v212
	v_mul_f32_e32 v212, v8, v137
	v_mul_f32_e32 v211, v4, v136
	v_mul_f32_e32 v212, v212, v133
	v_mul_f32_e32 v213, v12, v138
	v_mul_f32_e32 v211, v211, v133
	v_rndne_f32_e32 v212, v212
	v_mul_f32_e32 v213, v213, v133
	v_rndne_f32_e32 v211, v211
	v_med3_f32 v212, v212, s92, v207
	v_rndne_f32_e32 v213, v213
	v_med3_f32 v211, v211, s92, v207
	v_cvt_i32_f32_e32 v212, v212
	v_med3_f32 v213, v213, s92, v207
	v_cvt_i32_f32_e32 v211, v211
	v_cvt_i32_f32_sdwa v213, v213 dst_sel:WORD_1 dst_unused:UNUSED_PAD src0_sel:DWORD
; __device__ __forceinline__ void titem_finish(const TItem& t, const f32x4 (&x)[16], const float (&sc)[16], LAS float* scr_f, int lane) {
;     ...
;         for (int p = 0; p < 4; ++p)
; #pragma unroll
;             for (int e = 0; e < 4; ++e) {
;                 unsigned w = 0;
; #pragma unroll
;                 for (int j = 0; j < 4; ++j) { const float v = __builtin_amdgcn_fmed3f(__builtin_rintf(x[4 * p + j][e] * sc[4 * p + j] * inv[e]), -127.f, 127.f); w |= ((unsigned)(int)v & 255u) << (8 * j); }
;                 scr[(4 * c + e) * 17 + 4 * p + r] = w;
	v_cvt_i32_f32_e32 v214, v214
	v_lshlrev_b32_e32 v212, 8, v212
	v_and_b32_e32 v212, 0xff00, v212
	v_and_b32_e32 v213, 0xff0000, v213
	v_perm_b32 v211, v214, v211, s93
	v_or3_b32 v211, v211, v212, v213
	v_mul_f32_e32 v213, v9, v137
	v_mul_f32_e32 v212, v5, v136
	v_mul_f32_e32 v213, v213, v132
	v_mul_f32_e32 v214, v13, v138
	v_mul_f32_e32 v215, v17, v139
	v_mul_f32_e32 v212, v212, v132
	v_rndne_f32_e32 v213, v213
	v_mul_f32_e32 v214, v214, v132
	v_mul_f32_e32 v215, v215, v132
	v_rndne_f32_e32 v212, v212
	v_med3_f32 v213, v213, s92, v207
	v_rndne_f32_e32 v214, v214
	v_rndne_f32_e32 v215, v215
	v_med3_f32 v212, v212, s92, v207
	v_cvt_i32_f32_e32 v213, v213
	v_med3_f32 v214, v214, s92, v207
	v_med3_f32 v215, v215, s92, v207
	v_cvt_i32_f32_e32 v212, v212
	v_cvt_i32_f32_sdwa v214, v214 dst_sel:WORD_1 dst_unused:UNUSED_PAD src0_sel:DWORD
	v_cvt_i32_f32_e32 v215, v215
	v_lshlrev_b32_e32 v213, 8, v213
	v_and_b32_e32 v213, 0xff00, v213
	v_and_b32_e32 v214, 0xff0000, v214
	v_perm_b32 v212, v215, v212, s93
	v_or3_b32 v212, v212, v213, v214
	v_mul_f32_e32 v214, v22, v141
	v_mul_f32_e32 v213, v18, v140
	v_mul_f32_e32 v214, v214, v135
	v_mul_f32_e32 v215, v26, v142
	v_mul_f32_e32 v213, v213, v135
	v_rndne_f32_e32 v214, v214
	v_mul_f32_e32 v215, v215, v135
	v_rndne_f32_e32 v213, v213
	v_med3_f32 v214, v214, s92, v207
	v_rndne_f32_e32 v215, v215
	v_med3_f32 v213, v213, s92, v207
	v_cvt_i32_f32_e32 v214, v214
	v_med3_f32 v215, v215, s92, v207
	v_cvt_i32_f32_e32 v213, v213
	v_cvt_i32_f32_sdwa v215, v215 dst_sel:WORD_1 dst_unused:UNUSED_PAD src0_sel:DWORD
	v_lshlrev_b32_e32 v214, 8, v214
	v_and_b32_e32 v214, 0xff00, v214
	v_perm_b32 v213, v216, v213, s93
	v_and_b32_e32 v215, 0xff0000, v215
	v_or3_b32 v213, v213, v214, v215
	ds_write2_b32 v198, v157, v213 offset1:4
	v_mul_f32_e32 v213, v23, v141
	v_mul_f32_e32 v157, v19, v140
	v_mul_f32_e32 v213, v213, v134
	v_mul_f32_e32 v214, v27, v142
	v_mul_f32_e32 v215, v31, v143
	v_mul_f32_e32 v157, v157, v134
	v_rndne_f32_e32 v213, v213
	v_mul_f32_e32 v214, v214, v134
	v_mul_f32_e32 v215, v215, v134
	v_rndne_f32_e32 v157, v157
	v_med3_f32 v213, v213, s92, v207
	v_rndne_f32_e32 v214, v214
	v_rndne_f32_e32 v215, v215
	v_med3_f32 v157, v157, s92, v207
	v_cvt_i32_f32_e32 v213, v213
	v_med3_f32 v214, v214, s92, v207
	v_med3_f32 v215, v215, s92, v207
	v_cvt_i32_f32_e32 v157, v157
	v_cvt_i32_f32_sdwa v214, v214 dst_sel:WORD_1 dst_unused:UNUSED_PAD src0_sel:DWORD
	v_cvt_i32_f32_e32 v215, v215
	v_lshlrev_b32_e32 v213, 8, v213
	v_and_b32_e32 v213, 0xff00, v213
	v_and_b32_e32 v214, 0xff0000, v214
	v_perm_b32 v157, v215, v157, s93
	v_or3_b32 v157, v157, v213, v214
	ds_write2_b32 v198, v203, v157 offset0:17 offset1:21
	v_mul_f32_e32 v203, v24, v141
	v_mul_f32_e32 v157, v20, v140
	v_mul_f32_e32 v203, v203, v133
	v_mul_f32_e32 v213, v28, v142
	v_mul_f32_e32 v214, v32, v143
	v_mul_f32_e32 v157, v157, v133
	v_rndne_f32_e32 v203, v203
	v_mul_f32_e32 v213, v213, v133
	v_mul_f32_e32 v214, v214, v133
	v_rndne_f32_e32 v157, v157
	v_med3_f32 v203, v203, s92, v207
	v_rndne_f32_e32 v213, v213
	v_rndne_f32_e32 v214, v214
	v_med3_f32 v157, v157, s92, v207
	v_cvt_i32_f32_e32 v203, v203
	v_med3_f32 v213, v213, s92, v207
	v_med3_f32 v214, v214, s92, v207
	v_cvt_i32_f32_e32 v157, v157
	v_cvt_i32_f32_sdwa v213, v213 dst_sel:WORD_1 dst_unused:UNUSED_PAD src0_sel:DWORD
	v_cvt_i32_f32_e32 v214, v214
	v_lshlrev_b32_e32 v203, 8, v203
	v_and_b32_e32 v203, 0xff00, v203
	v_and_b32_e32 v213, 0xff0000, v213
	v_perm_b32 v157, v214, v157, s93
	v_or3_b32 v157, v157, v203, v213
	v_mul_f32_e32 v203, v25, v141
	ds_write2_b32 v198, v211, v157 offset0:34 offset1:38
	v_mul_f32_e32 v157, v21, v140
	v_mul_f32_e32 v203, v203, v132
	v_mul_f32_e32 v211, v29, v142
	v_mul_f32_e32 v213, v33, v143
	v_mul_f32_e32 v157, v157, v132
	v_rndne_f32_e32 v203, v203
	v_mul_f32_e32 v211, v211, v132
	v_mul_f32_e32 v213, v213, v132
	v_rndne_f32_e32 v157, v157
	v_med3_f32 v203, v203, s92, v207
	v_rndne_f32_e32 v211, v211
	v_rndne_f32_e32 v213, v213
	v_med3_f32 v157, v157, s92, v207
	v_cvt_i32_f32_e32 v203, v203
	v_med3_f32 v211, v211, s92, v207
	v_med3_f32 v213, v213, s92, v207
	v_cvt_i32_f32_e32 v157, v157
	v_cvt_i32_f32_sdwa v211, v211 dst_sel:WORD_1 dst_unused:UNUSED_PAD src0_sel:DWORD
	v_cvt_i32_f32_e32 v213, v213
	v_lshlrev_b32_e32 v203, 8, v203
	v_and_b32_e32 v203, 0xff00, v203
	v_and_b32_e32 v211, 0xff0000, v211
	v_perm_b32 v157, v213, v157, s93
	v_or3_b32 v157, v157, v203, v211
	v_mul_f32_e32 v203, v38, v145
	ds_write2_b32 v198, v212, v157 offset0:51 offset1:55
	v_mul_f32_e32 v157, v34, v144
	v_mul_f32_e32 v203, v203, v135
	v_mul_f32_e32 v211, v42, v146
	v_mul_f32_e32 v212, v46, v147
	v_mul_f32_e32 v157, v157, v135
	v_rndne_f32_e32 v203, v203
	v_mul_f32_e32 v211, v211, v135
	v_mul_f32_e32 v212, v212, v135
	v_rndne_f32_e32 v157, v157
	v_med3_f32 v203, v203, s92, v207
	v_rndne_f32_e32 v211, v211
	v_rndne_f32_e32 v212, v212
	v_med3_f32 v157, v157, s92, v207
	v_cvt_i32_f32_e32 v203, v203
	v_med3_f32 v211, v211, s92, v207
	v_med3_f32 v212, v212, s92, v207
	v_cvt_i32_f32_e32 v157, v157
	v_cvt_i32_f32_sdwa v211, v211 dst_sel:WORD_1 dst_unused:UNUSED_PAD src0_sel:DWORD
	v_cvt_i32_f32_e32 v212, v212
	v_lshlrev_b32_e32 v203, 8, v203
	v_and_b32_e32 v203, 0xff00, v203
	v_and_b32_e32 v211, 0xff0000, v211
	v_perm_b32 v157, v212, v157, s93
	v_or3_b32 v157, v157, v203, v211
	v_mul_f32_e32 v211, v39, v145
	v_mul_f32_e32 v203, v35, v144
	v_mul_f32_e32 v211, v211, v134
	v_mul_f32_e32 v212, v43, v146
	v_mul_f32_e32 v213, v47, v147
	v_mul_f32_e32 v203, v203, v134
	v_rndne_f32_e32 v211, v211
	v_mul_f32_e32 v212, v212, v134
	v_mul_f32_e32 v213, v213, v134
	v_rndne_f32_e32 v203, v203
	v_med3_f32 v211, v211, s92, v207
; #define LAS __attribute__((address_space(3)))
; #define LDS_WAIT() asm volatile("s_waitcnt lgkmcnt(0)" ::: "memory")
; __device__ __forceinline__ void titem_finish(const TItem& t, const f32x4 (&x)[16], const float (&sc)[16], LAS float* scr_f, int lane) {
;     ...
;         for (int p = 0; p < 4; ++p)
; #pragma unroll
;             for (int e = 0; e < 4; ++e) {
;                 unsigned w = 0;
; #pragma unroll
;                 for (int j = 0; j < 4; ++j) { const float v = __builtin_amdgcn_fmed3f(__builtin_rintf(x[4 * p + j][e] * sc[4 * p + j] * inv[e]), -127.f, 127.f); w |= ((unsigned)(int)v & 255u) << (8 * j); }
;                 scr[(4 * c + e) * 17 + 4 * p + r] = w;
;             }
;         LDS_WAIT(); asm volatile("" ::: "memory");
;         const int q4 = lane & 3;
; #pragma unroll
;         for (int j = 0; j < 4; ++j) { const int n = (lane >> 2) + 16 * j; const LAS unsigned* s = scr + n * 17 + 4 * q4;
;             u32x4 o; o.x = s[0]; o.y = s[1]; o.z = s[2]; o.w = s[3];
;             __builtin_nontemporal_store(o, (u32x4*)((unsigned char*)t.WT + (size_t)(n0 - t.noff + n) * t.K + k0 + 16 * q4));
	v_rndne_f32_e32 v212, v212
	v_rndne_f32_e32 v213, v213
	v_med3_f32 v203, v203, s92, v207
	v_cvt_i32_f32_e32 v211, v211
	v_med3_f32 v212, v212, s92, v207
	v_med3_f32 v213, v213, s92, v207
	v_cvt_i32_f32_e32 v203, v203
	v_cvt_i32_f32_sdwa v212, v212 dst_sel:WORD_1 dst_unused:UNUSED_PAD src0_sel:DWORD
	v_cvt_i32_f32_e32 v213, v213
	v_lshlrev_b32_e32 v211, 8, v211
	v_and_b32_e32 v211, 0xff00, v211
	v_and_b32_e32 v212, 0xff0000, v212
	v_perm_b32 v203, v213, v203, s93
	v_or3_b32 v203, v203, v211, v212
	v_mul_f32_e32 v212, v40, v145
	v_mul_f32_e32 v211, v36, v144
	v_mul_f32_e32 v212, v212, v133
	v_mul_f32_e32 v213, v44, v146
	v_mul_f32_e32 v214, v48, v147
	v_mul_f32_e32 v211, v211, v133
	v_rndne_f32_e32 v212, v212
	v_mul_f32_e32 v213, v213, v133
	v_mul_f32_e32 v214, v214, v133
	v_rndne_f32_e32 v211, v211
	v_med3_f32 v212, v212, s92, v207
	v_rndne_f32_e32 v213, v213
	v_rndne_f32_e32 v214, v214
	v_med3_f32 v211, v211, s92, v207
	v_cvt_i32_f32_e32 v212, v212
	v_med3_f32 v213, v213, s92, v207
	v_med3_f32 v214, v214, s92, v207
	v_cvt_i32_f32_e32 v211, v211
	v_cvt_i32_f32_sdwa v213, v213 dst_sel:WORD_1 dst_unused:UNUSED_PAD src0_sel:DWORD
	v_cvt_i32_f32_e32 v214, v214
	v_lshlrev_b32_e32 v212, 8, v212
	v_and_b32_e32 v212, 0xff00, v212
	v_and_b32_e32 v213, 0xff0000, v213
	v_perm_b32 v211, v214, v211, s93
	v_or3_b32 v211, v211, v212, v213
	v_mul_f32_e32 v213, v41, v145
	v_mul_f32_e32 v212, v37, v144
	v_mul_f32_e32 v213, v213, v132
	v_mul_f32_e32 v214, v45, v146
	v_mul_f32_e32 v215, v49, v147
	v_mul_f32_e32 v212, v212, v132
	v_rndne_f32_e32 v213, v213
	v_mul_f32_e32 v214, v214, v132
	v_mul_f32_e32 v215, v215, v132
	v_rndne_f32_e32 v212, v212
	v_med3_f32 v213, v213, s92, v207
	v_rndne_f32_e32 v214, v214
	v_rndne_f32_e32 v215, v215
	v_med3_f32 v212, v212, s92, v207
	v_cvt_i32_f32_e32 v213, v213
	v_med3_f32 v214, v214, s92, v207
	v_med3_f32 v215, v215, s92, v207
	v_cvt_i32_f32_e32 v212, v212
	v_cvt_i32_f32_sdwa v214, v214 dst_sel:WORD_1 dst_unused:UNUSED_PAD src0_sel:DWORD
	v_cvt_i32_f32_e32 v215, v215
	v_lshlrev_b32_e32 v213, 8, v213
	v_and_b32_e32 v213, 0xff00, v213
	v_and_b32_e32 v214, 0xff0000, v214
	v_perm_b32 v212, v215, v212, s93
	v_or3_b32 v212, v212, v213, v214
	v_mul_f32_e32 v214, v54, v149
	v_mul_f32_e32 v213, v50, v148
	v_mul_f32_e32 v214, v214, v135
	v_mul_f32_e32 v215, v58, v150
	v_mul_f32_e32 v216, v62, v151
	v_mul_f32_e32 v213, v213, v135
	v_rndne_f32_e32 v214, v214
	v_mul_f32_e32 v215, v215, v135
	v_mul_f32_e32 v135, v216, v135
	v_rndne_f32_e32 v213, v213
	v_med3_f32 v214, v214, s92, v207
	v_rndne_f32_e32 v215, v215
	v_rndne_f32_e32 v135, v135
	v_med3_f32 v213, v213, s92, v207
	v_cvt_i32_f32_e32 v214, v214
	v_med3_f32 v215, v215, s92, v207
	v_med3_f32 v135, v135, s92, v207
	v_cvt_i32_f32_e32 v213, v213
	v_cvt_i32_f32_sdwa v215, v215 dst_sel:WORD_1 dst_unused:UNUSED_PAD src0_sel:DWORD
	v_cvt_i32_f32_e32 v135, v135
	v_lshlrev_b32_e32 v214, 8, v214
	v_and_b32_e32 v214, 0xff00, v214
	v_and_b32_e32 v215, 0xff0000, v215
	v_perm_b32 v135, v135, v213, s93
	v_or3_b32 v135, v135, v214, v215
	ds_write2_b32 v198, v157, v135 offset0:8 offset1:12
	v_mul_f32_e32 v157, v55, v149
	v_mul_f32_e32 v135, v51, v148
	v_mul_f32_e32 v157, v157, v134
	v_mul_f32_e32 v213, v59, v150
	v_mul_f32_e32 v214, v63, v151
	v_mul_f32_e32 v135, v135, v134
	v_rndne_f32_e32 v157, v157
	v_mul_f32_e32 v213, v213, v134
	v_mul_f32_e32 v134, v214, v134
	v_rndne_f32_e32 v135, v135
	v_med3_f32 v157, v157, s92, v207
	v_rndne_f32_e32 v213, v213
	v_rndne_f32_e32 v134, v134
	v_med3_f32 v135, v135, s92, v207
	v_cvt_i32_f32_e32 v157, v157
	v_med3_f32 v213, v213, s92, v207
	v_med3_f32 v134, v134, s92, v207
	v_cvt_i32_f32_e32 v135, v135
	v_cvt_i32_f32_sdwa v213, v213 dst_sel:WORD_1 dst_unused:UNUSED_PAD src0_sel:DWORD
	v_cvt_i32_f32_e32 v134, v134
	v_lshlrev_b32_e32 v157, 8, v157
	v_and_b32_e32 v157, 0xff00, v157
	v_and_b32_e32 v213, 0xff0000, v213
	v_perm_b32 v134, v134, v135, s93
	v_or3_b32 v134, v134, v157, v213
	v_mul_f32_e32 v135, v56, v149
	ds_write2_b32 v198, v203, v134 offset0:25 offset1:29
	v_mul_f32_e32 v134, v52, v148
	v_mul_f32_e32 v135, v135, v133
	v_mul_f32_e32 v157, v60, v150
	v_mul_f32_e32 v203, v64, v151
	v_mul_f32_e32 v134, v134, v133
	v_rndne_f32_e32 v135, v135
	v_mul_f32_e32 v157, v157, v133
	v_mul_f32_e32 v133, v203, v133
	v_rndne_f32_e32 v134, v134
	v_med3_f32 v135, v135, s92, v207
	v_rndne_f32_e32 v157, v157
	v_rndne_f32_e32 v133, v133
	v_med3_f32 v134, v134, s92, v207
	v_cvt_i32_f32_e32 v135, v135
	v_med3_f32 v157, v157, s92, v207
	v_med3_f32 v133, v133, s92, v207
	v_cvt_i32_f32_e32 v134, v134
	v_cvt_i32_f32_sdwa v157, v157 dst_sel:WORD_1 dst_unused:UNUSED_PAD src0_sel:DWORD
	v_cvt_i32_f32_e32 v133, v133
	v_lshlrev_b32_e32 v135, 8, v135
	v_and_b32_e32 v135, 0xff00, v135
	v_and_b32_e32 v157, 0xff0000, v157
	v_perm_b32 v133, v133, v134, s93
	v_or3_b32 v133, v133, v135, v157
	v_mul_f32_e32 v134, v57, v149
	ds_write2_b32 v198, v211, v133 offset0:42 offset1:46
	v_mul_f32_e32 v133, v53, v148
	v_mul_f32_e32 v134, v134, v132
	v_mul_f32_e32 v135, v61, v150
	v_mul_f32_e32 v157, v65, v151
	v_mul_f32_e32 v133, v133, v132
	v_rndne_f32_e32 v134, v134
	v_mul_f32_e32 v135, v135, v132
	v_mul_f32_e32 v132, v157, v132
	v_rndne_f32_e32 v133, v133
	v_med3_f32 v134, v134, s92, v207
	v_rndne_f32_e32 v135, v135
	v_rndne_f32_e32 v132, v132
	v_med3_f32 v133, v133, s92, v207
	v_cvt_i32_f32_e32 v134, v134
	v_med3_f32 v135, v135, s92, v207
	v_med3_f32 v132, v132, s92, v207
	v_cvt_i32_f32_e32 v133, v133
	v_cvt_i32_f32_sdwa v135, v135 dst_sel:WORD_1 dst_unused:UNUSED_PAD src0_sel:DWORD
	v_cvt_i32_f32_e32 v132, v132
	v_lshlrev_b32_e32 v134, 8, v134
	v_and_b32_e32 v134, 0xff00, v134
	v_and_b32_e32 v135, 0xff0000, v135
	v_perm_b32 v132, v132, v133, s93
	v_or3_b32 v132, v132, v134, v135
	ds_write2_b32 v198, v212, v132 offset0:59 offset1:63
	s_waitcnt lgkmcnt(0)
	v_add_u32_e32 v157, s23, v152
	v_mov_b64_e32 v[212:213], s[4:5]
	v_mad_u64_u32 v[212:213], s[24:25], v157, s85, v[212:213]
	ds_read2_b32 v[132:133], v201 offset1:1
	ds_read2_b32 v[134:135], v201 offset0:2 offset1:3
	v_ashrrev_i32_e32 v203, 31, v157
	v_mov_b32_e32 v214, v213
	v_mad_u64_u32 v[214:215], s[24:25], v203, s85, v[214:215]
	v_mov_b32_e32 v213, v214
	v_lshl_add_u64 v[212:213], v[212:213], 0, s[0:1]
	v_lshl_add_u64 v[212:213], v[212:213], 0, v[154:155]
	s_and_b64 vcc, exec, s[56:57]
	s_waitcnt lgkmcnt(0)
	global_store_dwordx4 v[212:213], v[132:135], off sc1
	s_cbranch_vccz .LBB0_1025
; #define LAS __attribute__((address_space(3)))
; __device__ __forceinline__ void titem_finish(const TItem& t, const f32x4 (&x)[16], const float (&sc)[16], LAS float* scr_f, int lane) {
;     ...
;         for (int j = 0; j < 4; ++j) { const int n = (lane >> 2) + 16 * j; const LAS unsigned* s = scr + n * 17 + 4 * q4;
;             u32x4 o; o.x = s[0]; o.y = s[1]; o.z = s[2]; o.w = s[3];
;             __builtin_nontemporal_store(o, (u32x4*)((unsigned char*)t.WT + (size_t)(n0 - t.noff + n) * t.K + k0 + 16 * q4));
;             if (t.csum) {
;                 int cs = __builtin_amdgcn_sdot4((int)o.x, 0x01010101, 0, false); cs = __builtin_amdgcn_sdot4((int)o.y, 0x01010101, cs, false); cs = __builtin_amdgcn_sdot4((int)o.z, 0x01010101, cs, false); cs = __builtin_amdgcn_sdot4((int)o.w, 0x01010101, cs, false);
;                 cs += __shfl_xor(cs, 1); cs += __shfl_xor(cs, 2);
;                 if (q4 == 0) { atomicAdd(t.csum + n0 - t.noff + n, cs * 128); atomicAdd(t.csum + (1 + (k0 >> 10)) * DM + n0 - t.noff + n, cs * 128); }
;             } }
	v_mov_b32_e32 v157, v131
	v_dot4c_i32_i8_e32 v157, 0x1010101, v132
	v_dot4c_i32_i8_e32 v157, 0x1010101, v133
	v_dot4c_i32_i8_e32 v157, 0x1010101, v134
	v_and_b32_e32 v133, 64, v204
	v_dot4c_i32_i8_e32 v157, 0x1010101, v135
	v_xor_b32_e32 v132, 1, v204
	v_add_u32_e32 v135, 64, v133
	v_cmp_lt_i32_e32 vcc, v132, v135
	s_nop 1
	v_cndmask_b32_e32 v132, v204, v132, vcc
	v_lshlrev_b32_e32 v133, 2, v132
	ds_bpermute_b32 v132, v133, v157
	s_waitcnt lgkmcnt(0)
	v_add_u32_e32 v134, v132, v157
	v_xor_b32_e32 v132, 2, v204
	v_cmp_lt_i32_e32 vcc, v132, v135
	s_nop 1
	v_cndmask_b32_e32 v132, v204, v132, vcc
	v_lshlrev_b32_e32 v132, 2, v132
	ds_bpermute_b32 v135, v132, v134
	s_and_saveexec_b64 s[54:55], s[52:53]
	s_cbranch_execz .LBB0_1007
	s_lshl_b64 s[24:25], s[40:41], 2
	s_add_u32 s34, s16, s24
	s_addc_u32 s35, s17, s25
	s_lshl_b64 s[30:31], s[80:81], 2
	s_sub_u32 s34, s34, s30
	s_subb_u32 s35, s35, s31
	v_lshlrev_b64 v[212:213], 2, v[152:153]
	v_lshl_add_u64 v[214:215], s[34:35], 0, v[212:213]
	s_lshl_b64 s[34:35], s[42:43], 2
	s_add_u32 s34, s16, s34
	s_addc_u32 s35, s17, s35
	s_add_u32 s24, s34, s24
	s_addc_u32 s25, s35, s25
	s_sub_u32 s24, s24, s30
	s_waitcnt lgkmcnt(0)
	v_add_lshl_u32 v157, v134, v135, 7
	s_subb_u32 s25, s25, s31
	global_atomic_add v[214:215], v157, off
	v_lshl_add_u64 v[134:135], s[24:25], 0, v[212:213]
	global_atomic_add v[134:135], v157, off
	v_readlane_b32 s34, v255, 27
	v_readlane_b32 s35, v255, 28
	v_readlane_b32 s35, v255, 37
.LBB0_1007:
	s_or_b64 exec, exec, s[54:55]
	v_add_u32_e32 v134, 0x440, v201
	ds_read2_b32 v[212:213], v134 offset1:1
	v_add_u32_e32 v134, 0x448, v201
	ds_read2_b32 v[214:215], v134 offset1:1
	v_add_u32_e32 v157, s23, v194
	s_waitcnt lgkmcnt(2)
	v_mov_b64_e32 v[134:135], s[4:5]
	v_mad_u64_u32 v[134:135], s[24:25], v157, s85, v[134:135]
	v_ashrrev_i32_e32 v203, 31, v157
	v_mov_b32_e32 v216, v135
	v_mad_u64_u32 v[216:217], s[24:25], v203, s85, v[216:217]
	v_mov_b32_e32 v135, v216
	v_lshl_add_u64 v[134:135], v[134:135], 0, s[0:1]
	v_lshl_add_u64 v[134:135], v[134:135], 0, v[154:155]
	s_waitcnt lgkmcnt(0)
	global_store_dwordx4 v[134:135], v[212:215], off sc1
	v_mov_b32_e32 v134, v131
	v_dot4c_i32_i8_e32 v134, 0x1010101, v212
	v_dot4c_i32_i8_e32 v134, 0x1010101, v213
	v_dot4c_i32_i8_e32 v134, 0x1010101, v214
	v_dot4c_i32_i8_e32 v134, 0x1010101, v215
	s_nop 2
	ds_bpermute_b32 v133, v133, v134
	s_waitcnt lgkmcnt(0)
	v_add_u32_e32 v133, v133, v134
	ds_bpermute_b32 v132, v132, v133
	s_and_saveexec_b64 s[54:55], s[52:53]
	s_cbranch_execz .LBB0_1009
	s_lshl_b64 s[24:25], s[40:41], 2
	s_add_u32 s34, s16, s24
	s_addc_u32 s35, s17, s25
	s_lshl_b64 s[30:31], s[80:81], 2
	s_sub_u32 s34, s34, s30
	s_subb_u32 s35, s35, s31
	v_lshlrev_b64 v[134:135], 2, v[152:153]
	v_lshl_add_u64 v[212:213], s[34:35], 0, v[134:135]
	s_lshl_b64 s[34:35], s[42:43], 2
	s_add_u32 s34, s16, s34
	s_addc_u32 s35, s17, s35
	s_add_u32 s24, s34, s24
	s_addc_u32 s25, s35, s25
	s_sub_u32 s24, s24, s30
	s_waitcnt lgkmcnt(0)
	v_add_lshl_u32 v157, v133, v132, 7
	s_subb_u32 s25, s25, s31
	global_atomic_add v[212:213], v157, off offset:64
	v_lshl_add_u64 v[132:133], s[24:25], 0, v[134:135]
	global_atomic_add v[132:133], v157, off offset:64
	v_readlane_b32 s34, v255, 27
	v_readlane_b32 s35, v255, 28
	v_readlane_b32 s35, v255, 37

; #define LAS __attribute__((address_space(3)))
; __device__ __forceinline__ void titem_finish(const TItem& t, const f32x4 (&x)[16], const float (&sc)[16], LAS float* scr_f, int lane) {
;     ...
;         for (int j = 0; j < 4; ++j) { const int n = (lane >> 2) + 16 * j; const LAS unsigned* s = scr + n * 17 + 4 * q4;
;             u32x4 o; o.x = s[0]; o.y = s[1]; o.z = s[2]; o.w = s[3];
;             __builtin_nontemporal_store(o, (u32x4*)((unsigned char*)t.WT + (size_t)(n0 - t.noff + n) * t.K + k0 + 16 * q4));
;             if (t.csum) {
;                 int cs = __builtin_amdgcn_sdot4((int)o.x, 0x01010101, 0, false); cs = __builtin_amdgcn_sdot4((int)o.y, 0x01010101, cs, false); cs = __builtin_amdgcn_sdot4((int)o.z, 0x01010101, cs, false); cs = __builtin_amdgcn_sdot4((int)o.w, 0x01010101, cs, false);
;                 cs += __shfl_xor(cs, 1); cs += __shfl_xor(cs, 2);
;                 if (q4 == 0) { atomicAdd(t.csum + n0 - t.noff + n, cs * 128); atomicAdd(t.csum + (1 + (k0 >> 10)) * DM + n0 - t.noff + n, cs * 128); }
;             } }
.LBB0_1010:
	v_add_u32_e32 v157, s23, v194
	v_mov_b64_e32 v[212:213], s[4:5]
	s_waitcnt lgkmcnt(0)
	v_add_u32_e32 v132, 0x440, v201
	v_add_u32_e32 v134, 0x448, v201
	v_mad_u64_u32 v[212:213], s[24:25], v157, s85, v[212:213]
	ds_read2_b32 v[132:133], v132 offset1:1
	ds_read2_b32 v[134:135], v134 offset1:1
	v_ashrrev_i32_e32 v203, 31, v157
	v_mov_b32_e32 v214, v213
	v_mad_u64_u32 v[214:215], s[24:25], v203, s85, v[214:215]
	v_mov_b32_e32 v213, v214
	v_lshl_add_u64 v[212:213], v[212:213], 0, s[0:1]
	v_lshl_add_u64 v[212:213], v[212:213], 0, v[154:155]
	s_waitcnt lgkmcnt(0)
	global_store_dwordx4 v[212:213], v[132:135], off sc1
.LBB0_1011:
	v_add_u32_e32 v157, s23, v195
	v_mov_b64_e32 v[212:213], s[4:5]
	s_waitcnt lgkmcnt(0)
	v_add_u32_e32 v132, 0x880, v201
	v_add_u32_e32 v134, 0x888, v201
	v_mad_u64_u32 v[212:213], s[24:25], v157, s85, v[212:213]
	ds_read2_b32 v[132:133], v132 offset1:1
	ds_read2_b32 v[134:135], v134 offset1:1
	v_ashrrev_i32_e32 v203, 31, v157
	v_mov_b32_e32 v214, v213
	v_mad_u64_u32 v[214:215], s[24:25], v203, s85, v[214:215]
	v_mov_b32_e32 v213, v214
	v_lshl_add_u64 v[212:213], v[212:213], 0, s[0:1]
	v_cndmask_b32_e64 v157, 0, 1, s[56:57]
	v_lshl_add_u64 v[212:213], v[212:213], 0, v[154:155]
	v_cmp_ne_u32_e64 s[54:55], 1, v157
	s_andn2_b64 vcc, exec, s[56:57]
	s_waitcnt lgkmcnt(0)
	global_store_dwordx4 v[212:213], v[132:135], off sc1
	s_cbranch_vccnz .LBB0_1026
	v_mov_b32_e32 v211, v131
	v_dot4c_i32_i8_e32 v211, 0x1010101, v132
	v_and_b32_e32 v132, 64, v204
	v_xor_b32_e32 v203, 1, v204
	v_add_u32_e32 v157, 64, v132
	v_dot4c_i32_i8_e32 v211, 0x1010101, v133
	v_cmp_lt_i32_e32 vcc, v203, v157
	v_dot4c_i32_i8_e32 v211, 0x1010101, v134
	v_dot4c_i32_i8_e32 v211, 0x1010101, v135
	v_cndmask_b32_e32 v132, v204, v203, vcc
	v_lshlrev_b32_e32 v132, 2, v132
	s_nop 0
	ds_bpermute_b32 v132, v132, v211
	s_waitcnt lgkmcnt(0)
	v_add_u32_e32 v132, v132, v211
	v_xor_b32_e32 v211, 2, v204
	v_cmp_lt_i32_e32 vcc, v211, v157
	s_nop 1
	v_cndmask_b32_e32 v133, v204, v211, vcc
	v_lshlrev_b32_e32 v133, 2, v133
	ds_bpermute_b32 v133, v133, v132
	s_and_saveexec_b64 s[56:57], s[52:53]
	s_cbranch_execz .LBB0_1014
	s_lshl_b64 s[24:25], s[40:41], 2
	s_add_u32 s34, s16, s24
	s_addc_u32 s35, s17, s25
	s_lshl_b64 s[30:31], s[80:81], 2
	s_sub_u32 s34, s34, s30
	s_subb_u32 s35, s35, s31
	v_lshlrev_b64 v[134:135], 2, v[152:153]
	v_lshl_add_u64 v[212:213], s[34:35], 0, v[134:135]
	s_lshl_b64 s[34:35], s[42:43], 2
	s_add_u32 s34, s16, s34
	s_addc_u32 s35, s17, s35
	s_add_u32 s24, s34, s24
	s_addc_u32 s25, s35, s25
	s_sub_u32 s24, s24, s30
	s_waitcnt lgkmcnt(0)
	v_add_lshl_u32 v214, v132, v133, 7
	s_subb_u32 s25, s25, s31
	global_atomic_add v[212:213], v214, off offset:128
	v_lshl_add_u64 v[132:133], s[24:25], 0, v[134:135]
	global_atomic_add v[132:133], v214, off offset:128
	v_readlane_b32 s34, v255, 27
	v_readlane_b32 s35, v255, 28
	v_readlane_b32 s35, v255, 37
.LBB0_1014:
	s_or_b64 exec, exec, s[56:57]
	v_add_u32_e32 v214, s23, v196
	v_mov_b64_e32 v[212:213], s[4:5]
	v_add_u32_e32 v132, 0xcc0, v201
	v_add_u32_e32 v134, 0xcc8, v201
	v_mad_u64_u32 v[212:213], s[24:25], v214, s85, v[212:213]
	s_waitcnt lgkmcnt(0)
	ds_read2_b32 v[132:133], v132 offset1:1
	ds_read2_b32 v[134:135], v134 offset1:1
	v_ashrrev_i32_e32 v215, 31, v214
	v_mov_b32_e32 v214, v213
	v_mad_u64_u32 v[214:215], s[24:25], v215, s85, v[214:215]
	v_mov_b32_e32 v213, v214
	v_lshl_add_u64 v[212:213], v[212:213], 0, s[0:1]
	v_lshl_add_u64 v[212:213], v[212:213], 0, v[154:155]
	s_and_b64 vcc, exec, s[54:55]
	s_waitcnt lgkmcnt(0)
	global_store_dwordx4 v[212:213], v[132:135], off sc1
	s_cbranch_vccnz .LBB0_1018
	v_mov_b32_e32 v212, v131
	v_dot4c_i32_i8_e32 v212, 0x1010101, v132
	v_dot4c_i32_i8_e32 v212, 0x1010101, v133
	v_cmp_lt_i32_e32 vcc, v203, v157
	v_dot4c_i32_i8_e32 v212, 0x1010101, v134
	v_dot4c_i32_i8_e32 v212, 0x1010101, v135
	v_cndmask_b32_e32 v132, v204, v203, vcc
	v_lshlrev_b32_e32 v132, 2, v132
	v_cmp_lt_i32_e32 vcc, v211, v157
	ds_bpermute_b32 v132, v132, v212
	s_waitcnt lgkmcnt(0)
	v_add_u32_e32 v132, v132, v212
	v_cndmask_b32_e32 v133, v204, v211, vcc
	v_lshlrev_b32_e32 v133, 2, v133
	ds_bpermute_b32 v133, v133, v132
	s_and_saveexec_b64 s[54:55], s[52:53]
	s_cbranch_execz .LBB0_1017
	s_lshl_b64 s[24:25], s[40:41], 2
	s_add_u32 s34, s16, s24
	s_addc_u32 s35, s17, s25
	s_lshl_b64 s[30:31], s[80:81], 2
	s_sub_u32 s34, s34, s30
	s_subb_u32 s35, s35, s31
	v_lshlrev_b64 v[134:135], 2, v[152:153]
	v_lshl_add_u64 v[212:213], s[34:35], 0, v[134:135]
	s_lshl_b64 s[34:35], s[42:43], 2
	s_add_u32 s34, s16, s34
	s_addc_u32 s35, s17, s35
	s_add_u32 s24, s34, s24
	s_addc_u32 s25, s35, s25
	s_sub_u32 s24, s24, s30
	s_waitcnt lgkmcnt(0)
	v_add_lshl_u32 v157, v132, v133, 7
	s_subb_u32 s25, s25, s31
	global_atomic_add v[212:213], v157, off offset:192
	v_lshl_add_u64 v[132:133], s[24:25], 0, v[134:135]
	global_atomic_add v[132:133], v157, off offset:192
	v_readlane_b32 s34, v255, 27
	v_readlane_b32 s35, v255, 28
	v_readlane_b32 s35, v255, 37

; #define LAS __attribute__((address_space(3)))
; __device__ __forceinline__ void titem_finish(const TItem& t, const f32x4 (&x)[16], const float (&sc)[16], LAS float* scr_f, int lane) {
;     ...
;         for (int j = 0; j < 4; ++j) { const int n = (lane >> 2) + 16 * j; const LAS unsigned* s = scr + n * 17 + 4 * q4;
;             u32x4 o; o.x = s[0]; o.y = s[1]; o.z = s[2]; o.w = s[3];
;             __builtin_nontemporal_store(o, (u32x4*)((unsigned char*)t.WT + (size_t)(n0 - t.noff + n) * t.K + k0 + 16 * q4));
.LBB0_1019:
	v_add_u32_e32 v157, s23, v196
	v_mov_b64_e32 v[212:213], s[4:5]
	v_add_u32_e32 v132, 0xcc0, v201
	v_add_u32_e32 v134, 0xcc8, v201
	v_mad_u64_u32 v[212:213], s[24:25], v157, s85, v[212:213]
	s_waitcnt lgkmcnt(0)
	ds_read2_b32 v[132:133], v132 offset1:1
	ds_read2_b32 v[134:135], v134 offset1:1
	v_ashrrev_i32_e32 v203, 31, v157
	v_mov_b32_e32 v214, v213
	v_mad_u64_u32 v[214:215], s[24:25], v203, s85, v[214:215]
	v_mov_b32_e32 v213, v214
	v_lshl_add_u64 v[212:213], v[212:213], 0, s[0:1]
	v_lshl_add_u64 v[212:213], v[212:213], 0, v[154:155]
	s_waitcnt lgkmcnt(0)
	global_store_dwordx4 v[212:213], v[132:135], off sc1

; __device__ __forceinline__ unsigned cvtpk(float lo, float hi) { f32x2 v = {lo, hi}; bf16x2_t b = __builtin_convertvector(v, bf16x2_t); return __builtin_bit_cast(unsigned, b); }
; __device__ __forceinline__ void titem_finish(const TItem& t, const f32x4 (&x)[16], const float (&sc)[16], LAS float* scr_f, int lane) {
;     ...
; #pragma unroll
;     for (int p = 0; p < 8; ++p)
; #pragma unroll
;         for (int e = 0; e < 4; ++e) scr[(4 * c + e) * 33 + 4 * p + r] = cvtpk(x[2 * p][e] * sc[2 * p], x[2 * p + 1][e] * sc[2 * p + 1]);
.LBB0_1021:
	s_waitcnt vmcnt(15)
	v_mov_b32_e32 v132, v2
	s_waitcnt vmcnt(14) lgkmcnt(0)
	v_mov_b32_e32 v133, v6
	v_pk_mul_f32 v[132:133], v[132:133], v[136:137]
	s_ashr_i32 s1, s0, 31
	v_cvt_pk_bf16_f32 v134, v132, v133
	v_mov_b32_e32 v132, v3
	v_mov_b32_e32 v133, v7
	v_pk_mul_f32 v[132:133], v[132:133], v[136:137]
	s_lshl_b64 s[0:1], s[0:1], 1
	v_cvt_pk_bf16_f32 v135, v132, v133
	v_mov_b32_e32 v132, v4
	v_mov_b32_e32 v133, v8
	v_pk_mul_f32 v[132:133], v[132:133], v[136:137]
	s_nop 0
	v_cvt_pk_bf16_f32 v157, v132, v133
	v_mov_b32_e32 v132, v5
	v_mov_b32_e32 v133, v9
	v_pk_mul_f32 v[132:133], v[132:133], v[136:137]
	s_nop 0
	v_cvt_pk_bf16_f32 v203, v132, v133
	s_waitcnt vmcnt(13)
	v_mov_b32_e32 v132, v10
	s_waitcnt vmcnt(12)
	v_mov_b32_e32 v133, v14
	v_pk_mul_f32 v[132:133], v[132:133], v[138:139]
	s_nop 0
	v_cvt_pk_bf16_f32 v132, v132, v133
	ds_write2_b32 v199, v134, v132 offset1:4
	v_mov_b32_e32 v132, v11
	v_mov_b32_e32 v133, v15
	v_pk_mul_f32 v[132:133], v[132:133], v[138:139]
	s_nop 0
	v_cvt_pk_bf16_f32 v132, v132, v133
	ds_write2_b32 v199, v135, v132 offset0:33 offset1:37
	v_mov_b32_e32 v132, v12
	v_mov_b32_e32 v133, v16
	v_pk_mul_f32 v[132:133], v[132:133], v[138:139]
	s_nop 0
	v_cvt_pk_bf16_f32 v132, v132, v133
	ds_write2_b32 v199, v157, v132 offset0:66 offset1:70
	v_mov_b32_e32 v132, v13
	v_mov_b32_e32 v133, v17
	v_pk_mul_f32 v[132:133], v[132:133], v[138:139]
	s_nop 0
	v_cvt_pk_bf16_f32 v132, v132, v133
	ds_write2_b32 v199, v203, v132 offset0:99 offset1:103
	s_waitcnt vmcnt(11)
	v_mov_b32_e32 v132, v18
	s_waitcnt vmcnt(10)
	v_mov_b32_e32 v133, v22
	v_pk_mul_f32 v[132:133], v[132:133], v[140:141]
	s_nop 0
	v_cvt_pk_bf16_f32 v134, v132, v133
	v_mov_b32_e32 v132, v19
	v_mov_b32_e32 v133, v23
	v_pk_mul_f32 v[132:133], v[132:133], v[140:141]
	s_nop 0
	v_cvt_pk_bf16_f32 v135, v132, v133
	v_mov_b32_e32 v132, v20
	v_mov_b32_e32 v133, v24
	v_pk_mul_f32 v[132:133], v[132:133], v[140:141]
	s_nop 0
	v_cvt_pk_bf16_f32 v157, v132, v133
	v_mov_b32_e32 v132, v21
	v_mov_b32_e32 v133, v25
	v_pk_mul_f32 v[132:133], v[132:133], v[140:141]
	s_nop 0
	v_cvt_pk_bf16_f32 v203, v132, v133
	s_waitcnt vmcnt(9)
	v_mov_b32_e32 v132, v26
	s_waitcnt vmcnt(8)
	v_mov_b32_e32 v133, v30
	v_pk_mul_f32 v[132:133], v[132:133], v[142:143]
	s_nop 0
	v_cvt_pk_bf16_f32 v132, v132, v133
	ds_write2_b32 v199, v134, v132 offset0:8 offset1:12
	v_mov_b32_e32 v132, v27
	v_mov_b32_e32 v133, v31
	v_pk_mul_f32 v[132:133], v[132:133], v[142:143]
	s_nop 0
	v_cvt_pk_bf16_f32 v132, v132, v133
	ds_write2_b32 v199, v135, v132 offset0:41 offset1:45
	v_mov_b32_e32 v132, v28
	v_mov_b32_e32 v133, v32
	v_pk_mul_f32 v[132:133], v[132:133], v[142:143]
	s_nop 0
	v_cvt_pk_bf16_f32 v132, v132, v133
	ds_write2_b32 v199, v157, v132 offset0:74 offset1:78
	v_mov_b32_e32 v132, v29
	v_mov_b32_e32 v133, v33
	v_pk_mul_f32 v[132:133], v[132:133], v[142:143]
	s_nop 0
	v_cvt_pk_bf16_f32 v132, v132, v133
	ds_write2_b32 v199, v203, v132 offset0:107 offset1:111
	s_waitcnt vmcnt(7)
	v_mov_b32_e32 v132, v34
	s_waitcnt vmcnt(6)
	v_mov_b32_e32 v133, v38
	v_pk_mul_f32 v[132:133], v[132:133], v[144:145]
	s_nop 0
	v_cvt_pk_bf16_f32 v134, v132, v133
	v_mov_b32_e32 v132, v35
	v_mov_b32_e32 v133, v39
	v_pk_mul_f32 v[132:133], v[132:133], v[144:145]
	s_nop 0
	v_cvt_pk_bf16_f32 v135, v132, v133
	v_mov_b32_e32 v132, v36
	v_mov_b32_e32 v133, v40
	v_pk_mul_f32 v[132:133], v[132:133], v[144:145]
	s_nop 0
	v_cvt_pk_bf16_f32 v157, v132, v133
	v_mov_b32_e32 v132, v37
	v_mov_b32_e32 v133, v41
	v_pk_mul_f32 v[132:133], v[132:133], v[144:145]
	s_nop 0
	v_cvt_pk_bf16_f32 v203, v132, v133
	s_waitcnt vmcnt(5)
	v_mov_b32_e32 v132, v42
	s_waitcnt vmcnt(4)
	v_mov_b32_e32 v133, v46
	v_pk_mul_f32 v[132:133], v[132:133], v[146:147]
	s_nop 0
	v_cvt_pk_bf16_f32 v132, v132, v133
	ds_write2_b32 v199, v134, v132 offset0:16 offset1:20
	v_mov_b32_e32 v132, v43
	v_mov_b32_e32 v133, v47
	v_pk_mul_f32 v[132:133], v[132:133], v[146:147]
	s_nop 0
	v_cvt_pk_bf16_f32 v132, v132, v133
	ds_write2_b32 v199, v135, v132 offset0:49 offset1:53
	v_mov_b32_e32 v132, v44
	v_mov_b32_e32 v133, v48
	v_pk_mul_f32 v[132:133], v[132:133], v[146:147]
	s_nop 0
	v_cvt_pk_bf16_f32 v132, v132, v133
	ds_write2_b32 v199, v157, v132 offset0:82 offset1:86
	v_mov_b32_e32 v132, v45
	v_mov_b32_e32 v133, v49
	v_pk_mul_f32 v[132:133], v[132:133], v[146:147]
	s_nop 0
	v_cvt_pk_bf16_f32 v132, v132, v133
	ds_write2_b32 v199, v203, v132 offset0:115 offset1:119
	s_waitcnt vmcnt(3)
	v_mov_b32_e32 v132, v50
	s_waitcnt vmcnt(2)
	v_mov_b32_e32 v133, v54
	v_pk_mul_f32 v[132:133], v[132:133], v[148:149]
	s_nop 0
	v_cvt_pk_bf16_f32 v134, v132, v133
	v_mov_b32_e32 v132, v51
	v_mov_b32_e32 v133, v55
	v_pk_mul_f32 v[132:133], v[132:133], v[148:149]
	s_nop 0
	v_cvt_pk_bf16_f32 v135, v132, v133
	v_mov_b32_e32 v132, v52
	v_mov_b32_e32 v133, v56
	v_pk_mul_f32 v[132:133], v[132:133], v[148:149]
	s_nop 0
	v_cvt_pk_bf16_f32 v157, v132, v133
	v_mov_b32_e32 v132, v53
	v_mov_b32_e32 v133, v57
	v_pk_mul_f32 v[132:133], v[132:133], v[148:149]
	s_nop 0
	v_cvt_pk_bf16_f32 v203, v132, v133
	s_waitcnt vmcnt(1)
	v_mov_b32_e32 v132, v58
	s_waitcnt vmcnt(0)
; #define LAS __attribute__((address_space(3)))
; __device__ __forceinline__ unsigned cvtpk(float lo, float hi) { f32x2 v = {lo, hi}; bf16x2_t b = __builtin_convertvector(v, bf16x2_t); return __builtin_bit_cast(unsigned, b); }
; #define LDS_WAIT() asm volatile("s_waitcnt lgkmcnt(0)" ::: "memory")
; __device__ __forceinline__ void titem_finish(const TItem& t, const f32x4 (&x)[16], const float (&sc)[16], LAS float* scr_f, int lane) {
;     ...
; #pragma unroll
;     for (int p = 0; p < 8; ++p)
; #pragma unroll
;         for (int e = 0; e < 4; ++e) scr[(4 * c + e) * 33 + 4 * p + r] = cvtpk(x[2 * p][e] * sc[2 * p], x[2 * p + 1][e] * sc[2 * p + 1]);
;     LDS_WAIT(); asm volatile("" ::: "memory");
;     const int q = lane & 7;
; #pragma unroll
;     for (int j = 0; j < 8; ++j) { const int n = (lane >> 3) + 8 * j; const LAS unsigned* s = scr + n * 33 + 4 * q;
;         u32x4 o; o.x = s[0]; o.y = s[1]; o.z = s[2]; o.w = s[3];
;         __builtin_nontemporal_store(o, (u32x4*)(t.WT + (size_t)(n0 + n) * t.K + k0 + 8 * q)); }
	v_mov_b32_e32 v133, v62
	v_pk_mul_f32 v[132:133], v[132:133], v[150:151]
	s_nop 0
	v_cvt_pk_bf16_f32 v132, v132, v133
	ds_write2_b32 v199, v134, v132 offset0:24 offset1:28
	v_mov_b32_e32 v132, v59
	v_mov_b32_e32 v133, v63
	v_pk_mul_f32 v[132:133], v[132:133], v[150:151]
	s_nop 0
	v_cvt_pk_bf16_f32 v132, v132, v133
	ds_write2_b32 v199, v135, v132 offset0:57 offset1:61
	v_mov_b32_e32 v132, v60
	v_mov_b32_e32 v133, v64
	v_pk_mul_f32 v[132:133], v[132:133], v[150:151]
	s_nop 0
	v_cvt_pk_bf16_f32 v132, v132, v133
	ds_write2_b32 v199, v157, v132 offset0:90 offset1:94
	v_mov_b32_e32 v132, v61
	v_mov_b32_e32 v133, v65
	v_pk_mul_f32 v[132:133], v[132:133], v[150:151]
	s_nop 0
	v_cvt_pk_bf16_f32 v132, v132, v133
	ds_write2_b32 v199, v203, v132 offset0:123 offset1:127
	v_add_u32_e32 v203, s40, v197
	s_waitcnt lgkmcnt(0)
	v_mad_u64_u32 v[212:213], s[24:25], v203, s85, 0
	v_ashrrev_i32_e32 v157, 31, v203
	v_mov_b32_e32 v214, v213
	ds_read2_b32 v[132:133], v200 offset1:1
	ds_read2_b32 v[134:135], v200 offset0:2 offset1:3
	v_mad_u64_u32 v[214:215], s[24:25], v157, s85, v[214:215]
	v_mov_b32_e32 v213, v214
	v_lshl_add_u64 v[212:213], v[212:213], 1, s[4:5]
	v_lshl_add_u64 v[212:213], v[212:213], 0, s[0:1]
	v_mov_b32_e32 v157, v131
	v_lshl_add_u64 v[212:213], v[212:213], 0, v[156:157]
	v_add_u32_e32 v211, 8, v203
	s_waitcnt lgkmcnt(0)
	global_store_dwordx4 v[212:213], v[132:135], off sc1
	v_mad_u64_u32 v[212:213], s[24:25], v211, s85, 0
	s_nop 0
	v_add_u32_e32 v132, 0x420, v200
	v_add_u32_e32 v134, 0x428, v200
	v_ashrrev_i32_e32 v215, 31, v211
	v_mov_b32_e32 v214, v213
	ds_read2_b32 v[132:133], v132 offset1:1
	ds_read2_b32 v[134:135], v134 offset1:1
	v_mad_u64_u32 v[214:215], s[24:25], v215, s85, v[214:215]
	v_mov_b32_e32 v213, v214
	v_lshl_add_u64 v[212:213], v[212:213], 1, s[4:5]
	v_lshl_add_u64 v[212:213], v[212:213], 0, s[0:1]
	v_lshl_add_u64 v[212:213], v[212:213], 0, v[156:157]
	v_add_u32_e32 v211, 16, v203
	s_waitcnt lgkmcnt(0)
	global_store_dwordx4 v[212:213], v[132:135], off sc1
	v_mad_u64_u32 v[212:213], s[24:25], v211, s85, 0
	s_nop 0
	v_add_u32_e32 v132, 0x840, v200
	v_add_u32_e32 v134, 0x848, v200
	v_ashrrev_i32_e32 v215, 31, v211
	v_mov_b32_e32 v214, v213
	ds_read2_b32 v[132:133], v132 offset1:1
	ds_read2_b32 v[134:135], v134 offset1:1
	v_mad_u64_u32 v[214:215], s[24:25], v215, s85, v[214:215]
	v_mov_b32_e32 v213, v214
	v_lshl_add_u64 v[212:213], v[212:213], 1, s[4:5]
	v_lshl_add_u64 v[212:213], v[212:213], 0, s[0:1]
	v_lshl_add_u64 v[212:213], v[212:213], 0, v[156:157]
	v_add_u32_e32 v211, 24, v203
	s_waitcnt lgkmcnt(0)
	global_store_dwordx4 v[212:213], v[132:135], off sc1
	v_mad_u64_u32 v[212:213], s[24:25], v211, s85, 0
	s_nop 0
	v_add_u32_e32 v132, 0xc60, v200
	v_add_u32_e32 v134, 0xc68, v200
	v_ashrrev_i32_e32 v215, 31, v211
	v_mov_b32_e32 v214, v213
	ds_read2_b32 v[132:133], v132 offset1:1
	ds_read2_b32 v[134:135], v134 offset1:1
	v_mad_u64_u32 v[214:215], s[24:25], v215, s85, v[214:215]
	v_mov_b32_e32 v213, v214
	v_lshl_add_u64 v[212:213], v[212:213], 1, s[4:5]
	v_lshl_add_u64 v[212:213], v[212:213], 0, s[0:1]
	v_lshl_add_u64 v[212:213], v[212:213], 0, v[156:157]
	v_add_u32_e32 v211, 32, v203
	s_waitcnt lgkmcnt(0)
	global_store_dwordx4 v[212:213], v[132:135], off sc1
	v_mad_u64_u32 v[212:213], s[24:25], v211, s85, 0
	s_nop 0
	v_add_u32_e32 v132, 0x1080, v200
	v_add_u32_e32 v134, 0x1088, v200
	v_ashrrev_i32_e32 v215, 31, v211
	v_mov_b32_e32 v214, v213
	ds_read2_b32 v[132:133], v132 offset1:1
	ds_read2_b32 v[134:135], v134 offset1:1
	v_mad_u64_u32 v[214:215], s[24:25], v215, s85, v[214:215]
	v_mov_b32_e32 v213, v214
	v_lshl_add_u64 v[212:213], v[212:213], 1, s[4:5]
	v_lshl_add_u64 v[212:213], v[212:213], 0, s[0:1]
	v_lshl_add_u64 v[212:213], v[212:213], 0, v[156:157]
	v_add_u32_e32 v211, 40, v203
	s_waitcnt lgkmcnt(0)
	global_store_dwordx4 v[212:213], v[132:135], off sc1
	v_mad_u64_u32 v[212:213], s[24:25], v211, s85, 0
	s_nop 0
	v_add_u32_e32 v132, 0x14a0, v200
	v_add_u32_e32 v134, 0x14a8, v200
	v_ashrrev_i32_e32 v215, 31, v211
	v_mov_b32_e32 v214, v213
	ds_read2_b32 v[132:133], v132 offset1:1
	ds_read2_b32 v[134:135], v134 offset1:1
	v_mad_u64_u32 v[214:215], s[24:25], v215, s85, v[214:215]
	v_mov_b32_e32 v213, v214
	v_lshl_add_u64 v[212:213], v[212:213], 1, s[4:5]
	v_lshl_add_u64 v[212:213], v[212:213], 0, s[0:1]
	v_lshl_add_u64 v[212:213], v[212:213], 0, v[156:157]
	v_add_u32_e32 v211, 48, v203
	s_waitcnt lgkmcnt(0)
	global_store_dwordx4 v[212:213], v[132:135], off sc1
	v_mad_u64_u32 v[212:213], s[24:25], v211, s85, 0
	s_nop 0
	v_add_u32_e32 v132, 0x18c0, v200
	v_add_u32_e32 v134, 0x18c8, v200
	v_ashrrev_i32_e32 v215, 31, v211
	v_mov_b32_e32 v214, v213
	ds_read2_b32 v[132:133], v132 offset1:1
	ds_read2_b32 v[134:135], v134 offset1:1
	v_mad_u64_u32 v[214:215], s[24:25], v215, s85, v[214:215]
	v_mov_b32_e32 v213, v214
	v_lshl_add_u64 v[212:213], v[212:213], 1, s[4:5]
	v_lshl_add_u64 v[212:213], v[212:213], 0, s[0:1]
	v_lshl_add_u64 v[212:213], v[212:213], 0, v[156:157]
	v_add_u32_e32 v203, 56, v203
	s_waitcnt lgkmcnt(0)
	global_store_dwordx4 v[212:213], v[132:135], off sc1
	v_mad_u64_u32 v[212:213], s[24:25], v203, s85, 0
	s_nop 0
	v_add_u32_e32 v132, 0x1ce0, v200
	v_add_u32_e32 v134, 0x1ce8, v200
	v_ashrrev_i32_e32 v211, 31, v203
	v_mov_b32_e32 v214, v213
	ds_read2_b32 v[132:133], v132 offset1:1
	ds_read2_b32 v[134:135], v134 offset1:1
	v_mad_u64_u32 v[214:215], s[24:25], v211, s85, v[214:215]
	v_mov_b32_e32 v213, v214
	v_lshl_add_u64 v[212:213], v[212:213], 1, s[4:5]
	v_lshl_add_u64 v[212:213], v[212:213], 0, s[0:1]
	v_lshl_add_u64 v[212:213], v[212:213], 0, v[156:157]
	s_waitcnt lgkmcnt(0)
	global_store_dwordx4 v[212:213], v[132:135], off sc1
	s_waitcnt lgkmcnt(0)

; __device__ __forceinline__ u32x4 pack8(f32x4 a, f32x4 b) { u32x4 w; w.x = cvtpk(a[0], a[1]); w.y = cvtpk(a[2], a[3]); w.z = cvtpk(b[0], b[1]); w.w = cvtpk(b[2], b[3]); return w; }
;     __device__ __forceinline__ void operator()(f32x4 (&acc)[2][2][4][2], const Unit& u, int wr, int wc, int fr, int fq) const {
;     ...
; #pragma unroll
;         for (int ai = 0; ai < 2; ++ai)
; #pragma unroll
;             for (int m = 0; m < 4; ++m) {
;                 const int row = row0 + ai * HALF + m * 16;
;                 float s = 0.f; u32x4 pk[2];
; #pragma unroll
;                 for (int bj = 0; bj < 2; ++bj) {
;                     const f32x4 v0 = acc[ai][bj][m][0], v1 = acc[ai][bj][m][1];
;                     s += (v0[0] * v0[0] + v0[1] * v0[1]) + (v0[2] * v0[2] + v0[3] * v0[3]) + (v1[0] * v1[0] + v1[1] * v1[1]) + (v1[2] * v1[2] + v1[3] * v1[3]);
;                     pk[bj] = pack8(v0, v1);
;                 }
;                 store_pair(Y + (size_t)(rowg + ai * HALF + m * 16) * DM + colw, DM, fr, fq, pk[0], pk[1]);
;                 s += __shfl_xor(s, 16); s += __shfl_xor(s, 32);
;                 if (fq == 0) ssy[(size_t)row * 32 + u.pn * 4 + wc] = s;
;             }
.LBB0_1156:
	s_mov_b32 s9, s81
	s_lshl_b32 s9, s44, 8
	s_add_i32 s58, s9, s29
	s_lshl_b32 s9, s38, 8
	s_or_b32 s40, s9, s34
	v_readlane_b32 s46, v249, 10
	s_mov_b64 s[42:43], -1
	s_cmp_gt_i32 s80, -1
	v_cvt_pk_bf16_f32 v160, v126, v127
	v_cvt_pk_bf16_f32 v161, v128, v129
	v_cvt_pk_bf16_f32 v162, v122, v123
	v_cvt_pk_bf16_f32 v163, v124, v125
	v_cvt_pk_bf16_f32 v156, v118, v119
	v_cvt_pk_bf16_f32 v157, v120, v121
	v_cvt_pk_bf16_f32 v158, v114, v115
	v_cvt_pk_bf16_f32 v159, v116, v117
	v_lshlrev_b32_e32 v130, 1, v142
	v_lshlrev_b32_e32 v152, 1, v144
	v_lshlrev_b32_e32 v150, 1, v140
	v_readlane_b32 s47, v249, 11
	v_readlane_b32 s84, v255, 29
	v_readlane_b32 s49, v255, 32
	s_cbranch_scc1 .LBB0_1175
	v_mul_f32_e32 v127, v127, v127
	v_mul_f32_e32 v119, v119, v119
	v_fmac_f32_e32 v127, v126, v126
	v_mul_f32_e32 v126, v129, v129
	v_fmac_f32_e32 v119, v118, v118
	v_mul_f32_e32 v118, v121, v121
	v_fmac_f32_e32 v126, v128, v128
	v_mul_f32_e32 v123, v123, v123
	v_fmac_f32_e32 v118, v120, v120
	v_mul_f32_e32 v115, v115, v115
	v_and_b32_e32 v153, 64, v204
	v_add_f32_e32 v126, v127, v126
	v_fmac_f32_e32 v123, v122, v122
	v_add_f32_e32 v118, v119, v118
	v_fmac_f32_e32 v115, v114, v114
	v_xor_b32_e32 v151, 16, v204
	v_add_u32_e32 v153, 64, v153
	v_add_f32_e32 v122, v126, v123
	v_mul_f32_e32 v123, v125, v125
	v_add_f32_e32 v114, v118, v115
	v_mul_f32_e32 v115, v117, v117
	s_ashr_i32 s59, s58, 31
	s_ashr_i32 s41, s40, 31
	v_cmp_lt_i32_e32 vcc, v151, v153
	v_fmac_f32_e32 v123, v124, v124
	v_fmac_f32_e32 v115, v116, v116
	s_lshl_b64 s[42:43], s[58:59], 12
	v_readlane_b32 s9, v249, 28
	v_cndmask_b32_e32 v151, v204, v151, vcc
	v_add_f32_e32 v122, v123, v122
	v_add_f32_e32 v114, v115, v114
	s_add_u32 s9, s9, s42
	v_readlane_b32 s17, v253, 5
	v_lshlrev_b32_e32 v165, 2, v151
	v_add_f32_e32 v124, v122, v114
	s_addc_u32 s17, s17, s43
	s_lshl_b64 s[62:63], s[40:41], 1
	v_xor_b32_e32 v151, 32, v204
	s_add_u32 s42, s9, s62
	ds_bpermute_b32 v125, v165, v124
	v_cmp_lt_i32_e32 vcc, v151, v153
	s_addc_u32 s43, s17, s63
	v_cndmask_b32_e64 v114, v160, v156, s[52:53]
	v_cndmask_b32_e32 v151, v204, v151, vcc
	v_cndmask_b32_e64 v115, v161, v157, s[52:53]
	v_cndmask_b32_e64 v116, v162, v158, s[52:53]
	v_cndmask_b32_e64 v117, v163, v159, s[52:53]
	v_mov_b32_e32 v118, v131
	v_mov_b32_e32 v119, v131
	v_mov_b32_e32 v120, v131
	v_mov_b32_e32 v121, v131
	v_lshl_add_u64 v[122:123], s[42:43], 0, v[130:131]
	v_mov_b32_e32 v153, v131
	v_lshlrev_b32_e32 v164, 2, v151
	v_mov_b32_dpp v118, v114 row_ror:8 row_mask:0xf bank_mask:0xf
	v_mov_b32_dpp v119, v115 row_ror:8 row_mask:0xf bank_mask:0xf
	v_mov_b32_dpp v120, v116 row_ror:8 row_mask:0xf bank_mask:0xf
	v_mov_b32_dpp v121, v117 row_ror:8 row_mask:0xf bank_mask:0xf
	v_lshl_add_u64 v[122:123], v[122:123], 0, v[152:153]
	v_mov_b32_e32 v151, v131
	v_cndmask_b32_e64 v114, v118, v160, s[52:53]
	v_cndmask_b32_e64 v115, v119, v161, s[52:53]
	v_cndmask_b32_e64 v116, v120, v162, s[52:53]
	v_cndmask_b32_e64 v117, v121, v163, s[52:53]
	v_lshl_add_u64 v[122:123], v[122:123], 0, v[150:151]
	global_store_dwordx4 v[122:123], v[114:117], off sc1
	v_or_b32_e32 v154, s58, v141
	v_cndmask_b32_e64 v118, v156, v118, s[52:53]
	s_waitcnt lgkmcnt(0)
	v_add_f32_e32 v114, v124, v125
	ds_bpermute_b32 v115, v164, v114
	v_add_co_u32_e32 v116, vcc, 0x8000, v122
	v_cndmask_b32_e64 v119, v157, v119, s[52:53]
	v_cndmask_b32_e64 v120, v158, v120, s[52:53]
	v_cndmask_b32_e64 v121, v159, v121, s[52:53]
	v_addc_co_u32_e32 v117, vcc, 0, v123, vcc
	v_ashrrev_i32_e32 v155, 31, v154
	global_store_dwordx4 v[116:117], v[118:121], off sc1
	s_and_saveexec_b64 s[42:43], s[54:55]
	s_cbranch_execz .LBB0_1159
	v_readlane_b32 s60, v253, 6
	s_waitcnt lgkmcnt(0)
	v_add_f32_e32 v116, v114, v115
	s_lshl_b32 s44, s38, 2
	v_lshlrev_b64 v[114:115], 7, v[154:155]
	v_readlane_b32 s61, v253, 7
	s_ashr_i32 s45, s44, 31
	s_nop 0
	v_lshl_add_u64 v[114:115], s[60:61], 0, v[114:115]
	v_lshl_add_u64 v[114:115], s[44:45], 2, v[114:115]
	s_lshl_b32 s44, s25, 2
	s_mov_b32 s45, s81
	v_lshl_add_u64 v[114:115], v[114:115], 0, s[44:45]
	global_store_dword v[114:115], v116, off
.LBB0_1159:
	s_or_b64 exec, exec, s[42:43]
	v_mul_f32_e32 v119, v103, v103
	v_mul_f32_e32 v120, v105, v105
	v_mul_f32_e32 v114, v111, v111
	s_waitcnt lgkmcnt(0)
	v_mul_f32_e32 v115, v113, v113
	v_fmac_f32_e32 v119, v102, v102
	v_fmac_f32_e32 v120, v104, v104
	v_fmac_f32_e32 v114, v110, v110
	v_fmac_f32_e32 v115, v112, v112
	v_add_f32_e32 v119, v119, v120
	v_mul_f32_e32 v120, v99, v99
	v_add_f32_e32 v114, v114, v115
	v_mul_f32_e32 v115, v107, v107
	v_fmac_f32_e32 v120, v98, v98
	v_fmac_f32_e32 v115, v106, v106
	v_add_f32_e32 v119, v119, v120
	v_mul_f32_e32 v120, v101, v101
	v_add_f32_e32 v114, v114, v115
	v_mul_f32_e32 v115, v109, v109
	v_fmac_f32_e32 v120, v100, v100
	v_fmac_f32_e32 v115, v108, v108
	v_cvt_pk_bf16_f32 v116, v112, v113
	v_add_f32_e32 v119, v120, v119
	v_cvt_pk_bf16_f32 v120, v104, v105
	s_or_b32 s42, s58, 16
	v_add_f32_e32 v114, v115, v114
	v_cvt_pk_bf16_f32 v117, v106, v107
	v_cvt_pk_bf16_f32 v121, v98, v99
	s_ashr_i32 s43, s42, 31
	v_cndmask_b32_e64 v123, v116, v120, s[52:53]
	v_mov_b32_e32 v128, v131
	v_cvt_pk_bf16_f32 v115, v110, v111
	v_cvt_pk_bf16_f32 v118, v108, v109
	v_add_f32_e32 v124, v114, v119
	v_cvt_pk_bf16_f32 v119, v102, v103
	v_cvt_pk_bf16_f32 v122, v100, v101
	s_lshl_b64 s[42:43], s[42:43], 12
	v_readlane_b32 s9, v249, 28
	v_cndmask_b32_e64 v125, v117, v121, s[52:53]
	v_mov_b32_dpp v128, v123 row_ror:8 row_mask:0xf bank_mask:0xf
	v_mov_b32_e32 v123, v131
	s_add_u32 s9, s9, s42
	v_readlane_b32 s17, v253, 5
	v_cndmask_b32_e64 v114, v115, v119, s[52:53]
	v_cndmask_b32_e64 v126, v118, v122, s[52:53]
	v_mov_b32_e32 v127, v131
	v_mov_b32_dpp v123, v125 row_ror:8 row_mask:0xf bank_mask:0xf
	v_mov_b32_e32 v125, v131
	s_addc_u32 s17, s17, s43
	v_mov_b32_dpp v127, v114 row_ror:8 row_mask:0xf bank_mask:0xf
	v_mov_b32_dpp v125, v126 row_ror:8 row_mask:0xf bank_mask:0xf
	s_add_u32 s42, s9, s62
	v_cndmask_b32_e64 v114, v127, v115, s[52:53]
	v_cndmask_b32_e64 v115, v128, v116, s[52:53]
	v_cndmask_b32_e64 v116, v123, v117, s[52:53]
	v_cndmask_b32_e64 v117, v125, v118, s[52:53]
	v_cndmask_b32_e64 v118, v119, v127, s[52:53]
	v_cndmask_b32_e64 v119, v120, v128, s[52:53]
	v_cndmask_b32_e64 v120, v121, v123, s[52:53]
	v_cndmask_b32_e64 v121, v122, v125, s[52:53]
	ds_bpermute_b32 v125, v165, v124
	s_addc_u32 s43, s17, s63
	v_lshl_add_u64 v[122:123], s[42:43], 0, v[130:131]
	v_lshl_add_u64 v[122:123], v[122:123], 0, v[152:153]
	v_lshl_add_u64 v[122:123], v[122:123], 0, v[150:151]
	global_store_dwordx4 v[122:123], v[114:117], off sc1
	s_waitcnt lgkmcnt(0)
	s_nop 0
	v_add_f32_e32 v114, v124, v125
	ds_bpermute_b32 v115, v164, v114
	v_add_co_u32_e32 v116, vcc, 0x8000, v122
	s_nop 1
	v_addc_co_u32_e32 v117, vcc, 0, v123, vcc
	global_store_dwordx4 v[116:117], v[118:121], off sc1
	s_and_saveexec_b64 s[42:43], s[54:55]
	s_cbranch_execz .LBB0_1161
; __device__ __forceinline__ u32x4 pack8(f32x4 a, f32x4 b) { u32x4 w; w.x = cvtpk(a[0], a[1]); w.y = cvtpk(a[2], a[3]); w.z = cvtpk(b[0], b[1]); w.w = cvtpk(b[2], b[3]); return w; }
;     __device__ __forceinline__ void operator()(f32x4 (&acc)[2][2][4][2], const Unit& u, int wr, int wc, int fr, int fq) const {
;     ...
; #pragma unroll
;         for (int ai = 0; ai < 2; ++ai)
; #pragma unroll
;             for (int m = 0; m < 4; ++m) {
;                 const int row = row0 + ai * HALF + m * 16;
;                 float s = 0.f; u32x4 pk[2];
; #pragma unroll
;                 for (int bj = 0; bj < 2; ++bj) {
;                     const f32x4 v0 = acc[ai][bj][m][0], v1 = acc[ai][bj][m][1];
;                     s += (v0[0] * v0[0] + v0[1] * v0[1]) + (v0[2] * v0[2] + v0[3] * v0[3]) + (v1[0] * v1[0] + v1[1] * v1[1]) + (v1[2] * v1[2] + v1[3] * v1[3]);
;                     pk[bj] = pack8(v0, v1);
;                 }
;                 store_pair(Y + (size_t)(rowg + ai * HALF + m * 16) * DM + colw, DM, fr, fq, pk[0], pk[1]);
;                 s += __shfl_xor(s, 16); s += __shfl_xor(s, 32);
;                 if (fq == 0) ssy[(size_t)row * 32 + u.pn * 4 + wc] = s;
;             }
	v_or_b32_e32 v116, 16, v154
	v_ashrrev_i32_e32 v117, 31, v116
	v_readlane_b32 s60, v253, 6
	s_waitcnt lgkmcnt(0)
	v_add_f32_e32 v118, v114, v115
	s_lshl_b32 s44, s38, 2
	v_lshlrev_b64 v[114:115], 7, v[116:117]
	v_readlane_b32 s61, v253, 7
	s_ashr_i32 s45, s44, 31
	s_nop 0
	v_lshl_add_u64 v[114:115], s[60:61], 0, v[114:115]
	v_lshl_add_u64 v[114:115], s[44:45], 2, v[114:115]
	s_lshl_b32 s44, s25, 2
	s_mov_b32 s45, s81
	v_lshl_add_u64 v[114:115], v[114:115], 0, s[44:45]
	global_store_dword v[114:115], v118, off
.LBB0_1161:
	s_or_b64 exec, exec, s[42:43]
	v_mul_f32_e32 v119, v87, v87
	v_mul_f32_e32 v120, v89, v89
	v_mul_f32_e32 v114, v95, v95
	s_waitcnt lgkmcnt(0)
	v_mul_f32_e32 v115, v97, v97
	v_fmac_f32_e32 v119, v86, v86
	v_fmac_f32_e32 v120, v88, v88
	v_fmac_f32_e32 v114, v94, v94
	v_fmac_f32_e32 v115, v96, v96
	v_add_f32_e32 v119, v119, v120
	v_mul_f32_e32 v120, v83, v83
	v_add_f32_e32 v114, v114, v115
	v_mul_f32_e32 v115, v91, v91
	v_fmac_f32_e32 v120, v82, v82
	v_fmac_f32_e32 v115, v90, v90
	v_add_f32_e32 v119, v119, v120
	v_mul_f32_e32 v120, v85, v85
	s_or_b32 s42, s58, 32
	v_add_f32_e32 v114, v114, v115
	v_mul_f32_e32 v115, v93, v93
	v_fmac_f32_e32 v120, v84, v84
	s_ashr_i32 s43, s42, 31
	v_fmac_f32_e32 v115, v92, v92
	v_cvt_pk_bf16_f32 v116, v96, v97
	v_add_f32_e32 v119, v120, v119
	v_cvt_pk_bf16_f32 v120, v88, v89
	s_lshl_b64 s[42:43], s[42:43], 12
	v_readlane_b32 s9, v249, 28
	v_add_f32_e32 v114, v115, v114
	v_cvt_pk_bf16_f32 v117, v90, v91
	v_cvt_pk_bf16_f32 v121, v82, v83
	s_add_u32 s9, s9, s42
	v_readlane_b32 s17, v253, 5
	v_cndmask_b32_e64 v123, v116, v120, s[52:53]
	v_mov_b32_e32 v128, v131
	v_cvt_pk_bf16_f32 v115, v94, v95
	v_cvt_pk_bf16_f32 v118, v92, v93
	v_add_f32_e32 v124, v114, v119
	v_cvt_pk_bf16_f32 v119, v86, v87
	v_cvt_pk_bf16_f32 v122, v84, v85
	s_addc_u32 s17, s17, s43
	v_cndmask_b32_e64 v125, v117, v121, s[52:53]
	v_mov_b32_dpp v128, v123 row_ror:8 row_mask:0xf bank_mask:0xf
	v_mov_b32_e32 v123, v131
	s_add_u32 s42, s9, s62
	v_cndmask_b32_e64 v114, v115, v119, s[52:53]
	v_cndmask_b32_e64 v126, v118, v122, s[52:53]
	v_mov_b32_e32 v127, v131
	v_mov_b32_dpp v123, v125 row_ror:8 row_mask:0xf bank_mask:0xf
	v_mov_b32_e32 v125, v131
	s_addc_u32 s43, s17, s63
	v_mov_b32_dpp v127, v114 row_ror:8 row_mask:0xf bank_mask:0xf
	v_mov_b32_dpp v125, v126 row_ror:8 row_mask:0xf bank_mask:0xf
	v_cndmask_b32_e64 v114, v127, v115, s[52:53]
	v_cndmask_b32_e64 v115, v128, v116, s[52:53]
	v_cndmask_b32_e64 v116, v123, v117, s[52:53]
	v_cndmask_b32_e64 v117, v125, v118, s[52:53]
	v_cndmask_b32_e64 v118, v119, v127, s[52:53]
	v_cndmask_b32_e64 v119, v120, v128, s[52:53]
	v_cndmask_b32_e64 v120, v121, v123, s[52:53]
	v_cndmask_b32_e64 v121, v122, v125, s[52:53]
	v_lshl_add_u64 v[122:123], s[42:43], 0, v[130:131]
	v_mov_b32_e32 v153, v131
	v_lshl_add_u64 v[122:123], v[122:123], 0, v[152:153]
	v_mov_b32_e32 v151, v131
	v_lshl_add_u64 v[122:123], v[122:123], 0, v[150:151]
	global_store_dwordx4 v[122:123], v[114:117], off sc1
	s_nop 1
	v_add_co_u32_e32 v114, vcc, 0x8000, v122
	s_nop 1
	v_addc_co_u32_e32 v115, vcc, 0, v123, vcc
	global_store_dwordx4 v[114:115], v[118:121], off sc1
	ds_bpermute_b32 v114, v165, v124
	s_waitcnt lgkmcnt(0)
	v_add_f32_e32 v114, v124, v114
	ds_bpermute_b32 v115, v164, v114
	s_and_saveexec_b64 s[42:43], s[54:55]
	s_cbranch_execz .LBB0_1163
	v_or_b32_e32 v116, 32, v154
	v_ashrrev_i32_e32 v117, 31, v116
	v_readlane_b32 s60, v253, 6
	s_waitcnt lgkmcnt(0)
	v_add_f32_e32 v118, v114, v115
	s_lshl_b32 s44, s38, 2
	v_lshlrev_b64 v[114:115], 7, v[116:117]
	v_readlane_b32 s61, v253, 7
	s_ashr_i32 s45, s44, 31
	s_nop 0
	v_lshl_add_u64 v[114:115], s[60:61], 0, v[114:115]
	v_lshl_add_u64 v[114:115], s[44:45], 2, v[114:115]
	s_lshl_b32 s44, s25, 2
	s_mov_b32 s45, s81
	v_lshl_add_u64 v[114:115], v[114:115], 0, s[44:45]
	global_store_dword v[114:115], v118, off
.LBB0_1163:
	s_or_b64 exec, exec, s[42:43]
	v_mul_f32_e32 v119, v71, v71
	v_mul_f32_e32 v120, v73, v73
	v_mul_f32_e32 v114, v79, v79
	s_waitcnt lgkmcnt(0)
	v_mul_f32_e32 v115, v81, v81
	v_fmac_f32_e32 v119, v70, v70
	v_fmac_f32_e32 v120, v72, v72
	v_fmac_f32_e32 v114, v78, v78
	v_fmac_f32_e32 v115, v80, v80
	v_add_f32_e32 v119, v119, v120
	v_mul_f32_e32 v120, v67, v67
	v_add_f32_e32 v114, v114, v115
	v_mul_f32_e32 v115, v75, v75
	v_fmac_f32_e32 v120, v66, v66
	v_fmac_f32_e32 v115, v74, v74
	v_add_f32_e32 v119, v119, v120
	v_mul_f32_e32 v120, v69, v69
	v_add_f32_e32 v114, v114, v115
	v_mul_f32_e32 v115, v77, v77
	v_fmac_f32_e32 v120, v68, v68
	v_fmac_f32_e32 v115, v76, v76
	v_cvt_pk_bf16_f32 v116, v80, v81
	v_add_f32_e32 v119, v120, v119
	v_cvt_pk_bf16_f32 v120, v72, v73
	s_or_b32 s42, s58, 48
	v_add_f32_e32 v114, v115, v114
	v_cvt_pk_bf16_f32 v117, v74, v75
	v_cvt_pk_bf16_f32 v121, v66, v67
	s_ashr_i32 s43, s42, 31
	v_cndmask_b32_e64 v123, v116, v120, s[52:53]
	v_mov_b32_e32 v128, v131
	v_cvt_pk_bf16_f32 v115, v78, v79
	v_cvt_pk_bf16_f32 v118, v76, v77
	v_add_f32_e32 v124, v114, v119
	v_cvt_pk_bf16_f32 v119, v70, v71
	v_cvt_pk_bf16_f32 v122, v68, v69
	s_lshl_b64 s[42:43], s[42:43], 12
	v_readlane_b32 s9, v249, 28
	v_cndmask_b32_e64 v125, v117, v121, s[52:53]
	v_mov_b32_dpp v128, v123 row_ror:8 row_mask:0xf bank_mask:0xf
	v_mov_b32_e32 v123, v131
	s_add_u32 s9, s9, s42
	v_readlane_b32 s17, v253, 5
	v_cndmask_b32_e64 v114, v115, v119, s[52:53]
	v_cndmask_b32_e64 v126, v118, v122, s[52:53]
	v_mov_b32_e32 v127, v131
	v_mov_b32_dpp v123, v125 row_ror:8 row_mask:0xf bank_mask:0xf
	v_mov_b32_e32 v125, v131
	s_addc_u32 s17, s17, s43
	v_mov_b32_dpp v127, v114 row_ror:8 row_mask:0xf bank_mask:0xf
	v_mov_b32_dpp v125, v126 row_ror:8 row_mask:0xf bank_mask:0xf
	s_add_u32 s42, s9, s62
	v_cndmask_b32_e64 v114, v127, v115, s[52:53]
	v_cndmask_b32_e64 v115, v128, v116, s[52:53]
	v_cndmask_b32_e64 v116, v123, v117, s[52:53]
	v_cndmask_b32_e64 v117, v125, v118, s[52:53]
	v_cndmask_b32_e64 v118, v119, v127, s[52:53]
	v_cndmask_b32_e64 v119, v120, v128, s[52:53]
	v_cndmask_b32_e64 v120, v121, v123, s[52:53]
	v_cndmask_b32_e64 v121, v122, v125, s[52:53]
	ds_bpermute_b32 v125, v165, v124
	s_addc_u32 s43, s17, s63
	v_lshl_add_u64 v[122:123], s[42:43], 0, v[130:131]
	v_lshl_add_u64 v[122:123], v[122:123], 0, v[152:153]
	v_lshl_add_u64 v[122:123], v[122:123], 0, v[150:151]
	global_store_dwordx4 v[122:123], v[114:117], off sc1
	s_waitcnt lgkmcnt(0)
	s_nop 0
	v_add_f32_e32 v114, v124, v125
	ds_bpermute_b32 v115, v164, v114
	v_add_co_u32_e32 v116, vcc, 0x8000, v122
	s_nop 1
	v_addc_co_u32_e32 v117, vcc, 0, v123, vcc
	global_store_dwordx4 v[116:117], v[118:121], off sc1
	s_and_saveexec_b64 s[42:43], s[54:55]
	s_cbranch_execz .LBB0_1165
; __device__ __forceinline__ u32x4 pack8(f32x4 a, f32x4 b) { u32x4 w; w.x = cvtpk(a[0], a[1]); w.y = cvtpk(a[2], a[3]); w.z = cvtpk(b[0], b[1]); w.w = cvtpk(b[2], b[3]); return w; }
;     __device__ __forceinline__ void operator()(f32x4 (&acc)[2][2][4][2], const Unit& u, int wr, int wc, int fr, int fq) const {
;     ...
; #pragma unroll
;         for (int ai = 0; ai < 2; ++ai)
; #pragma unroll
;             for (int m = 0; m < 4; ++m) {
;                 const int row = row0 + ai * HALF + m * 16;
;                 float s = 0.f; u32x4 pk[2];
; #pragma unroll
;                 for (int bj = 0; bj < 2; ++bj) {
;                     const f32x4 v0 = acc[ai][bj][m][0], v1 = acc[ai][bj][m][1];
;                     s += (v0[0] * v0[0] + v0[1] * v0[1]) + (v0[2] * v0[2] + v0[3] * v0[3]) + (v1[0] * v1[0] + v1[1] * v1[1]) + (v1[2] * v1[2] + v1[3] * v1[3]);
;                     pk[bj] = pack8(v0, v1);
;                 }
;                 store_pair(Y + (size_t)(rowg + ai * HALF + m * 16) * DM + colw, DM, fr, fq, pk[0], pk[1]);
;                 s += __shfl_xor(s, 16); s += __shfl_xor(s, 32);
;                 if (fq == 0) ssy[(size_t)row * 32 + u.pn * 4 + wc] = s;
;             }
	v_or_b32_e32 v116, 48, v154
	v_ashrrev_i32_e32 v117, 31, v116
	v_readlane_b32 s60, v253, 6
	s_waitcnt lgkmcnt(0)
	v_add_f32_e32 v118, v114, v115
	s_lshl_b32 s44, s38, 2
	v_lshlrev_b64 v[114:115], 7, v[116:117]
	v_readlane_b32 s61, v253, 7
	s_ashr_i32 s45, s44, 31
	s_nop 0
	v_lshl_add_u64 v[114:115], s[60:61], 0, v[114:115]
	v_lshl_add_u64 v[114:115], s[44:45], 2, v[114:115]
	s_lshl_b32 s44, s25, 2
	s_mov_b32 s45, s81
	v_lshl_add_u64 v[114:115], v[114:115], 0, s[44:45]
	global_store_dword v[114:115], v118, off
.LBB0_1165:
	s_or_b64 exec, exec, s[42:43]
	v_mul_f32_e32 v119, v55, v55
	v_mul_f32_e32 v120, v57, v57
	v_mul_f32_e32 v114, v63, v63
	s_waitcnt lgkmcnt(0)
	v_mul_f32_e32 v115, v65, v65
	v_fmac_f32_e32 v119, v54, v54
	v_fmac_f32_e32 v120, v56, v56
	v_fmac_f32_e32 v114, v62, v62
	v_fmac_f32_e32 v115, v64, v64
	v_add_f32_e32 v119, v119, v120
	v_mul_f32_e32 v120, v51, v51
	v_add_f32_e32 v114, v114, v115
	v_mul_f32_e32 v115, v59, v59
	v_fmac_f32_e32 v120, v50, v50
	v_fmac_f32_e32 v115, v58, v58
	v_add_f32_e32 v119, v119, v120
	v_mul_f32_e32 v120, v53, v53
	v_add_f32_e32 v114, v114, v115
	v_mul_f32_e32 v115, v61, v61
	v_fmac_f32_e32 v120, v52, v52
	v_fmac_f32_e32 v115, v60, v60
	v_cvt_pk_bf16_f32 v116, v64, v65
	v_add_f32_e32 v119, v120, v119
	v_cvt_pk_bf16_f32 v120, v56, v57
	s_lshl_b64 s[42:43], s[58:59], 12
	v_readlane_b32 s9, v249, 28
	v_add_f32_e32 v114, v115, v114
	v_cvt_pk_bf16_f32 v117, v58, v59
	v_cvt_pk_bf16_f32 v121, v50, v51
	s_add_u32 s9, s9, s42
	v_readlane_b32 s17, v253, 5
	v_cndmask_b32_e64 v123, v116, v120, s[52:53]
	v_mov_b32_e32 v128, v131
	v_cvt_pk_bf16_f32 v115, v62, v63
	v_cvt_pk_bf16_f32 v118, v60, v61
	v_add_f32_e32 v126, v114, v119
	v_cvt_pk_bf16_f32 v119, v54, v55
	v_cvt_pk_bf16_f32 v122, v52, v53
	s_addc_u32 s17, s17, s43
	v_cndmask_b32_e64 v124, v117, v121, s[52:53]
	v_mov_b32_dpp v128, v123 row_ror:8 row_mask:0xf bank_mask:0xf
	v_mov_b32_e32 v123, v131
	s_add_u32 s44, s9, s62
	v_cndmask_b32_e64 v114, v115, v119, s[52:53]
	v_cndmask_b32_e64 v125, v118, v122, s[52:53]
	v_mov_b32_e32 v127, v131
	v_mov_b32_dpp v123, v124 row_ror:8 row_mask:0xf bank_mask:0xf
	v_mov_b32_e32 v124, v131
	s_addc_u32 s45, s17, s63
	v_mov_b32_dpp v127, v114 row_ror:8 row_mask:0xf bank_mask:0xf
	v_mov_b32_dpp v124, v125 row_ror:8 row_mask:0xf bank_mask:0xf
	v_cndmask_b32_e64 v114, v127, v115, s[52:53]
	v_cndmask_b32_e64 v115, v128, v116, s[52:53]
	v_cndmask_b32_e64 v116, v123, v117, s[52:53]
	v_cndmask_b32_e64 v117, v124, v118, s[52:53]
	v_cndmask_b32_e64 v118, v119, v127, s[52:53]
	v_cndmask_b32_e64 v119, v120, v128, s[52:53]
	v_cndmask_b32_e64 v120, v121, v123, s[52:53]
	v_cndmask_b32_e64 v121, v122, v124, s[52:53]
	v_lshl_add_u64 v[122:123], s[44:45], 0, v[130:131]
	v_mov_b32_e32 v153, v131
	v_lshl_add_u64 v[122:123], v[122:123], 0, v[152:153]
	v_mov_b32_e32 v151, v131
	v_lshl_add_u64 v[122:123], v[122:123], 0, v[150:151]
	s_mov_b32 s9, 0x80000
	v_add_co_u32_e32 v124, vcc, s9, v122
	s_nop 1
	v_addc_co_u32_e32 v125, vcc, 0, v123, vcc
	global_store_dwordx4 v[124:125], v[114:117], off sc1
	s_nop 1
	v_add_co_u32_e32 v114, vcc, 0x88000, v122
	s_nop 1
	v_addc_co_u32_e32 v115, vcc, 0, v123, vcc
	global_store_dwordx4 v[114:115], v[118:121], off sc1
	ds_bpermute_b32 v114, v165, v126
	s_waitcnt lgkmcnt(0)
	v_add_f32_e32 v114, v126, v114
	ds_bpermute_b32 v115, v164, v114
	s_and_saveexec_b64 s[82:83], s[54:55]
	s_cbranch_execz .LBB0_1167
	v_readlane_b32 s60, v253, 6
	s_waitcnt lgkmcnt(0)
	v_add_f32_e32 v116, v114, v115
	v_lshlrev_b64 v[114:115], 7, v[154:155]
	s_lshl_b32 s44, s38, 2
	v_readlane_b32 s61, v253, 7
	s_ashr_i32 s45, s44, 31
	s_nop 0
	v_lshl_add_u64 v[114:115], s[60:61], 0, v[114:115]
	v_lshl_add_u64 v[114:115], s[44:45], 2, v[114:115]
	s_lshl_b32 s44, s25, 2
	s_mov_b32 s45, s81
	v_lshl_add_u64 v[114:115], v[114:115], 0, s[44:45]
	v_add_co_u32_e32 v114, vcc, 0x4000, v114
	s_nop 1
	v_addc_co_u32_e32 v115, vcc, 0, v115, vcc
	global_store_dword v[114:115], v116, off
.LBB0_1167:
	s_or_b64 exec, exec, s[82:83]
	v_mul_f32_e32 v119, v39, v39
	v_mul_f32_e32 v120, v41, v41
	v_mul_f32_e32 v114, v47, v47
	s_waitcnt lgkmcnt(0)
	v_mul_f32_e32 v115, v49, v49
	v_fmac_f32_e32 v119, v38, v38
	v_fmac_f32_e32 v120, v40, v40
	v_fmac_f32_e32 v114, v46, v46
	v_fmac_f32_e32 v115, v48, v48
	v_add_f32_e32 v119, v119, v120
	v_mul_f32_e32 v120, v35, v35
	v_add_f32_e32 v114, v114, v115
	v_mul_f32_e32 v115, v43, v43
	v_fmac_f32_e32 v120, v34, v34
	v_fmac_f32_e32 v115, v42, v42
	v_add_f32_e32 v119, v119, v120
	v_mul_f32_e32 v120, v37, v37
	v_add_f32_e32 v114, v114, v115
	v_mul_f32_e32 v115, v45, v45
	v_fmac_f32_e32 v120, v36, v36
	v_fmac_f32_e32 v115, v44, v44
	v_cvt_pk_bf16_f32 v116, v48, v49
	v_add_f32_e32 v119, v120, v119
	v_cvt_pk_bf16_f32 v120, v40, v41
	v_readlane_b32 s9, v249, 28
	v_add_f32_e32 v114, v115, v114
	v_cvt_pk_bf16_f32 v117, v42, v43
	v_cvt_pk_bf16_f32 v121, v34, v35
	s_add_u32 s9, s9, s42
	v_readlane_b32 s17, v253, 5
	v_cndmask_b32_e64 v123, v116, v120, s[52:53]
	v_mov_b32_e32 v128, v131
	v_cvt_pk_bf16_f32 v115, v46, v47
	v_cvt_pk_bf16_f32 v118, v44, v45
	v_add_f32_e32 v126, v114, v119
	v_cvt_pk_bf16_f32 v119, v38, v39
	v_cvt_pk_bf16_f32 v122, v36, v37
	s_addc_u32 s17, s17, s43
	v_cndmask_b32_e64 v124, v117, v121, s[52:53]
	v_mov_b32_dpp v128, v123 row_ror:8 row_mask:0xf bank_mask:0xf
	v_mov_b32_e32 v123, v131
	s_add_u32 s42, s9, s62
	v_cndmask_b32_e64 v114, v115, v119, s[52:53]
	v_cndmask_b32_e64 v125, v118, v122, s[52:53]
	v_mov_b32_e32 v127, v131
	v_mov_b32_dpp v123, v124 row_ror:8 row_mask:0xf bank_mask:0xf
	v_mov_b32_e32 v124, v131
	s_addc_u32 s43, s17, s63
	v_mov_b32_dpp v127, v114 row_ror:8 row_mask:0xf bank_mask:0xf
	v_mov_b32_dpp v124, v125 row_ror:8 row_mask:0xf bank_mask:0xf
	v_cndmask_b32_e64 v114, v127, v115, s[52:53]
	v_cndmask_b32_e64 v115, v128, v116, s[52:53]
	v_cndmask_b32_e64 v116, v123, v117, s[52:53]
	v_cndmask_b32_e64 v117, v124, v118, s[52:53]
	v_cndmask_b32_e64 v118, v119, v127, s[52:53]
	v_cndmask_b32_e64 v119, v120, v128, s[52:53]
	v_cndmask_b32_e64 v120, v121, v123, s[52:53]
	v_cndmask_b32_e64 v121, v122, v124, s[52:53]
	v_lshl_add_u64 v[122:123], s[42:43], 0, v[130:131]
	ds_bpermute_b32 v127, v165, v126
	v_lshl_add_u64 v[122:123], v[122:123], 0, v[152:153]
	v_lshl_add_u64 v[122:123], v[122:123], 0, v[150:151]
	s_mov_b32 s9, 0x90000
	v_add_co_u32_e32 v124, vcc, s9, v122
	s_nop 1
	v_addc_co_u32_e32 v125, vcc, 0, v123, vcc
	global_store_dwordx4 v[124:125], v[114:117], off sc1
	s_waitcnt lgkmcnt(0)
	s_nop 0
	v_add_f32_e32 v114, v126, v127
	ds_bpermute_b32 v115, v164, v114
	v_add_co_u32_e32 v116, vcc, 0x98000, v122
	s_nop 1
	v_addc_co_u32_e32 v117, vcc, 0, v123, vcc
	global_store_dwordx4 v[116:117], v[118:121], off sc1
	s_and_saveexec_b64 s[42:43], s[54:55]
	s_cbranch_execz .LBB0_1169
; __device__ __forceinline__ u32x4 pack8(f32x4 a, f32x4 b) { u32x4 w; w.x = cvtpk(a[0], a[1]); w.y = cvtpk(a[2], a[3]); w.z = cvtpk(b[0], b[1]); w.w = cvtpk(b[2], b[3]); return w; }
;     __device__ __forceinline__ void operator()(f32x4 (&acc)[2][2][4][2], const Unit& u, int wr, int wc, int fr, int fq) const {
;     ...
; #pragma unroll
;         for (int ai = 0; ai < 2; ++ai)
; #pragma unroll
;             for (int m = 0; m < 4; ++m) {
;                 const int row = row0 + ai * HALF + m * 16;
;                 float s = 0.f; u32x4 pk[2];
; #pragma unroll
;                 for (int bj = 0; bj < 2; ++bj) {
;                     const f32x4 v0 = acc[ai][bj][m][0], v1 = acc[ai][bj][m][1];
;                     s += (v0[0] * v0[0] + v0[1] * v0[1]) + (v0[2] * v0[2] + v0[3] * v0[3]) + (v1[0] * v1[0] + v1[1] * v1[1]) + (v1[2] * v1[2] + v1[3] * v1[3]);
;                     pk[bj] = pack8(v0, v1);
;                 }
;                 store_pair(Y + (size_t)(rowg + ai * HALF + m * 16) * DM + colw, DM, fr, fq, pk[0], pk[1]);
;                 s += __shfl_xor(s, 16); s += __shfl_xor(s, 32);
;                 if (fq == 0) ssy[(size_t)row * 32 + u.pn * 4 + wc] = s;
;             }
	v_readlane_b32 s60, v253, 6
	s_waitcnt lgkmcnt(0)
	v_add_f32_e32 v116, v114, v115
	v_lshlrev_b64 v[114:115], 7, v[154:155]
	s_lshl_b32 s44, s38, 2
	v_readlane_b32 s61, v253, 7
	s_ashr_i32 s45, s44, 31
	s_nop 0
	v_lshl_add_u64 v[114:115], s[60:61], 0, v[114:115]
	v_lshl_add_u64 v[114:115], s[44:45], 2, v[114:115]
	s_lshl_b32 s44, s25, 2
	s_mov_b32 s45, s81
	v_lshl_add_u64 v[114:115], v[114:115], 0, s[44:45]
	v_add_co_u32_e32 v114, vcc, 0x4000, v114
	s_nop 1
	v_addc_co_u32_e32 v115, vcc, 0, v115, vcc
	global_store_dword v[114:115], v116, off offset:2048
.LBB0_1169:
	s_or_b64 exec, exec, s[42:43]
	v_mul_f32_e32 v119, v23, v23
	v_mul_f32_e32 v120, v25, v25
	v_mul_f32_e32 v114, v31, v31
	s_waitcnt lgkmcnt(0)
	v_mul_f32_e32 v115, v33, v33
	v_fmac_f32_e32 v119, v22, v22
	v_fmac_f32_e32 v120, v24, v24
	v_fmac_f32_e32 v114, v30, v30
	v_fmac_f32_e32 v115, v32, v32
	v_add_f32_e32 v119, v119, v120
	v_mul_f32_e32 v120, v19, v19
	v_add_f32_e32 v114, v114, v115
	v_mul_f32_e32 v115, v27, v27
	v_fmac_f32_e32 v120, v18, v18
	v_fmac_f32_e32 v115, v26, v26
	v_add_f32_e32 v119, v119, v120
	v_mul_f32_e32 v120, v21, v21
	v_add_f32_e32 v114, v114, v115
	v_mul_f32_e32 v115, v29, v29
	v_fmac_f32_e32 v120, v20, v20
	v_fmac_f32_e32 v115, v28, v28
	v_cvt_pk_bf16_f32 v116, v32, v33
	v_add_f32_e32 v119, v120, v119
	v_cvt_pk_bf16_f32 v120, v24, v25
	s_lshl_b64 s[42:43], s[58:59], 12
	v_readlane_b32 s9, v249, 28
	v_add_f32_e32 v114, v115, v114
	v_cvt_pk_bf16_f32 v117, v26, v27
	v_cvt_pk_bf16_f32 v121, v18, v19
	s_add_u32 s9, s9, s42
	v_readlane_b32 s17, v253, 5
	v_cndmask_b32_e64 v123, v116, v120, s[52:53]
	v_mov_b32_e32 v128, v131
	v_cvt_pk_bf16_f32 v115, v30, v31
	v_cvt_pk_bf16_f32 v118, v28, v29
	v_add_f32_e32 v126, v114, v119
	v_cvt_pk_bf16_f32 v119, v22, v23
	v_cvt_pk_bf16_f32 v122, v20, v21
	s_addc_u32 s17, s17, s43
	v_cndmask_b32_e64 v124, v117, v121, s[52:53]
	v_mov_b32_dpp v128, v123 row_ror:8 row_mask:0xf bank_mask:0xf
	v_mov_b32_e32 v123, v131
	s_add_u32 s44, s9, s62
	v_cndmask_b32_e64 v114, v115, v119, s[52:53]
	v_cndmask_b32_e64 v125, v118, v122, s[52:53]
	v_mov_b32_e32 v127, v131
	v_mov_b32_dpp v123, v124 row_ror:8 row_mask:0xf bank_mask:0xf
	v_mov_b32_e32 v124, v131
	s_addc_u32 s45, s17, s63
	v_mov_b32_dpp v127, v114 row_ror:8 row_mask:0xf bank_mask:0xf
	v_mov_b32_dpp v124, v125 row_ror:8 row_mask:0xf bank_mask:0xf
	v_cndmask_b32_e64 v114, v127, v115, s[52:53]
	v_cndmask_b32_e64 v115, v128, v116, s[52:53]
	v_cndmask_b32_e64 v116, v123, v117, s[52:53]
	v_cndmask_b32_e64 v117, v124, v118, s[52:53]
	v_cndmask_b32_e64 v118, v119, v127, s[52:53]
	v_cndmask_b32_e64 v119, v120, v128, s[52:53]
	v_cndmask_b32_e64 v120, v121, v123, s[52:53]
	v_cndmask_b32_e64 v121, v122, v124, s[52:53]
	v_lshl_add_u64 v[122:123], s[44:45], 0, v[130:131]
	v_mov_b32_e32 v153, v131
	v_lshl_add_u64 v[122:123], v[122:123], 0, v[152:153]
	v_mov_b32_e32 v151, v131
	v_lshl_add_u64 v[122:123], v[122:123], 0, v[150:151]
	s_mov_b32 s9, 0xa0000
	v_add_co_u32_e32 v124, vcc, s9, v122
	s_nop 1
	v_addc_co_u32_e32 v125, vcc, 0, v123, vcc
	global_store_dwordx4 v[124:125], v[114:117], off sc1
	s_nop 1
	v_add_co_u32_e32 v114, vcc, 0xa8000, v122
	s_nop 1
	v_addc_co_u32_e32 v115, vcc, 0, v123, vcc
	global_store_dwordx4 v[114:115], v[118:121], off sc1
	ds_bpermute_b32 v114, v165, v126
	s_waitcnt lgkmcnt(0)
	v_add_f32_e32 v114, v126, v114
	ds_bpermute_b32 v115, v164, v114
	s_and_saveexec_b64 s[82:83], s[54:55]
	s_cbranch_execz .LBB0_1171
	v_readlane_b32 s60, v253, 6
	s_waitcnt lgkmcnt(0)
	v_add_f32_e32 v116, v114, v115
	v_lshlrev_b64 v[114:115], 7, v[154:155]
	s_lshl_b32 s44, s38, 2
	v_readlane_b32 s61, v253, 7
	s_ashr_i32 s45, s44, 31
	s_nop 0
	v_lshl_add_u64 v[114:115], s[60:61], 0, v[114:115]
	v_lshl_add_u64 v[114:115], s[44:45], 2, v[114:115]
	s_lshl_b32 s44, s25, 2
	s_mov_b32 s45, s81
	v_lshl_add_u64 v[114:115], v[114:115], 0, s[44:45]
	v_add_co_u32_e32 v114, vcc, 0x5000, v114
	s_nop 1
	v_addc_co_u32_e32 v115, vcc, 0, v115, vcc
	global_store_dword v[114:115], v116, off
; __device__ __forceinline__ u32x4 pack8(f32x4 a, f32x4 b) { u32x4 w; w.x = cvtpk(a[0], a[1]); w.y = cvtpk(a[2], a[3]); w.z = cvtpk(b[0], b[1]); w.w = cvtpk(b[2], b[3]); return w; }
;     __device__ __forceinline__ void operator()(f32x4 (&acc)[2][2][4][2], const Unit& u, int wr, int wc, int fr, int fq) const {
;     ...
; #pragma unroll
;         for (int ai = 0; ai < 2; ++ai)
; #pragma unroll
;             for (int m = 0; m < 4; ++m) {
;                 const int row = row0 + ai * HALF + m * 16;
;                 float s = 0.f; u32x4 pk[2];
; #pragma unroll
;                 for (int bj = 0; bj < 2; ++bj) {
;                     const f32x4 v0 = acc[ai][bj][m][0], v1 = acc[ai][bj][m][1];
;                     s += (v0[0] * v0[0] + v0[1] * v0[1]) + (v0[2] * v0[2] + v0[3] * v0[3]) + (v1[0] * v1[0] + v1[1] * v1[1]) + (v1[2] * v1[2] + v1[3] * v1[3]);
;                     pk[bj] = pack8(v0, v1);
;                 }
;                 store_pair(Y + (size_t)(rowg + ai * HALF + m * 16) * DM + colw, DM, fr, fq, pk[0], pk[1]);
;                 s += __shfl_xor(s, 16); s += __shfl_xor(s, 32);
;                 if (fq == 0) ssy[(size_t)row * 32 + u.pn * 4 + wc] = s;
;             }
.LBB0_1171:
	s_or_b64 exec, exec, s[82:83]
	v_mul_f32_e32 v119, v7, v7
	v_mul_f32_e32 v120, v9, v9
	v_mul_f32_e32 v114, v15, v15
	s_waitcnt lgkmcnt(0)
	v_mul_f32_e32 v115, v17, v17
	v_fmac_f32_e32 v119, v6, v6
	v_fmac_f32_e32 v120, v8, v8
	v_fmac_f32_e32 v114, v14, v14
	v_fmac_f32_e32 v115, v16, v16
	v_add_f32_e32 v119, v119, v120
	v_mul_f32_e32 v120, v3, v3
	v_add_f32_e32 v114, v114, v115
	v_mul_f32_e32 v115, v11, v11
	v_fmac_f32_e32 v120, v2, v2
	v_fmac_f32_e32 v115, v10, v10
	v_add_f32_e32 v119, v119, v120
	v_mul_f32_e32 v120, v5, v5
	v_add_f32_e32 v114, v114, v115
	v_mul_f32_e32 v115, v13, v13
	v_fmac_f32_e32 v120, v4, v4
	v_fmac_f32_e32 v115, v12, v12
	v_cvt_pk_bf16_f32 v116, v16, v17
	v_add_f32_e32 v119, v120, v119
	v_cvt_pk_bf16_f32 v120, v8, v9
	v_readlane_b32 s9, v249, 28
	v_add_f32_e32 v114, v115, v114
	v_cvt_pk_bf16_f32 v117, v10, v11
	v_cvt_pk_bf16_f32 v121, v2, v3
	s_add_u32 s9, s9, s42
	v_readlane_b32 s17, v253, 5
	v_cndmask_b32_e64 v123, v116, v120, s[52:53]
	v_mov_b32_e32 v128, v131
	v_cvt_pk_bf16_f32 v115, v14, v15
	v_cvt_pk_bf16_f32 v118, v12, v13
	v_add_f32_e32 v126, v114, v119
	v_cvt_pk_bf16_f32 v119, v6, v7
	v_cvt_pk_bf16_f32 v122, v4, v5
	s_addc_u32 s17, s17, s43
	v_cndmask_b32_e64 v124, v117, v121, s[52:53]
	v_mov_b32_dpp v128, v123 row_ror:8 row_mask:0xf bank_mask:0xf
	v_mov_b32_e32 v123, v131
	s_add_u32 s42, s9, s62
	v_cndmask_b32_e64 v114, v115, v119, s[52:53]
	v_cndmask_b32_e64 v125, v118, v122, s[52:53]
	v_mov_b32_e32 v127, v131
	v_mov_b32_dpp v123, v124 row_ror:8 row_mask:0xf bank_mask:0xf
	v_mov_b32_e32 v124, v131
	s_addc_u32 s43, s17, s63
	v_mov_b32_dpp v127, v114 row_ror:8 row_mask:0xf bank_mask:0xf
	v_mov_b32_dpp v124, v125 row_ror:8 row_mask:0xf bank_mask:0xf
	v_cndmask_b32_e64 v114, v127, v115, s[52:53]
	v_cndmask_b32_e64 v115, v128, v116, s[52:53]
	v_cndmask_b32_e64 v116, v123, v117, s[52:53]
	v_cndmask_b32_e64 v117, v124, v118, s[52:53]
	v_cndmask_b32_e64 v118, v119, v127, s[52:53]
	v_cndmask_b32_e64 v119, v120, v128, s[52:53]
	v_cndmask_b32_e64 v120, v121, v123, s[52:53]
	v_cndmask_b32_e64 v121, v122, v124, s[52:53]
	v_lshl_add_u64 v[122:123], s[42:43], 0, v[130:131]
	ds_bpermute_b32 v127, v165, v126
	v_lshl_add_u64 v[122:123], v[122:123], 0, v[152:153]
	v_lshl_add_u64 v[122:123], v[122:123], 0, v[150:151]
	s_mov_b32 s9, 0xb0000
	v_add_co_u32_e32 v124, vcc, s9, v122
	s_nop 1
	v_addc_co_u32_e32 v125, vcc, 0, v123, vcc
	global_store_dwordx4 v[124:125], v[114:117], off sc1
	s_waitcnt lgkmcnt(0)
	s_nop 0
	v_add_f32_e32 v114, v126, v127
	ds_bpermute_b32 v115, v164, v114
	v_add_co_u32_e32 v116, vcc, 0xb8000, v122
	s_nop 1
	v_addc_co_u32_e32 v117, vcc, 0, v123, vcc
	global_store_dwordx4 v[116:117], v[118:121], off sc1
	s_and_saveexec_b64 s[42:43], s[54:55]
	s_cbranch_execz .LBB0_1173
	v_readlane_b32 s44, v253, 6
	s_waitcnt lgkmcnt(0)
	v_add_f32_e32 v116, v114, v115
	v_lshlrev_b64 v[114:115], 7, v[154:155]
	s_lshl_b32 s38, s38, 2
	v_readlane_b32 s45, v253, 7
	s_ashr_i32 s39, s38, 31
	s_nop 0
	v_lshl_add_u64 v[114:115], s[44:45], 0, v[114:115]
	v_lshl_add_u64 v[114:115], s[38:39], 2, v[114:115]
	s_lshl_b32 s38, s25, 2
	s_mov_b32 s39, s81
	v_lshl_add_u64 v[114:115], v[114:115], 0, s[38:39]
	v_add_co_u32_e32 v114, vcc, 0x5000, v114
	s_nop 1
	v_addc_co_u32_e32 v115, vcc, 0, v115, vcc
	global_store_dword v[114:115], v116, off offset:2048

; __device__ __forceinline__ u32x4 pack8(f32x4 a, f32x4 b) { u32x4 w; w.x = cvtpk(a[0], a[1]); w.y = cvtpk(a[2], a[3]); w.z = cvtpk(b[0], b[1]); w.w = cvtpk(b[2], b[3]); return w; }
;     __device__ __forceinline__ void operator()(f32x4 (&acc)[2][2][4][2], const Unit& u, int wr, int wc, int fr, int fq) const {
;     ...
;         if (u.ks >= 0) {
;             bf16_t* base = (bf16_t*)yp + ((size_t)u.ks * MS + (rowg - MP)) * DM + colw;
; #pragma unroll
;             for (int ai = 0; ai < 2; ++ai)
; #pragma unroll
;                 for (int m = 0; m < 4; ++m)
;                     store_pair(base + (size_t)(ai * HALF + m * 16) * DM, DM, fr, fq, pack8(acc[ai][0][m][0], acc[ai][0][m][1]), pack8(acc[ai][1][m][0], acc[ai][1][m][1]));
;             return;
.LBB0_1175:
	s_and_b64 vcc, exec, s[42:43]
	s_cbranch_vccz .LBB0_1174
	s_ashr_i32 s59, s58, 31
	s_lshl_b64 s[38:39], s[58:59], 12
	s_lshl_b64 s[42:43], s[80:81], 22
	s_add_u32 s9, s33, s42
	s_addc_u32 s17, s15, s43
	s_add_u32 s9, s9, s38
	s_addc_u32 s17, s17, s39
	s_ashr_i32 s41, s40, 31
	s_lshl_b64 s[38:39], s[40:41], 1
	s_add_u32 s38, s9, s38
	s_addc_u32 s39, s17, s39
	s_waitcnt lgkmcnt(0)
	v_lshl_add_u64 v[114:115], s[38:39], 0, v[130:131]
	v_mov_b32_e32 v153, v131
	v_lshl_add_u64 v[114:115], v[114:115], 0, v[152:153]
	v_mov_b32_e32 v151, v131
	v_lshl_add_u64 v[114:115], v[114:115], 0, v[150:151]
	v_cndmask_b32_e64 v116, v160, v156, s[52:53]
	v_cndmask_b32_e64 v117, v161, v157, s[52:53]
	v_cndmask_b32_e64 v118, v162, v158, s[52:53]
	v_cndmask_b32_e64 v119, v163, v159, s[52:53]
	v_mov_b32_e32 v120, v131
	v_mov_b32_e32 v121, v131
	v_mov_b32_e32 v122, v131
	v_mov_b32_e32 v123, v131
	s_brev_b32 s9, 63
	v_mov_b32_dpp v120, v116 row_ror:8 row_mask:0xf bank_mask:0xf
	v_mov_b32_dpp v121, v117 row_ror:8 row_mask:0xf bank_mask:0xf
	v_mov_b32_dpp v122, v118 row_ror:8 row_mask:0xf bank_mask:0xf
	v_mov_b32_dpp v123, v119 row_ror:8 row_mask:0xf bank_mask:0xf
	v_add_co_u32_e32 v124, vcc, s9, v114
	v_cndmask_b32_e64 v116, v120, v160, s[52:53]
	v_cndmask_b32_e64 v117, v121, v161, s[52:53]
	v_cndmask_b32_e64 v118, v122, v162, s[52:53]
	v_cndmask_b32_e64 v119, v123, v163, s[52:53]
	v_addc_co_u32_e32 v125, vcc, -1, v115, vcc
	s_mov_b32 s9, 0xfc008000
	v_cvt_pk_bf16_f32 v106, v106, v107
	v_cvt_pk_bf16_f32 v102, v102, v103
	v_cvt_pk_bf16_f32 v103, v104, v105
	v_cvt_pk_bf16_f32 v104, v98, v99
	global_store_dwordx4 v[124:125], v[116:119], off sc1
	v_cvt_pk_bf16_f32 v110, v110, v111
	v_cvt_pk_bf16_f32 v111, v112, v113
	v_add_co_u32_e32 v116, vcc, s9, v114
	v_cvt_pk_bf16_f32 v107, v108, v109
	v_cvt_pk_bf16_f32 v105, v100, v101
	v_cndmask_b32_e64 v100, v106, v104, s[52:53]
	v_mov_b32_e32 v112, v131
	v_addc_co_u32_e32 v117, vcc, -1, v115, vcc
	v_cndmask_b32_e64 v98, v110, v102, s[52:53]
	v_cndmask_b32_e64 v99, v111, v103, s[52:53]
	v_cndmask_b32_e64 v101, v107, v105, s[52:53]
	v_mov_b32_e32 v108, v131
	v_mov_b32_e32 v109, v131
	v_mov_b32_dpp v112, v100 row_ror:8 row_mask:0xf bank_mask:0xf
	v_mov_b32_e32 v113, v131
	s_mov_b32 s9, 0xfc010000
	v_mov_b32_dpp v108, v98 row_ror:8 row_mask:0xf bank_mask:0xf
	v_mov_b32_dpp v109, v99 row_ror:8 row_mask:0xf bank_mask:0xf
	v_mov_b32_dpp v113, v101 row_ror:8 row_mask:0xf bank_mask:0xf
	v_cndmask_b32_e64 v100, v112, v106, s[52:53]
	v_add_co_u32_e32 v106, vcc, s9, v114
	v_cndmask_b32_e64 v98, v108, v110, s[52:53]
	v_cndmask_b32_e64 v99, v109, v111, s[52:53]
	v_cndmask_b32_e64 v101, v113, v107, s[52:53]
	v_addc_co_u32_e32 v107, vcc, -1, v115, vcc
	s_mov_b32 s9, 0xfc018000
	v_cvt_pk_bf16_f32 v90, v90, v91
	v_cvt_pk_bf16_f32 v86, v86, v87
	v_cvt_pk_bf16_f32 v87, v88, v89
	v_cvt_pk_bf16_f32 v88, v82, v83
	global_store_dwordx4 v[106:107], v[98:101], off sc1
	v_cvt_pk_bf16_f32 v94, v94, v95
	v_cvt_pk_bf16_f32 v95, v96, v97
	v_add_co_u32_e32 v98, vcc, s9, v114
	v_cvt_pk_bf16_f32 v91, v92, v93
	v_cvt_pk_bf16_f32 v89, v84, v85
	v_cndmask_b32_e64 v84, v90, v88, s[52:53]
	v_mov_b32_e32 v96, v131
	v_addc_co_u32_e32 v99, vcc, -1, v115, vcc
	v_cndmask_b32_e64 v82, v94, v86, s[52:53]
	v_cndmask_b32_e64 v83, v95, v87, s[52:53]
	v_cndmask_b32_e64 v85, v91, v89, s[52:53]
	v_mov_b32_e32 v92, v131
	v_mov_b32_e32 v93, v131
	v_mov_b32_dpp v96, v84 row_ror:8 row_mask:0xf bank_mask:0xf
	v_mov_b32_e32 v97, v131
	s_mov_b32 s9, 0xfc020000
	v_mov_b32_dpp v92, v82 row_ror:8 row_mask:0xf bank_mask:0xf
	v_mov_b32_dpp v93, v83 row_ror:8 row_mask:0xf bank_mask:0xf
	v_mov_b32_dpp v97, v85 row_ror:8 row_mask:0xf bank_mask:0xf
	v_cndmask_b32_e64 v84, v96, v90, s[52:53]
	v_add_co_u32_e32 v90, vcc, s9, v114
	v_cndmask_b32_e64 v82, v92, v94, s[52:53]
	v_cndmask_b32_e64 v83, v93, v95, s[52:53]
	v_cndmask_b32_e64 v85, v97, v91, s[52:53]
	v_addc_co_u32_e32 v91, vcc, -1, v115, vcc
	s_mov_b32 s9, 0xfc028000
	v_cvt_pk_bf16_f32 v74, v74, v75
	v_cvt_pk_bf16_f32 v70, v70, v71
	v_cvt_pk_bf16_f32 v71, v72, v73
	v_cvt_pk_bf16_f32 v72, v66, v67
	global_store_dwordx4 v[90:91], v[82:85], off sc1
	v_cvt_pk_bf16_f32 v78, v78, v79
	v_cvt_pk_bf16_f32 v79, v80, v81
	v_add_co_u32_e32 v82, vcc, s9, v114
	v_cvt_pk_bf16_f32 v75, v76, v77
	v_cvt_pk_bf16_f32 v73, v68, v69
	v_cndmask_b32_e64 v68, v74, v72, s[52:53]
	v_mov_b32_e32 v80, v131
	v_addc_co_u32_e32 v83, vcc, -1, v115, vcc
	v_cndmask_b32_e64 v66, v78, v70, s[52:53]
	v_cndmask_b32_e64 v67, v79, v71, s[52:53]
	v_cndmask_b32_e64 v69, v75, v73, s[52:53]
	v_mov_b32_e32 v76, v131
	v_mov_b32_e32 v77, v131
	v_mov_b32_dpp v80, v68 row_ror:8 row_mask:0xf bank_mask:0xf
	v_mov_b32_e32 v81, v131
	s_mov_b32 s9, 0xfc030000
	v_mov_b32_dpp v76, v66 row_ror:8 row_mask:0xf bank_mask:0xf
	v_mov_b32_dpp v77, v67 row_ror:8 row_mask:0xf bank_mask:0xf
	v_mov_b32_dpp v81, v69 row_ror:8 row_mask:0xf bank_mask:0xf
	v_cndmask_b32_e64 v68, v80, v74, s[52:53]
	v_add_co_u32_e32 v74, vcc, s9, v114
	v_cndmask_b32_e64 v66, v76, v78, s[52:53]
	v_cndmask_b32_e64 v67, v77, v79, s[52:53]
	v_cndmask_b32_e64 v69, v81, v75, s[52:53]
	v_addc_co_u32_e32 v75, vcc, -1, v115, vcc
	s_mov_b32 s9, 0xfc038000
	v_cvt_pk_bf16_f32 v58, v58, v59
	v_cvt_pk_bf16_f32 v54, v54, v55
	v_cvt_pk_bf16_f32 v55, v56, v57
	v_cvt_pk_bf16_f32 v56, v50, v51
	global_store_dwordx4 v[74:75], v[66:69], off sc1
	v_cvt_pk_bf16_f32 v62, v62, v63
	v_cvt_pk_bf16_f32 v63, v64, v65
	v_add_co_u32_e32 v66, vcc, s9, v114
	v_cvt_pk_bf16_f32 v59, v60, v61
	v_cvt_pk_bf16_f32 v57, v52, v53
	v_cndmask_b32_e64 v52, v58, v56, s[52:53]
	v_mov_b32_e32 v64, v131
	v_addc_co_u32_e32 v67, vcc, -1, v115, vcc
; __device__ __forceinline__ u32x4 pack8(f32x4 a, f32x4 b) { u32x4 w; w.x = cvtpk(a[0], a[1]); w.y = cvtpk(a[2], a[3]); w.z = cvtpk(b[0], b[1]); w.w = cvtpk(b[2], b[3]); return w; }
;     __device__ __forceinline__ void operator()(f32x4 (&acc)[2][2][4][2], const Unit& u, int wr, int wc, int fr, int fq) const {
;     ...
;         if (u.ks >= 0) {
;             bf16_t* base = (bf16_t*)yp + ((size_t)u.ks * MS + (rowg - MP)) * DM + colw;
; #pragma unroll
;             for (int ai = 0; ai < 2; ++ai)
; #pragma unroll
;                 for (int m = 0; m < 4; ++m)
;                     store_pair(base + (size_t)(ai * HALF + m * 16) * DM, DM, fr, fq, pack8(acc[ai][0][m][0], acc[ai][0][m][1]), pack8(acc[ai][1][m][0], acc[ai][1][m][1]));
;             return;
	v_cndmask_b32_e64 v50, v62, v54, s[52:53]
	v_cndmask_b32_e64 v51, v63, v55, s[52:53]
	v_cndmask_b32_e64 v53, v59, v57, s[52:53]
	v_mov_b32_e32 v60, v131
	v_mov_b32_e32 v61, v131
	v_mov_b32_dpp v64, v52 row_ror:8 row_mask:0xf bank_mask:0xf
	v_mov_b32_e32 v65, v131
	s_mov_b32 s9, 0xfc080000
	v_mov_b32_dpp v60, v50 row_ror:8 row_mask:0xf bank_mask:0xf
	v_mov_b32_dpp v61, v51 row_ror:8 row_mask:0xf bank_mask:0xf
	v_mov_b32_dpp v65, v53 row_ror:8 row_mask:0xf bank_mask:0xf
	v_cndmask_b32_e64 v52, v64, v58, s[52:53]
	v_add_co_u32_e32 v58, vcc, s9, v114
	v_cndmask_b32_e64 v50, v60, v62, s[52:53]
	v_cndmask_b32_e64 v51, v61, v63, s[52:53]
	v_cndmask_b32_e64 v53, v65, v59, s[52:53]
	v_addc_co_u32_e32 v59, vcc, -1, v115, vcc
	s_mov_b32 s9, 0xfc088000
	v_cvt_pk_bf16_f32 v42, v42, v43
	v_cvt_pk_bf16_f32 v38, v38, v39
	v_cvt_pk_bf16_f32 v39, v40, v41
	v_cvt_pk_bf16_f32 v40, v34, v35
	global_store_dwordx4 v[58:59], v[50:53], off sc1
	v_cvt_pk_bf16_f32 v46, v46, v47
	v_cvt_pk_bf16_f32 v47, v48, v49
	v_add_co_u32_e32 v50, vcc, s9, v114
	v_cvt_pk_bf16_f32 v43, v44, v45
	v_cvt_pk_bf16_f32 v41, v36, v37
	v_cndmask_b32_e64 v36, v42, v40, s[52:53]
	v_mov_b32_e32 v48, v131
	v_addc_co_u32_e32 v51, vcc, -1, v115, vcc
	v_cndmask_b32_e64 v34, v46, v38, s[52:53]
	v_cndmask_b32_e64 v35, v47, v39, s[52:53]
	v_cndmask_b32_e64 v37, v43, v41, s[52:53]
	v_mov_b32_e32 v44, v131
	v_mov_b32_e32 v45, v131
	v_mov_b32_dpp v48, v36 row_ror:8 row_mask:0xf bank_mask:0xf
	v_mov_b32_e32 v49, v131
	s_mov_b32 s9, 0xfc090000
	v_mov_b32_dpp v44, v34 row_ror:8 row_mask:0xf bank_mask:0xf
	v_mov_b32_dpp v45, v35 row_ror:8 row_mask:0xf bank_mask:0xf
	v_mov_b32_dpp v49, v37 row_ror:8 row_mask:0xf bank_mask:0xf
	v_cndmask_b32_e64 v36, v48, v42, s[52:53]
	v_add_co_u32_e32 v42, vcc, s9, v114
	v_cndmask_b32_e64 v34, v44, v46, s[52:53]
	v_cndmask_b32_e64 v35, v45, v47, s[52:53]
	v_cndmask_b32_e64 v37, v49, v43, s[52:53]
	v_addc_co_u32_e32 v43, vcc, -1, v115, vcc
	s_mov_b32 s9, 0xfc098000
	v_cvt_pk_bf16_f32 v26, v26, v27
	v_cvt_pk_bf16_f32 v22, v22, v23
	v_cvt_pk_bf16_f32 v23, v24, v25
	v_cvt_pk_bf16_f32 v24, v18, v19
	global_store_dwordx4 v[42:43], v[34:37], off sc1
	v_cvt_pk_bf16_f32 v30, v30, v31
	v_cvt_pk_bf16_f32 v31, v32, v33
	v_add_co_u32_e32 v34, vcc, s9, v114
	v_cvt_pk_bf16_f32 v27, v28, v29
	v_cvt_pk_bf16_f32 v25, v20, v21
	v_cndmask_b32_e64 v20, v26, v24, s[52:53]
	v_mov_b32_e32 v32, v131
	v_addc_co_u32_e32 v35, vcc, -1, v115, vcc
	v_cndmask_b32_e64 v18, v30, v22, s[52:53]
	v_cndmask_b32_e64 v19, v31, v23, s[52:53]
	v_cndmask_b32_e64 v21, v27, v25, s[52:53]
	v_mov_b32_e32 v28, v131
	v_mov_b32_e32 v29, v131
	v_mov_b32_dpp v32, v20 row_ror:8 row_mask:0xf bank_mask:0xf
	v_mov_b32_e32 v33, v131
	s_mov_b32 s9, 0xfc0a0000
	v_mov_b32_dpp v28, v18 row_ror:8 row_mask:0xf bank_mask:0xf
	v_mov_b32_dpp v29, v19 row_ror:8 row_mask:0xf bank_mask:0xf
	v_mov_b32_dpp v33, v21 row_ror:8 row_mask:0xf bank_mask:0xf
	v_cndmask_b32_e64 v20, v32, v26, s[52:53]
	v_add_co_u32_e32 v26, vcc, s9, v114
	v_cndmask_b32_e64 v18, v28, v30, s[52:53]
	v_cndmask_b32_e64 v19, v29, v31, s[52:53]
	v_cndmask_b32_e64 v21, v33, v27, s[52:53]
	v_addc_co_u32_e32 v27, vcc, -1, v115, vcc
	s_mov_b32 s9, 0xfc0a8000
	v_cvt_pk_bf16_f32 v10, v10, v11
	v_cvt_pk_bf16_f32 v6, v6, v7
	v_cvt_pk_bf16_f32 v7, v8, v9
	v_cvt_pk_bf16_f32 v8, v2, v3
	global_store_dwordx4 v[26:27], v[18:21], off sc1
	v_cvt_pk_bf16_f32 v14, v14, v15
	v_cvt_pk_bf16_f32 v15, v16, v17
	v_add_co_u32_e32 v18, vcc, s9, v114
	v_cvt_pk_bf16_f32 v11, v12, v13
	v_cvt_pk_bf16_f32 v9, v4, v5
	v_cndmask_b32_e64 v4, v10, v8, s[52:53]
	v_mov_b32_e32 v16, v131
	v_addc_co_u32_e32 v19, vcc, -1, v115, vcc
	v_cndmask_b32_e64 v2, v14, v6, s[52:53]
	v_cndmask_b32_e64 v3, v15, v7, s[52:53]
	v_cndmask_b32_e64 v5, v11, v9, s[52:53]
	v_mov_b32_e32 v12, v131
	v_mov_b32_e32 v13, v131
	v_mov_b32_dpp v16, v4 row_ror:8 row_mask:0xf bank_mask:0xf
	v_mov_b32_e32 v17, v131
	v_mov_b32_dpp v12, v2 row_ror:8 row_mask:0xf bank_mask:0xf
	v_mov_b32_dpp v13, v3 row_ror:8 row_mask:0xf bank_mask:0xf
	v_mov_b32_dpp v17, v5 row_ror:8 row_mask:0xf bank_mask:0xf
	v_cndmask_b32_e64 v4, v16, v10, s[52:53]
	v_add_co_u32_e32 v10, vcc, 0xfc0b0000, v114
	v_cndmask_b32_e64 v2, v12, v14, s[52:53]
	v_cndmask_b32_e64 v3, v13, v15, s[52:53]
	v_cndmask_b32_e64 v5, v17, v11, s[52:53]
	v_addc_co_u32_e32 v11, vcc, -1, v115, vcc
	global_store_dwordx4 v[10:11], v[2:5], off sc1
	v_cndmask_b32_e64 v120, v156, v120, s[52:53]
	v_cndmask_b32_e64 v121, v157, v121, s[52:53]
	v_add_co_u32_e32 v2, vcc, 0xfc0b8000, v114
	v_cndmask_b32_e64 v122, v158, v122, s[52:53]
	v_cndmask_b32_e64 v123, v159, v123, s[52:53]
	v_cndmask_b32_e64 v102, v102, v108, s[52:53]
	v_cndmask_b32_e64 v103, v103, v109, s[52:53]
	v_cndmask_b32_e64 v104, v104, v112, s[52:53]
	v_cndmask_b32_e64 v105, v105, v113, s[52:53]
	v_cndmask_b32_e64 v86, v86, v92, s[52:53]
	v_cndmask_b32_e64 v87, v87, v93, s[52:53]
	v_cndmask_b32_e64 v88, v88, v96, s[52:53]
	v_cndmask_b32_e64 v89, v89, v97, s[52:53]
	v_cndmask_b32_e64 v70, v70, v76, s[52:53]
	v_cndmask_b32_e64 v71, v71, v77, s[52:53]
	v_cndmask_b32_e64 v72, v72, v80, s[52:53]
	v_cndmask_b32_e64 v73, v73, v81, s[52:53]
	v_cndmask_b32_e64 v54, v54, v60, s[52:53]
	v_cndmask_b32_e64 v55, v55, v61, s[52:53]
	v_cndmask_b32_e64 v56, v56, v64, s[52:53]
	v_cndmask_b32_e64 v57, v57, v65, s[52:53]
	v_cndmask_b32_e64 v38, v38, v44, s[52:53]
	v_cndmask_b32_e64 v39, v39, v45, s[52:53]
	v_cndmask_b32_e64 v40, v40, v48, s[52:53]
	v_cndmask_b32_e64 v41, v41, v49, s[52:53]
	v_cndmask_b32_e64 v22, v22, v28, s[52:53]
	v_cndmask_b32_e64 v23, v23, v29, s[52:53]
	v_cndmask_b32_e64 v24, v24, v32, s[52:53]
	v_cndmask_b32_e64 v25, v25, v33, s[52:53]
	v_cndmask_b32_e64 v6, v6, v12, s[52:53]
	v_cndmask_b32_e64 v7, v7, v13, s[52:53]
	v_cndmask_b32_e64 v8, v8, v16, s[52:53]
	v_cndmask_b32_e64 v9, v9, v17, s[52:53]
	v_addc_co_u32_e32 v3, vcc, -1, v115, vcc
	global_store_dwordx4 v[116:117], v[120:123], off sc1
	global_store_dwordx4 v[98:99], v[102:105], off sc1
	global_store_dwordx4 v[82:83], v[86:89], off sc1
	global_store_dwordx4 v[66:67], v[70:73], off sc1
	global_store_dwordx4 v[50:51], v[54:57], off sc1
	global_store_dwordx4 v[34:35], v[38:41], off sc1
	global_store_dwordx4 v[18:19], v[22:25], off sc1
	global_store_dwordx4 v[2:3], v[6:9], off sc1
	s_andn2_b64 vcc, exec, s[56:57]
	s_mov_b64 s[40:41], -1
	s_cbranch_vccnz .LBB0_1147

; __device__ __forceinline__ u32x4 pack8(f32x4 a, f32x4 b) { u32x4 w; w.x = cvtpk(a[0], a[1]); w.y = cvtpk(a[2], a[3]); w.z = cvtpk(b[0], b[1]); w.w = cvtpk(b[2], b[3]); return w; }
;     __device__ __forceinline__ void operator()(f32x4 (&acc)[2][2][4][2], const Unit& u, int wr, int wc, int fr, int fq) const {
;         const int rowg = u.pm * BM + wr * 64, colw = u.pn * BM + wc * 64, row0 = rowg + fr, col0 = colw + 8 * fq;
;         u32x4 cv[4]; v4i_t ov[4];
; #pragma unroll
;         for (int k = 0; k < 4; ++k) { cv[k] = *(const u32x4*)(cmax + col0 + (k >> 1) * CBJ + (k & 1) * 4); ov[k] = *(const v4i_t*)(csum + (u.ks < 0 ? 0 : (1 + u.ks) * DM) + col0 + (k >> 1) * CBJ + (k & 1) * 4); }
;         float rv[8];
; #pragma unroll
;         for (int k = 0; k < 8; ++k) rv[k] = __uint_as_float(rmax[row0 + (k >> 2) * HALF + (k & 3) * 16]) * (1.0f / (255.0f * 127.0f));
; #pragma unroll
;         for (int ai = 0; ai < 2; ++ai)
; #pragma unroll
;             for (int m = 0; m < 4; ++m) {
;                 const int row = row0 + ai * HALF + m * 16;
;                 const float sr = rv[ai * 4 + m];
;                 float s = 0.f; u32x4 pk[2];
; #pragma unroll
;                 for (int bj = 0; bj < 2; ++bj) {
;                     const v4i_t i0 = __builtin_bit_cast(v4i_t, acc[ai][bj][m][0]) + ov[bj * 2], i1 = __builtin_bit_cast(v4i_t, acc[ai][bj][m][1]) + ov[bj * 2 + 1];
;                     const u32x4 c0_ = cv[bj * 2], c1_ = cv[bj * 2 + 1];
;                     f32x4 v0, v1;
; #pragma unroll
;                     for (int j = 0; j < 4; ++j) { v0[j] = (float)i0[j] * (sr * __uint_as_float(c0_[j])); v1[j] = (float)i1[j] * (sr * __uint_as_float(c1_[j])); }
;                     s += (v0[0] * v0[0] + v0[1] * v0[1]) + (v0[2] * v0[2] + v0[3] * v0[3]) + (v1[0] * v1[0] + v1[1] * v1[1]) + (v1[2] * v1[2] + v1[3] * v1[3]);
;                     pk[bj] = pack8(v0, v1);
.LBB0_1577:
	s_mov_b32 s0, s81
	s_lshl_b32 s0, s21, 8
	s_or_b32 s82, s0, s49
	s_lshl_b32 s0, s62, 11
	s_addk_i32 s0, 0x800
	s_cmp_lt_i32 s62, 0
	s_cselect_b64 s[42:43], -1, 0
	s_and_b64 vcc, s[42:43], exec
	s_cselect_b32 s80, 0, s0
	v_or_b32_e32 v50, s82, v172
	s_lshl_b64 s[0:1], s[80:81], 2
	v_ashrrev_i32_e32 v51, 31, v50
	s_add_u32 s0, s24, s0
	v_lshlrev_b64 v[50:51], 2, v[50:51]
	s_addc_u32 s1, s25, s1
	v_lshl_add_u64 v[74:75], s[0:1], 0, v[50:51]
	s_lshl_b32 s0, s14, 8
	s_add_i32 s0, s0, s39
	v_or_b32_e32 v182, s0, v173
	v_ashrrev_i32_e32 v183, 31, v182
	v_lshl_add_u64 v[54:55], s[16:17], 0, v[50:51]
	v_lshl_add_u64 v[184:185], v[182:183], 2, s[8:9]
	global_load_dwordx4 v[62:65], v[54:55], off offset:16
	global_load_dwordx4 v[66:69], v[54:55], off
	global_load_dwordx4 v[70:73], v[74:75], off offset:16
	global_load_dwordx4 v[78:81], v[74:75], off
	global_load_dwordx4 v[50:53], v[54:55], off offset:144
	s_nop 0
	global_load_dwordx4 v[54:57], v[54:55], off offset:128
	s_nop 0
	global_load_dwordx4 v[58:61], v[74:75], off offset:144
	s_nop 0
	global_load_dwordx4 v[74:77], v[74:75], off offset:128
	s_ashr_i32 s83, s82, 31
	global_load_dword v130, v[184:185], off
	global_load_dword v194, v[184:185], off offset:64
	global_load_dword v193, v[184:185], off offset:128
	global_load_dword v192, v[184:185], off offset:192
	global_load_dword v191, v[184:185], off offset:512
	global_load_dword v190, v[184:185], off offset:576
	global_load_dword v189, v[184:185], off offset:640
	global_load_dword v188, v[184:185], off offset:704
	s_mov_b64 s[56:57], -1
	v_readlane_b32 s97, v249, 8
	s_mov_b32 s46, 0x8000
	s_waitcnt vmcnt(0)
	v_add_u32_e32 v156, v70, v156
	v_add_u32_e32 v157, v71, v157
	v_cvt_f32_i32_e32 v157, v157
	v_cvt_f32_i32_e32 v156, v156
	v_add_u32_e32 v160, v78, v160
	v_add_u32_e32 v161, v79, v161
	v_add_u32_e32 v184, v80, v162
	v_mul_f32_e32 v130, 0x38018388, v130
	v_add_u32_e32 v185, v81, v163
	v_cvt_f32_i32_e32 v161, v161
	v_cvt_f32_i32_e32 v160, v160
	v_add_u32_e32 v186, v72, v158
	v_add_u32_e32 v187, v73, v159
	v_pk_mul_f32 v[158:159], v[62:63], v[130:131] op_sel_hi:[1,0]
	v_pk_mul_f32 v[162:163], v[66:67], v[130:131] op_sel_hi:[1,0]
	v_pk_mul_f32 v[156:157], v[158:159], v[156:157]
	v_cvt_f32_i32_e32 v159, v185
	v_cvt_f32_i32_e32 v158, v184
	v_pk_mul_f32 v[160:161], v[162:163], v[160:161]
	v_pk_mul_f32 v[162:163], v[68:69], v[130:131] op_sel_hi:[1,0]
	v_add_u32_e32 v152, v74, v152
	v_pk_mul_f32 v[158:159], v[162:163], v[158:159]
	v_cvt_f32_i32_e32 v163, v187
	v_cvt_f32_i32_e32 v162, v186
	v_add_u32_e32 v153, v75, v153
	v_add_u32_e32 v148, v58, v148
	v_add_u32_e32 v149, v59, v149
	v_cvt_f32_i32_e32 v153, v153
	v_cvt_f32_i32_e32 v152, v152
	v_cvt_f32_i32_e32 v149, v149
	v_cvt_f32_i32_e32 v148, v148
	v_pk_mul_f32 v[184:185], v[64:65], v[130:131] op_sel_hi:[1,0]
	v_add_u32_e32 v186, v60, v150
	v_pk_mul_f32 v[162:163], v[184:185], v[162:163]
	v_add_u32_e32 v184, v76, v154
	v_add_u32_e32 v185, v77, v155
	v_pk_mul_f32 v[154:155], v[54:55], v[130:131] op_sel_hi:[1,0]
	v_add_u32_e32 v187, v61, v151
	v_pk_mul_f32 v[150:151], v[50:51], v[130:131] op_sel_hi:[1,0]
	v_pk_mul_f32 v[152:153], v[154:155], v[152:153]
	v_pk_mul_f32 v[154:155], v[150:151], v[148:149]
	v_cvt_f32_i32_e32 v149, v185
	v_cvt_f32_i32_e32 v148, v184
	v_pk_mul_f32 v[150:151], v[56:57], v[130:131] op_sel_hi:[1,0]
	v_cvt_pk_bf16_f32 v195, v160, v161
	v_cvt_pk_bf16_f32 v196, v158, v159
	v_pk_mul_f32 v[184:185], v[150:151], v[148:149]
	v_cvt_f32_i32_e32 v149, v187
	v_cvt_f32_i32_e32 v148, v186
	v_pk_mul_f32 v[150:151], v[52:53], v[130:131] op_sel_hi:[1,0]
	v_cvt_pk_bf16_f32 v197, v156, v157
	v_cvt_pk_bf16_f32 v198, v162, v163
	v_pk_mul_f32 v[186:187], v[150:151], v[148:149]
	v_cvt_pk_bf16_f32 v199, v152, v153
	v_cvt_pk_bf16_f32 v200, v184, v185
	v_cvt_pk_bf16_f32 v201, v154, v155
	v_cvt_pk_bf16_f32 v202, v186, v187
	v_cndmask_b32_e64 v213, v195, v199, s[52:53]
	v_cndmask_b32_e64 v212, v196, v200, s[52:53]
	v_cndmask_b32_e64 v211, v197, v201, s[52:53]
	v_cndmask_b32_e64 v203, v198, v202, s[52:53]
	v_lshlrev_b32_e32 v130, 1, v174
	v_lshlrev_b32_e32 v150, 1, v176
	v_lshlrev_b32_e32 v148, 1, v172
	s_cbranch_vccz .LBB0_1581
; __device__ __forceinline__ u32x4 pack8(f32x4 a, f32x4 b) { u32x4 w; w.x = cvtpk(a[0], a[1]); w.y = cvtpk(a[2], a[3]); w.z = cvtpk(b[0], b[1]); w.w = cvtpk(b[2], b[3]); return w; }
;     __device__ __forceinline__ void operator()(f32x4 (&acc)[2][2][4][2], const Unit& u, int wr, int wc, int fr, int fq) const {
;     ...
;                 float s = 0.f; u32x4 pk[2];
; #pragma unroll
;                 for (int bj = 0; bj < 2; ++bj) {
;                     const v4i_t i0 = __builtin_bit_cast(v4i_t, acc[ai][bj][m][0]) + ov[bj * 2], i1 = __builtin_bit_cast(v4i_t, acc[ai][bj][m][1]) + ov[bj * 2 + 1];
;                     const u32x4 c0_ = cv[bj * 2], c1_ = cv[bj * 2 + 1];
;                     f32x4 v0, v1;
; #pragma unroll
;                     for (int j = 0; j < 4; ++j) { v0[j] = (float)i0[j] * (sr * __uint_as_float(c0_[j])); v1[j] = (float)i1[j] * (sr * __uint_as_float(c1_[j])); }
;                     s += (v0[0] * v0[0] + v0[1] * v0[1]) + (v0[2] * v0[2] + v0[3] * v0[3]) + (v1[0] * v1[0] + v1[1] * v1[1]) + (v1[2] * v1[2] + v1[3] * v1[3]);
;                     pk[bj] = pack8(v0, v1);
;                 }
;                 if (u.ks >= 0) store_pair((bf16_t*)yp + ((size_t)u.ks * MS + (rowg - MP) + ai * HALF + m * 16) * DM + colw, DM, fr, fq, pk[0], pk[1]);
;                 else {
;                     store_pair(Y + (size_t)(rowg + ai * HALF + m * 16) * DM + colw, DM, fr, fq, pk[0], pk[1]);
;                     s += __shfl_xor(s, 16); s += __shfl_xor(s, 32);
;                     if (fq == 0) ssy[(size_t)row * 32 + u.pn * 4 + wc] = s;
;                 }
	v_pk_mul_f32 v[152:153], v[152:153], v[152:153]
	v_pk_mul_f32 v[184:185], v[184:185], v[184:185]
	v_pk_mul_f32 v[154:155], v[154:155], v[154:155]
	v_add_f32_e32 v149, v184, v185
	v_add_f32_e32 v151, v152, v153
	v_pk_mul_f32 v[186:187], v[186:187], v[186:187]
	v_add_f32_e32 v149, v151, v149
	v_add_f32_e32 v151, v154, v155
	v_pk_mul_f32 v[160:161], v[160:161], v[160:161]
	v_pk_mul_f32 v[158:159], v[158:159], v[158:159]
	v_add_f32_e32 v149, v151, v149
	v_add_f32_e32 v151, v186, v187
	v_pk_mul_f32 v[156:157], v[156:157], v[156:157]
	v_add_f32_e32 v149, v151, v149
	v_add_f32_e32 v151, v158, v159
	v_add_f32_e32 v152, v160, v161
	v_pk_mul_f32 v[162:163], v[162:163], v[162:163]
	v_add_f32_e32 v151, v152, v151
	v_add_f32_e32 v152, v156, v157
	v_add_f32_e32 v151, v152, v151
	v_add_f32_e32 v152, v162, v163
	v_add_f32_e32 v151, v152, v151
	v_add_f32_e32 v162, v151, v149
	v_mov_b32_e32 v149, v131
	s_ashr_i32 s1, s0, 31
	v_and_b32_e32 v163, 64, v204
	v_mov_b32_dpp v149, v213 row_ror:8 row_mask:0xf bank_mask:0xf
	s_lshl_b64 s[22:23], s[0:1], 12
	v_readlane_b32 s1, v249, 28
	v_cndmask_b32_e64 v152, v149, v195, s[52:53]
	v_cndmask_b32_e64 v156, v199, v149, s[52:53]
	v_xor_b32_e32 v149, 16, v204
	v_add_u32_e32 v163, 64, v163
	s_add_u32 s1, s1, s22
	v_readlane_b32 s14, v253, 5
	v_cmp_lt_i32_e32 vcc, v149, v163
	s_addc_u32 s14, s14, s23
	s_lshl_b64 s[22:23], s[82:83], 1
	v_cndmask_b32_e32 v149, v204, v149, vcc
	s_add_u32 s22, s1, s22
	v_mov_b32_e32 v151, v131
	v_lshlrev_b32_e32 v149, 2, v149
	s_addc_u32 s23, s14, s23
	v_mov_b32_dpp v151, v212 row_ror:8 row_mask:0xf bank_mask:0xf
	ds_bpermute_b32 v184, v149, v162
	v_cndmask_b32_e64 v153, v151, v196, s[52:53]
	v_cndmask_b32_e64 v157, v200, v151, s[52:53]
	v_lshl_add_u64 v[160:161], s[22:23], 0, v[130:131]
	v_mov_b32_e32 v151, v131
	v_lshl_add_u64 v[160:161], v[160:161], 0, v[150:151]
	v_xor_b32_e32 v151, 32, v204
	v_cmp_lt_i32_e32 vcc, v151, v163
	v_mov_b32_e32 v149, v131
	v_lshl_add_u64 v[160:161], v[160:161], 0, v[148:149]
	v_cndmask_b32_e32 v151, v204, v151, vcc
	s_waitcnt lgkmcnt(0)
	v_add_f32_e32 v149, v162, v184
	v_lshlrev_b32_e32 v151, 2, v151
	v_mov_b32_e32 v158, v131
	v_mov_b32_e32 v159, v131
	ds_bpermute_b32 v151, v151, v149
	v_mov_b32_dpp v158, v211 row_ror:8 row_mask:0xf bank_mask:0xf
	v_mov_b32_dpp v159, v203 row_ror:8 row_mask:0xf bank_mask:0xf
	v_cndmask_b32_e64 v154, v158, v197, s[52:53]
	v_cndmask_b32_e64 v155, v159, v198, s[52:53]
	global_store_dwordx4 v[160:161], v[152:155], off sc1
	v_cndmask_b32_e64 v158, v201, v158, s[52:53]
	v_cndmask_b32_e64 v159, v202, v159, s[52:53]
	v_add_co_u32_e32 v152, vcc, s46, v160
	s_nop 1
	v_addc_co_u32_e32 v153, vcc, 0, v161, vcc
	global_store_dwordx4 v[152:153], v[156:159], off sc1
	s_and_saveexec_b64 s[40:41], s[54:55]
	s_cbranch_execz .LBB0_1580
	v_readlane_b32 s44, v253, 6
	s_lshl_b32 s22, s21, 2
	v_lshlrev_b64 v[152:153], 7, v[182:183]
	v_readlane_b32 s45, v253, 7
	s_ashr_i32 s23, s22, 31
	s_lshl_b32 s80, s38, 2
	v_lshl_add_u64 v[152:153], s[44:45], 0, v[152:153]
	v_lshl_add_u64 v[152:153], s[22:23], 2, v[152:153]
	s_waitcnt lgkmcnt(0)
	v_add_f32_e32 v149, v149, v151
	v_lshl_add_u64 v[152:153], v[152:153], 0, s[80:81]
	global_store_dword v[152:153], v149, off

; __device__ __forceinline__ u32x4 pack8(f32x4 a, f32x4 b) { u32x4 w; w.x = cvtpk(a[0], a[1]); w.y = cvtpk(a[2], a[3]); w.z = cvtpk(b[0], b[1]); w.w = cvtpk(b[2], b[3]); return w; }
;     __device__ __forceinline__ void operator()(f32x4 (&acc)[2][2][4][2], const Unit& u, int wr, int wc, int fr, int fq) const {
;     ...
;                     pk[bj] = pack8(v0, v1);
;                 }
;                 if (u.ks >= 0) store_pair((bf16_t*)yp + ((size_t)u.ks * MS + (rowg - MP) + ai * HALF + m * 16) * DM + colw, DM, fr, fq, pk[0], pk[1]);
.LBB0_1581:
	s_add_i32 s40, s0, 0xffffc000
	s_andn2_b64 vcc, exec, s[56:57]
	s_ashr_i32 s41, s40, 31
	s_cbranch_vccnz .LBB0_1583
	s_mov_b32 s63, s81
	s_lshl_b64 s[22:23], s[62:63], 22
	s_lshl_b64 s[44:45], s[40:41], 12
	s_add_u32 s1, s88, s22
	s_addc_u32 s14, s89, s23
	s_add_u32 s1, s1, s44
	s_addc_u32 s14, s14, s45
	s_lshl_b64 s[22:23], s[82:83], 1
	s_add_u32 s22, s1, s22
	s_waitcnt lgkmcnt(0)
	v_mov_b32_e32 v151, v131
	s_addc_u32 s23, s14, s23
	v_mov_b32_e32 v149, v131
	v_mov_b32_dpp v151, v212 row_ror:8 row_mask:0xf bank_mask:0xf
	v_mov_b32_e32 v158, v131
	v_mov_b32_dpp v149, v213 row_ror:8 row_mask:0xf bank_mask:0xf
	v_mov_b32_e32 v159, v131
	v_cndmask_b32_e64 v153, v151, v196, s[52:53]
	v_cndmask_b32_e64 v157, v200, v151, s[52:53]
	v_lshl_add_u64 v[160:161], s[22:23], 0, v[130:131]
	v_mov_b32_e32 v151, v131
	v_mov_b32_dpp v158, v211 row_ror:8 row_mask:0xf bank_mask:0xf
	v_mov_b32_dpp v159, v203 row_ror:8 row_mask:0xf bank_mask:0xf
	v_cndmask_b32_e64 v152, v149, v195, s[52:53]
	v_cndmask_b32_e64 v156, v199, v149, s[52:53]
	v_lshl_add_u64 v[160:161], v[160:161], 0, v[150:151]
	v_mov_b32_e32 v149, v131
	v_cndmask_b32_e64 v154, v158, v197, s[52:53]
	v_cndmask_b32_e64 v155, v159, v198, s[52:53]
	v_lshl_add_u64 v[160:161], v[160:161], 0, v[148:149]
	global_store_dwordx4 v[160:161], v[152:155], off sc1
	v_cndmask_b32_e64 v158, v201, v158, s[52:53]
	v_cndmask_b32_e64 v159, v202, v159, s[52:53]
	v_add_co_u32_e32 v152, vcc, 0x8000, v160
	s_nop 1
	v_addc_co_u32_e32 v153, vcc, 0, v161, vcc
	global_store_dwordx4 v[152:153], v[156:159], off sc1
; __device__ __forceinline__ u32x4 pack8(f32x4 a, f32x4 b) { u32x4 w; w.x = cvtpk(a[0], a[1]); w.y = cvtpk(a[2], a[3]); w.z = cvtpk(b[0], b[1]); w.w = cvtpk(b[2], b[3]); return w; }
;     __device__ __forceinline__ void operator()(f32x4 (&acc)[2][2][4][2], const Unit& u, int wr, int wc, int fr, int fq) const {
;     ...
; #pragma unroll
;                 for (int bj = 0; bj < 2; ++bj) {
;                     const v4i_t i0 = __builtin_bit_cast(v4i_t, acc[ai][bj][m][0]) + ov[bj * 2], i1 = __builtin_bit_cast(v4i_t, acc[ai][bj][m][1]) + ov[bj * 2 + 1];
;                     const u32x4 c0_ = cv[bj * 2], c1_ = cv[bj * 2 + 1];
;                     f32x4 v0, v1;
; #pragma unroll
;                     for (int j = 0; j < 4; ++j) { v0[j] = (float)i0[j] * (sr * __uint_as_float(c0_[j])); v1[j] = (float)i1[j] * (sr * __uint_as_float(c1_[j])); }
;                     s += (v0[0] * v0[0] + v0[1] * v0[1]) + (v0[2] * v0[2] + v0[3] * v0[3]) + (v1[0] * v1[0] + v1[1] * v1[1]) + (v1[2] * v1[2] + v1[3] * v1[3]);
;                     pk[bj] = pack8(v0, v1);
;                 }
;                 if (u.ks >= 0) store_pair((bf16_t*)yp + ((size_t)u.ks * MS + (rowg - MP) + ai * HALF + m * 16) * DM + colw, DM, fr, fq, pk[0], pk[1]);
;                 else {
;                     store_pair(Y + (size_t)(rowg + ai * HALF + m * 16) * DM + colw, DM, fr, fq, pk[0], pk[1]);
;                     s += __shfl_xor(s, 16); s += __shfl_xor(s, 32);
;                     if (fq == 0) ssy[(size_t)row * 32 + u.pn * 4 + wc] = s;
;                 }
.LBB0_1583:
	v_add_u32_e32 v144, v78, v144
	v_add_u32_e32 v145, v79, v145
	v_cvt_f32_i32_e32 v145, v145
	v_cvt_f32_i32_e32 v144, v144
	v_mul_f32_e32 v156, 0x38018388, v194
	v_pk_mul_f32 v[152:153], v[66:67], v[156:157] op_sel_hi:[1,0]
	v_add_u32_e32 v149, v80, v146
	s_waitcnt lgkmcnt(0)
	v_add_u32_e32 v151, v81, v147
	v_pk_mul_f32 v[144:145], v[152:153], v[144:145]
	v_cvt_f32_i32_e32 v153, v151
	v_cvt_f32_i32_e32 v152, v149
	v_add_u32_e32 v136, v74, v136
	v_add_u32_e32 v137, v75, v137
	v_cvt_f32_i32_e32 v137, v137
	v_cvt_f32_i32_e32 v136, v136
	v_pk_mul_f32 v[154:155], v[62:63], v[156:157] op_sel_hi:[1,0]
	v_add_u32_e32 v157, v72, v142
	v_add_u32_e32 v158, v73, v143
	v_pk_mul_f32 v[142:143], v[68:69], v[156:157] op_sel_hi:[1,0]
	v_add_u32_e32 v149, v76, v138
	v_pk_mul_f32 v[142:143], v[142:143], v[152:153]
	v_cvt_f32_i32_e32 v153, v158
	v_pk_mul_f32 v[158:159], v[54:55], v[156:157] op_sel_hi:[1,0]
	v_add_u32_e32 v151, v77, v139
	v_pk_mul_f32 v[146:147], v[64:65], v[156:157] op_sel_hi:[1,0]
	v_cvt_f32_i32_e32 v152, v157
	v_pk_mul_f32 v[160:161], v[50:51], v[156:157] op_sel_hi:[1,0]
	v_pk_mul_f32 v[136:137], v[158:159], v[136:137]
	v_add_u32_e32 v158, v60, v134
	v_add_u32_e32 v159, v61, v135
	v_pk_mul_f32 v[134:135], v[56:57], v[156:157] op_sel_hi:[1,0]
	v_pk_mul_f32 v[138:139], v[52:53], v[156:157] op_sel_hi:[1,0]
	v_cvt_f32_i32_e32 v157, v151
	v_cvt_f32_i32_e32 v156, v149
	v_add_u32_e32 v140, v70, v140
	v_add_u32_e32 v141, v71, v141
	v_add_u32_e32 v132, v58, v132
	v_add_u32_e32 v133, v59, v133
	v_cvt_f32_i32_e32 v141, v141
	v_cvt_f32_i32_e32 v140, v140
	v_cvt_f32_i32_e32 v133, v133
	v_cvt_f32_i32_e32 v132, v132
	v_pk_mul_f32 v[134:135], v[134:135], v[156:157]
	v_cvt_f32_i32_e32 v157, v159
	v_cvt_f32_i32_e32 v156, v158
	v_pk_mul_f32 v[140:141], v[154:155], v[140:141]
	v_pk_mul_f32 v[146:147], v[146:147], v[152:153]
	v_pk_mul_f32 v[132:133], v[160:161], v[132:133]
	v_pk_mul_f32 v[138:139], v[138:139], v[156:157]
	v_cvt_pk_bf16_f32 v152, v144, v145
	v_cvt_pk_bf16_f32 v153, v142, v143
	v_cvt_pk_bf16_f32 v154, v140, v141
	v_cvt_pk_bf16_f32 v155, v146, v147
	v_cvt_pk_bf16_f32 v156, v136, v137
	v_cvt_pk_bf16_f32 v157, v134, v135
	v_cvt_pk_bf16_f32 v158, v132, v133
	v_cvt_pk_bf16_f32 v159, v138, v139
	v_cndmask_b32_e64 v149, 0, 1, s[42:43]
	s_mov_b64 s[44:45], -1
	v_cmp_ne_u32_e64 s[56:57], 1, v149
	s_andn2_b64 vcc, exec, s[42:43]
	v_cndmask_b32_e64 v163, v152, v156, s[52:53]
	v_cndmask_b32_e64 v162, v153, v157, s[52:53]
	v_cndmask_b32_e64 v161, v154, v158, s[52:53]
	v_cndmask_b32_e64 v160, v155, v159, s[52:53]
	s_cbranch_vccnz .LBB0_1587
	v_pk_mul_f32 v[136:137], v[136:137], v[136:137]
	v_pk_mul_f32 v[134:135], v[134:135], v[134:135]
	v_pk_mul_f32 v[132:133], v[132:133], v[132:133]
	v_add_f32_e32 v134, v134, v135
	v_add_f32_e32 v135, v136, v137
	s_or_b32 s22, s0, 16
	v_pk_mul_f32 v[138:139], v[138:139], v[138:139]
	v_add_f32_e32 v134, v135, v134
	v_add_f32_e32 v132, v132, v133
	s_ashr_i32 s23, s22, 31
	v_pk_mul_f32 v[144:145], v[144:145], v[144:145]
	v_pk_mul_f32 v[142:143], v[142:143], v[142:143]
	v_add_f32_e32 v132, v132, v134
	v_add_f32_e32 v133, v138, v139
	s_lshl_b64 s[22:23], s[22:23], 12
	v_readlane_b32 s1, v249, 28
	v_pk_mul_f32 v[140:141], v[140:141], v[140:141]
	v_add_f32_e32 v132, v133, v132
	v_add_f32_e32 v133, v142, v143
	v_add_f32_e32 v134, v144, v145
	s_add_u32 s1, s1, s22
	v_readlane_b32 s14, v253, 5
	v_and_b32_e32 v144, 64, v204
	v_pk_mul_f32 v[146:147], v[146:147], v[146:147]
	v_add_f32_e32 v133, v134, v133
	v_add_f32_e32 v134, v140, v141
	s_addc_u32 s14, s14, s23
	s_lshl_b64 s[22:23], s[82:83], 1
	v_xor_b32_e32 v143, 16, v204
	v_add_u32_e32 v144, 64, v144
	v_add_f32_e32 v133, v134, v133
	v_add_f32_e32 v134, v146, v147
	s_add_u32 s22, s1, s22
	v_cmp_lt_i32_e32 vcc, v143, v144
	v_add_f32_e32 v133, v134, v133
	s_addc_u32 s23, s14, s23
	v_cndmask_b32_e32 v143, v204, v143, vcc
	v_add_f32_e32 v142, v133, v132
	v_mov_b32_e32 v136, v131
	v_mov_b32_e32 v137, v131
	v_mov_b32_e32 v138, v131
	v_mov_b32_e32 v139, v131
	v_lshl_add_u64 v[140:141], s[22:23], 0, v[130:131]
	v_mov_b32_e32 v151, v131
	v_lshlrev_b32_e32 v143, 2, v143
	v_mov_b32_dpp v136, v163 row_ror:8 row_mask:0xf bank_mask:0xf
	v_mov_b32_dpp v137, v162 row_ror:8 row_mask:0xf bank_mask:0xf
	v_mov_b32_dpp v138, v161 row_ror:8 row_mask:0xf bank_mask:0xf
	v_mov_b32_dpp v139, v160 row_ror:8 row_mask:0xf bank_mask:0xf
	ds_bpermute_b32 v143, v143, v142
	v_lshl_add_u64 v[140:141], v[140:141], 0, v[150:151]
	v_mov_b32_e32 v149, v131
	v_cndmask_b32_e64 v132, v136, v152, s[52:53]
	v_cndmask_b32_e64 v133, v137, v153, s[52:53]
	v_cndmask_b32_e64 v134, v138, v154, s[52:53]
	v_cndmask_b32_e64 v135, v139, v155, s[52:53]
	v_lshl_add_u64 v[140:141], v[140:141], 0, v[148:149]
	global_store_dwordx4 v[140:141], v[132:135], off sc1
	v_cndmask_b32_e64 v136, v156, v136, s[52:53]
	v_cndmask_b32_e64 v137, v157, v137, s[52:53]
	v_xor_b32_e32 v133, 32, v204
	v_cmp_lt_i32_e32 vcc, v133, v144
	s_waitcnt lgkmcnt(0)
	v_add_f32_e32 v132, v142, v143
	v_cndmask_b32_e64 v138, v158, v138, s[52:53]
	v_cndmask_b32_e32 v133, v204, v133, vcc
	v_lshlrev_b32_e32 v133, 2, v133
	ds_bpermute_b32 v133, v133, v132
	v_add_co_u32_e32 v134, vcc, s46, v140
	v_cndmask_b32_e64 v139, v159, v139, s[52:53]
	s_nop 0
	v_addc_co_u32_e32 v135, vcc, 0, v141, vcc
	global_store_dwordx4 v[134:135], v[136:139], off sc1
	s_and_saveexec_b64 s[42:43], s[54:55]
	s_cbranch_execz .LBB0_1586
	v_or_b32_e32 v134, 16, v182
	v_ashrrev_i32_e32 v135, 31, v134
	v_readlane_b32 s44, v253, 6
	s_waitcnt lgkmcnt(0)
	v_add_f32_e32 v136, v132, v133
	s_lshl_b32 s22, s21, 2
	v_lshlrev_b64 v[132:133], 7, v[134:135]
	v_readlane_b32 s45, v253, 7
	s_ashr_i32 s23, s22, 31
	s_lshl_b32 s80, s38, 2
	v_lshl_add_u64 v[132:133], s[44:45], 0, v[132:133]
	v_lshl_add_u64 v[132:133], s[22:23], 2, v[132:133]
	v_lshl_add_u64 v[132:133], v[132:133], 0, s[80:81]
	global_store_dword v[132:133], v136, off

; __device__ __forceinline__ u32x4 pack8(f32x4 a, f32x4 b) { u32x4 w; w.x = cvtpk(a[0], a[1]); w.y = cvtpk(a[2], a[3]); w.z = cvtpk(b[0], b[1]); w.w = cvtpk(b[2], b[3]); return w; }
;     __device__ __forceinline__ void operator()(f32x4 (&acc)[2][2][4][2], const Unit& u, int wr, int wc, int fr, int fq) const {
;     ...
;                     pk[bj] = pack8(v0, v1);
;                 }
;                 if (u.ks >= 0) store_pair((bf16_t*)yp + ((size_t)u.ks * MS + (rowg - MP) + ai * HALF + m * 16) * DM + colw, DM, fr, fq, pk[0], pk[1]);
.LBB0_1587:
	s_andn2_b64 vcc, exec, s[44:45]
	s_cbranch_vccnz .LBB0_1589
	s_mov_b32 s63, s81
	s_lshl_b64 s[22:23], s[62:63], 22
	s_lshl_b64 s[42:43], s[40:41], 12
	s_add_u32 s1, s88, s22
	s_addc_u32 s14, s89, s23
	s_add_u32 s1, s1, s42
	s_addc_u32 s14, s14, s43
	s_lshl_b64 s[22:23], s[82:83], 1
	s_add_u32 s22, s1, s22
	s_addc_u32 s23, s14, s23
	v_lshl_add_u64 v[140:141], s[22:23], 0, v[130:131]
	v_mov_b32_e32 v151, v131
	v_lshl_add_u64 v[140:141], v[140:141], 0, v[150:151]
	v_mov_b32_e32 v149, v131
	v_mov_b32_e32 v136, v131
	v_mov_b32_e32 v137, v131
	v_mov_b32_e32 v138, v131
	v_mov_b32_e32 v139, v131
	v_lshl_add_u64 v[140:141], v[140:141], 0, v[148:149]
	v_mov_b32_dpp v136, v163 row_ror:8 row_mask:0xf bank_mask:0xf
	v_mov_b32_dpp v137, v162 row_ror:8 row_mask:0xf bank_mask:0xf
	v_mov_b32_dpp v138, v161 row_ror:8 row_mask:0xf bank_mask:0xf
	v_mov_b32_dpp v139, v160 row_ror:8 row_mask:0xf bank_mask:0xf
	v_add_co_u32_e32 v142, vcc, 0x10000, v140
	v_cndmask_b32_e64 v132, v136, v152, s[52:53]
	s_waitcnt lgkmcnt(0)
	v_cndmask_b32_e64 v133, v137, v153, s[52:53]
	v_cndmask_b32_e64 v134, v138, v154, s[52:53]
	v_cndmask_b32_e64 v135, v139, v155, s[52:53]
	v_addc_co_u32_e32 v143, vcc, 0, v141, vcc
	global_store_dwordx4 v[142:143], v[132:135], off sc1
	v_cndmask_b32_e64 v136, v156, v136, s[52:53]
	v_cndmask_b32_e64 v137, v157, v137, s[52:53]
	v_add_co_u32_e32 v132, vcc, 0x18000, v140
	v_cndmask_b32_e64 v138, v158, v138, s[52:53]
	v_cndmask_b32_e64 v139, v159, v139, s[52:53]
	v_addc_co_u32_e32 v133, vcc, 0, v141, vcc
	global_store_dwordx4 v[132:133], v[136:139], off sc1
; __device__ __forceinline__ u32x4 pack8(f32x4 a, f32x4 b) { u32x4 w; w.x = cvtpk(a[0], a[1]); w.y = cvtpk(a[2], a[3]); w.z = cvtpk(b[0], b[1]); w.w = cvtpk(b[2], b[3]); return w; }
;     __device__ __forceinline__ void operator()(f32x4 (&acc)[2][2][4][2], const Unit& u, int wr, int wc, int fr, int fq) const {
;     ...
; #pragma unroll
;                 for (int bj = 0; bj < 2; ++bj) {
;                     const v4i_t i0 = __builtin_bit_cast(v4i_t, acc[ai][bj][m][0]) + ov[bj * 2], i1 = __builtin_bit_cast(v4i_t, acc[ai][bj][m][1]) + ov[bj * 2 + 1];
;                     const u32x4 c0_ = cv[bj * 2], c1_ = cv[bj * 2 + 1];
;                     f32x4 v0, v1;
; #pragma unroll
;                     for (int j = 0; j < 4; ++j) { v0[j] = (float)i0[j] * (sr * __uint_as_float(c0_[j])); v1[j] = (float)i1[j] * (sr * __uint_as_float(c1_[j])); }
;                     s += (v0[0] * v0[0] + v0[1] * v0[1]) + (v0[2] * v0[2] + v0[3] * v0[3]) + (v1[0] * v1[0] + v1[1] * v1[1]) + (v1[2] * v1[2] + v1[3] * v1[3]);
;                     pk[bj] = pack8(v0, v1);
;                 }
;                 if (u.ks >= 0) store_pair((bf16_t*)yp + ((size_t)u.ks * MS + (rowg - MP) + ai * HALF + m * 16) * DM + colw, DM, fr, fq, pk[0], pk[1]);
;                 else {
;                     store_pair(Y + (size_t)(rowg + ai * HALF + m * 16) * DM + colw, DM, fr, fq, pk[0], pk[1]);
;                     s += __shfl_xor(s, 16); s += __shfl_xor(s, 32);
;                     if (fq == 0) ssy[(size_t)row * 32 + u.pn * 4 + wc] = s;
;                 }
.LBB0_1589:
	v_add_u32_e32 v126, v78, v126
	v_add_u32_e32 v127, v79, v127
	v_cvt_f32_i32_e32 v127, v127
	v_cvt_f32_i32_e32 v126, v126
	v_mul_f32_e32 v136, 0x38018388, v193
	s_waitcnt lgkmcnt(0)
	v_pk_mul_f32 v[132:133], v[66:67], v[136:137] op_sel_hi:[1,0]
	v_pk_mul_f32 v[134:135], v[62:63], v[136:137] op_sel_hi:[1,0]
	v_add_u32_e32 v137, v80, v128
	v_add_u32_e32 v138, v81, v129
	v_pk_mul_f32 v[126:127], v[132:133], v[126:127]
	v_cvt_f32_i32_e32 v133, v138
	v_cvt_f32_i32_e32 v132, v137
	v_add_u32_e32 v118, v74, v118
	v_add_u32_e32 v119, v75, v119
	v_cvt_f32_i32_e32 v119, v119
	v_cvt_f32_i32_e32 v118, v118
	v_add_u32_e32 v139, v72, v124
	v_add_u32_e32 v140, v73, v125
	v_pk_mul_f32 v[124:125], v[68:69], v[136:137] op_sel_hi:[1,0]
	v_pk_mul_f32 v[128:129], v[64:65], v[136:137] op_sel_hi:[1,0]
	v_pk_mul_f32 v[124:125], v[124:125], v[132:133]
	v_cvt_f32_i32_e32 v133, v140
	v_cvt_f32_i32_e32 v132, v139
	v_pk_mul_f32 v[138:139], v[54:55], v[136:137] op_sel_hi:[1,0]
	v_pk_mul_f32 v[140:141], v[50:51], v[136:137] op_sel_hi:[1,0]
	v_add_u32_e32 v142, v76, v120
	v_add_u32_e32 v137, v77, v121
	v_pk_mul_f32 v[118:119], v[138:139], v[118:119]
	v_add_u32_e32 v138, v60, v116
	v_add_u32_e32 v139, v61, v117
	v_pk_mul_f32 v[116:117], v[56:57], v[136:137] op_sel_hi:[1,0]
	v_pk_mul_f32 v[120:121], v[52:53], v[136:137] op_sel_hi:[1,0]
	v_cvt_f32_i32_e32 v137, v137
	v_cvt_f32_i32_e32 v136, v142
	v_add_u32_e32 v122, v70, v122
	v_add_u32_e32 v123, v71, v123
	v_add_u32_e32 v114, v58, v114
	v_add_u32_e32 v115, v59, v115
	v_cvt_f32_i32_e32 v123, v123
	v_cvt_f32_i32_e32 v122, v122
	v_cvt_f32_i32_e32 v115, v115
	v_cvt_f32_i32_e32 v114, v114
	v_pk_mul_f32 v[116:117], v[116:117], v[136:137]
	v_cvt_f32_i32_e32 v137, v139
	v_cvt_f32_i32_e32 v136, v138
	v_pk_mul_f32 v[122:123], v[134:135], v[122:123]
	v_pk_mul_f32 v[128:129], v[128:129], v[132:133]
	v_pk_mul_f32 v[114:115], v[140:141], v[114:115]
	v_pk_mul_f32 v[120:121], v[120:121], v[136:137]
	v_cvt_pk_bf16_f32 v132, v126, v127
	v_cvt_pk_bf16_f32 v133, v124, v125
	v_cvt_pk_bf16_f32 v134, v122, v123
	v_cvt_pk_bf16_f32 v135, v128, v129
	v_cvt_pk_bf16_f32 v136, v118, v119
	v_cvt_pk_bf16_f32 v137, v116, v117
	v_cvt_pk_bf16_f32 v138, v114, v115
	v_cvt_pk_bf16_f32 v139, v120, v121
	s_mov_b64 s[42:43], -1
	s_and_b64 vcc, exec, s[56:57]
	v_cndmask_b32_e64 v143, v132, v136, s[52:53]
	v_cndmask_b32_e64 v142, v133, v137, s[52:53]
	v_cndmask_b32_e64 v141, v134, v138, s[52:53]
	v_cndmask_b32_e64 v140, v135, v139, s[52:53]
	s_cbranch_vccnz .LBB0_1593
	v_pk_mul_f32 v[118:119], v[118:119], v[118:119]
	v_pk_mul_f32 v[116:117], v[116:117], v[116:117]
	v_pk_mul_f32 v[114:115], v[114:115], v[114:115]
	v_add_f32_e32 v116, v116, v117
	v_add_f32_e32 v117, v118, v119
	s_or_b32 s22, s0, 32
	v_pk_mul_f32 v[120:121], v[120:121], v[120:121]
	v_add_f32_e32 v116, v117, v116
	v_add_f32_e32 v114, v114, v115
	s_ashr_i32 s23, s22, 31
	v_pk_mul_f32 v[126:127], v[126:127], v[126:127]
	v_pk_mul_f32 v[124:125], v[124:125], v[124:125]
	v_add_f32_e32 v114, v114, v116
	v_add_f32_e32 v115, v120, v121
	s_lshl_b64 s[22:23], s[22:23], 12
	v_readlane_b32 s1, v249, 28
	v_pk_mul_f32 v[122:123], v[122:123], v[122:123]
	v_add_f32_e32 v114, v115, v114
	v_add_f32_e32 v115, v124, v125
	v_add_f32_e32 v116, v126, v127
	s_add_u32 s1, s1, s22
	v_readlane_b32 s14, v253, 5
	v_and_b32_e32 v126, 64, v204
	v_pk_mul_f32 v[128:129], v[128:129], v[128:129]
	v_add_f32_e32 v115, v116, v115
	v_add_f32_e32 v116, v122, v123
	s_addc_u32 s14, s14, s23
	s_lshl_b64 s[22:23], s[82:83], 1
	v_xor_b32_e32 v125, 16, v204
	v_add_u32_e32 v126, 64, v126
	v_add_f32_e32 v115, v116, v115
	v_add_f32_e32 v116, v128, v129
	s_add_u32 s22, s1, s22
	v_cmp_lt_i32_e32 vcc, v125, v126
	v_add_f32_e32 v115, v116, v115
	s_addc_u32 s23, s14, s23
	v_cndmask_b32_e32 v125, v204, v125, vcc
	v_add_f32_e32 v124, v115, v114
	v_mov_b32_e32 v118, v131
	v_mov_b32_e32 v119, v131
	v_mov_b32_e32 v120, v131
	v_mov_b32_e32 v121, v131
	v_lshl_add_u64 v[122:123], s[22:23], 0, v[130:131]
	v_mov_b32_e32 v151, v131
	v_lshlrev_b32_e32 v125, 2, v125
	v_mov_b32_dpp v118, v143 row_ror:8 row_mask:0xf bank_mask:0xf
	v_mov_b32_dpp v119, v142 row_ror:8 row_mask:0xf bank_mask:0xf
	v_mov_b32_dpp v120, v141 row_ror:8 row_mask:0xf bank_mask:0xf
	v_mov_b32_dpp v121, v140 row_ror:8 row_mask:0xf bank_mask:0xf
	ds_bpermute_b32 v125, v125, v124
	v_lshl_add_u64 v[122:123], v[122:123], 0, v[150:151]
	v_mov_b32_e32 v149, v131
	v_cndmask_b32_e64 v114, v118, v132, s[52:53]
	v_cndmask_b32_e64 v115, v119, v133, s[52:53]
	v_cndmask_b32_e64 v116, v120, v134, s[52:53]
	v_cndmask_b32_e64 v117, v121, v135, s[52:53]
	v_lshl_add_u64 v[122:123], v[122:123], 0, v[148:149]
	global_store_dwordx4 v[122:123], v[114:117], off sc1
	v_cndmask_b32_e64 v118, v136, v118, s[52:53]
	v_cndmask_b32_e64 v119, v137, v119, s[52:53]
	v_xor_b32_e32 v115, 32, v204
	v_cmp_lt_i32_e32 vcc, v115, v126
	s_waitcnt lgkmcnt(0)
	v_add_f32_e32 v114, v124, v125
	v_cndmask_b32_e64 v120, v138, v120, s[52:53]
	v_cndmask_b32_e32 v115, v204, v115, vcc
	v_lshlrev_b32_e32 v115, 2, v115
	ds_bpermute_b32 v115, v115, v114
	v_add_co_u32_e32 v116, vcc, s46, v122
	v_cndmask_b32_e64 v121, v139, v121, s[52:53]
	s_nop 0
	v_addc_co_u32_e32 v117, vcc, 0, v123, vcc
	global_store_dwordx4 v[116:117], v[118:121], off sc1
	s_and_saveexec_b64 s[42:43], s[54:55]
	s_cbranch_execz .LBB0_1592
	v_or_b32_e32 v116, 32, v182
	v_ashrrev_i32_e32 v117, 31, v116
	v_readlane_b32 s44, v253, 6
	s_waitcnt lgkmcnt(0)
	v_add_f32_e32 v118, v114, v115
	s_lshl_b32 s22, s21, 2
	v_lshlrev_b64 v[114:115], 7, v[116:117]
	v_readlane_b32 s45, v253, 7
	s_ashr_i32 s23, s22, 31
	s_lshl_b32 s80, s38, 2
	v_lshl_add_u64 v[114:115], s[44:45], 0, v[114:115]
	v_lshl_add_u64 v[114:115], s[22:23], 2, v[114:115]
	v_lshl_add_u64 v[114:115], v[114:115], 0, s[80:81]
	global_store_dword v[114:115], v118, off

; __device__ __forceinline__ u32x4 pack8(f32x4 a, f32x4 b) { u32x4 w; w.x = cvtpk(a[0], a[1]); w.y = cvtpk(a[2], a[3]); w.z = cvtpk(b[0], b[1]); w.w = cvtpk(b[2], b[3]); return w; }
;     __device__ __forceinline__ void operator()(f32x4 (&acc)[2][2][4][2], const Unit& u, int wr, int wc, int fr, int fq) const {
;     ...
;                     pk[bj] = pack8(v0, v1);
;                 }
;                 if (u.ks >= 0) store_pair((bf16_t*)yp + ((size_t)u.ks * MS + (rowg - MP) + ai * HALF + m * 16) * DM + colw, DM, fr, fq, pk[0], pk[1]);
.LBB0_1593:
	s_andn2_b64 vcc, exec, s[42:43]
	s_cbranch_vccnz .LBB0_1595
	s_mov_b32 s63, s81
	s_lshl_b64 s[22:23], s[62:63], 22
	s_lshl_b64 s[42:43], s[40:41], 12
	s_add_u32 s1, s88, s22
	s_addc_u32 s14, s89, s23
	s_add_u32 s1, s1, s42
	s_addc_u32 s14, s14, s43
	s_lshl_b64 s[22:23], s[82:83], 1
	s_add_u32 s22, s1, s22
	s_addc_u32 s23, s14, s23
	v_lshl_add_u64 v[122:123], s[22:23], 0, v[130:131]
	v_mov_b32_e32 v151, v131
	v_lshl_add_u64 v[122:123], v[122:123], 0, v[150:151]
	v_mov_b32_e32 v149, v131
	v_mov_b32_e32 v118, v131
	v_mov_b32_e32 v119, v131
	v_mov_b32_e32 v120, v131
	v_mov_b32_e32 v121, v131
	v_lshl_add_u64 v[122:123], v[122:123], 0, v[148:149]
	v_mov_b32_dpp v118, v143 row_ror:8 row_mask:0xf bank_mask:0xf
	v_mov_b32_dpp v119, v142 row_ror:8 row_mask:0xf bank_mask:0xf
	v_mov_b32_dpp v120, v141 row_ror:8 row_mask:0xf bank_mask:0xf
	v_mov_b32_dpp v121, v140 row_ror:8 row_mask:0xf bank_mask:0xf
	v_add_co_u32_e32 v124, vcc, 0x20000, v122
	v_cndmask_b32_e64 v114, v118, v132, s[52:53]
	s_waitcnt lgkmcnt(0)
	v_cndmask_b32_e64 v115, v119, v133, s[52:53]
	v_cndmask_b32_e64 v116, v120, v134, s[52:53]
	v_cndmask_b32_e64 v117, v121, v135, s[52:53]
	v_addc_co_u32_e32 v125, vcc, 0, v123, vcc
	global_store_dwordx4 v[124:125], v[114:117], off sc1
	v_cndmask_b32_e64 v118, v136, v118, s[52:53]
	v_cndmask_b32_e64 v119, v137, v119, s[52:53]
	v_add_co_u32_e32 v114, vcc, 0x28000, v122
	v_cndmask_b32_e64 v120, v138, v120, s[52:53]
	v_cndmask_b32_e64 v121, v139, v121, s[52:53]
	v_addc_co_u32_e32 v115, vcc, 0, v123, vcc
	global_store_dwordx4 v[114:115], v[118:121], off sc1
; __device__ __forceinline__ u32x4 pack8(f32x4 a, f32x4 b) { u32x4 w; w.x = cvtpk(a[0], a[1]); w.y = cvtpk(a[2], a[3]); w.z = cvtpk(b[0], b[1]); w.w = cvtpk(b[2], b[3]); return w; }
;     __device__ __forceinline__ void operator()(f32x4 (&acc)[2][2][4][2], const Unit& u, int wr, int wc, int fr, int fq) const {
;     ...
; #pragma unroll
;                 for (int bj = 0; bj < 2; ++bj) {
;                     const v4i_t i0 = __builtin_bit_cast(v4i_t, acc[ai][bj][m][0]) + ov[bj * 2], i1 = __builtin_bit_cast(v4i_t, acc[ai][bj][m][1]) + ov[bj * 2 + 1];
;                     const u32x4 c0_ = cv[bj * 2], c1_ = cv[bj * 2 + 1];
;                     f32x4 v0, v1;
; #pragma unroll
;                     for (int j = 0; j < 4; ++j) { v0[j] = (float)i0[j] * (sr * __uint_as_float(c0_[j])); v1[j] = (float)i1[j] * (sr * __uint_as_float(c1_[j])); }
;                     s += (v0[0] * v0[0] + v0[1] * v0[1]) + (v0[2] * v0[2] + v0[3] * v0[3]) + (v1[0] * v1[0] + v1[1] * v1[1]) + (v1[2] * v1[2] + v1[3] * v1[3]);
;                     pk[bj] = pack8(v0, v1);
;                 }
;                 if (u.ks >= 0) store_pair((bf16_t*)yp + ((size_t)u.ks * MS + (rowg - MP) + ai * HALF + m * 16) * DM + colw, DM, fr, fq, pk[0], pk[1]);
;                 else {
;                     store_pair(Y + (size_t)(rowg + ai * HALF + m * 16) * DM + colw, DM, fr, fq, pk[0], pk[1]);
;                     s += __shfl_xor(s, 16); s += __shfl_xor(s, 32);
;                     if (fq == 0) ssy[(size_t)row * 32 + u.pn * 4 + wc] = s;
;                 }
.LBB0_1595:
	v_add_u32_e32 v110, v78, v110
	v_add_u32_e32 v111, v79, v111
	v_cvt_f32_i32_e32 v111, v111
	v_cvt_f32_i32_e32 v110, v110
	v_mul_f32_e32 v118, 0x38018388, v192
	s_waitcnt lgkmcnt(0)
	v_pk_mul_f32 v[114:115], v[66:67], v[118:119] op_sel_hi:[1,0]
	v_pk_mul_f32 v[116:117], v[62:63], v[118:119] op_sel_hi:[1,0]
	v_add_u32_e32 v119, v80, v112
	v_add_u32_e32 v120, v81, v113
	v_pk_mul_f32 v[110:111], v[114:115], v[110:111]
	v_cvt_f32_i32_e32 v115, v120
	v_cvt_f32_i32_e32 v114, v119
	v_add_u32_e32 v102, v74, v102
	v_add_u32_e32 v103, v75, v103
	v_cvt_f32_i32_e32 v103, v103
	v_cvt_f32_i32_e32 v102, v102
	v_add_u32_e32 v121, v72, v108
	v_add_u32_e32 v122, v73, v109
	v_pk_mul_f32 v[108:109], v[68:69], v[118:119] op_sel_hi:[1,0]
	v_pk_mul_f32 v[112:113], v[64:65], v[118:119] op_sel_hi:[1,0]
	v_pk_mul_f32 v[108:109], v[108:109], v[114:115]
	v_cvt_f32_i32_e32 v115, v122
	v_cvt_f32_i32_e32 v114, v121
	v_pk_mul_f32 v[120:121], v[54:55], v[118:119] op_sel_hi:[1,0]
	v_pk_mul_f32 v[122:123], v[50:51], v[118:119] op_sel_hi:[1,0]
	v_add_u32_e32 v124, v76, v104
	v_add_u32_e32 v119, v77, v105
	v_pk_mul_f32 v[102:103], v[120:121], v[102:103]
	v_add_u32_e32 v120, v60, v100
	v_add_u32_e32 v121, v61, v101
	v_pk_mul_f32 v[100:101], v[56:57], v[118:119] op_sel_hi:[1,0]
	v_pk_mul_f32 v[104:105], v[52:53], v[118:119] op_sel_hi:[1,0]
	v_cvt_f32_i32_e32 v119, v119
	v_cvt_f32_i32_e32 v118, v124
	v_add_u32_e32 v106, v70, v106
	v_add_u32_e32 v107, v71, v107
	v_add_u32_e32 v98, v58, v98
	v_add_u32_e32 v99, v59, v99
	v_cvt_f32_i32_e32 v107, v107
	v_cvt_f32_i32_e32 v106, v106
	v_cvt_f32_i32_e32 v99, v99
	v_cvt_f32_i32_e32 v98, v98
	v_pk_mul_f32 v[100:101], v[100:101], v[118:119]
	v_cvt_f32_i32_e32 v119, v121
	v_cvt_f32_i32_e32 v118, v120
	v_pk_mul_f32 v[106:107], v[116:117], v[106:107]
	v_pk_mul_f32 v[112:113], v[112:113], v[114:115]
	v_pk_mul_f32 v[98:99], v[122:123], v[98:99]
	v_pk_mul_f32 v[104:105], v[104:105], v[118:119]
	v_cvt_pk_bf16_f32 v114, v110, v111
	v_cvt_pk_bf16_f32 v115, v108, v109
	v_cvt_pk_bf16_f32 v116, v106, v107
	v_cvt_pk_bf16_f32 v117, v112, v113
	v_cvt_pk_bf16_f32 v118, v102, v103
	v_cvt_pk_bf16_f32 v119, v100, v101
	v_cvt_pk_bf16_f32 v120, v98, v99
	v_cvt_pk_bf16_f32 v121, v104, v105
	s_mov_b64 s[42:43], -1
	s_and_b64 vcc, exec, s[56:57]
	v_cndmask_b32_e64 v125, v114, v118, s[52:53]
	v_cndmask_b32_e64 v124, v115, v119, s[52:53]
	v_cndmask_b32_e64 v123, v116, v120, s[52:53]
	v_cndmask_b32_e64 v122, v117, v121, s[52:53]
	s_cbranch_vccnz .LBB0_1599
	v_pk_mul_f32 v[102:103], v[102:103], v[102:103]
	v_pk_mul_f32 v[100:101], v[100:101], v[100:101]
	v_pk_mul_f32 v[98:99], v[98:99], v[98:99]
	v_add_f32_e32 v100, v100, v101
	v_add_f32_e32 v101, v102, v103
	s_or_b32 s22, s0, 48
	v_pk_mul_f32 v[104:105], v[104:105], v[104:105]
	v_add_f32_e32 v100, v101, v100
	v_add_f32_e32 v98, v98, v99
	s_ashr_i32 s23, s22, 31
	v_pk_mul_f32 v[110:111], v[110:111], v[110:111]
	v_pk_mul_f32 v[108:109], v[108:109], v[108:109]
	v_add_f32_e32 v98, v98, v100
	v_add_f32_e32 v99, v104, v105
	s_lshl_b64 s[22:23], s[22:23], 12
	v_readlane_b32 s1, v249, 28
	v_pk_mul_f32 v[106:107], v[106:107], v[106:107]
	v_add_f32_e32 v98, v99, v98
	v_add_f32_e32 v99, v108, v109
	v_add_f32_e32 v100, v110, v111
	s_add_u32 s1, s1, s22
	v_readlane_b32 s14, v253, 5
	v_and_b32_e32 v110, 64, v204
	v_pk_mul_f32 v[112:113], v[112:113], v[112:113]
	v_add_f32_e32 v99, v100, v99
	v_add_f32_e32 v100, v106, v107
	s_addc_u32 s14, s14, s23
	s_lshl_b64 s[22:23], s[82:83], 1
	v_xor_b32_e32 v109, 16, v204
	v_add_u32_e32 v110, 64, v110
	v_add_f32_e32 v99, v100, v99
	v_add_f32_e32 v100, v112, v113
	s_add_u32 s22, s1, s22
	v_cmp_lt_i32_e32 vcc, v109, v110
	v_add_f32_e32 v99, v100, v99
	s_addc_u32 s23, s14, s23
	v_cndmask_b32_e32 v109, v204, v109, vcc
	v_add_f32_e32 v108, v99, v98
	v_mov_b32_e32 v102, v131
	v_mov_b32_e32 v103, v131
	v_mov_b32_e32 v104, v131
	v_mov_b32_e32 v105, v131
	v_lshl_add_u64 v[106:107], s[22:23], 0, v[130:131]
	v_mov_b32_e32 v151, v131
	v_lshlrev_b32_e32 v109, 2, v109
	v_mov_b32_dpp v102, v125 row_ror:8 row_mask:0xf bank_mask:0xf
	v_mov_b32_dpp v103, v124 row_ror:8 row_mask:0xf bank_mask:0xf
	v_mov_b32_dpp v104, v123 row_ror:8 row_mask:0xf bank_mask:0xf
	v_mov_b32_dpp v105, v122 row_ror:8 row_mask:0xf bank_mask:0xf
	ds_bpermute_b32 v109, v109, v108
	v_lshl_add_u64 v[106:107], v[106:107], 0, v[150:151]
	v_mov_b32_e32 v149, v131
	v_cndmask_b32_e64 v98, v102, v114, s[52:53]
	v_cndmask_b32_e64 v99, v103, v115, s[52:53]
	v_cndmask_b32_e64 v100, v104, v116, s[52:53]
	v_cndmask_b32_e64 v101, v105, v117, s[52:53]
	v_lshl_add_u64 v[106:107], v[106:107], 0, v[148:149]
	global_store_dwordx4 v[106:107], v[98:101], off sc1
	v_cndmask_b32_e64 v102, v118, v102, s[52:53]
	v_cndmask_b32_e64 v103, v119, v103, s[52:53]
	v_xor_b32_e32 v99, 32, v204
	v_cmp_lt_i32_e32 vcc, v99, v110
	s_waitcnt lgkmcnt(0)
	v_add_f32_e32 v98, v108, v109
	v_cndmask_b32_e64 v104, v120, v104, s[52:53]
	v_cndmask_b32_e32 v99, v204, v99, vcc
	v_lshlrev_b32_e32 v99, 2, v99
	ds_bpermute_b32 v99, v99, v98
	v_add_co_u32_e32 v100, vcc, s46, v106
	v_cndmask_b32_e64 v105, v121, v105, s[52:53]
	s_nop 0
	v_addc_co_u32_e32 v101, vcc, 0, v107, vcc
	global_store_dwordx4 v[100:101], v[102:105], off sc1
	s_and_saveexec_b64 s[42:43], s[54:55]
	s_cbranch_execz .LBB0_1598
	v_or_b32_e32 v100, 48, v182
	v_ashrrev_i32_e32 v101, 31, v100
	v_readlane_b32 s44, v253, 6
	s_waitcnt lgkmcnt(0)
	v_add_f32_e32 v102, v98, v99
	s_lshl_b32 s22, s21, 2
	v_lshlrev_b64 v[98:99], 7, v[100:101]
	v_readlane_b32 s45, v253, 7
	s_ashr_i32 s23, s22, 31
	s_lshl_b32 s80, s38, 2
	v_lshl_add_u64 v[98:99], s[44:45], 0, v[98:99]
	v_lshl_add_u64 v[98:99], s[22:23], 2, v[98:99]
	v_lshl_add_u64 v[98:99], v[98:99], 0, s[80:81]
	global_store_dword v[98:99], v102, off

; __device__ __forceinline__ u32x4 pack8(f32x4 a, f32x4 b) { u32x4 w; w.x = cvtpk(a[0], a[1]); w.y = cvtpk(a[2], a[3]); w.z = cvtpk(b[0], b[1]); w.w = cvtpk(b[2], b[3]); return w; }
;     __device__ __forceinline__ void operator()(f32x4 (&acc)[2][2][4][2], const Unit& u, int wr, int wc, int fr, int fq) const {
;     ...
;                     pk[bj] = pack8(v0, v1);
;                 }
;                 if (u.ks >= 0) store_pair((bf16_t*)yp + ((size_t)u.ks * MS + (rowg - MP) + ai * HALF + m * 16) * DM + colw, DM, fr, fq, pk[0], pk[1]);
.LBB0_1599:
	s_andn2_b64 vcc, exec, s[42:43]
	s_cbranch_vccnz .LBB0_1601
	s_mov_b32 s63, s81
	s_lshl_b64 s[22:23], s[62:63], 22
	s_lshl_b64 s[42:43], s[40:41], 12
	s_add_u32 s1, s88, s22
	s_addc_u32 s14, s89, s23
	s_add_u32 s1, s1, s42
	s_addc_u32 s14, s14, s43
	s_lshl_b64 s[22:23], s[82:83], 1
	s_add_u32 s22, s1, s22
	s_addc_u32 s23, s14, s23
	v_lshl_add_u64 v[106:107], s[22:23], 0, v[130:131]
	v_mov_b32_e32 v151, v131
	v_lshl_add_u64 v[106:107], v[106:107], 0, v[150:151]
	v_mov_b32_e32 v149, v131
	v_mov_b32_e32 v102, v131
	v_mov_b32_e32 v103, v131
	v_mov_b32_e32 v104, v131
	v_mov_b32_e32 v105, v131
	v_lshl_add_u64 v[106:107], v[106:107], 0, v[148:149]
	v_mov_b32_dpp v102, v125 row_ror:8 row_mask:0xf bank_mask:0xf
	v_mov_b32_dpp v103, v124 row_ror:8 row_mask:0xf bank_mask:0xf
	v_mov_b32_dpp v104, v123 row_ror:8 row_mask:0xf bank_mask:0xf
	v_mov_b32_dpp v105, v122 row_ror:8 row_mask:0xf bank_mask:0xf
	v_add_co_u32_e32 v108, vcc, 0x30000, v106
	v_cndmask_b32_e64 v98, v102, v114, s[52:53]
	s_waitcnt lgkmcnt(0)
	v_cndmask_b32_e64 v99, v103, v115, s[52:53]
	v_cndmask_b32_e64 v100, v104, v116, s[52:53]
	v_cndmask_b32_e64 v101, v105, v117, s[52:53]
	v_addc_co_u32_e32 v109, vcc, 0, v107, vcc
	global_store_dwordx4 v[108:109], v[98:101], off sc1
	v_cndmask_b32_e64 v102, v118, v102, s[52:53]
	v_cndmask_b32_e64 v103, v119, v103, s[52:53]
	v_add_co_u32_e32 v98, vcc, 0x38000, v106
	v_cndmask_b32_e64 v104, v120, v104, s[52:53]
	v_cndmask_b32_e64 v105, v121, v105, s[52:53]
	v_addc_co_u32_e32 v99, vcc, 0, v107, vcc
	global_store_dwordx4 v[98:99], v[102:105], off sc1
; __device__ __forceinline__ u32x4 pack8(f32x4 a, f32x4 b) { u32x4 w; w.x = cvtpk(a[0], a[1]); w.y = cvtpk(a[2], a[3]); w.z = cvtpk(b[0], b[1]); w.w = cvtpk(b[2], b[3]); return w; }
;     __device__ __forceinline__ void operator()(f32x4 (&acc)[2][2][4][2], const Unit& u, int wr, int wc, int fr, int fq) const {
;     ...
; #pragma unroll
;                 for (int bj = 0; bj < 2; ++bj) {
;                     const v4i_t i0 = __builtin_bit_cast(v4i_t, acc[ai][bj][m][0]) + ov[bj * 2], i1 = __builtin_bit_cast(v4i_t, acc[ai][bj][m][1]) + ov[bj * 2 + 1];
;                     const u32x4 c0_ = cv[bj * 2], c1_ = cv[bj * 2 + 1];
;                     f32x4 v0, v1;
; #pragma unroll
;                     for (int j = 0; j < 4; ++j) { v0[j] = (float)i0[j] * (sr * __uint_as_float(c0_[j])); v1[j] = (float)i1[j] * (sr * __uint_as_float(c1_[j])); }
;                     s += (v0[0] * v0[0] + v0[1] * v0[1]) + (v0[2] * v0[2] + v0[3] * v0[3]) + (v1[0] * v1[0] + v1[1] * v1[1]) + (v1[2] * v1[2] + v1[3] * v1[3]);
;                     pk[bj] = pack8(v0, v1);
;                 }
;                 if (u.ks >= 0) store_pair((bf16_t*)yp + ((size_t)u.ks * MS + (rowg - MP) + ai * HALF + m * 16) * DM + colw, DM, fr, fq, pk[0], pk[1]);
;                 else {
;                     store_pair(Y + (size_t)(rowg + ai * HALF + m * 16) * DM + colw, DM, fr, fq, pk[0], pk[1]);
;                     s += __shfl_xor(s, 16); s += __shfl_xor(s, 32);
;                     if (fq == 0) ssy[(size_t)row * 32 + u.pn * 4 + wc] = s;
;                 }
.LBB0_1601:
	v_add_u32_e32 v94, v78, v94
	v_add_u32_e32 v95, v79, v95
	v_cvt_f32_i32_e32 v95, v95
	v_cvt_f32_i32_e32 v94, v94
	v_mul_f32_e32 v102, 0x38018388, v191
	s_waitcnt lgkmcnt(0)
	v_pk_mul_f32 v[98:99], v[66:67], v[102:103] op_sel_hi:[1,0]
	v_pk_mul_f32 v[100:101], v[62:63], v[102:103] op_sel_hi:[1,0]
	v_add_u32_e32 v103, v80, v96
	v_add_u32_e32 v104, v81, v97
	v_pk_mul_f32 v[94:95], v[98:99], v[94:95]
	v_cvt_f32_i32_e32 v99, v104
	v_cvt_f32_i32_e32 v98, v103
	v_add_u32_e32 v86, v74, v86
	v_add_u32_e32 v87, v75, v87
	v_cvt_f32_i32_e32 v87, v87
	v_cvt_f32_i32_e32 v86, v86
	v_add_u32_e32 v105, v72, v92
	v_add_u32_e32 v106, v73, v93
	v_pk_mul_f32 v[92:93], v[68:69], v[102:103] op_sel_hi:[1,0]
	v_pk_mul_f32 v[96:97], v[64:65], v[102:103] op_sel_hi:[1,0]
	v_pk_mul_f32 v[92:93], v[92:93], v[98:99]
	v_cvt_f32_i32_e32 v99, v106
	v_cvt_f32_i32_e32 v98, v105
	v_pk_mul_f32 v[104:105], v[54:55], v[102:103] op_sel_hi:[1,0]
	v_pk_mul_f32 v[106:107], v[50:51], v[102:103] op_sel_hi:[1,0]
	v_add_u32_e32 v108, v76, v88
	v_add_u32_e32 v103, v77, v89
	v_pk_mul_f32 v[86:87], v[104:105], v[86:87]
	v_add_u32_e32 v104, v60, v84
	v_add_u32_e32 v105, v61, v85
	v_pk_mul_f32 v[84:85], v[56:57], v[102:103] op_sel_hi:[1,0]
	v_pk_mul_f32 v[88:89], v[52:53], v[102:103] op_sel_hi:[1,0]
	v_cvt_f32_i32_e32 v103, v103
	v_cvt_f32_i32_e32 v102, v108
	v_add_u32_e32 v90, v70, v90
	v_add_u32_e32 v91, v71, v91
	v_add_u32_e32 v82, v58, v82
	v_add_u32_e32 v83, v59, v83
	v_cvt_f32_i32_e32 v91, v91
	v_cvt_f32_i32_e32 v90, v90
	v_cvt_f32_i32_e32 v83, v83
	v_cvt_f32_i32_e32 v82, v82
	v_pk_mul_f32 v[84:85], v[84:85], v[102:103]
	v_cvt_f32_i32_e32 v103, v105
	v_cvt_f32_i32_e32 v102, v104
	v_pk_mul_f32 v[90:91], v[100:101], v[90:91]
	v_pk_mul_f32 v[96:97], v[96:97], v[98:99]
	v_pk_mul_f32 v[82:83], v[106:107], v[82:83]
	v_pk_mul_f32 v[88:89], v[88:89], v[102:103]
	v_cvt_pk_bf16_f32 v98, v94, v95
	v_cvt_pk_bf16_f32 v99, v92, v93
	v_cvt_pk_bf16_f32 v100, v90, v91
	v_cvt_pk_bf16_f32 v101, v96, v97
	v_cvt_pk_bf16_f32 v102, v86, v87
	v_cvt_pk_bf16_f32 v103, v84, v85
	v_cvt_pk_bf16_f32 v104, v82, v83
	v_cvt_pk_bf16_f32 v105, v88, v89
	s_mov_b64 s[42:43], -1
	s_and_b64 vcc, exec, s[56:57]
	v_cndmask_b32_e64 v109, v98, v102, s[52:53]
	v_cndmask_b32_e64 v108, v99, v103, s[52:53]
	v_cndmask_b32_e64 v107, v100, v104, s[52:53]
	v_cndmask_b32_e64 v106, v101, v105, s[52:53]
	s_cbranch_vccnz .LBB0_1605
	v_pk_mul_f32 v[86:87], v[86:87], v[86:87]
	v_pk_mul_f32 v[84:85], v[84:85], v[84:85]
	s_ashr_i32 s1, s0, 31
	v_pk_mul_f32 v[82:83], v[82:83], v[82:83]
	v_add_f32_e32 v84, v84, v85
	v_add_f32_e32 v85, v86, v87
	s_lshl_b64 s[22:23], s[0:1], 12
	v_readlane_b32 s1, v249, 28
	v_pk_mul_f32 v[88:89], v[88:89], v[88:89]
	v_add_f32_e32 v84, v85, v84
	v_add_f32_e32 v82, v82, v83
	s_add_u32 s1, s1, s22
	v_readlane_b32 s14, v253, 5
	v_pk_mul_f32 v[94:95], v[94:95], v[94:95]
	v_pk_mul_f32 v[92:93], v[92:93], v[92:93]
	v_add_f32_e32 v82, v82, v84
	v_add_f32_e32 v83, v88, v89
	s_addc_u32 s14, s14, s23
	s_lshl_b64 s[22:23], s[82:83], 1
	v_pk_mul_f32 v[90:91], v[90:91], v[90:91]
	v_add_f32_e32 v82, v83, v82
	v_add_f32_e32 v83, v92, v93
	v_add_f32_e32 v84, v94, v95
	s_add_u32 s22, s1, s22
	v_and_b32_e32 v93, 64, v204
	v_pk_mul_f32 v[96:97], v[96:97], v[96:97]
	v_add_f32_e32 v83, v84, v83
	v_add_f32_e32 v84, v90, v91
	s_addc_u32 s23, s14, s23
	v_xor_b32_e32 v92, 16, v204
	v_add_u32_e32 v95, 64, v93
	v_add_f32_e32 v83, v84, v83
	v_add_f32_e32 v84, v96, v97
	v_lshl_add_u64 v[90:91], s[22:23], 0, v[130:131]
	v_mov_b32_e32 v151, v131
	v_cmp_lt_i32_e32 vcc, v92, v95
	v_add_f32_e32 v83, v84, v83
	v_lshl_add_u64 v[90:91], v[90:91], 0, v[150:151]
	v_mov_b32_e32 v149, v131
	v_cndmask_b32_e32 v92, v204, v92, vcc
	v_add_f32_e32 v94, v83, v82
	v_mov_b32_e32 v86, v131
	v_mov_b32_e32 v87, v131
	v_mov_b32_e32 v88, v131
	v_mov_b32_e32 v89, v131
	v_lshl_add_u64 v[90:91], v[90:91], 0, v[148:149]
	v_lshlrev_b32_e32 v92, 2, v92
	s_mov_b32 s1, 0x80000
	v_mov_b32_dpp v86, v109 row_ror:8 row_mask:0xf bank_mask:0xf
	v_mov_b32_dpp v87, v108 row_ror:8 row_mask:0xf bank_mask:0xf
	v_mov_b32_dpp v88, v107 row_ror:8 row_mask:0xf bank_mask:0xf
	v_mov_b32_dpp v89, v106 row_ror:8 row_mask:0xf bank_mask:0xf
	ds_bpermute_b32 v96, v92, v94
	v_add_co_u32_e32 v92, vcc, s1, v90
	v_cndmask_b32_e64 v82, v86, v98, s[52:53]
	v_cndmask_b32_e64 v83, v87, v99, s[52:53]
	v_cndmask_b32_e64 v84, v88, v100, s[52:53]
	v_cndmask_b32_e64 v85, v89, v101, s[52:53]
	v_addc_co_u32_e32 v93, vcc, 0, v91, vcc
	global_store_dwordx4 v[92:93], v[82:85], off sc1
	s_mov_b32 s1, 0x88000
	v_cndmask_b32_e64 v86, v102, v86, s[52:53]
	v_xor_b32_e32 v83, 32, v204
	v_cmp_lt_i32_e32 vcc, v83, v95
	s_waitcnt lgkmcnt(0)
	v_add_f32_e32 v82, v94, v96
	v_cndmask_b32_e64 v87, v103, v87, s[52:53]
	v_cndmask_b32_e32 v83, v204, v83, vcc
	v_lshlrev_b32_e32 v83, 2, v83
	ds_bpermute_b32 v83, v83, v82
	v_add_co_u32_e32 v84, vcc, s1, v90
	v_cndmask_b32_e64 v88, v104, v88, s[52:53]
	v_cndmask_b32_e64 v89, v105, v89, s[52:53]
	v_addc_co_u32_e32 v85, vcc, 0, v91, vcc
	global_store_dwordx4 v[84:85], v[86:89], off sc1
	s_and_saveexec_b64 s[42:43], s[54:55]
	s_cbranch_execz .LBB0_1604
	v_readlane_b32 s44, v253, 6
	v_lshlrev_b64 v[84:85], 7, v[182:183]
	s_lshl_b32 s22, s21, 2
	v_readlane_b32 s45, v253, 7
	s_waitcnt lgkmcnt(0)
	v_add_f32_e32 v86, v82, v83
	s_ashr_i32 s23, s22, 31
	v_lshl_add_u64 v[82:83], s[44:45], 0, v[84:85]
	v_lshl_add_u64 v[82:83], s[22:23], 2, v[82:83]
	s_lshl_b32 s80, s38, 2
	v_lshl_add_u64 v[82:83], v[82:83], 0, s[80:81]
	v_add_co_u32_e32 v82, vcc, 0x4000, v82
	s_nop 1
	v_addc_co_u32_e32 v83, vcc, 0, v83, vcc
	global_store_dword v[82:83], v86, off

; __device__ __forceinline__ u32x4 pack8(f32x4 a, f32x4 b) { u32x4 w; w.x = cvtpk(a[0], a[1]); w.y = cvtpk(a[2], a[3]); w.z = cvtpk(b[0], b[1]); w.w = cvtpk(b[2], b[3]); return w; }
;     __device__ __forceinline__ void operator()(f32x4 (&acc)[2][2][4][2], const Unit& u, int wr, int wc, int fr, int fq) const {
;     ...
;                     pk[bj] = pack8(v0, v1);
;                 }
;                 if (u.ks >= 0) store_pair((bf16_t*)yp + ((size_t)u.ks * MS + (rowg - MP) + ai * HALF + m * 16) * DM + colw, DM, fr, fq, pk[0], pk[1]);
.LBB0_1605:
	s_andn2_b64 vcc, exec, s[42:43]
	s_cbranch_vccnz .LBB0_1607
	s_mov_b32 s63, s81
	s_lshl_b64 s[22:23], s[62:63], 22
	s_lshl_b64 s[42:43], s[40:41], 12
	s_add_u32 s1, s88, s22
	s_addc_u32 s14, s89, s23
	s_add_u32 s1, s1, s42
	s_addc_u32 s14, s14, s43
	s_lshl_b64 s[22:23], s[82:83], 1
	s_add_u32 s22, s1, s22
	s_addc_u32 s23, s14, s23
	v_lshl_add_u64 v[90:91], s[22:23], 0, v[130:131]
	v_mov_b32_e32 v151, v131
	v_lshl_add_u64 v[90:91], v[90:91], 0, v[150:151]
	v_mov_b32_e32 v149, v131
	v_mov_b32_e32 v86, v131
	v_mov_b32_e32 v87, v131
	v_mov_b32_e32 v88, v131
	v_mov_b32_e32 v89, v131
	v_lshl_add_u64 v[90:91], v[90:91], 0, v[148:149]
	v_mov_b32_dpp v86, v109 row_ror:8 row_mask:0xf bank_mask:0xf
	v_mov_b32_dpp v87, v108 row_ror:8 row_mask:0xf bank_mask:0xf
	v_mov_b32_dpp v88, v107 row_ror:8 row_mask:0xf bank_mask:0xf
	v_mov_b32_dpp v89, v106 row_ror:8 row_mask:0xf bank_mask:0xf
	v_add_co_u32_e32 v92, vcc, 0x80000, v90
	v_cndmask_b32_e64 v82, v86, v98, s[52:53]
	s_waitcnt lgkmcnt(0)
	v_cndmask_b32_e64 v83, v87, v99, s[52:53]
	v_cndmask_b32_e64 v84, v88, v100, s[52:53]
	v_cndmask_b32_e64 v85, v89, v101, s[52:53]
	v_addc_co_u32_e32 v93, vcc, 0, v91, vcc
	global_store_dwordx4 v[92:93], v[82:85], off sc1
	v_cndmask_b32_e64 v86, v102, v86, s[52:53]
	v_cndmask_b32_e64 v87, v103, v87, s[52:53]
	v_add_co_u32_e32 v82, vcc, 0x88000, v90
	v_cndmask_b32_e64 v88, v104, v88, s[52:53]
	v_cndmask_b32_e64 v89, v105, v89, s[52:53]
	v_addc_co_u32_e32 v83, vcc, 0, v91, vcc
	global_store_dwordx4 v[82:83], v[86:89], off sc1
; __device__ __forceinline__ void store_pair(bf16_t* grp  , size_t ld, int fr, int fq, u32x4 P0, u32x4 P1) {
;     const bool up = (fr & 8) != 0;
;     u32x4 snd, rcv;
;     snd.x = up ? P0.x : P1.x; snd.y = up ? P0.y : P1.y; snd.z = up ? P0.z : P1.z; snd.w = up ? P0.w : P1.w;
;     rcv.x = dpp_ror8(snd.x); rcv.y = dpp_ror8(snd.y); rcv.z = dpp_ror8(snd.z); rcv.w = dpp_ror8(snd.w);
;     u32x4 dA, dB;
;     dA.x = up ? rcv.x : P0.x; dA.y = up ? rcv.y : P0.y; dA.z = up ? rcv.z : P0.z; dA.w = up ? rcv.w : P0.w;
;     dB.x = up ? P1.x : rcv.x; dB.y = up ? P1.y : rcv.y; dB.z = up ? P1.z : rcv.z; dB.w = up ? P1.w : rcv.w;
;     bf16_t* p = grp + (size_t)(fr & 7) * ld + (up ? CBJ : 0) + 8 * fq;
;     __builtin_nontemporal_store(dA, (u32x4*)p); __builtin_nontemporal_store(dB, (u32x4*)(p + 8 * ld));
;     __device__ __forceinline__ void operator()(f32x4 (&acc)[2][2][4][2], const Unit& u, int wr, int wc, int fr, int fq) const {
;     ...
;                 const int row = row0 + ai * HALF + m * 16;
;                 const float sr = rv[ai * 4 + m];
;                 float s = 0.f; u32x4 pk[2];
; #pragma unroll
;                 for (int bj = 0; bj < 2; ++bj) {
;                     const v4i_t i0 = __builtin_bit_cast(v4i_t, acc[ai][bj][m][0]) + ov[bj * 2], i1 = __builtin_bit_cast(v4i_t, acc[ai][bj][m][1]) + ov[bj * 2 + 1];
;                     const u32x4 c0_ = cv[bj * 2], c1_ = cv[bj * 2 + 1];
;                     f32x4 v0, v1;
; #pragma unroll
;                     for (int j = 0; j < 4; ++j) { v0[j] = (float)i0[j] * (sr * __uint_as_float(c0_[j])); v1[j] = (float)i1[j] * (sr * __uint_as_float(c1_[j])); }
;                     s += (v0[0] * v0[0] + v0[1] * v0[1]) + (v0[2] * v0[2] + v0[3] * v0[3]) + (v1[0] * v1[0] + v1[1] * v1[1]) + (v1[2] * v1[2] + v1[3] * v1[3]);
;                     pk[bj] = pack8(v0, v1);
;                 }
;                 if (u.ks >= 0) store_pair((bf16_t*)yp + ((size_t)u.ks * MS + (rowg - MP) + ai * HALF + m * 16) * DM + colw, DM, fr, fq, pk[0], pk[1]);
;                 else {
;                     store_pair(Y + (size_t)(rowg + ai * HALF + m * 16) * DM + colw, DM, fr, fq, pk[0], pk[1]);
;                     s += __shfl_xor(s, 16); s += __shfl_xor(s, 32);
;                     if (fq == 0) ssy[(size_t)row * 32 + u.pn * 4 + wc] = s;
;                 }
.LBB0_1607:
	v_add_u32_e32 v46, v78, v46
	v_add_u32_e32 v47, v79, v47
	v_cvt_f32_i32_e32 v47, v47
	v_cvt_f32_i32_e32 v46, v46
	v_mul_f32_e32 v86, 0x38018388, v190
	s_waitcnt lgkmcnt(0)
	v_pk_mul_f32 v[82:83], v[66:67], v[86:87] op_sel_hi:[1,0]
	v_pk_mul_f32 v[84:85], v[62:63], v[86:87] op_sel_hi:[1,0]
	v_add_u32_e32 v87, v80, v48
	v_add_u32_e32 v88, v81, v49
	v_pk_mul_f32 v[46:47], v[82:83], v[46:47]
	v_cvt_f32_i32_e32 v83, v88
	v_cvt_f32_i32_e32 v82, v87
	v_add_u32_e32 v38, v74, v38
	v_add_u32_e32 v39, v75, v39
	v_cvt_f32_i32_e32 v39, v39
	v_cvt_f32_i32_e32 v38, v38
	v_add_u32_e32 v89, v72, v44
	v_add_u32_e32 v90, v73, v45
	v_pk_mul_f32 v[44:45], v[68:69], v[86:87] op_sel_hi:[1,0]
	v_pk_mul_f32 v[48:49], v[64:65], v[86:87] op_sel_hi:[1,0]
	v_pk_mul_f32 v[44:45], v[44:45], v[82:83]
	v_cvt_f32_i32_e32 v83, v90
	v_cvt_f32_i32_e32 v82, v89
	v_pk_mul_f32 v[88:89], v[54:55], v[86:87] op_sel_hi:[1,0]
	v_pk_mul_f32 v[90:91], v[50:51], v[86:87] op_sel_hi:[1,0]
	v_add_u32_e32 v92, v76, v40
	v_add_u32_e32 v87, v77, v41
	v_pk_mul_f32 v[38:39], v[88:89], v[38:39]
	v_add_u32_e32 v88, v60, v36
	v_add_u32_e32 v89, v61, v37
	v_pk_mul_f32 v[36:37], v[56:57], v[86:87] op_sel_hi:[1,0]
	v_pk_mul_f32 v[40:41], v[52:53], v[86:87] op_sel_hi:[1,0]
	v_cvt_f32_i32_e32 v87, v87
	v_cvt_f32_i32_e32 v86, v92
	v_add_u32_e32 v42, v70, v42
	v_add_u32_e32 v43, v71, v43
	v_add_u32_e32 v34, v58, v34
	v_add_u32_e32 v35, v59, v35
	v_cvt_f32_i32_e32 v43, v43
	v_cvt_f32_i32_e32 v42, v42
	v_cvt_f32_i32_e32 v35, v35
	v_cvt_f32_i32_e32 v34, v34
	v_pk_mul_f32 v[36:37], v[36:37], v[86:87]
	v_cvt_f32_i32_e32 v87, v89
	v_cvt_f32_i32_e32 v86, v88
	v_pk_mul_f32 v[42:43], v[84:85], v[42:43]
	v_pk_mul_f32 v[48:49], v[48:49], v[82:83]
	v_pk_mul_f32 v[34:35], v[90:91], v[34:35]
	v_pk_mul_f32 v[40:41], v[40:41], v[86:87]
	v_cvt_pk_bf16_f32 v82, v46, v47
	v_cvt_pk_bf16_f32 v83, v44, v45
	v_cvt_pk_bf16_f32 v84, v42, v43
	v_cvt_pk_bf16_f32 v85, v48, v49
	v_cvt_pk_bf16_f32 v86, v38, v39
	v_cvt_pk_bf16_f32 v87, v36, v37
	v_cvt_pk_bf16_f32 v88, v34, v35
	v_cvt_pk_bf16_f32 v89, v40, v41
	s_mov_b64 s[42:43], -1
	s_and_b64 vcc, exec, s[56:57]
	v_cndmask_b32_e64 v93, v82, v86, s[52:53]
	v_cndmask_b32_e64 v92, v83, v87, s[52:53]
	v_cndmask_b32_e64 v91, v84, v88, s[52:53]
	v_cndmask_b32_e64 v90, v85, v89, s[52:53]
	s_cbranch_vccnz .LBB0_1611
	v_pk_mul_f32 v[38:39], v[38:39], v[38:39]
	v_pk_mul_f32 v[36:37], v[36:37], v[36:37]
	s_ashr_i32 s1, s0, 31
	v_pk_mul_f32 v[34:35], v[34:35], v[34:35]
	v_add_f32_e32 v36, v36, v37
	v_add_f32_e32 v37, v38, v39
	s_lshl_b64 s[22:23], s[0:1], 12
	v_readlane_b32 s1, v249, 28
	v_pk_mul_f32 v[40:41], v[40:41], v[40:41]
	v_add_f32_e32 v36, v37, v36
	v_add_f32_e32 v34, v34, v35
	s_add_u32 s1, s1, s22
	v_readlane_b32 s14, v253, 5
	v_pk_mul_f32 v[46:47], v[46:47], v[46:47]
	v_pk_mul_f32 v[44:45], v[44:45], v[44:45]
	v_add_f32_e32 v34, v34, v36
	v_add_f32_e32 v35, v40, v41
	s_addc_u32 s14, s14, s23
	s_lshl_b64 s[22:23], s[82:83], 1
	v_pk_mul_f32 v[42:43], v[42:43], v[42:43]
	v_add_f32_e32 v34, v35, v34
	v_add_f32_e32 v35, v44, v45
	v_add_f32_e32 v36, v46, v47
	s_add_u32 s22, s1, s22
	v_and_b32_e32 v45, 64, v204
	v_pk_mul_f32 v[48:49], v[48:49], v[48:49]
	v_add_f32_e32 v35, v36, v35
	v_add_f32_e32 v36, v42, v43
	s_addc_u32 s23, s14, s23
	v_xor_b32_e32 v44, 16, v204
	v_add_u32_e32 v47, 64, v45
	v_add_f32_e32 v35, v36, v35
	v_add_f32_e32 v36, v48, v49
	v_lshl_add_u64 v[42:43], s[22:23], 0, v[130:131]
	v_mov_b32_e32 v151, v131
	v_cmp_lt_i32_e32 vcc, v44, v47
	v_add_f32_e32 v35, v36, v35
	v_lshl_add_u64 v[42:43], v[42:43], 0, v[150:151]
	v_mov_b32_e32 v149, v131
	v_cndmask_b32_e32 v44, v204, v44, vcc
	v_add_f32_e32 v46, v35, v34
	v_mov_b32_e32 v38, v131
	v_mov_b32_e32 v39, v131
	v_mov_b32_e32 v40, v131
	v_mov_b32_e32 v41, v131
	v_lshl_add_u64 v[42:43], v[42:43], 0, v[148:149]
	v_lshlrev_b32_e32 v44, 2, v44
	s_mov_b32 s1, 0x90000
	v_mov_b32_dpp v38, v93 row_ror:8 row_mask:0xf bank_mask:0xf
	v_mov_b32_dpp v39, v92 row_ror:8 row_mask:0xf bank_mask:0xf
	v_mov_b32_dpp v40, v91 row_ror:8 row_mask:0xf bank_mask:0xf
	v_mov_b32_dpp v41, v90 row_ror:8 row_mask:0xf bank_mask:0xf
	ds_bpermute_b32 v48, v44, v46
	v_add_co_u32_e32 v44, vcc, s1, v42
	v_cndmask_b32_e64 v34, v38, v82, s[52:53]
	v_cndmask_b32_e64 v35, v39, v83, s[52:53]
	v_cndmask_b32_e64 v36, v40, v84, s[52:53]
	v_cndmask_b32_e64 v37, v41, v85, s[52:53]
	v_addc_co_u32_e32 v45, vcc, 0, v43, vcc
	global_store_dwordx4 v[44:45], v[34:37], off sc1
	s_mov_b32 s1, 0x98000
	v_cndmask_b32_e64 v38, v86, v38, s[52:53]
	v_xor_b32_e32 v35, 32, v204
	v_cmp_lt_i32_e32 vcc, v35, v47
	s_waitcnt lgkmcnt(0)
	v_add_f32_e32 v34, v46, v48
	v_cndmask_b32_e64 v39, v87, v39, s[52:53]
	v_cndmask_b32_e32 v35, v204, v35, vcc
	v_lshlrev_b32_e32 v35, 2, v35
	ds_bpermute_b32 v35, v35, v34
	v_add_co_u32_e32 v36, vcc, s1, v42
	v_cndmask_b32_e64 v40, v88, v40, s[52:53]
	v_cndmask_b32_e64 v41, v89, v41, s[52:53]
	v_addc_co_u32_e32 v37, vcc, 0, v43, vcc
	global_store_dwordx4 v[36:37], v[38:41], off sc1
	s_and_saveexec_b64 s[42:43], s[54:55]
	s_cbranch_execz .LBB0_1610
	v_readlane_b32 s44, v253, 6
	s_waitcnt lgkmcnt(0)
	v_add_f32_e32 v36, v34, v35
	v_lshlrev_b64 v[34:35], 7, v[182:183]
	s_lshl_b32 s22, s21, 2
	v_readlane_b32 s45, v253, 7
	s_ashr_i32 s23, s22, 31
	s_lshl_b32 s80, s38, 2
	v_lshl_add_u64 v[34:35], s[44:45], 0, v[34:35]
	v_lshl_add_u64 v[34:35], s[22:23], 2, v[34:35]
	v_lshl_add_u64 v[34:35], v[34:35], 0, s[80:81]
	v_add_co_u32_e32 v34, vcc, 0x4000, v34
	s_nop 1
	v_addc_co_u32_e32 v35, vcc, 0, v35, vcc
	global_store_dword v[34:35], v36, off offset:2048

; __device__ __forceinline__ unsigned dpp_ror8(unsigned v) { return (unsigned)__builtin_amdgcn_update_dpp(0, (int)v, 0x128, 0xF, 0xF, false); }
; __device__ __forceinline__ void store_pair(bf16_t* grp  , size_t ld, int fr, int fq, u32x4 P0, u32x4 P1) {
;     const bool up = (fr & 8) != 0;
;     u32x4 snd, rcv;
;     snd.x = up ? P0.x : P1.x; snd.y = up ? P0.y : P1.y; snd.z = up ? P0.z : P1.z; snd.w = up ? P0.w : P1.w;
;     rcv.x = dpp_ror8(snd.x); rcv.y = dpp_ror8(snd.y); rcv.z = dpp_ror8(snd.z); rcv.w = dpp_ror8(snd.w);
;     u32x4 dA, dB;
;     dA.x = up ? rcv.x : P0.x; dA.y = up ? rcv.y : P0.y; dA.z = up ? rcv.z : P0.z; dA.w = up ? rcv.w : P0.w;
;     dB.x = up ? P1.x : rcv.x; dB.y = up ? P1.y : rcv.y; dB.z = up ? P1.z : rcv.z; dB.w = up ? P1.w : rcv.w;
;     bf16_t* p = grp + (size_t)(fr & 7) * ld + (up ? CBJ : 0) + 8 * fq;
;     __builtin_nontemporal_store(dA, (u32x4*)p); __builtin_nontemporal_store(dB, (u32x4*)(p + 8 * ld));
;     __device__ __forceinline__ void operator()(f32x4 (&acc)[2][2][4][2], const Unit& u, int wr, int wc, int fr, int fq) const {
;     ...
;                 if (u.ks >= 0) store_pair((bf16_t*)yp + ((size_t)u.ks * MS + (rowg - MP) + ai * HALF + m * 16) * DM + colw, DM, fr, fq, pk[0], pk[1]);
;                 else {
;                     store_pair(Y + (size_t)(rowg + ai * HALF + m * 16) * DM + colw, DM, fr, fq, pk[0], pk[1]);
;                     s += __shfl_xor(s, 16); s += __shfl_xor(s, 32);
;                     if (fq == 0) ssy[(size_t)row * 32 + u.pn * 4 + wc] = s;
;                 }
.LBB0_1611:
	s_andn2_b64 vcc, exec, s[42:43]
	s_cbranch_vccnz .LBB0_1613
	s_mov_b32 s63, s81
	s_lshl_b64 s[22:23], s[62:63], 22
	s_lshl_b64 s[42:43], s[40:41], 12
	s_add_u32 s1, s88, s22
	s_addc_u32 s14, s89, s23
	s_add_u32 s1, s1, s42
	s_addc_u32 s14, s14, s43
	s_lshl_b64 s[22:23], s[82:83], 1
	s_add_u32 s22, s1, s22
	s_addc_u32 s23, s14, s23
	v_lshl_add_u64 v[42:43], s[22:23], 0, v[130:131]
	v_mov_b32_e32 v151, v131
	v_lshl_add_u64 v[42:43], v[42:43], 0, v[150:151]
	v_mov_b32_e32 v149, v131
	v_mov_b32_e32 v38, v131
	v_mov_b32_e32 v39, v131
	v_mov_b32_e32 v40, v131
	v_mov_b32_e32 v41, v131
	v_lshl_add_u64 v[42:43], v[42:43], 0, v[148:149]
	v_mov_b32_dpp v38, v93 row_ror:8 row_mask:0xf bank_mask:0xf
	v_mov_b32_dpp v39, v92 row_ror:8 row_mask:0xf bank_mask:0xf
	v_mov_b32_dpp v40, v91 row_ror:8 row_mask:0xf bank_mask:0xf
	v_mov_b32_dpp v41, v90 row_ror:8 row_mask:0xf bank_mask:0xf
	v_add_co_u32_e32 v44, vcc, 0x90000, v42
	v_cndmask_b32_e64 v34, v38, v82, s[52:53]
	s_waitcnt lgkmcnt(0)
	v_cndmask_b32_e64 v35, v39, v83, s[52:53]
	v_cndmask_b32_e64 v36, v40, v84, s[52:53]
	v_cndmask_b32_e64 v37, v41, v85, s[52:53]
	v_addc_co_u32_e32 v45, vcc, 0, v43, vcc
	global_store_dwordx4 v[44:45], v[34:37], off sc1
	v_cndmask_b32_e64 v38, v86, v38, s[52:53]
	v_cndmask_b32_e64 v39, v87, v39, s[52:53]
	v_add_co_u32_e32 v34, vcc, 0x98000, v42
	v_cndmask_b32_e64 v40, v88, v40, s[52:53]
	v_cndmask_b32_e64 v41, v89, v41, s[52:53]
	v_addc_co_u32_e32 v35, vcc, 0, v43, vcc
	global_store_dwordx4 v[34:35], v[38:41], off sc1
.LBB0_1613:
	v_add_u32_e32 v30, v78, v30
	v_add_u32_e32 v31, v79, v31
	v_cvt_f32_i32_e32 v31, v31
	v_cvt_f32_i32_e32 v30, v30
	v_mul_f32_e32 v38, 0x38018388, v189
	s_waitcnt lgkmcnt(0)
	v_pk_mul_f32 v[34:35], v[66:67], v[38:39] op_sel_hi:[1,0]
	v_pk_mul_f32 v[36:37], v[62:63], v[38:39] op_sel_hi:[1,0]
	v_add_u32_e32 v39, v80, v32
	v_add_u32_e32 v40, v81, v33
	v_pk_mul_f32 v[30:31], v[34:35], v[30:31]
	v_cvt_f32_i32_e32 v35, v40
	v_cvt_f32_i32_e32 v34, v39
	v_add_u32_e32 v22, v74, v22
	v_add_u32_e32 v23, v75, v23
	v_cvt_f32_i32_e32 v23, v23
	v_cvt_f32_i32_e32 v22, v22
	v_add_u32_e32 v41, v72, v28
	v_add_u32_e32 v42, v73, v29
	v_pk_mul_f32 v[28:29], v[68:69], v[38:39] op_sel_hi:[1,0]
	v_pk_mul_f32 v[32:33], v[64:65], v[38:39] op_sel_hi:[1,0]
	v_pk_mul_f32 v[28:29], v[28:29], v[34:35]
	v_cvt_f32_i32_e32 v35, v42
	v_cvt_f32_i32_e32 v34, v41
	v_pk_mul_f32 v[40:41], v[54:55], v[38:39] op_sel_hi:[1,0]
	v_pk_mul_f32 v[42:43], v[50:51], v[38:39] op_sel_hi:[1,0]
	v_add_u32_e32 v44, v76, v24
	v_add_u32_e32 v39, v77, v25
	v_pk_mul_f32 v[22:23], v[40:41], v[22:23]
	v_add_u32_e32 v40, v60, v20
	v_add_u32_e32 v41, v61, v21
	v_pk_mul_f32 v[20:21], v[56:57], v[38:39] op_sel_hi:[1,0]
	v_pk_mul_f32 v[24:25], v[52:53], v[38:39] op_sel_hi:[1,0]
	v_cvt_f32_i32_e32 v39, v39
	v_cvt_f32_i32_e32 v38, v44
	v_add_u32_e32 v26, v70, v26
	v_add_u32_e32 v27, v71, v27
	v_add_u32_e32 v18, v58, v18
	v_add_u32_e32 v19, v59, v19
	v_cvt_f32_i32_e32 v27, v27
	v_cvt_f32_i32_e32 v26, v26
	v_cvt_f32_i32_e32 v19, v19
	v_cvt_f32_i32_e32 v18, v18
	v_pk_mul_f32 v[20:21], v[20:21], v[38:39]
	v_cvt_f32_i32_e32 v39, v41
	v_cvt_f32_i32_e32 v38, v40
	v_pk_mul_f32 v[26:27], v[36:37], v[26:27]
	v_pk_mul_f32 v[32:33], v[32:33], v[34:35]
	v_pk_mul_f32 v[18:19], v[42:43], v[18:19]
	v_pk_mul_f32 v[24:25], v[24:25], v[38:39]
	v_cvt_pk_bf16_f32 v34, v30, v31
	v_cvt_pk_bf16_f32 v35, v28, v29
	v_cvt_pk_bf16_f32 v36, v26, v27
	v_cvt_pk_bf16_f32 v37, v32, v33
	v_cvt_pk_bf16_f32 v38, v22, v23
	v_cvt_pk_bf16_f32 v39, v20, v21
	v_cvt_pk_bf16_f32 v40, v18, v19
	v_cvt_pk_bf16_f32 v41, v24, v25
	s_mov_b64 s[42:43], -1
	s_and_b64 vcc, exec, s[56:57]
	v_cndmask_b32_e64 v45, v34, v38, s[52:53]
	v_cndmask_b32_e64 v44, v35, v39, s[52:53]
	v_cndmask_b32_e64 v43, v36, v40, s[52:53]
	v_cndmask_b32_e64 v42, v37, v41, s[52:53]
	s_cbranch_vccnz .LBB0_1617
	v_pk_mul_f32 v[22:23], v[22:23], v[22:23]
	v_pk_mul_f32 v[20:21], v[20:21], v[20:21]
	s_ashr_i32 s1, s0, 31
	v_pk_mul_f32 v[18:19], v[18:19], v[18:19]
	v_add_f32_e32 v20, v20, v21
	v_add_f32_e32 v21, v22, v23
	s_lshl_b64 s[22:23], s[0:1], 12
	v_readlane_b32 s1, v249, 28
	v_pk_mul_f32 v[24:25], v[24:25], v[24:25]
	v_add_f32_e32 v20, v21, v20
	v_add_f32_e32 v18, v18, v19
	s_add_u32 s1, s1, s22
	v_readlane_b32 s14, v253, 5
	v_pk_mul_f32 v[30:31], v[30:31], v[30:31]
	v_pk_mul_f32 v[28:29], v[28:29], v[28:29]
	v_add_f32_e32 v18, v18, v20
	v_add_f32_e32 v19, v24, v25
	s_addc_u32 s14, s14, s23
	s_lshl_b64 s[22:23], s[82:83], 1
	v_pk_mul_f32 v[26:27], v[26:27], v[26:27]
	v_add_f32_e32 v18, v19, v18
	v_add_f32_e32 v19, v28, v29
	v_add_f32_e32 v20, v30, v31
	s_add_u32 s22, s1, s22
	v_and_b32_e32 v29, 64, v204
	v_pk_mul_f32 v[32:33], v[32:33], v[32:33]
	v_add_f32_e32 v19, v20, v19
	v_add_f32_e32 v20, v26, v27
	s_addc_u32 s23, s14, s23
	v_xor_b32_e32 v28, 16, v204
	v_add_u32_e32 v31, 64, v29
	v_add_f32_e32 v19, v20, v19
	v_add_f32_e32 v20, v32, v33
	v_lshl_add_u64 v[26:27], s[22:23], 0, v[130:131]
	v_mov_b32_e32 v151, v131
	v_cmp_lt_i32_e32 vcc, v28, v31
	v_add_f32_e32 v19, v20, v19
	v_lshl_add_u64 v[26:27], v[26:27], 0, v[150:151]
	v_mov_b32_e32 v149, v131
	v_cndmask_b32_e32 v28, v204, v28, vcc
	v_add_f32_e32 v30, v19, v18
	v_mov_b32_e32 v22, v131
	v_mov_b32_e32 v23, v131
	v_mov_b32_e32 v24, v131
	v_mov_b32_e32 v25, v131
	v_lshl_add_u64 v[26:27], v[26:27], 0, v[148:149]
	v_lshlrev_b32_e32 v28, 2, v28
	s_mov_b32 s1, 0xa0000
	v_mov_b32_dpp v22, v45 row_ror:8 row_mask:0xf bank_mask:0xf
	v_mov_b32_dpp v23, v44 row_ror:8 row_mask:0xf bank_mask:0xf
	v_mov_b32_dpp v24, v43 row_ror:8 row_mask:0xf bank_mask:0xf
	v_mov_b32_dpp v25, v42 row_ror:8 row_mask:0xf bank_mask:0xf
	ds_bpermute_b32 v32, v28, v30
	v_add_co_u32_e32 v28, vcc, s1, v26
	v_cndmask_b32_e64 v18, v22, v34, s[52:53]
	v_cndmask_b32_e64 v19, v23, v35, s[52:53]
	v_cndmask_b32_e64 v20, v24, v36, s[52:53]
	v_cndmask_b32_e64 v21, v25, v37, s[52:53]
	v_addc_co_u32_e32 v29, vcc, 0, v27, vcc
	global_store_dwordx4 v[28:29], v[18:21], off sc1
	s_mov_b32 s1, 0xa8000
	v_cndmask_b32_e64 v22, v38, v22, s[52:53]
	v_xor_b32_e32 v19, 32, v204
	v_cmp_lt_i32_e32 vcc, v19, v31
	s_waitcnt lgkmcnt(0)
	v_add_f32_e32 v18, v30, v32
	v_cndmask_b32_e64 v23, v39, v23, s[52:53]
	v_cndmask_b32_e32 v19, v204, v19, vcc
	v_lshlrev_b32_e32 v19, 2, v19
	ds_bpermute_b32 v19, v19, v18
	v_add_co_u32_e32 v20, vcc, s1, v26
	v_cndmask_b32_e64 v24, v40, v24, s[52:53]
	v_cndmask_b32_e64 v25, v41, v25, s[52:53]
	v_addc_co_u32_e32 v21, vcc, 0, v27, vcc
	global_store_dwordx4 v[20:21], v[22:25], off sc1
	s_and_saveexec_b64 s[42:43], s[54:55]
	s_cbranch_execz .LBB0_1616
	v_readlane_b32 s44, v253, 6
	s_waitcnt lgkmcnt(0)
	v_add_f32_e32 v20, v18, v19
	v_lshlrev_b64 v[18:19], 7, v[182:183]
	s_lshl_b32 s22, s21, 2
	v_readlane_b32 s45, v253, 7
	s_ashr_i32 s23, s22, 31
	s_lshl_b32 s80, s38, 2
	v_lshl_add_u64 v[18:19], s[44:45], 0, v[18:19]
	v_lshl_add_u64 v[18:19], s[22:23], 2, v[18:19]
	v_lshl_add_u64 v[18:19], v[18:19], 0, s[80:81]
	v_add_co_u32_e32 v18, vcc, 0x5000, v18
	s_nop 1
	v_addc_co_u32_e32 v19, vcc, 0, v19, vcc
	global_store_dword v[18:19], v20, off

; __device__ __forceinline__ unsigned dpp_ror8(unsigned v) { return (unsigned)__builtin_amdgcn_update_dpp(0, (int)v, 0x128, 0xF, 0xF, false); }
; __device__ __forceinline__ void store_pair(bf16_t* grp  , size_t ld, int fr, int fq, u32x4 P0, u32x4 P1) {
;     const bool up = (fr & 8) != 0;
;     u32x4 snd, rcv;
;     snd.x = up ? P0.x : P1.x; snd.y = up ? P0.y : P1.y; snd.z = up ? P0.z : P1.z; snd.w = up ? P0.w : P1.w;
;     rcv.x = dpp_ror8(snd.x); rcv.y = dpp_ror8(snd.y); rcv.z = dpp_ror8(snd.z); rcv.w = dpp_ror8(snd.w);
;     u32x4 dA, dB;
;     dA.x = up ? rcv.x : P0.x; dA.y = up ? rcv.y : P0.y; dA.z = up ? rcv.z : P0.z; dA.w = up ? rcv.w : P0.w;
;     dB.x = up ? P1.x : rcv.x; dB.y = up ? P1.y : rcv.y; dB.z = up ? P1.z : rcv.z; dB.w = up ? P1.w : rcv.w;
;     bf16_t* p = grp + (size_t)(fr & 7) * ld + (up ? CBJ : 0) + 8 * fq;
;     __builtin_nontemporal_store(dA, (u32x4*)p); __builtin_nontemporal_store(dB, (u32x4*)(p + 8 * ld));
;     __device__ __forceinline__ void operator()(f32x4 (&acc)[2][2][4][2], const Unit& u, int wr, int wc, int fr, int fq) const {
;     ...
;                 if (u.ks >= 0) store_pair((bf16_t*)yp + ((size_t)u.ks * MS + (rowg - MP) + ai * HALF + m * 16) * DM + colw, DM, fr, fq, pk[0], pk[1]);
;                 else {
;                     store_pair(Y + (size_t)(rowg + ai * HALF + m * 16) * DM + colw, DM, fr, fq, pk[0], pk[1]);
;                     s += __shfl_xor(s, 16); s += __shfl_xor(s, 32);
;                     if (fq == 0) ssy[(size_t)row * 32 + u.pn * 4 + wc] = s;
;                 }
.LBB0_1617:
	s_andn2_b64 vcc, exec, s[42:43]
	s_cbranch_vccnz .LBB0_1619
	s_mov_b32 s63, s81
	s_lshl_b64 s[22:23], s[62:63], 22
	s_lshl_b64 s[42:43], s[40:41], 12
	s_add_u32 s1, s88, s22
	s_addc_u32 s14, s89, s23
	s_add_u32 s1, s1, s42
	s_addc_u32 s14, s14, s43
	s_lshl_b64 s[22:23], s[82:83], 1
	s_add_u32 s22, s1, s22
	s_addc_u32 s23, s14, s23
	v_lshl_add_u64 v[26:27], s[22:23], 0, v[130:131]
	v_mov_b32_e32 v151, v131
	v_lshl_add_u64 v[26:27], v[26:27], 0, v[150:151]
	v_mov_b32_e32 v149, v131
	v_mov_b32_e32 v22, v131
	v_mov_b32_e32 v23, v131
	v_mov_b32_e32 v24, v131
	v_mov_b32_e32 v25, v131
	v_lshl_add_u64 v[26:27], v[26:27], 0, v[148:149]
	v_mov_b32_dpp v22, v45 row_ror:8 row_mask:0xf bank_mask:0xf
	v_mov_b32_dpp v23, v44 row_ror:8 row_mask:0xf bank_mask:0xf
	v_mov_b32_dpp v24, v43 row_ror:8 row_mask:0xf bank_mask:0xf
	v_mov_b32_dpp v25, v42 row_ror:8 row_mask:0xf bank_mask:0xf
	v_add_co_u32_e32 v28, vcc, 0xa0000, v26
	v_cndmask_b32_e64 v18, v22, v34, s[52:53]
	s_waitcnt lgkmcnt(0)
	v_cndmask_b32_e64 v19, v23, v35, s[52:53]
	v_cndmask_b32_e64 v20, v24, v36, s[52:53]
	v_cndmask_b32_e64 v21, v25, v37, s[52:53]
	v_addc_co_u32_e32 v29, vcc, 0, v27, vcc
	global_store_dwordx4 v[28:29], v[18:21], off sc1
	v_cndmask_b32_e64 v22, v38, v22, s[52:53]
	v_cndmask_b32_e64 v23, v39, v23, s[52:53]
	v_add_co_u32_e32 v18, vcc, 0xa8000, v26
	v_cndmask_b32_e64 v24, v40, v24, s[52:53]
	v_cndmask_b32_e64 v25, v41, v25, s[52:53]
	v_addc_co_u32_e32 v19, vcc, 0, v27, vcc
	global_store_dwordx4 v[18:19], v[22:25], off sc1
.LBB0_1619:
	v_add_u32_e32 v14, v78, v14
	v_add_u32_e32 v15, v79, v15
	v_mul_f32_e32 v22, 0x38018388, v188
	v_cvt_f32_i32_e32 v15, v15
	v_cvt_f32_i32_e32 v14, v14
	v_add_u32_e32 v10, v70, v10
	v_add_u32_e32 v11, v71, v11
	s_waitcnt lgkmcnt(0)
	v_pk_mul_f32 v[18:19], v[66:67], v[22:23] op_sel_hi:[1,0]
	v_pk_mul_f32 v[20:21], v[62:63], v[22:23] op_sel_hi:[1,0]
	v_add_u32_e32 v23, v80, v16
	v_add_u32_e32 v24, v81, v17
	v_cvt_f32_i32_e32 v17, v11
	v_cvt_f32_i32_e32 v16, v10
	v_add_u32_e32 v6, v74, v6
	v_add_u32_e32 v7, v75, v7
	v_pk_mul_f32 v[10:11], v[18:19], v[14:15]
	v_add_u32_e32 v18, v72, v12
	v_add_u32_e32 v19, v73, v13
	v_cvt_f32_i32_e32 v7, v7
	v_cvt_f32_i32_e32 v6, v6
	v_add_u32_e32 v2, v58, v2
	v_add_u32_e32 v3, v59, v3
	v_pk_mul_f32 v[12:13], v[20:21], v[16:17]
	v_cvt_f32_i32_e32 v15, v24
	v_cvt_f32_i32_e32 v14, v23
	v_cvt_f32_i32_e32 v17, v19
	v_cvt_f32_i32_e32 v16, v18
	v_pk_mul_f32 v[18:19], v[68:69], v[22:23] op_sel_hi:[1,0]
	v_pk_mul_f32 v[20:21], v[64:65], v[22:23] op_sel_hi:[1,0]
	v_pk_mul_f32 v[24:25], v[54:55], v[22:23] op_sel_hi:[1,0]
	v_pk_mul_f32 v[26:27], v[50:51], v[22:23] op_sel_hi:[1,0]
	v_add_u32_e32 v23, v76, v8
	v_add_u32_e32 v28, v77, v9
	v_cvt_f32_i32_e32 v9, v3
	v_cvt_f32_i32_e32 v8, v2
	v_pk_mul_f32 v[2:3], v[24:25], v[6:7]
	v_add_u32_e32 v24, v60, v4
	v_add_u32_e32 v25, v61, v5
	v_pk_mul_f32 v[4:5], v[26:27], v[8:9]
	v_cvt_f32_i32_e32 v7, v28
	v_cvt_f32_i32_e32 v6, v23
	v_cvt_f32_i32_e32 v9, v25
	v_cvt_f32_i32_e32 v8, v24
	v_pk_mul_f32 v[24:25], v[56:57], v[22:23] op_sel_hi:[1,0]
	v_pk_mul_f32 v[22:23], v[52:53], v[22:23] op_sel_hi:[1,0]
	v_pk_mul_f32 v[14:15], v[18:19], v[14:15]
	v_pk_mul_f32 v[16:17], v[20:21], v[16:17]
	v_pk_mul_f32 v[6:7], v[24:25], v[6:7]
	v_pk_mul_f32 v[8:9], v[22:23], v[8:9]
	v_cvt_pk_bf16_f32 v18, v10, v11
	v_cvt_pk_bf16_f32 v19, v14, v15
	v_cvt_pk_bf16_f32 v20, v12, v13
	v_cvt_pk_bf16_f32 v21, v16, v17
	v_cvt_pk_bf16_f32 v22, v2, v3
	v_cvt_pk_bf16_f32 v23, v6, v7
	v_cvt_pk_bf16_f32 v24, v4, v5
	v_cvt_pk_bf16_f32 v25, v8, v9
	s_mov_b64 s[42:43], -1
	s_and_b64 vcc, exec, s[56:57]
	v_cndmask_b32_e64 v29, v18, v22, s[52:53]
	v_cndmask_b32_e64 v28, v19, v23, s[52:53]
	v_cndmask_b32_e64 v27, v20, v24, s[52:53]
	v_cndmask_b32_e64 v26, v21, v25, s[52:53]
	s_cbranch_vccnz .LBB0_1623
	v_pk_mul_f32 v[2:3], v[2:3], v[2:3]
	v_pk_mul_f32 v[6:7], v[6:7], v[6:7]
	v_pk_mul_f32 v[4:5], v[4:5], v[4:5]
	v_add_f32_e32 v6, v6, v7
	v_add_f32_e32 v2, v2, v3
	s_ashr_i32 s1, s0, 31
	v_pk_mul_f32 v[8:9], v[8:9], v[8:9]
	v_add_f32_e32 v2, v2, v6
	v_add_f32_e32 v3, v4, v5
	s_lshl_b64 s[0:1], s[0:1], 12
	v_readlane_b32 s14, v249, 28
	v_pk_mul_f32 v[10:11], v[10:11], v[10:11]
	v_pk_mul_f32 v[14:15], v[14:15], v[14:15]
	v_add_f32_e32 v2, v3, v2
	v_add_f32_e32 v3, v8, v9
	s_add_u32 s14, s14, s0
	v_readlane_b32 s0, v253, 5
	v_pk_mul_f32 v[12:13], v[12:13], v[12:13]
	v_add_f32_e32 v2, v3, v2
	v_add_f32_e32 v3, v14, v15
	v_add_f32_e32 v4, v10, v11
	s_addc_u32 s22, s0, s1
	s_lshl_b64 s[0:1], s[82:83], 1
	v_add_f32_e32 v3, v4, v3
	v_add_f32_e32 v4, v12, v13
	s_add_u32 s0, s14, s0
	v_and_b32_e32 v13, 64, v204
	v_pk_mul_f32 v[16:17], v[16:17], v[16:17]
	s_addc_u32 s1, s22, s1
	v_xor_b32_e32 v12, 16, v204
	v_add_u32_e32 v15, 64, v13
	v_add_f32_e32 v3, v4, v3
	v_add_f32_e32 v4, v16, v17
	v_lshl_add_u64 v[10:11], s[0:1], 0, v[130:131]
	v_mov_b32_e32 v151, v131
	v_cmp_lt_i32_e32 vcc, v12, v15
	v_add_f32_e32 v3, v4, v3
	v_lshl_add_u64 v[10:11], v[10:11], 0, v[150:151]
	v_mov_b32_e32 v149, v131
	v_cndmask_b32_e32 v12, v204, v12, vcc
	v_add_f32_e32 v14, v3, v2
	v_mov_b32_e32 v6, v131
	v_mov_b32_e32 v7, v131
	v_mov_b32_e32 v8, v131
	v_mov_b32_e32 v9, v131
	v_lshl_add_u64 v[10:11], v[10:11], 0, v[148:149]
	v_lshlrev_b32_e32 v12, 2, v12
	s_mov_b32 s0, 0xb0000
	v_mov_b32_dpp v6, v29 row_ror:8 row_mask:0xf bank_mask:0xf
	v_mov_b32_dpp v7, v28 row_ror:8 row_mask:0xf bank_mask:0xf
	v_mov_b32_dpp v8, v27 row_ror:8 row_mask:0xf bank_mask:0xf
	v_mov_b32_dpp v9, v26 row_ror:8 row_mask:0xf bank_mask:0xf
	ds_bpermute_b32 v16, v12, v14
	v_add_co_u32_e32 v12, vcc, s0, v10
	v_cndmask_b32_e64 v2, v6, v18, s[52:53]
	v_cndmask_b32_e64 v3, v7, v19, s[52:53]
	v_cndmask_b32_e64 v4, v8, v20, s[52:53]
	v_cndmask_b32_e64 v5, v9, v21, s[52:53]
	v_addc_co_u32_e32 v13, vcc, 0, v11, vcc
	global_store_dwordx4 v[12:13], v[2:5], off sc1
	s_mov_b32 s0, 0xb8000
	v_cndmask_b32_e64 v6, v22, v6, s[52:53]
	v_xor_b32_e32 v3, 32, v204
	v_cmp_lt_i32_e32 vcc, v3, v15
	s_waitcnt lgkmcnt(0)
	v_add_f32_e32 v2, v14, v16
	v_cndmask_b32_e64 v7, v23, v7, s[52:53]
	v_cndmask_b32_e32 v3, v204, v3, vcc
	v_lshlrev_b32_e32 v3, 2, v3
	ds_bpermute_b32 v3, v3, v2
	v_add_co_u32_e32 v4, vcc, s0, v10
	v_cndmask_b32_e64 v8, v24, v8, s[52:53]
	v_cndmask_b32_e64 v9, v25, v9, s[52:53]
	v_addc_co_u32_e32 v5, vcc, 0, v11, vcc
	global_store_dwordx4 v[4:5], v[6:9], off sc1
	s_and_saveexec_b64 s[0:1], s[54:55]
	s_cbranch_execz .LBB0_1622
	v_readlane_b32 s42, v253, 6
	s_waitcnt lgkmcnt(0)
	v_add_f32_e32 v4, v2, v3
	v_lshlrev_b64 v[2:3], 7, v[182:183]
	s_lshl_b32 s22, s21, 2
	v_readlane_b32 s43, v253, 7
	s_ashr_i32 s23, s22, 31
	s_lshl_b32 s80, s38, 2
	v_lshl_add_u64 v[2:3], s[42:43], 0, v[2:3]
	v_lshl_add_u64 v[2:3], s[22:23], 2, v[2:3]
	v_lshl_add_u64 v[2:3], v[2:3], 0, s[80:81]
	v_add_co_u32_e32 v2, vcc, 0x5000, v2
	s_nop 1
	v_addc_co_u32_e32 v3, vcc, 0, v3, vcc
	global_store_dword v[2:3], v4, off offset:2048

; __device__ __forceinline__ unsigned dpp_ror8(unsigned v) { return (unsigned)__builtin_amdgcn_update_dpp(0, (int)v, 0x128, 0xF, 0xF, false); }
; __device__ __forceinline__ void store_pair(bf16_t* grp  , size_t ld, int fr, int fq, u32x4 P0, u32x4 P1) {
;     const bool up = (fr & 8) != 0;
;     u32x4 snd, rcv;
;     snd.x = up ? P0.x : P1.x; snd.y = up ? P0.y : P1.y; snd.z = up ? P0.z : P1.z; snd.w = up ? P0.w : P1.w;
;     rcv.x = dpp_ror8(snd.x); rcv.y = dpp_ror8(snd.y); rcv.z = dpp_ror8(snd.z); rcv.w = dpp_ror8(snd.w);
;     u32x4 dA, dB;
;     dA.x = up ? rcv.x : P0.x; dA.y = up ? rcv.y : P0.y; dA.z = up ? rcv.z : P0.z; dA.w = up ? rcv.w : P0.w;
;     dB.x = up ? P1.x : rcv.x; dB.y = up ? P1.y : rcv.y; dB.z = up ? P1.z : rcv.z; dB.w = up ? P1.w : rcv.w;
;     bf16_t* p = grp + (size_t)(fr & 7) * ld + (up ? CBJ : 0) + 8 * fq;
;     __builtin_nontemporal_store(dA, (u32x4*)p); __builtin_nontemporal_store(dB, (u32x4*)(p + 8 * ld));
;     __device__ __forceinline__ void operator()(f32x4 (&acc)[2][2][4][2], const Unit& u, int wr, int wc, int fr, int fq) const {
;     ...
;                 if (u.ks >= 0) store_pair((bf16_t*)yp + ((size_t)u.ks * MS + (rowg - MP) + ai * HALF + m * 16) * DM + colw, DM, fr, fq, pk[0], pk[1]);
;                 else {
;                     store_pair(Y + (size_t)(rowg + ai * HALF + m * 16) * DM + colw, DM, fr, fq, pk[0], pk[1]);
.LBB0_1624:
	s_mov_b32 s63, s81
	s_lshl_b64 s[0:1], s[62:63], 22
	s_lshl_b64 s[22:23], s[40:41], 12
	s_add_u32 s0, s88, s0
	s_addc_u32 s1, s89, s1
	s_add_u32 s14, s0, s22
	s_addc_u32 s21, s1, s23
	s_lshl_b64 s[0:1], s[82:83], 1
	s_add_u32 s0, s14, s0
	s_addc_u32 s1, s21, s1
	v_lshl_add_u64 v[10:11], s[0:1], 0, v[130:131]
	v_mov_b32_e32 v151, v131
	v_lshl_add_u64 v[10:11], v[10:11], 0, v[150:151]
	v_mov_b32_e32 v149, v131
	v_mov_b32_e32 v6, v131
	v_mov_b32_e32 v7, v131
	v_mov_b32_e32 v8, v131
	v_mov_b32_e32 v9, v131
	v_lshl_add_u64 v[10:11], v[10:11], 0, v[148:149]
	v_mov_b32_dpp v6, v29 row_ror:8 row_mask:0xf bank_mask:0xf
	v_mov_b32_dpp v7, v28 row_ror:8 row_mask:0xf bank_mask:0xf
	v_mov_b32_dpp v8, v27 row_ror:8 row_mask:0xf bank_mask:0xf
	v_mov_b32_dpp v9, v26 row_ror:8 row_mask:0xf bank_mask:0xf
	v_add_co_u32_e32 v12, vcc, 0xb0000, v10
	v_cndmask_b32_e64 v2, v6, v18, s[52:53]
	s_waitcnt lgkmcnt(0)
	v_cndmask_b32_e64 v3, v7, v19, s[52:53]
	v_cndmask_b32_e64 v4, v8, v20, s[52:53]
	v_cndmask_b32_e64 v5, v9, v21, s[52:53]
	v_addc_co_u32_e32 v13, vcc, 0, v11, vcc
	global_store_dwordx4 v[12:13], v[2:5], off sc1
	v_cndmask_b32_e64 v6, v22, v6, s[52:53]
	v_cndmask_b32_e64 v7, v23, v7, s[52:53]
	v_add_co_u32_e32 v2, vcc, 0xb8000, v10
	v_cndmask_b32_e64 v8, v24, v8, s[52:53]
	v_cndmask_b32_e64 v9, v25, v9, s[52:53]
	v_addc_co_u32_e32 v3, vcc, 0, v11, vcc
	global_store_dwordx4 v[2:3], v[6:9], off sc1
